# indexer score pass: kh=1 k_idx fragment loads issued one block early into their own registers
# speedup vs baseline: 1.0055x; 1.0055x over previous
; #define LAS __attribute__((address_space(3)))
; __device__ __forceinline__ unsigned fkey(float f) { const unsigned u = __float_as_uint(f); return (u & 0x80000000u) ? ~u : (u | 0x80000000u); }
; #define SEL_HADD(idx_) __hip_atomic_fetch_add(&hist[(idx_)], 1u, __ATOMIC_RELAXED, __HIP_MEMORY_SCOPE_WORKGROUP)
; __device__ __forceinline__ void sel_unit(LAS char* lds, int b, int u, const bf16_t* QI, const bf16_t* KIDX, const float* WIDX, unsigned long long* MASK) {
;     ...
;     const int nj = (c - wid + 8) >> 3;
;     u32x4 sc[8][4];
; #pragma unroll
;     for (int j = 0; j < 8; ++j) {
;         if (j < nj) {
;             int t = wid + 8 * j; asm volatile("" : "+s"(t));
; #pragma unroll
;             for (int kh = 0; kh < 2; ++kh) {
;             bf16x8 kf[2][2];
; #pragma unroll
;             for (int kb = 0; kb < 2; ++kb)
; #pragma unroll
;                 for (int ks = 0; ks < 2; ++ks) kf[kb][ks] = *(const bf16x8*)(KIDX + (rowbase + 64 * t + 32 * kh + 16 * kb + q16) * 64 + 32 * ks + 8 * kg);
; #pragma unroll
;             for (int kb = 0; kb < 2; ++kb) {
;                 f32x4 s = (f32x4){0.f, 0.f, 0.f, 0.f};
; #pragma unroll
;                 for (int hh = 0; hh < 8; ++hh) {
;                     f32x4 a = (f32x4){0.f, 0.f, 0.f, 0.f};
; #pragma unroll
;                     for (int ks = 0; ks < 2; ++ks) {
;                         const bf16x8 qv = *(const LAS bf16x8*)(lds + L_QI + q16 * 1024 + (((hh * 8 + 4 * ks + kg) ^ q16) << 4));
;                         a = __builtin_amdgcn_mfma_f32_16x16x32_bf16(kf[kb][ks], qv, a, 0, 0, 0);
;                     }
;                     const float wh = wl[hh * 16];
; #pragma unroll
;                     for (int i = 0; i < 4; ++i) s[i] += wh * fmaxf(a[i], 0.f);
;                 }
;                 u32x4 kk; kk.x = fkey(s[0]); kk.y = fkey(s[1]); kk.z = fkey(s[2]); kk.w = fkey(s[3]);
;                 sc[j][2 * kh + kb] = kk;
; #pragma unroll
;                 for (int i = 0; i < 4; ++i) SEL_HADD((kk[i] >> 24) * 16 + q16);
;                 __builtin_amdgcn_sched_barrier(0);
.LBB0_656:
	s_or_b64 exec, exec, s[2:3]
	s_ashr_i32 s46, s47, 6
	s_sub_i32 s2, s34, s46
	s_add_i32 s2, s2, 8
	s_ashr_i32 s4, s2, 3
	v_bfe_u32 v2, v2, 4, 2
	v_lshl_add_u32 v60, v59, 2, 0
	v_or_b32_e32 v18, s0, v59
	s_movk_i32 s0, 0x3fc
	s_cmp_gt_i32 s4, 0
	v_lshlrev_b32_e32 v0, 4, v2
	v_mad_u32_u24 v150, v59, s0, v60
	s_movk_i32 s0, 0xfc04
	s_cselect_b64 s[22:23], -1, 0
	v_mov_b32_e32 v19, s1
	v_lshl_add_u64 v[20:21], s[62:63], 0, v[0:1]
	v_mad_i32_i24 v0, v59, s0, v150
	s_and_b64 vcc, exec, s[22:23]
	v_xor_b32_e32 v182, v2, v59
	v_bitop3_b32 v183, v2, v59, 4 bitop3:0x36
	v_add_u32_e32 v137, 0x8800, v60
	v_bitop3_b32 v184, v2, v59, 8 bitop3:0x36
	v_bitop3_b32 v185, v2, v59, 12 bitop3:0x36
	v_bitop3_b32 v179, v2, v59, 16 bitop3:0x36
	v_bitop3_b32 v180, v2, v59, 20 bitop3:0x36
	v_bitop3_b32 v176, v2, v59, 24 bitop3:0x36
	v_bitop3_b32 v159, v2, v59, 28 bitop3:0x36
	v_bitop3_b32 v158, v2, v59, 32 bitop3:0x36
	v_bitop3_b32 v157, v2, v59, 36 bitop3:0x36
	v_bitop3_b32 v156, v2, v59, 40 bitop3:0x36
	v_bitop3_b32 v155, v2, v59, 44 bitop3:0x36
	v_bitop3_b32 v154, v2, v59, 48 bitop3:0x36
	v_bitop3_b32 v153, v2, v59, 52 bitop3:0x36
	v_bitop3_b32 v152, v2, v59, 56 bitop3:0x36
	v_bitop3_b32 v151, v2, v59, 60 bitop3:0x36
	s_waitcnt lgkmcnt(0)
	s_barrier
	s_cbranch_vccz .LBB0_658
	s_mov_b32 s0, s46
	s_lshl_b32 s0, s0, 6
	s_ashr_i32 s1, s0, 31
	v_lshl_add_u64 v[2:3], v[18:19], 0, s[0:1]
	v_lshlrev_b64 v[2:3], 7, v[2:3]
	v_lshl_add_u64 v[22:23], v[20:21], 0, v[2:3]
	global_load_dwordx4 v[14:17], v[22:23], off
	global_load_dwordx4 v[10:13], v[22:23], off offset:64
	v_lshl_add_u32 v88, v182, 4, v150
	v_lshl_add_u32 v87, v183, 4, v150
	v_lshl_add_u32 v85, v185, 4, v150
	v_lshl_add_u32 v83, v180, 4, v150
	v_lshl_add_u32 v82, v159, 4, v150
	v_lshl_add_u32 v86, v184, 4, v150
	ds_read_b128 v[2:5], v88
	v_lshl_add_u32 v84, v179, 4, v150
	ds_read_b128 v[6:9], v87
	ds_read_b128 v[24:27], v86
	v_lshl_add_u32 v81, v176, 4, v150
	ds_read_b128 v[28:31], v85
	ds_read_b128 v[32:35], v84
	ds_read_b128 v[36:39], v83
	ds_read_b128 v[40:43], v81
	v_lshl_add_u32 v80, v158, 4, v150
	ds_read_b128 v[44:47], v82
	ds_read_b128 v[48:51], v80
	v_lshl_add_u32 v79, v157, 4, v150
	ds_read_b128 v[52:55], v79
	v_lshl_add_u32 v76, v156, 4, v150
	v_lshl_add_u32 v75, v155, 4, v150
	ds_read_b128 v[62:65], v76
	ds_read_b128 v[66:69], v75
	v_lshl_add_u32 v78, v154, 4, v150
	v_lshl_add_u32 v77, v153, 4, v150
	v_lshl_add_u32 v74, v152, 4, v150
	s_waitcnt vmcnt(1) lgkmcnt(11)
	v_mfma_f32_16x16x32_bf16 v[2:5], v[14:17], v[2:5], 0
	s_waitcnt lgkmcnt(9)
	v_mfma_f32_16x16x32_bf16 v[24:27], v[14:17], v[24:27], 0
	s_waitcnt lgkmcnt(7)
	v_mfma_f32_16x16x32_bf16 v[32:35], v[14:17], v[32:35], 0
	s_waitcnt lgkmcnt(5)
	v_mfma_f32_16x16x32_bf16 v[40:43], v[14:17], v[40:43], 0
	s_waitcnt lgkmcnt(3)
	v_mfma_f32_16x16x32_bf16 v[48:51], v[14:17], v[48:51], 0
	s_waitcnt vmcnt(0)
	v_mfma_f32_16x16x32_bf16 v[70:73], v[10:13], v[6:9], v[2:5]
	v_mfma_f32_16x16x32_bf16 v[24:27], v[10:13], v[28:31], v[24:27]
	v_mfma_f32_16x16x32_bf16 v[28:31], v[10:13], v[36:39], v[32:35]
	v_mfma_f32_16x16x32_bf16 v[32:35], v[10:13], v[44:47], v[40:43]
	ds_read2_b32 v[44:45], v137 offset0:80 offset1:96
	ds_read2_b32 v[46:47], v137 offset0:112 offset1:128
	s_nop 3
	s_waitcnt lgkmcnt(4)
	v_mfma_f32_16x16x32_bf16 v[36:39], v[10:13], v[52:55], v[48:51]
	s_nop 0
	ds_read2_b32 v[48:49], v137 offset0:144 offset1:160
	global_load_dwordx4 v[6:9], v[22:23], off offset:2048
	global_load_dwordx4 v[2:5], v[22:23], off offset:2112
	v_mov_b32_e32 v252, 0x1000
	v_mov_b32_e32 v253, 0
	v_lshl_add_u64 v[252:253], v[252:253], 0, v[22:23]
	global_load_dwordx4 v[236:239], v[252:253], off
	global_load_dwordx4 v[240:243], v[252:253], off offset:64
	global_load_dwordx4 v[244:247], v[252:253], off offset:2048
	global_load_dwordx4 v[248:251], v[252:253], off offset:2112
	s_waitcnt lgkmcnt(4)
	v_mfma_f32_16x16x32_bf16 v[62:65], v[14:17], v[62:65], 0
	s_nop 0
	v_max_f32_e32 v54, v24, v24
	s_nop 0
	s_waitcnt lgkmcnt(3)
	v_mfma_f32_16x16x32_bf16 v[40:43], v[10:13], v[66:69], v[62:65]
	v_max_f32_e32 v61, v39, v39
	v_max_f32_e32 v24, 0, v73
	v_max_f32_e32 v39, 0, v25
	v_max_f32_e32 v64, 0, v26
	v_max_f32_e32 v25, 0, v27
	v_max_f32_e32 v26, 0, v31
	v_max_f32_e32 v27, 0, v35
	v_max_f32_e32 v50, v70, v70
	v_max_f32_e32 v51, v71, v71
	v_max_f32_e32 v53, 0, v37
	s_waitcnt lgkmcnt(2)
	v_mul_f32_e32 v56, v45, v64
	v_pk_mul_f32 v[64:65], v[44:45], v[24:25]
	s_waitcnt lgkmcnt(1)
	v_pk_mul_f32 v[70:71], v[46:47], v[26:27]
	ds_read_b128 v[24:27], v78
	v_max_f32_e32 v62, v40, v40
	v_max_f32_e32 v40, 0, v28
	v_max_f32_e32 v28, 0, v30
	v_max_f32_e32 v63, v41, v41
	v_max_f32_e32 v41, 0, v29
	v_max_f32_e32 v29, 0, v34
	v_max_f32_e32 v30, 0, v38
	v_mul_f32_e32 v66, v46, v28
	v_max_f32_e32 v28, 0, v42
	v_mul_f32_e32 v68, v47, v29
	s_waitcnt lgkmcnt(1)
	v_mul_f32_e32 v90, v48, v30
	v_mul_f32_e32 v92, v49, v28
	ds_read_b128 v[28:31], v77
	s_waitcnt lgkmcnt(1)
	v_mfma_f32_16x16x32_bf16 v[24:27], v[14:17], v[24:27], 0
	v_max_f32_e32 v37, 0, v51
	s_waitcnt lgkmcnt(0)
	v_mfma_f32_16x16x32_bf16 v[24:27], v[10:13], v[28:31], v[24:27]
	ds_read_b128 v[28:31], v74
	v_max_f32_e32 v51, 0, v33
	v_max_f32_e32 v55, v36, v36
	v_max_f32_e32 v36, 0, v50
	v_max_f32_e32 v50, 0, v32
	v_max_f32_e32 v32, 0, v61
	v_max_f32_e32 v33, 0, v43
	v_lshl_add_u32 v73, v151, 4, v150
	v_pk_mul_f32 v[94:95], v[48:49], v[32:33]
	ds_read_b128 v[32:35], v73
	s_waitcnt lgkmcnt(1)
	v_mfma_f32_16x16x32_bf16 v[14:17], v[14:17], v[28:31], 0
	s_nop 0
	v_max_f32_e32 v42, 0, v72
	v_max_f32_e32 v38, 0, v54
	s_waitcnt lgkmcnt(0)
; #define LAS __attribute__((address_space(3)))
; __device__ __forceinline__ unsigned fkey(float f) { const unsigned u = __float_as_uint(f); return (u & 0x80000000u) ? ~u : (u | 0x80000000u); }
; #define SEL_HADD(idx_) __hip_atomic_fetch_add(&hist[(idx_)], 1u, __ATOMIC_RELAXED, __HIP_MEMORY_SCOPE_WORKGROUP)
; __device__ __forceinline__ void sel_unit(LAS char* lds, int b, int u, const bf16_t* QI, const bf16_t* KIDX, const float* WIDX, unsigned long long* MASK) {
;     ...
;                 for (int ks = 0; ks < 2; ++ks) kf[kb][ks] = *(const bf16x8*)(KIDX + (rowbase + 64 * t + 32 * kh + 16 * kb + q16) * 64 + 32 * ks + 8 * kg);
; #pragma unroll
;             for (int kb = 0; kb < 2; ++kb) {
;                 f32x4 s = (f32x4){0.f, 0.f, 0.f, 0.f};
; #pragma unroll
;                 for (int hh = 0; hh < 8; ++hh) {
;                     f32x4 a = (f32x4){0.f, 0.f, 0.f, 0.f};
; #pragma unroll
;                     for (int ks = 0; ks < 2; ++ks) {
;                         const bf16x8 qv = *(const LAS bf16x8*)(lds + L_QI + q16 * 1024 + (((hh * 8 + 4 * ks + kg) ^ q16) << 4));
;                         a = __builtin_amdgcn_mfma_f32_16x16x32_bf16(kf[kb][ks], qv, a, 0, 0, 0);
;                     }
;                     const float wh = wl[hh * 16];
; #pragma unroll
;                     for (int i = 0; i < 4; ++i) s[i] += wh * fmaxf(a[i], 0.f);
;                 }
;                 u32x4 kk; kk.x = fkey(s[0]); kk.y = fkey(s[1]); kk.z = fkey(s[2]); kk.w = fkey(s[3]);
;                 sc[j][2 * kh + kb] = kk;
; #pragma unroll
;                 for (int i = 0; i < 4; ++i) SEL_HADD((kk[i] >> 24) * 16 + q16);
;                 __builtin_amdgcn_sched_barrier(0);
	v_mfma_f32_16x16x32_bf16 v[10:13], v[10:13], v[32:35], v[14:17]
	v_max_f32_e32 v52, 0, v55
	v_max_f32_e32 v54, 0, v62
	v_max_f32_e32 v55, 0, v63
	ds_read2_b32 v[62:63], v137 offset0:176 offset1:192
	s_nop 0
	s_nop 2
	v_max_f32_e32 v28, 0, v27
	v_max_f32_e32 v29, 0, v13
	s_waitcnt lgkmcnt(0)
	v_pk_mul_f32 v[14:15], v[62:63], v[28:29]
	v_pk_fma_f32 v[16:17], v[44:45], v[36:37], 0 op_sel_hi:[0,1,0]
	v_mov_b32_e32 v28, v45
	v_pk_fma_f32 v[16:17], v[28:29], v[38:39], v[16:17] op_sel_hi:[0,1,1]
	v_pk_fma_f32 v[16:17], v[46:47], v[40:41], v[16:17] op_sel_hi:[0,1,1]
	v_mov_b32_e32 v28, v47
	v_pk_fma_f32 v[16:17], v[28:29], v[50:51], v[16:17] op_sel_hi:[0,1,1]
	v_pk_fma_f32 v[16:17], v[48:49], v[52:53], v[16:17] op_sel_hi:[0,1,1]
	v_mov_b32_e32 v28, v49
	v_max_f32_e32 v24, 0, v24
	v_max_f32_e32 v25, 0, v25
	v_pk_fma_f32 v[16:17], v[28:29], v[54:55], v[16:17] op_sel_hi:[0,1,1]
	v_max_f32_e32 v10, 0, v10
	v_max_f32_e32 v11, 0, v11
	v_pk_fma_f32 v[16:17], v[62:63], v[24:25], v[16:17] op_sel_hi:[0,1,1]
	v_mov_b32_e32 v24, v63
	v_pk_fma_f32 v[10:11], v[24:25], v[10:11], v[16:17] op_sel_hi:[0,1,1]
	v_and_b32_e32 v17, 0x7fffffff, v11
	v_and_b32_e32 v16, 0x7fffffff, v10
	v_mul_f32_e32 v42, v44, v42
	v_xor_b32_e32 v13, -1, v11
	v_pk_add_f32 v[16:17], v[16:17], 0 neg_lo:[1,1] neg_hi:[1,1]
	v_cmp_gt_i32_e32 vcc, 0, v11
	v_mov_b32_e32 v43, v64
	v_xor_b32_e32 v24, -1, v10
	v_cndmask_b32_e32 v61, v17, v13, vcc
	v_cmp_gt_i32_e32 vcc, 0, v10
	v_pk_add_f32 v[10:11], v[42:43], 0 op_sel_hi:[1,0]
	v_mov_b32_e32 v57, v65
	v_pk_add_f32 v[10:11], v[10:11], v[56:57]
	v_mov_b32_e32 v67, v70
	v_pk_add_f32 v[10:11], v[10:11], v[66:67]
	v_mov_b32_e32 v69, v71
	v_pk_add_f32 v[10:11], v[10:11], v[68:69]
	v_mov_b32_e32 v91, v94
	v_max_f32_e32 v26, 0, v26
	v_pk_add_f32 v[10:11], v[10:11], v[90:91]
	v_mov_b32_e32 v93, v95
	v_mul_f32_e32 v26, v62, v26
	v_max_f32_e32 v12, 0, v12
	v_pk_add_f32 v[10:11], v[10:11], v[92:93]
	v_mov_b32_e32 v27, v14
	v_mul_f32_e32 v12, v63, v12
	v_pk_add_f32 v[10:11], v[10:11], v[26:27]
	v_mov_b32_e32 v13, v15
	v_pk_add_f32 v[10:11], v[10:11], v[12:13]
	v_cndmask_b32_e32 v62, v16, v24, vcc
	v_and_b32_e32 v13, 0x7fffffff, v11
	v_and_b32_e32 v12, 0x7fffffff, v10
	v_xor_b32_e32 v14, -1, v11
	v_pk_add_f32 v[12:13], v[12:13], 0 neg_lo:[1,1] neg_hi:[1,1]
	v_cmp_gt_i32_e32 vcc, 0, v11
	v_xor_b32_e32 v15, -1, v10
	s_nop 0
	v_cndmask_b32_e32 v63, v13, v14, vcc
	v_cmp_gt_i32_e32 vcc, 0, v10
	v_lshrrev_b32_e32 v10, 24, v62
	v_lshl_add_u32 v10, v10, 6, v0
	ds_add_u32 v10, v205 offset:16384
	v_lshrrev_b32_e32 v10, 24, v61
	v_cndmask_b32_e32 v64, v12, v15, vcc
	v_lshl_add_u32 v10, v10, 6, v0
	ds_add_u32 v10, v205 offset:16384
	v_lshrrev_b32_e32 v10, 24, v64
	v_lshl_add_u32 v10, v10, 6, v0
	ds_add_u32 v10, v205 offset:16384
	v_lshrrev_b32_e32 v10, 24, v63
	v_lshl_add_u32 v10, v10, 6, v0
	ds_add_u32 v10, v205 offset:16384
	ds_read_b128 v[10:13], v88
	ds_read_b128 v[14:17], v87
	ds_read_b128 v[24:27], v86
	ds_read_b128 v[28:31], v85
	ds_read2_b32 v[32:33], v137 offset0:80 offset1:96
	ds_read2_b32 v[40:41], v137 offset0:112 offset1:128
	s_waitcnt vmcnt(5) lgkmcnt(5)
	v_mfma_f32_16x16x32_bf16 v[10:13], v[6:9], v[10:13], 0
	ds_read2_b32 v[52:53], v137 offset0:144 offset1:160
	s_waitcnt vmcnt(4) lgkmcnt(5)
	v_mfma_f32_16x16x32_bf16 v[10:13], v[2:5], v[14:17], v[10:13]
	ds_read_b128 v[14:17], v84
	s_waitcnt lgkmcnt(5)
	v_mfma_f32_16x16x32_bf16 v[24:27], v[6:9], v[24:27], 0
	s_nop 4
	v_max_f32_e32 v34, 0, v10
	v_max_f32_e32 v10, 0, v12
	v_max_f32_e32 v35, 0, v11
	s_waitcnt lgkmcnt(3)
	v_mul_f32_e32 v36, v32, v10
	v_max_f32_e32 v38, 0, v13
	v_mfma_f32_16x16x32_bf16 v[10:13], v[2:5], v[28:31], v[24:27]
	s_nop 2
	ds_read_b128 v[24:27], v83
	s_waitcnt lgkmcnt(1)
	v_mfma_f32_16x16x32_bf16 v[14:17], v[6:9], v[14:17], 0
	s_nop 1
	v_max_f32_e32 v28, 0, v10
	v_max_f32_e32 v29, 0, v11
	v_max_f32_e32 v10, 0, v12
	v_mul_f32_e32 v30, v33, v10
	v_max_f32_e32 v39, 0, v13
	s_waitcnt lgkmcnt(0)
	v_mfma_f32_16x16x32_bf16 v[10:13], v[2:5], v[24:27], v[14:17]
	ds_read_b128 v[24:27], v82
	v_pk_mul_f32 v[38:39], v[32:33], v[38:39]
	s_nop 0
	ds_read_b128 v[14:17], v81
	s_waitcnt lgkmcnt(0)
	v_mfma_f32_16x16x32_bf16 v[14:17], v[6:9], v[14:17], 0
	s_nop 1
	v_max_f32_e32 v42, 0, v10
	v_max_f32_e32 v43, 0, v11
	v_max_f32_e32 v10, 0, v12
	v_mul_f32_e32 v44, v40, v10
	s_nop 0
	v_max_f32_e32 v46, 0, v13
	v_mfma_f32_16x16x32_bf16 v[10:13], v[2:5], v[24:27], v[14:17]
	ds_read_b128 v[24:27], v79
	v_mov_b32_e32 v37, v38
	v_mov_b32_e32 v31, v39
	ds_read_b128 v[14:17], v80
	s_waitcnt lgkmcnt(0)
	v_mfma_f32_16x16x32_bf16 v[14:17], v[6:9], v[14:17], 0
	s_nop 1
	v_max_f32_e32 v48, 0, v10
	v_max_f32_e32 v49, 0, v11
	v_max_f32_e32 v10, 0, v12
	v_mul_f32_e32 v50, v41, v10
	s_nop 0
	v_max_f32_e32 v47, 0, v13
	v_mfma_f32_16x16x32_bf16 v[10:13], v[2:5], v[24:27], v[14:17]
	ds_read_b128 v[24:27], v75
	v_pk_mul_f32 v[46:47], v[40:41], v[46:47]
	s_nop 0
	ds_read_b128 v[14:17], v76
	s_waitcnt lgkmcnt(0)
	v_mfma_f32_16x16x32_bf16 v[14:17], v[6:9], v[14:17], 0
	s_nop 1
	v_max_f32_e32 v54, 0, v10
	v_max_f32_e32 v55, 0, v11
	v_max_f32_e32 v10, 0, v12
	v_mul_f32_e32 v56, v52, v10
	s_nop 0
	v_max_f32_e32 v66, 0, v13
	v_mfma_f32_16x16x32_bf16 v[10:13], v[2:5], v[24:27], v[14:17]
	ds_read_b128 v[24:27], v77
	v_mov_b32_e32 v45, v46
	v_mov_b32_e32 v51, v47
	ds_read_b128 v[14:17], v78
	s_waitcnt lgkmcnt(0)
	v_mfma_f32_16x16x32_bf16 v[14:17], v[6:9], v[14:17], 0
	s_nop 1
	v_max_f32_e32 v68, 0, v10
	v_max_f32_e32 v69, 0, v11
	v_max_f32_e32 v10, 0, v12
	v_mul_f32_e32 v70, v53, v10
	s_nop 0
	v_max_f32_e32 v67, 0, v13
	v_mfma_f32_16x16x32_bf16 v[10:13], v[2:5], v[24:27], v[14:17]
	ds_read_b128 v[24:27], v73
	v_pk_mul_f32 v[90:91], v[52:53], v[66:67]
	ds_read2_b32 v[66:67], v137 offset0:176 offset1:192
	ds_read_b128 v[14:17], v74
	s_waitcnt lgkmcnt(0)
; #define LAS __attribute__((address_space(3)))
; __device__ __forceinline__ unsigned fkey(float f) { const unsigned u = __float_as_uint(f); return (u & 0x80000000u) ? ~u : (u | 0x80000000u); }
; #define SEL_HADD(idx_) __hip_atomic_fetch_add(&hist[(idx_)], 1u, __ATOMIC_RELAXED, __HIP_MEMORY_SCOPE_WORKGROUP)
; __device__ __forceinline__ void sel_unit(LAS char* lds, int b, int u, const bf16_t* QI, const bf16_t* KIDX, const float* WIDX, unsigned long long* MASK) {
;     ...
;                 for (int ks = 0; ks < 2; ++ks) kf[kb][ks] = *(const bf16x8*)(KIDX + (rowbase + 64 * t + 32 * kh + 16 * kb + q16) * 64 + 32 * ks + 8 * kg);
; #pragma unroll
;             for (int kb = 0; kb < 2; ++kb) {
;                 f32x4 s = (f32x4){0.f, 0.f, 0.f, 0.f};
; #pragma unroll
;                 for (int hh = 0; hh < 8; ++hh) {
;                     f32x4 a = (f32x4){0.f, 0.f, 0.f, 0.f};
; #pragma unroll
;                     for (int ks = 0; ks < 2; ++ks) {
;                         const bf16x8 qv = *(const LAS bf16x8*)(lds + L_QI + q16 * 1024 + (((hh * 8 + 4 * ks + kg) ^ q16) << 4));
;                         a = __builtin_amdgcn_mfma_f32_16x16x32_bf16(kf[kb][ks], qv, a, 0, 0, 0);
;                     }
;                     const float wh = wl[hh * 16];
; #pragma unroll
;                     for (int i = 0; i < 4; ++i) s[i] += wh * fmaxf(a[i], 0.f);
;                 }
;                 u32x4 kk; kk.x = fkey(s[0]); kk.y = fkey(s[1]); kk.z = fkey(s[2]); kk.w = fkey(s[3]);
;                 sc[j][2 * kh + kb] = kk;
; #pragma unroll
;                 for (int i = 0; i < 4; ++i) SEL_HADD((kk[i] >> 24) * 16 + q16);
;                 __builtin_amdgcn_sched_barrier(0);
	v_mfma_f32_16x16x32_bf16 v[6:9], v[6:9], v[14:17], 0
	s_nop 1
	s_nop 0
	v_max_f32_e32 v14, 0, v13
	s_nop 0
	v_mfma_f32_16x16x32_bf16 v[2:5], v[2:5], v[24:27], v[6:9]
	s_nop 0
	v_max_f32_e32 v10, 0, v10
	v_max_f32_e32 v11, 0, v11
	v_pk_fma_f32 v[8:9], v[32:33], v[34:35], 0 op_sel_hi:[0,1,0]
	s_nop 0
	s_nop 2
	v_max_f32_e32 v15, 0, v5
	v_pk_mul_f32 v[6:7], v[66:67], v[14:15]
	v_mov_b32_e32 v14, v33
	v_pk_fma_f32 v[8:9], v[14:15], v[28:29], v[8:9] op_sel_hi:[0,1,1]
	v_pk_fma_f32 v[8:9], v[40:41], v[42:43], v[8:9] op_sel_hi:[0,1,1]
	v_mov_b32_e32 v14, v41
	v_pk_fma_f32 v[8:9], v[14:15], v[48:49], v[8:9] op_sel_hi:[0,1,1]
	v_pk_fma_f32 v[8:9], v[52:53], v[54:55], v[8:9] op_sel_hi:[0,1,1]
	v_mov_b32_e32 v14, v53
	v_pk_fma_f32 v[8:9], v[14:15], v[68:69], v[8:9] op_sel_hi:[0,1,1]
	v_max_f32_e32 v2, 0, v2
	v_max_f32_e32 v3, 0, v3
	v_pk_fma_f32 v[8:9], v[66:67], v[10:11], v[8:9] op_sel_hi:[0,1,1]
	v_mov_b32_e32 v10, v67
	v_pk_fma_f32 v[2:3], v[10:11], v[2:3], v[8:9] op_sel_hi:[0,1,1]
	v_and_b32_e32 v9, 0x7fffffff, v3
	v_and_b32_e32 v8, 0x7fffffff, v2
	v_xor_b32_e32 v5, -1, v3
	v_pk_add_f32 v[8:9], v[8:9], 0 neg_lo:[1,1] neg_hi:[1,1]
	v_cmp_gt_i32_e32 vcc, 0, v3
	v_xor_b32_e32 v10, -1, v2
	v_mov_b32_e32 v57, v90
	v_cndmask_b32_e32 v65, v9, v5, vcc
	v_cmp_gt_i32_e32 vcc, 0, v2
	v_pk_add_f32 v[2:3], v[36:37], 0 op_sel_hi:[1,0]
	v_max_f32_e32 v12, 0, v12
	v_pk_add_f32 v[2:3], v[2:3], v[30:31]
	v_pk_add_f32 v[2:3], v[2:3], v[44:45]
	v_mov_b32_e32 v71, v91
	v_pk_add_f32 v[2:3], v[2:3], v[50:51]
	v_mul_f32_e32 v12, v66, v12
	v_pk_add_f32 v[2:3], v[2:3], v[56:57]
	v_max_f32_e32 v4, 0, v4
	v_pk_add_f32 v[2:3], v[2:3], v[70:71]
	v_mov_b32_e32 v13, v6
	v_mul_f32_e32 v4, v67, v4
	v_pk_add_f32 v[2:3], v[2:3], v[12:13]
	v_mov_b32_e32 v5, v7
	v_pk_add_f32 v[2:3], v[2:3], v[4:5]
	v_cndmask_b32_e32 v66, v8, v10, vcc
	v_and_b32_e32 v5, 0x7fffffff, v3
	v_and_b32_e32 v4, 0x7fffffff, v2
	v_xor_b32_e32 v6, -1, v3
	v_pk_add_f32 v[4:5], v[4:5], 0 neg_lo:[1,1] neg_hi:[1,1]
	v_cmp_gt_i32_e32 vcc, 0, v3
	v_xor_b32_e32 v7, -1, v2
	s_nop 0
	v_cndmask_b32_e32 v67, v5, v6, vcc
	v_cmp_gt_i32_e32 vcc, 0, v2
	v_lshrrev_b32_e32 v2, 24, v66
	v_lshl_add_u32 v2, v2, 6, v0
	ds_add_u32 v2, v205 offset:16384
	v_lshrrev_b32_e32 v2, 24, v65
	v_cndmask_b32_e32 v68, v4, v7, vcc
	v_lshl_add_u32 v2, v2, 6, v0
	ds_add_u32 v2, v205 offset:16384
	v_lshrrev_b32_e32 v2, 24, v68
	v_lshl_add_u32 v2, v2, 6, v0
	ds_add_u32 v2, v205 offset:16384
	v_lshrrev_b32_e32 v2, 24, v67
	v_lshl_add_u32 v2, v2, 6, v0
	ds_add_u32 v2, v205 offset:16384
	ds_read_b128 v[22:25], v88
	ds_read_b128 v[26:29], v87
	s_waitcnt vmcnt(3) lgkmcnt(1)
	v_mfma_f32_16x16x32_bf16 v[22:25], v[236:239], v[22:25], 0
	ds_read_b128 v[32:35], v85
	ds_read_b128 v[38:41], v83
	ds_read_b128 v[44:47], v82
	s_waitcnt vmcnt(2) lgkmcnt(3)
	v_mfma_f32_16x16x32_bf16 v[26:29], v[240:243], v[26:29], v[22:25]
	ds_read_b128 v[50:53], v79
	ds_read_b128 v[90:93], v75
	ds_read_b128 v[94:97], v77
	ds_read2_b32 v[24:25], v137 offset0:80 offset1:96
	s_nop 3
	v_max_f32_e32 v26, 0, v26
	v_max_f32_e32 v27, 0, v27
	v_max_f32_e32 v22, v28, v28
	v_max_f32_e32 v23, v29, v29
	ds_read_b128 v[28:31], v86
	s_waitcnt lgkmcnt(0)
	v_mfma_f32_16x16x32_bf16 v[28:31], v[236:239], v[28:31], 0
	v_max_f32_e32 v36, 0, v23
	v_max_f32_e32 v22, 0, v22
	v_mul_f32_e32 v22, v24, v22
	v_mfma_f32_16x16x32_bf16 v[28:31], v[240:243], v[32:35], v[28:31]
	s_nop 7
	v_max_f32_e32 v32, 0, v28
	v_max_f32_e32 v33, 0, v29
	v_max_f32_e32 v23, 0, v30
	v_mul_f32_e32 v28, v25, v23
	v_max_f32_e32 v37, 0, v31
	v_pk_mul_f32 v[30:31], v[24:25], v[36:37]
	ds_read_b128 v[34:37], v84
	s_waitcnt lgkmcnt(0)
	v_mfma_f32_16x16x32_bf16 v[34:37], v[236:239], v[34:37], 0
	v_mov_b32_e32 v29, v31
	v_mfma_f32_16x16x32_bf16 v[38:41], v[240:243], v[38:41], v[34:37]
	s_nop 5
	ds_read2_b32 v[36:37], v137 offset0:112 offset1:128
	s_nop 0
	v_max_f32_e32 v38, 0, v38
	v_max_f32_e32 v39, 0, v39
	v_max_f32_e32 v23, 0, v40
	s_waitcnt lgkmcnt(0)
	v_mul_f32_e32 v34, v36, v23
	v_max_f32_e32 v23, v41, v41
	ds_read_b128 v[40:43], v81
	s_waitcnt lgkmcnt(0)
	v_mfma_f32_16x16x32_bf16 v[40:43], v[236:239], v[40:43], 0
	v_max_f32_e32 v48, 0, v23
	v_mfma_f32_16x16x32_bf16 v[40:43], v[240:243], v[44:47], v[40:43]
	s_nop 7
	v_max_f32_e32 v44, 0, v40
	v_max_f32_e32 v45, 0, v41
	v_max_f32_e32 v23, 0, v42
	v_mul_f32_e32 v40, v37, v23
	v_max_f32_e32 v49, 0, v43
	v_pk_mul_f32 v[42:43], v[36:37], v[48:49]
	ds_read_b128 v[46:49], v80
	s_waitcnt lgkmcnt(0)
	v_mfma_f32_16x16x32_bf16 v[46:49], v[236:239], v[46:49], 0
	v_mov_b32_e32 v35, v42
	v_mov_b32_e32 v41, v43
	v_mfma_f32_16x16x32_bf16 v[50:53], v[240:243], v[50:53], v[46:49]
	s_nop 4
	ds_read2_b32 v[48:49], v137 offset0:144 offset1:160
	s_nop 1
	v_max_f32_e32 v50, 0, v50
	v_max_f32_e32 v51, 0, v51
	v_max_f32_e32 v23, 0, v52
	s_waitcnt lgkmcnt(0)
	v_mul_f32_e32 v46, v48, v23
	v_max_f32_e32 v23, v53, v53
	ds_read_b128 v[52:55], v76
	s_waitcnt lgkmcnt(0)
	v_mfma_f32_16x16x32_bf16 v[52:55], v[236:239], v[52:55], 0
	v_max_f32_e32 v70, 0, v23
	v_mfma_f32_16x16x32_bf16 v[52:55], v[240:243], v[90:93], v[52:55]
	ds_read_b128 v[90:93], v78
	s_waitcnt lgkmcnt(0)
	v_mfma_f32_16x16x32_bf16 v[90:93], v[236:239], v[90:93], 0
	s_nop 4
	v_max_f32_e32 v56, 0, v52
	v_max_f32_e32 v57, 0, v53
	v_max_f32_e32 v23, 0, v54
	v_mfma_f32_16x16x32_bf16 v[90:93], v[240:243], v[94:97], v[90:93]
	v_mul_f32_e32 v52, v49, v23
	s_nop 0
	v_max_f32_e32 v71, 0, v55
	v_pk_mul_f32 v[54:55], v[48:49], v[70:71]
	ds_read2_b32 v[70:71], v137 offset0:176 offset1:192
	s_nop 2
	v_max_f32_e32 v94, 0, v90
	v_max_f32_e32 v95, 0, v91
	v_max_f32_e32 v23, 0, v92
	s_waitcnt lgkmcnt(0)
	v_mul_f32_e32 v96, v70, v23
	v_max_f32_e32 v23, v93, v93
	ds_read_b128 v[90:93], v74
	s_waitcnt lgkmcnt(0)
; #define LAS __attribute__((address_space(3)))
; __device__ __forceinline__ unsigned fkey(float f) { const unsigned u = __float_as_uint(f); return (u & 0x80000000u) ? ~u : (u | 0x80000000u); }
; #define SEL_HADD(idx_) __hip_atomic_fetch_add(&hist[(idx_)], 1u, __ATOMIC_RELAXED, __HIP_MEMORY_SCOPE_WORKGROUP)
; __device__ __forceinline__ void sel_unit(LAS char* lds, int b, int u, const bf16_t* QI, const bf16_t* KIDX, const float* WIDX, unsigned long long* MASK) {
;     ...
;                 for (int ks = 0; ks < 2; ++ks) kf[kb][ks] = *(const bf16x8*)(KIDX + (rowbase + 64 * t + 32 * kh + 16 * kb + q16) * 64 + 32 * ks + 8 * kg);
; #pragma unroll
;             for (int kb = 0; kb < 2; ++kb) {
;                 f32x4 s = (f32x4){0.f, 0.f, 0.f, 0.f};
; #pragma unroll
;                 for (int hh = 0; hh < 8; ++hh) {
;                     f32x4 a = (f32x4){0.f, 0.f, 0.f, 0.f};
; #pragma unroll
;                     for (int ks = 0; ks < 2; ++ks) {
;                         const bf16x8 qv = *(const LAS bf16x8*)(lds + L_QI + q16 * 1024 + (((hh * 8 + 4 * ks + kg) ^ q16) << 4));
;                         a = __builtin_amdgcn_mfma_f32_16x16x32_bf16(kf[kb][ks], qv, a, 0, 0, 0);
;                     }
;                     const float wh = wl[hh * 16];
; #pragma unroll
;                     for (int i = 0; i < 4; ++i) s[i] += wh * fmaxf(a[i], 0.f);
;                 }
;                 u32x4 kk; kk.x = fkey(s[0]); kk.y = fkey(s[1]); kk.z = fkey(s[2]); kk.w = fkey(s[3]);
;                 sc[j][2 * kh + kb] = kk;
; #pragma unroll
;                 for (int i = 0; i < 4; ++i) SEL_HADD((kk[i] >> 24) * 16 + q16);
;                 __builtin_amdgcn_sched_barrier(0);
	v_mfma_f32_16x16x32_bf16 v[14:17], v[236:239], v[90:93], 0
	ds_read_b128 v[90:93], v73
	v_max_f32_e32 v98, 0, v23
	v_mov_b32_e32 v47, v54
	s_waitcnt lgkmcnt(0)
	v_mfma_f32_16x16x32_bf16 v[10:13], v[240:243], v[90:93], v[14:17]
	v_mov_b32_e32 v53, v55
	s_nop 1
	v_pk_fma_f32 v[16:17], v[24:25], v[26:27], 0 op_sel_hi:[0,1,0]
	v_mov_b32_e32 v24, v25
	v_pk_fma_f32 v[16:17], v[24:25], v[32:33], v[16:17] op_sel_hi:[0,1,1]
	v_pk_fma_f32 v[16:17], v[36:37], v[38:39], v[16:17] op_sel_hi:[0,1,1]
	v_mov_b32_e32 v24, v37
	v_pk_fma_f32 v[16:17], v[24:25], v[44:45], v[16:17] op_sel_hi:[0,1,1]
	v_pk_fma_f32 v[16:17], v[48:49], v[50:51], v[16:17] op_sel_hi:[0,1,1]
	v_mov_b32_e32 v24, v49
	v_pk_fma_f32 v[16:17], v[24:25], v[56:57], v[16:17] op_sel_hi:[0,1,1]
	v_max_f32_e32 v10, 0, v10
	v_max_f32_e32 v11, 0, v11
	v_pk_fma_f32 v[16:17], v[70:71], v[94:95], v[16:17] op_sel_hi:[0,1,1]
	v_mov_b32_e32 v24, v71
	v_pk_fma_f32 v[10:11], v[24:25], v[10:11], v[16:17] op_sel_hi:[0,1,1]
	v_and_b32_e32 v17, 0x7fffffff, v11
	v_and_b32_e32 v16, 0x7fffffff, v10
	v_max_f32_e32 v99, 0, v13
	v_xor_b32_e32 v23, -1, v10
	v_pk_add_f32 v[16:17], v[16:17], 0 neg_lo:[1,1] neg_hi:[1,1]
	v_cmp_gt_i32_e32 vcc, 0, v10
	v_pk_mul_f32 v[14:15], v[70:71], v[98:99]
	v_xor_b32_e32 v13, -1, v11
	v_cndmask_b32_e32 v70, v16, v23, vcc
	v_mov_b32_e32 v23, v30
	v_cmp_gt_i32_e64 s[2:3], 0, v11
	v_pk_add_f32 v[10:11], v[22:23], 0 op_sel_hi:[1,0]
	v_pk_add_f32 v[10:11], v[10:11], v[28:29]
	v_max_f32_e32 v12, 0, v12
	v_pk_add_f32 v[10:11], v[10:11], v[34:35]
	v_mov_b32_e32 v97, v14
	v_pk_add_f32 v[10:11], v[10:11], v[40:41]
	v_mul_f32_e32 v12, v71, v12
	v_pk_add_f32 v[10:11], v[10:11], v[46:47]
	v_cndmask_b32_e64 v69, v17, v13, s[2:3]
	v_pk_add_f32 v[10:11], v[10:11], v[52:53]
	v_mov_b32_e32 v13, v15
	v_pk_add_f32 v[10:11], v[10:11], v[96:97]
	s_nop 0
	v_pk_add_f32 v[10:11], v[10:11], v[12:13]
	s_nop 0
	v_xor_b32_e32 v15, -1, v10
	v_and_b32_e32 v12, 0x7fffffff, v10
	v_cmp_gt_i32_e32 vcc, 0, v10
	v_lshrrev_b32_e32 v10, 24, v70
	v_and_b32_e32 v13, 0x7fffffff, v11
	v_lshl_add_u32 v10, v10, 6, v0
	v_pk_add_f32 v[12:13], v[12:13], 0 neg_lo:[1,1] neg_hi:[1,1]
	ds_add_u32 v10, v205 offset:16384
	v_lshrrev_b32_e32 v10, 24, v69
	v_cndmask_b32_e32 v72, v12, v15, vcc
	v_lshl_add_u32 v10, v10, 6, v0
	v_xor_b32_e32 v14, -1, v11
	v_cmp_gt_i32_e64 s[2:3], 0, v11
	ds_add_u32 v10, v205 offset:16384
	v_lshrrev_b32_e32 v10, 24, v72
	v_cndmask_b32_e64 v71, v13, v14, s[2:3]
	v_lshl_add_u32 v10, v10, 6, v0
	ds_add_u32 v10, v205 offset:16384
	v_lshrrev_b32_e32 v10, 24, v71
	v_lshl_add_u32 v10, v10, 6, v0
	ds_add_u32 v10, v205 offset:16384
	ds_read_b128 v[10:13], v88
	ds_read_b128 v[14:17], v87
	ds_read_b128 v[22:25], v86
	ds_read_b128 v[26:29], v85
	ds_read2_b32 v[48:49], v137 offset0:144 offset1:160
	s_waitcnt vmcnt(1) lgkmcnt(4)
	v_mfma_f32_16x16x32_bf16 v[10:13], v[244:247], v[10:13], 0
	ds_read_b128 v[36:39], v82
	ds_read_b128 v[42:45], v79
	s_waitcnt lgkmcnt(4)
	v_mfma_f32_16x16x32_bf16 v[22:25], v[244:247], v[22:25], 0
	s_waitcnt vmcnt(0)
	v_mfma_f32_16x16x32_bf16 v[14:17], v[248:251], v[14:17], v[10:13]
	s_waitcnt lgkmcnt(3)
	v_mfma_f32_16x16x32_bf16 v[24:27], v[248:251], v[26:29], v[22:25]
	s_nop 0
	ds_read2_b32 v[12:13], v137 offset0:80 offset1:96
	s_nop 3
	v_max_f32_e32 v30, 0, v17
	v_max_f32_e32 v14, 0, v14
	v_max_f32_e32 v24, 0, v24
	v_max_f32_e32 v25, 0, v25
	v_max_f32_e32 v11, 0, v26
	v_max_f32_e32 v15, 0, v15
	v_max_f32_e32 v10, v16, v16
	s_waitcnt lgkmcnt(0)
	v_mul_f32_e32 v16, v13, v11
	v_max_f32_e32 v11, v27, v27
	ds_read_b128 v[26:29], v84
	v_max_f32_e32 v31, 0, v11
	v_pk_mul_f32 v[22:23], v[12:13], v[30:31]
	ds_read_b128 v[30:33], v83
	s_waitcnt lgkmcnt(1)
	v_mfma_f32_16x16x32_bf16 v[26:29], v[244:247], v[26:29], 0
	v_max_f32_e32 v10, 0, v10
	v_mul_f32_e32 v10, v12, v10
	v_mov_b32_e32 v17, v23
	s_waitcnt lgkmcnt(0)
	v_mfma_f32_16x16x32_bf16 v[30:33], v[248:251], v[30:33], v[26:29]
	s_nop 2
	ds_read2_b32 v[28:29], v137 offset0:112 offset1:128
	s_nop 3
	v_max_f32_e32 v30, 0, v30
	v_max_f32_e32 v31, 0, v31
	v_max_f32_e32 v11, 0, v32
	s_waitcnt lgkmcnt(0)
	v_mul_f32_e32 v26, v28, v11
	v_max_f32_e32 v11, v33, v33
	ds_read_b128 v[32:35], v81
	s_waitcnt lgkmcnt(0)
	v_mfma_f32_16x16x32_bf16 v[32:35], v[244:247], v[32:35], 0
	v_max_f32_e32 v40, 0, v11
	v_mfma_f32_16x16x32_bf16 v[32:35], v[248:251], v[36:39], v[32:35]
	s_nop 7
	v_max_f32_e32 v36, 0, v32
	v_max_f32_e32 v37, 0, v33
	v_max_f32_e32 v11, 0, v34
	v_mul_f32_e32 v32, v29, v11
	v_max_f32_e32 v41, 0, v35
	v_pk_mul_f32 v[34:35], v[28:29], v[40:41]
	ds_read_b128 v[38:41], v80
	s_waitcnt lgkmcnt(0)
	v_mfma_f32_16x16x32_bf16 v[38:41], v[244:247], v[38:41], 0
	v_mov_b32_e32 v27, v34
	v_mov_b32_e32 v33, v35
	v_mfma_f32_16x16x32_bf16 v[38:41], v[248:251], v[42:45], v[38:41]
	ds_read_b128 v[44:47], v75
	s_nop 6
	v_max_f32_e32 v50, 0, v38
	v_max_f32_e32 v51, 0, v39
	v_max_f32_e32 v11, 0, v40
	v_mul_f32_e32 v38, v48, v11
	v_max_f32_e32 v11, v41, v41
	ds_read_b128 v[40:43], v76
	s_waitcnt lgkmcnt(0)
	v_mfma_f32_16x16x32_bf16 v[40:43], v[244:247], v[40:43], 0
	v_max_f32_e32 v52, 0, v11
	v_mfma_f32_16x16x32_bf16 v[40:43], v[248:251], v[44:47], v[40:43]
	ds_read_b128 v[44:47], v77
	s_nop 6
	v_max_f32_e32 v54, 0, v40
	v_max_f32_e32 v55, 0, v41
	v_max_f32_e32 v11, 0, v42
	v_mul_f32_e32 v56, v49, v11
	v_max_f32_e32 v11, v43, v43
	ds_read_b128 v[40:43], v78
	s_waitcnt lgkmcnt(0)
	v_mfma_f32_16x16x32_bf16 v[40:43], v[244:247], v[40:43], 0
	v_max_f32_e32 v53, 0, v11
	v_pk_mul_f32 v[52:53], v[48:49], v[52:53]
	v_mfma_f32_16x16x32_bf16 v[40:43], v[248:251], v[44:47], v[40:43]
	ds_read2_b32 v[44:45], v137 offset0:176 offset1:192
	v_mov_b32_e32 v39, v52
	v_mov_b32_e32 v57, v53
	s_nop 4
	v_max_f32_e32 v46, 0, v40
	v_max_f32_e32 v47, 0, v41
	v_max_f32_e32 v11, 0, v42
	s_waitcnt lgkmcnt(0)
; #define LAS __attribute__((address_space(3)))
; __device__ __forceinline__ unsigned fkey(float f) { const unsigned u = __float_as_uint(f); return (u & 0x80000000u) ? ~u : (u | 0x80000000u); }
; #define SEL_HADD(idx_) __hip_atomic_fetch_add(&hist[(idx_)], 1u, __ATOMIC_RELAXED, __HIP_MEMORY_SCOPE_WORKGROUP)
; __device__ __forceinline__ void sel_unit(LAS char* lds, int b, int u, const bf16_t* QI, const bf16_t* KIDX, const float* WIDX, unsigned long long* MASK) {
;     ...
;     for (int j = 0; j < 8; ++j) {
;         if (j < nj) {
;             int t = wid + 8 * j; asm volatile("" : "+s"(t));
; #pragma unroll
;             for (int kh = 0; kh < 2; ++kh) {
;             bf16x8 kf[2][2];
; #pragma unroll
;             for (int kb = 0; kb < 2; ++kb)
; #pragma unroll
;                 for (int ks = 0; ks < 2; ++ks) kf[kb][ks] = *(const bf16x8*)(KIDX + (rowbase + 64 * t + 32 * kh + 16 * kb + q16) * 64 + 32 * ks + 8 * kg);
; #pragma unroll
;             for (int kb = 0; kb < 2; ++kb) {
;                 f32x4 s = (f32x4){0.f, 0.f, 0.f, 0.f};
; #pragma unroll
;                 for (int hh = 0; hh < 8; ++hh) {
;                     f32x4 a = (f32x4){0.f, 0.f, 0.f, 0.f};
; #pragma unroll
;                     for (int ks = 0; ks < 2; ++ks) {
;                         const bf16x8 qv = *(const LAS bf16x8*)(lds + L_QI + q16 * 1024 + (((hh * 8 + 4 * ks + kg) ^ q16) << 4));
;                         a = __builtin_amdgcn_mfma_f32_16x16x32_bf16(kf[kb][ks], qv, a, 0, 0, 0);
;                     }
;                     const float wh = wl[hh * 16];
; #pragma unroll
;                     for (int i = 0; i < 4; ++i) s[i] += wh * fmaxf(a[i], 0.f);
;                 }
;                 u32x4 kk; kk.x = fkey(s[0]); kk.y = fkey(s[1]); kk.z = fkey(s[2]); kk.w = fkey(s[3]);
;                 sc[j][2 * kh + kb] = kk;
; #pragma unroll
;                 for (int i = 0; i < 4; ++i) SEL_HADD((kk[i] >> 24) * 16 + q16);
;                 __builtin_amdgcn_sched_barrier(0);
	v_mul_f32_e32 v76, v44, v11
	v_max_f32_e32 v11, v43, v43
	ds_read_b128 v[40:43], v74
	s_waitcnt lgkmcnt(0)
	v_mfma_f32_16x16x32_bf16 v[6:9], v[244:247], v[40:43], 0
	ds_read_b128 v[40:43], v73
	v_max_f32_e32 v78, 0, v11
	s_waitcnt lgkmcnt(0)
	v_mfma_f32_16x16x32_bf16 v[2:5], v[248:251], v[40:43], v[6:9]
	s_nop 3
	v_fma_f32 v8, v12, v14, 0
	v_fma_f32 v9, v12, v15, 0
	v_mov_b32_e32 v12, v13
	v_pk_fma_f32 v[8:9], v[12:13], v[24:25], v[8:9] op_sel_hi:[0,1,1]
	v_pk_fma_f32 v[8:9], v[28:29], v[30:31], v[8:9] op_sel_hi:[0,1,1]
	v_mov_b32_e32 v12, v29
	v_pk_fma_f32 v[8:9], v[12:13], v[36:37], v[8:9] op_sel_hi:[0,1,1]
	v_pk_fma_f32 v[8:9], v[48:49], v[50:51], v[8:9] op_sel_hi:[0,1,1]
	v_mov_b32_e32 v12, v49
	v_pk_fma_f32 v[8:9], v[12:13], v[54:55], v[8:9] op_sel_hi:[0,1,1]
	v_max_f32_e32 v2, 0, v2
	v_max_f32_e32 v3, 0, v3
	v_pk_fma_f32 v[8:9], v[44:45], v[46:47], v[8:9] op_sel_hi:[0,1,1]
	v_mov_b32_e32 v12, v45
	v_pk_fma_f32 v[2:3], v[12:13], v[2:3], v[8:9] op_sel_hi:[0,1,1]
	v_and_b32_e32 v9, 0x7fffffff, v3
	v_and_b32_e32 v8, 0x7fffffff, v2
	v_xor_b32_e32 v11, -1, v2
	v_pk_add_f32 v[8:9], v[8:9], 0 neg_lo:[1,1] neg_hi:[1,1]
	v_cmp_gt_i32_e32 vcc, 0, v2
	v_max_f32_e32 v79, 0, v5
	s_nop 0
	v_cndmask_b32_e32 v74, v8, v11, vcc
	v_mov_b32_e32 v11, v22
	v_xor_b32_e32 v5, -1, v3
	v_cmp_gt_i32_e64 s[2:3], 0, v3
	v_pk_add_f32 v[2:3], v[10:11], 0 op_sel_hi:[1,0]
	v_pk_add_f32 v[2:3], v[2:3], v[16:17]
	v_pk_mul_f32 v[6:7], v[44:45], v[78:79]
	v_pk_add_f32 v[2:3], v[2:3], v[26:27]
	v_max_f32_e32 v4, 0, v4
	v_pk_add_f32 v[2:3], v[2:3], v[32:33]
	v_mov_b32_e32 v77, v6
	v_pk_add_f32 v[2:3], v[2:3], v[38:39]
	v_mul_f32_e32 v4, v45, v4
	v_pk_add_f32 v[2:3], v[2:3], v[56:57]
	v_cndmask_b32_e64 v73, v9, v5, s[2:3]
	v_pk_add_f32 v[2:3], v[2:3], v[76:77]
	v_mov_b32_e32 v5, v7
	v_pk_add_f32 v[2:3], v[2:3], v[4:5]
	s_nop 0
	v_xor_b32_e32 v7, -1, v2
	v_and_b32_e32 v4, 0x7fffffff, v2
	v_cmp_gt_i32_e32 vcc, 0, v2
	v_lshrrev_b32_e32 v2, 24, v74
	v_and_b32_e32 v5, 0x7fffffff, v3
	v_lshl_add_u32 v2, v2, 6, v0
	v_pk_add_f32 v[4:5], v[4:5], 0 neg_lo:[1,1] neg_hi:[1,1]
	ds_add_u32 v2, v205 offset:16384
	v_lshrrev_b32_e32 v2, 24, v73
	v_cndmask_b32_e32 v76, v4, v7, vcc
	v_lshl_add_u32 v2, v2, 6, v0
	v_xor_b32_e32 v6, -1, v3
	v_cmp_gt_i32_e64 s[2:3], 0, v3
	ds_add_u32 v2, v205 offset:16384
	v_lshrrev_b32_e32 v2, 24, v76
	v_cndmask_b32_e64 v75, v5, v6, s[2:3]
	v_lshl_add_u32 v2, v2, 6, v0
	ds_add_u32 v2, v205 offset:16384
	v_lshrrev_b32_e32 v2, 24, v75
	v_lshl_add_u32 v2, v2, 6, v0
	ds_add_u32 v2, v205 offset:16384
.LBB0_658:
	s_cmp_gt_i32 s4, 1
	s_cselect_b64 s[18:19], -1, 0
	s_cmp_lt_i32 s4, 2
	s_cbranch_scc1 .LBB0_660
	s_add_i32 s0, s46, 8
	s_lshl_b32 s0, s0, 6
	s_ashr_i32 s1, s0, 31
	v_lshl_add_u64 v[2:3], v[18:19], 0, s[0:1]
	v_lshlrev_b64 v[2:3], 7, v[2:3]
	v_lshl_add_u64 v[22:23], v[20:21], 0, v[2:3]
	global_load_dwordx4 v[14:17], v[22:23], off
	global_load_dwordx4 v[10:13], v[22:23], off offset:64
	v_lshl_add_u32 v95, v182, 4, v150
	v_lshl_add_u32 v96, v183, 4, v150
	v_lshl_add_u32 v93, v185, 4, v150
	v_lshl_add_u32 v89, v180, 4, v150
	v_lshl_add_u32 v94, v159, 4, v150
	v_lshl_add_u32 v92, v184, 4, v150
	ds_read_b128 v[2:5], v95
	v_lshl_add_u32 v90, v179, 4, v150
	ds_read_b128 v[6:9], v96
	ds_read_b128 v[24:27], v92
	v_lshl_add_u32 v91, v176, 4, v150
	ds_read_b128 v[28:31], v93
	ds_read_b128 v[32:35], v90
	ds_read_b128 v[36:39], v89
	ds_read_b128 v[40:43], v91
	v_lshl_add_u32 v97, v158, 4, v150
	ds_read_b128 v[44:47], v94
	ds_read_b128 v[48:51], v97
	v_lshl_add_u32 v98, v157, 4, v150
	ds_read_b128 v[52:55], v98
	v_lshl_add_u32 v99, v156, 4, v150
	v_lshl_add_u32 v100, v155, 4, v150
	ds_read_b128 v[78:81], v99
	ds_read_b128 v[82:85], v100
	v_lshl_add_u32 v101, v154, 4, v150
	s_waitcnt vmcnt(1) lgkmcnt(11)
	v_mfma_f32_16x16x32_bf16 v[2:5], v[14:17], v[2:5], 0
	s_waitcnt lgkmcnt(9)
	v_mfma_f32_16x16x32_bf16 v[24:27], v[14:17], v[24:27], 0
	s_waitcnt lgkmcnt(7)
	v_mfma_f32_16x16x32_bf16 v[32:35], v[14:17], v[32:35], 0
	s_waitcnt lgkmcnt(5)
	v_mfma_f32_16x16x32_bf16 v[40:43], v[14:17], v[40:43], 0
	s_waitcnt lgkmcnt(3)
	v_mfma_f32_16x16x32_bf16 v[48:51], v[14:17], v[48:51], 0
	s_waitcnt vmcnt(0)
	v_mfma_f32_16x16x32_bf16 v[102:105], v[10:13], v[6:9], v[2:5]
	v_mfma_f32_16x16x32_bf16 v[24:27], v[10:13], v[28:31], v[24:27]
	v_mfma_f32_16x16x32_bf16 v[28:31], v[10:13], v[36:39], v[32:35]
	v_mfma_f32_16x16x32_bf16 v[32:35], v[10:13], v[44:47], v[40:43]
	ds_read2_b32 v[44:45], v137 offset0:80 offset1:96
	ds_read2_b32 v[46:47], v137 offset0:112 offset1:128
	s_nop 3
	s_waitcnt lgkmcnt(4)
	v_mfma_f32_16x16x32_bf16 v[36:39], v[10:13], v[52:55], v[48:51]
	s_nop 0
	ds_read2_b32 v[48:49], v137 offset0:144 offset1:160
	global_load_dwordx4 v[6:9], v[22:23], off offset:2048
	global_load_dwordx4 v[2:5], v[22:23], off offset:2112
	v_mov_b32_e32 v252, 0x1000
	v_mov_b32_e32 v253, 0
	v_lshl_add_u64 v[252:253], v[252:253], 0, v[22:23]
	global_load_dwordx4 v[236:239], v[252:253], off
	global_load_dwordx4 v[240:243], v[252:253], off offset:64
	global_load_dwordx4 v[244:247], v[252:253], off offset:2048
	global_load_dwordx4 v[248:251], v[252:253], off offset:2112
	s_waitcnt lgkmcnt(4)
	v_mfma_f32_16x16x32_bf16 v[78:81], v[14:17], v[78:81], 0
	s_nop 0
	v_max_f32_e32 v54, v24, v24
	s_nop 0
	s_waitcnt lgkmcnt(3)
	v_mfma_f32_16x16x32_bf16 v[40:43], v[10:13], v[82:85], v[78:81]
	v_max_f32_e32 v77, v39, v39
	v_max_f32_e32 v24, 0, v105
	v_max_f32_e32 v39, 0, v25
	v_max_f32_e32 v80, 0, v26
	v_max_f32_e32 v25, 0, v27
	v_max_f32_e32 v26, 0, v31
	v_max_f32_e32 v27, 0, v35
	v_max_f32_e32 v53, 0, v37
	s_waitcnt lgkmcnt(2)
	v_mul_f32_e32 v56, v45, v80
	v_pk_mul_f32 v[80:81], v[44:45], v[24:25]
	s_waitcnt lgkmcnt(1)
; #define LAS __attribute__((address_space(3)))
; __device__ __forceinline__ unsigned fkey(float f) { const unsigned u = __float_as_uint(f); return (u & 0x80000000u) ? ~u : (u | 0x80000000u); }
; #define SEL_HADD(idx_) __hip_atomic_fetch_add(&hist[(idx_)], 1u, __ATOMIC_RELAXED, __HIP_MEMORY_SCOPE_WORKGROUP)
; __device__ __forceinline__ void sel_unit(LAS char* lds, int b, int u, const bf16_t* QI, const bf16_t* KIDX, const float* WIDX, unsigned long long* MASK) {
;     ...
;     for (int j = 0; j < 8; ++j) {
;         if (j < nj) {
;             int t = wid + 8 * j; asm volatile("" : "+s"(t));
; #pragma unroll
;             for (int kh = 0; kh < 2; ++kh) {
;             bf16x8 kf[2][2];
; #pragma unroll
;             for (int kb = 0; kb < 2; ++kb)
; #pragma unroll
;                 for (int ks = 0; ks < 2; ++ks) kf[kb][ks] = *(const bf16x8*)(KIDX + (rowbase + 64 * t + 32 * kh + 16 * kb + q16) * 64 + 32 * ks + 8 * kg);
; #pragma unroll
;             for (int kb = 0; kb < 2; ++kb) {
;                 f32x4 s = (f32x4){0.f, 0.f, 0.f, 0.f};
; #pragma unroll
;                 for (int hh = 0; hh < 8; ++hh) {
;                     f32x4 a = (f32x4){0.f, 0.f, 0.f, 0.f};
; #pragma unroll
;                     for (int ks = 0; ks < 2; ++ks) {
;                         const bf16x8 qv = *(const LAS bf16x8*)(lds + L_QI + q16 * 1024 + (((hh * 8 + 4 * ks + kg) ^ q16) << 4));
;                         a = __builtin_amdgcn_mfma_f32_16x16x32_bf16(kf[kb][ks], qv, a, 0, 0, 0);
;                     }
;                     const float wh = wl[hh * 16];
; #pragma unroll
;                     for (int i = 0; i < 4; ++i) s[i] += wh * fmaxf(a[i], 0.f);
;                 }
;                 u32x4 kk; kk.x = fkey(s[0]); kk.y = fkey(s[1]); kk.z = fkey(s[2]); kk.w = fkey(s[3]);
;                 sc[j][2 * kh + kb] = kk;
; #pragma unroll
;                 for (int i = 0; i < 4; ++i) SEL_HADD((kk[i] >> 24) * 16 + q16);
;                 __builtin_amdgcn_sched_barrier(0);
	v_pk_mul_f32 v[86:87], v[46:47], v[26:27]
	ds_read_b128 v[24:27], v101
	v_max_f32_e32 v78, v40, v40
	v_max_f32_e32 v40, 0, v28
	v_max_f32_e32 v28, 0, v30
	v_max_f32_e32 v50, v102, v102
	v_max_f32_e32 v79, v41, v41
	v_max_f32_e32 v41, 0, v29
	v_max_f32_e32 v29, 0, v34
	v_max_f32_e32 v30, 0, v38
	v_mul_f32_e32 v82, v46, v28
	v_max_f32_e32 v28, 0, v42
	v_lshl_add_u32 v102, v153, 4, v150
	v_mul_f32_e32 v84, v47, v29
	s_waitcnt lgkmcnt(1)
	v_mul_f32_e32 v106, v48, v30
	v_mul_f32_e32 v108, v49, v28
	ds_read_b128 v[28:31], v102
	s_waitcnt lgkmcnt(1)
	v_mfma_f32_16x16x32_bf16 v[24:27], v[14:17], v[24:27], 0
	v_max_f32_e32 v51, v103, v103
	v_lshl_add_u32 v103, v152, 4, v150
	s_waitcnt lgkmcnt(0)
	v_mfma_f32_16x16x32_bf16 v[24:27], v[10:13], v[28:31], v[24:27]
	ds_read_b128 v[28:31], v103
	v_max_f32_e32 v37, 0, v51
	v_max_f32_e32 v51, 0, v33
	v_max_f32_e32 v52, v104, v104
	v_max_f32_e32 v55, v36, v36
	v_max_f32_e32 v36, 0, v50
	v_max_f32_e32 v50, 0, v32
	v_max_f32_e32 v32, 0, v77
	v_max_f32_e32 v33, 0, v43
	v_lshl_add_u32 v104, v151, 4, v150
	v_pk_mul_f32 v[110:111], v[48:49], v[32:33]
	ds_read_b128 v[32:35], v104
	s_waitcnt lgkmcnt(1)
	v_mfma_f32_16x16x32_bf16 v[14:17], v[14:17], v[28:31], 0
	v_max_f32_e32 v42, 0, v52
	v_max_f32_e32 v38, 0, v54
	v_max_f32_e32 v52, 0, v55
	s_waitcnt lgkmcnt(0)
	v_mfma_f32_16x16x32_bf16 v[10:13], v[10:13], v[32:35], v[14:17]
	v_max_f32_e32 v54, 0, v78
	v_max_f32_e32 v55, 0, v79
	ds_read2_b32 v[78:79], v137 offset0:176 offset1:192
	s_nop 0
	v_max_f32_e32 v28, 0, v27
	s_nop 2
	v_max_f32_e32 v29, 0, v13
	s_waitcnt lgkmcnt(0)
	v_pk_mul_f32 v[14:15], v[78:79], v[28:29]
	v_pk_fma_f32 v[16:17], v[44:45], v[36:37], 0 op_sel_hi:[0,1,0]
	v_mov_b32_e32 v28, v45
	v_pk_fma_f32 v[16:17], v[28:29], v[38:39], v[16:17] op_sel_hi:[0,1,1]
	v_pk_fma_f32 v[16:17], v[46:47], v[40:41], v[16:17] op_sel_hi:[0,1,1]
	v_mov_b32_e32 v28, v47
	v_pk_fma_f32 v[16:17], v[28:29], v[50:51], v[16:17] op_sel_hi:[0,1,1]
	v_pk_fma_f32 v[16:17], v[48:49], v[52:53], v[16:17] op_sel_hi:[0,1,1]
	v_mov_b32_e32 v28, v49
	v_max_f32_e32 v24, 0, v24
	v_max_f32_e32 v25, 0, v25
	v_pk_fma_f32 v[16:17], v[28:29], v[54:55], v[16:17] op_sel_hi:[0,1,1]
	v_max_f32_e32 v10, 0, v10
	v_max_f32_e32 v11, 0, v11
	v_pk_fma_f32 v[16:17], v[78:79], v[24:25], v[16:17] op_sel_hi:[0,1,1]
	v_mov_b32_e32 v24, v79
	v_pk_fma_f32 v[10:11], v[24:25], v[10:11], v[16:17] op_sel_hi:[0,1,1]
	v_and_b32_e32 v17, 0x7fffffff, v11
	v_and_b32_e32 v16, 0x7fffffff, v10
	v_mul_f32_e32 v42, v44, v42
	v_xor_b32_e32 v13, -1, v11
	v_pk_add_f32 v[16:17], v[16:17], 0 neg_lo:[1,1] neg_hi:[1,1]
	v_cmp_gt_i32_e32 vcc, 0, v11
	v_mov_b32_e32 v43, v80
	v_xor_b32_e32 v24, -1, v10
	v_cndmask_b32_e32 v77, v17, v13, vcc
	v_cmp_gt_i32_e32 vcc, 0, v10
	v_pk_add_f32 v[10:11], v[42:43], 0 op_sel_hi:[1,0]
	v_mov_b32_e32 v57, v81
	v_pk_add_f32 v[10:11], v[10:11], v[56:57]
	v_mov_b32_e32 v83, v86
	v_pk_add_f32 v[10:11], v[10:11], v[82:83]
	v_mov_b32_e32 v85, v87
	v_pk_add_f32 v[10:11], v[10:11], v[84:85]
	v_mov_b32_e32 v107, v110
	v_max_f32_e32 v26, 0, v26
	v_pk_add_f32 v[10:11], v[10:11], v[106:107]
	v_mov_b32_e32 v109, v111
	v_mul_f32_e32 v26, v78, v26
	v_max_f32_e32 v12, 0, v12
	v_pk_add_f32 v[10:11], v[10:11], v[108:109]
	v_mov_b32_e32 v27, v14
	v_mul_f32_e32 v12, v79, v12
	v_pk_add_f32 v[10:11], v[10:11], v[26:27]
	v_mov_b32_e32 v13, v15
	v_pk_add_f32 v[10:11], v[10:11], v[12:13]
	v_cndmask_b32_e32 v78, v16, v24, vcc
	v_and_b32_e32 v13, 0x7fffffff, v11
	v_and_b32_e32 v12, 0x7fffffff, v10
	v_xor_b32_e32 v14, -1, v11
	v_pk_add_f32 v[12:13], v[12:13], 0 neg_lo:[1,1] neg_hi:[1,1]
	v_cmp_gt_i32_e32 vcc, 0, v11
	v_xor_b32_e32 v15, -1, v10
	s_nop 0
	v_cndmask_b32_e32 v79, v13, v14, vcc
	v_cmp_gt_i32_e32 vcc, 0, v10
	v_lshrrev_b32_e32 v10, 24, v78
	v_lshl_add_u32 v10, v10, 6, v0
	ds_add_u32 v10, v205 offset:16384
	v_lshrrev_b32_e32 v10, 24, v77
	v_cndmask_b32_e32 v80, v12, v15, vcc
	v_lshl_add_u32 v10, v10, 6, v0
	ds_add_u32 v10, v205 offset:16384
	v_lshrrev_b32_e32 v10, 24, v80
	v_lshl_add_u32 v10, v10, 6, v0
	ds_add_u32 v10, v205 offset:16384
	v_lshrrev_b32_e32 v10, 24, v79
	v_lshl_add_u32 v10, v10, 6, v0
	ds_add_u32 v10, v205 offset:16384
	ds_read_b128 v[10:13], v95
	ds_read_b128 v[14:17], v96
	ds_read_b128 v[24:27], v92
	ds_read_b128 v[28:31], v93
	ds_read2_b32 v[32:33], v137 offset0:80 offset1:96
	ds_read2_b32 v[40:41], v137 offset0:112 offset1:128
	s_waitcnt vmcnt(5) lgkmcnt(5)
	v_mfma_f32_16x16x32_bf16 v[10:13], v[6:9], v[10:13], 0
	ds_read2_b32 v[52:53], v137 offset0:144 offset1:160
	s_waitcnt vmcnt(4) lgkmcnt(5)
	v_mfma_f32_16x16x32_bf16 v[10:13], v[2:5], v[14:17], v[10:13]
	ds_read_b128 v[14:17], v90
	s_waitcnt lgkmcnt(5)
	v_mfma_f32_16x16x32_bf16 v[24:27], v[6:9], v[24:27], 0
	s_nop 4
	v_max_f32_e32 v34, 0, v10
	v_max_f32_e32 v10, 0, v12
	v_max_f32_e32 v35, 0, v11
	s_waitcnt lgkmcnt(3)
	v_mul_f32_e32 v36, v32, v10
	v_max_f32_e32 v38, 0, v13
	v_mfma_f32_16x16x32_bf16 v[10:13], v[2:5], v[28:31], v[24:27]
	s_nop 2
	ds_read_b128 v[24:27], v89
	s_waitcnt lgkmcnt(1)
	v_mfma_f32_16x16x32_bf16 v[14:17], v[6:9], v[14:17], 0
	s_nop 1
	v_max_f32_e32 v28, 0, v10
	v_max_f32_e32 v29, 0, v11
	v_max_f32_e32 v10, 0, v12
	v_mul_f32_e32 v30, v33, v10
	v_max_f32_e32 v39, 0, v13
	s_waitcnt lgkmcnt(0)
	v_mfma_f32_16x16x32_bf16 v[10:13], v[2:5], v[24:27], v[14:17]
	ds_read_b128 v[24:27], v94
	v_pk_mul_f32 v[38:39], v[32:33], v[38:39]
	s_nop 0
	ds_read_b128 v[14:17], v91
	s_waitcnt lgkmcnt(0)
	v_mfma_f32_16x16x32_bf16 v[14:17], v[6:9], v[14:17], 0
	s_nop 1
	v_max_f32_e32 v42, 0, v10
	v_max_f32_e32 v43, 0, v11
	v_max_f32_e32 v10, 0, v12
	v_mul_f32_e32 v44, v40, v10
	s_nop 0
	v_max_f32_e32 v46, 0, v13
	v_mfma_f32_16x16x32_bf16 v[10:13], v[2:5], v[24:27], v[14:17]
	ds_read_b128 v[24:27], v98
	v_mov_b32_e32 v37, v38
	v_mov_b32_e32 v31, v39
	ds_read_b128 v[14:17], v97
	s_waitcnt lgkmcnt(0)
; #define LAS __attribute__((address_space(3)))
; __device__ __forceinline__ unsigned fkey(float f) { const unsigned u = __float_as_uint(f); return (u & 0x80000000u) ? ~u : (u | 0x80000000u); }
; #define SEL_HADD(idx_) __hip_atomic_fetch_add(&hist[(idx_)], 1u, __ATOMIC_RELAXED, __HIP_MEMORY_SCOPE_WORKGROUP)
; __device__ __forceinline__ void sel_unit(LAS char* lds, int b, int u, const bf16_t* QI, const bf16_t* KIDX, const float* WIDX, unsigned long long* MASK) {
;     ...
;     for (int j = 0; j < 8; ++j) {
;         if (j < nj) {
;             int t = wid + 8 * j; asm volatile("" : "+s"(t));
; #pragma unroll
;             for (int kh = 0; kh < 2; ++kh) {
;             bf16x8 kf[2][2];
; #pragma unroll
;             for (int kb = 0; kb < 2; ++kb)
; #pragma unroll
;                 for (int ks = 0; ks < 2; ++ks) kf[kb][ks] = *(const bf16x8*)(KIDX + (rowbase + 64 * t + 32 * kh + 16 * kb + q16) * 64 + 32 * ks + 8 * kg);
; #pragma unroll
;             for (int kb = 0; kb < 2; ++kb) {
;                 f32x4 s = (f32x4){0.f, 0.f, 0.f, 0.f};
; #pragma unroll
;                 for (int hh = 0; hh < 8; ++hh) {
;                     f32x4 a = (f32x4){0.f, 0.f, 0.f, 0.f};
; #pragma unroll
;                     for (int ks = 0; ks < 2; ++ks) {
;                         const bf16x8 qv = *(const LAS bf16x8*)(lds + L_QI + q16 * 1024 + (((hh * 8 + 4 * ks + kg) ^ q16) << 4));
;                         a = __builtin_amdgcn_mfma_f32_16x16x32_bf16(kf[kb][ks], qv, a, 0, 0, 0);
;                     }
;                     const float wh = wl[hh * 16];
; #pragma unroll
;                     for (int i = 0; i < 4; ++i) s[i] += wh * fmaxf(a[i], 0.f);
;                 }
;                 u32x4 kk; kk.x = fkey(s[0]); kk.y = fkey(s[1]); kk.z = fkey(s[2]); kk.w = fkey(s[3]);
;                 sc[j][2 * kh + kb] = kk;
; #pragma unroll
;                 for (int i = 0; i < 4; ++i) SEL_HADD((kk[i] >> 24) * 16 + q16);
;                 __builtin_amdgcn_sched_barrier(0);
	v_mfma_f32_16x16x32_bf16 v[14:17], v[6:9], v[14:17], 0
	s_nop 1
	v_max_f32_e32 v48, 0, v10
	v_max_f32_e32 v49, 0, v11
	v_max_f32_e32 v10, 0, v12
	v_mul_f32_e32 v50, v41, v10
	s_nop 0
	v_max_f32_e32 v47, 0, v13
	v_mfma_f32_16x16x32_bf16 v[10:13], v[2:5], v[24:27], v[14:17]
	ds_read_b128 v[24:27], v100
	v_pk_mul_f32 v[46:47], v[40:41], v[46:47]
	s_nop 0
	ds_read_b128 v[14:17], v99
	s_waitcnt lgkmcnt(0)
	v_mfma_f32_16x16x32_bf16 v[14:17], v[6:9], v[14:17], 0
	s_nop 1
	v_max_f32_e32 v54, 0, v10
	v_max_f32_e32 v55, 0, v11
	v_max_f32_e32 v10, 0, v12
	v_mul_f32_e32 v56, v52, v10
	s_nop 0
	v_max_f32_e32 v82, 0, v13
	v_mfma_f32_16x16x32_bf16 v[10:13], v[2:5], v[24:27], v[14:17]
	ds_read_b128 v[24:27], v102
	v_mov_b32_e32 v45, v46
	v_mov_b32_e32 v51, v47
	ds_read_b128 v[14:17], v101
	s_waitcnt lgkmcnt(0)
	v_mfma_f32_16x16x32_bf16 v[14:17], v[6:9], v[14:17], 0
	s_nop 1
	v_max_f32_e32 v84, 0, v10
	v_max_f32_e32 v85, 0, v11
	v_max_f32_e32 v10, 0, v12
	v_mul_f32_e32 v86, v53, v10
	s_nop 0
	v_max_f32_e32 v83, 0, v13
	v_mfma_f32_16x16x32_bf16 v[10:13], v[2:5], v[24:27], v[14:17]
	ds_read_b128 v[24:27], v104
	v_pk_mul_f32 v[106:107], v[52:53], v[82:83]
	ds_read2_b32 v[82:83], v137 offset0:176 offset1:192
	ds_read_b128 v[14:17], v103
	s_waitcnt lgkmcnt(0)
	v_mfma_f32_16x16x32_bf16 v[6:9], v[6:9], v[14:17], 0
	s_nop 1
	s_nop 0
	v_max_f32_e32 v14, 0, v13
	s_nop 0
	v_mfma_f32_16x16x32_bf16 v[2:5], v[2:5], v[24:27], v[6:9]
	s_nop 0
	v_max_f32_e32 v10, 0, v10
	v_max_f32_e32 v11, 0, v11
	v_pk_fma_f32 v[8:9], v[32:33], v[34:35], 0 op_sel_hi:[0,1,0]
	s_nop 0
	s_nop 2
	v_max_f32_e32 v15, 0, v5
	v_pk_mul_f32 v[6:7], v[82:83], v[14:15]
	v_mov_b32_e32 v14, v33
	v_pk_fma_f32 v[8:9], v[14:15], v[28:29], v[8:9] op_sel_hi:[0,1,1]
	v_pk_fma_f32 v[8:9], v[40:41], v[42:43], v[8:9] op_sel_hi:[0,1,1]
	v_mov_b32_e32 v14, v41
	v_pk_fma_f32 v[8:9], v[14:15], v[48:49], v[8:9] op_sel_hi:[0,1,1]
	v_pk_fma_f32 v[8:9], v[52:53], v[54:55], v[8:9] op_sel_hi:[0,1,1]
	v_mov_b32_e32 v14, v53
	v_pk_fma_f32 v[8:9], v[14:15], v[84:85], v[8:9] op_sel_hi:[0,1,1]
	v_max_f32_e32 v2, 0, v2
	v_max_f32_e32 v3, 0, v3
	v_pk_fma_f32 v[8:9], v[82:83], v[10:11], v[8:9] op_sel_hi:[0,1,1]
	v_mov_b32_e32 v10, v83
	v_pk_fma_f32 v[2:3], v[10:11], v[2:3], v[8:9] op_sel_hi:[0,1,1]
	v_and_b32_e32 v9, 0x7fffffff, v3
	v_and_b32_e32 v8, 0x7fffffff, v2
	v_xor_b32_e32 v5, -1, v3
	v_pk_add_f32 v[8:9], v[8:9], 0 neg_lo:[1,1] neg_hi:[1,1]
	v_cmp_gt_i32_e32 vcc, 0, v3
	v_xor_b32_e32 v10, -1, v2
	v_mov_b32_e32 v57, v106
	v_cndmask_b32_e32 v81, v9, v5, vcc
	v_cmp_gt_i32_e32 vcc, 0, v2
	v_pk_add_f32 v[2:3], v[36:37], 0 op_sel_hi:[1,0]
	v_max_f32_e32 v12, 0, v12
	v_pk_add_f32 v[2:3], v[2:3], v[30:31]
	v_pk_add_f32 v[2:3], v[2:3], v[44:45]
	v_mov_b32_e32 v87, v107
	v_pk_add_f32 v[2:3], v[2:3], v[50:51]
	v_mul_f32_e32 v12, v82, v12
	v_pk_add_f32 v[2:3], v[2:3], v[56:57]
	v_max_f32_e32 v4, 0, v4
	v_pk_add_f32 v[2:3], v[2:3], v[86:87]
	v_mov_b32_e32 v13, v6
	v_mul_f32_e32 v4, v83, v4
	v_pk_add_f32 v[2:3], v[2:3], v[12:13]
	v_mov_b32_e32 v5, v7
	v_pk_add_f32 v[2:3], v[2:3], v[4:5]
	v_cndmask_b32_e32 v82, v8, v10, vcc
	v_and_b32_e32 v5, 0x7fffffff, v3
	v_and_b32_e32 v4, 0x7fffffff, v2
	v_xor_b32_e32 v6, -1, v3
	v_pk_add_f32 v[4:5], v[4:5], 0 neg_lo:[1,1] neg_hi:[1,1]
	v_cmp_gt_i32_e32 vcc, 0, v3
	v_xor_b32_e32 v7, -1, v2
	s_nop 0
	v_cndmask_b32_e32 v83, v5, v6, vcc
	v_cmp_gt_i32_e32 vcc, 0, v2
	v_lshrrev_b32_e32 v2, 24, v82
	v_lshl_add_u32 v2, v2, 6, v0
	ds_add_u32 v2, v205 offset:16384
	v_lshrrev_b32_e32 v2, 24, v81
	v_cndmask_b32_e32 v84, v4, v7, vcc
	v_lshl_add_u32 v2, v2, 6, v0
	ds_add_u32 v2, v205 offset:16384
	v_lshrrev_b32_e32 v2, 24, v84
	v_lshl_add_u32 v2, v2, 6, v0
	ds_add_u32 v2, v205 offset:16384
	v_lshrrev_b32_e32 v2, 24, v83
	v_lshl_add_u32 v2, v2, 6, v0
	ds_add_u32 v2, v205 offset:16384
	ds_read_b128 v[22:25], v95
	ds_read_b128 v[26:29], v96
	s_waitcnt vmcnt(3) lgkmcnt(1)
	v_mfma_f32_16x16x32_bf16 v[22:25], v[236:239], v[22:25], 0
	ds_read_b128 v[32:35], v93
	ds_read_b128 v[38:41], v89
	ds_read_b128 v[44:47], v94
	s_waitcnt vmcnt(2) lgkmcnt(3)
	v_mfma_f32_16x16x32_bf16 v[26:29], v[240:243], v[26:29], v[22:25]
	ds_read_b128 v[50:53], v98
	ds_read_b128 v[106:109], v100
	ds_read_b128 v[110:113], v102
	ds_read2_b32 v[24:25], v137 offset0:80 offset1:96
	s_nop 3
	v_max_f32_e32 v26, 0, v26
	v_max_f32_e32 v27, 0, v27
	v_max_f32_e32 v22, v28, v28
	v_max_f32_e32 v23, v29, v29
	ds_read_b128 v[28:31], v92
	s_waitcnt lgkmcnt(0)
	v_mfma_f32_16x16x32_bf16 v[28:31], v[236:239], v[28:31], 0
	v_max_f32_e32 v36, 0, v23
	v_max_f32_e32 v22, 0, v22
	v_mul_f32_e32 v22, v24, v22
	v_mfma_f32_16x16x32_bf16 v[28:31], v[240:243], v[32:35], v[28:31]
	s_nop 7
	v_max_f32_e32 v32, 0, v28
	v_max_f32_e32 v33, 0, v29
	v_max_f32_e32 v23, 0, v30
	v_mul_f32_e32 v28, v25, v23
	v_max_f32_e32 v37, 0, v31
	v_pk_mul_f32 v[30:31], v[24:25], v[36:37]
	ds_read_b128 v[34:37], v90
	s_waitcnt lgkmcnt(0)
	v_mfma_f32_16x16x32_bf16 v[34:37], v[236:239], v[34:37], 0
	v_mov_b32_e32 v29, v31
	v_mfma_f32_16x16x32_bf16 v[38:41], v[240:243], v[38:41], v[34:37]
	s_nop 5
	ds_read2_b32 v[36:37], v137 offset0:112 offset1:128
	s_nop 0
	v_max_f32_e32 v38, 0, v38
	v_max_f32_e32 v39, 0, v39
	v_max_f32_e32 v23, 0, v40
	s_waitcnt lgkmcnt(0)
	v_mul_f32_e32 v34, v36, v23
	v_max_f32_e32 v23, v41, v41
	ds_read_b128 v[40:43], v91
	s_waitcnt lgkmcnt(0)
	v_mfma_f32_16x16x32_bf16 v[40:43], v[236:239], v[40:43], 0
	v_max_f32_e32 v48, 0, v23
	v_mfma_f32_16x16x32_bf16 v[40:43], v[240:243], v[44:47], v[40:43]
	s_nop 7
	v_max_f32_e32 v44, 0, v40
	v_max_f32_e32 v45, 0, v41
	v_max_f32_e32 v23, 0, v42
	v_mul_f32_e32 v40, v37, v23
	v_max_f32_e32 v49, 0, v43
	v_pk_mul_f32 v[42:43], v[36:37], v[48:49]
	ds_read_b128 v[46:49], v97
	s_waitcnt lgkmcnt(0)
; #define LAS __attribute__((address_space(3)))
; __device__ __forceinline__ unsigned fkey(float f) { const unsigned u = __float_as_uint(f); return (u & 0x80000000u) ? ~u : (u | 0x80000000u); }
; #define SEL_HADD(idx_) __hip_atomic_fetch_add(&hist[(idx_)], 1u, __ATOMIC_RELAXED, __HIP_MEMORY_SCOPE_WORKGROUP)
; __device__ __forceinline__ void sel_unit(LAS char* lds, int b, int u, const bf16_t* QI, const bf16_t* KIDX, const float* WIDX, unsigned long long* MASK) {
;     ...
;     for (int j = 0; j < 8; ++j) {
;         if (j < nj) {
;             int t = wid + 8 * j; asm volatile("" : "+s"(t));
; #pragma unroll
;             for (int kh = 0; kh < 2; ++kh) {
;             bf16x8 kf[2][2];
; #pragma unroll
;             for (int kb = 0; kb < 2; ++kb)
; #pragma unroll
;                 for (int ks = 0; ks < 2; ++ks) kf[kb][ks] = *(const bf16x8*)(KIDX + (rowbase + 64 * t + 32 * kh + 16 * kb + q16) * 64 + 32 * ks + 8 * kg);
; #pragma unroll
;             for (int kb = 0; kb < 2; ++kb) {
;                 f32x4 s = (f32x4){0.f, 0.f, 0.f, 0.f};
; #pragma unroll
;                 for (int hh = 0; hh < 8; ++hh) {
;                     f32x4 a = (f32x4){0.f, 0.f, 0.f, 0.f};
; #pragma unroll
;                     for (int ks = 0; ks < 2; ++ks) {
;                         const bf16x8 qv = *(const LAS bf16x8*)(lds + L_QI + q16 * 1024 + (((hh * 8 + 4 * ks + kg) ^ q16) << 4));
;                         a = __builtin_amdgcn_mfma_f32_16x16x32_bf16(kf[kb][ks], qv, a, 0, 0, 0);
;                     }
;                     const float wh = wl[hh * 16];
; #pragma unroll
;                     for (int i = 0; i < 4; ++i) s[i] += wh * fmaxf(a[i], 0.f);
;                 }
;                 u32x4 kk; kk.x = fkey(s[0]); kk.y = fkey(s[1]); kk.z = fkey(s[2]); kk.w = fkey(s[3]);
;                 sc[j][2 * kh + kb] = kk;
; #pragma unroll
;                 for (int i = 0; i < 4; ++i) SEL_HADD((kk[i] >> 24) * 16 + q16);
;                 __builtin_amdgcn_sched_barrier(0);
	v_mfma_f32_16x16x32_bf16 v[46:49], v[236:239], v[46:49], 0
	v_mov_b32_e32 v35, v42
	v_mov_b32_e32 v41, v43
	v_mfma_f32_16x16x32_bf16 v[50:53], v[240:243], v[50:53], v[46:49]
	s_nop 4
	ds_read2_b32 v[48:49], v137 offset0:144 offset1:160
	s_nop 1
	v_max_f32_e32 v50, 0, v50
	v_max_f32_e32 v51, 0, v51
	v_max_f32_e32 v23, 0, v52
	s_waitcnt lgkmcnt(0)
	v_mul_f32_e32 v46, v48, v23
	v_max_f32_e32 v23, v53, v53
	ds_read_b128 v[52:55], v99
	s_waitcnt lgkmcnt(0)
	v_mfma_f32_16x16x32_bf16 v[52:55], v[236:239], v[52:55], 0
	v_max_f32_e32 v86, 0, v23
	v_mfma_f32_16x16x32_bf16 v[52:55], v[240:243], v[106:109], v[52:55]
	ds_read_b128 v[106:109], v101
	s_waitcnt lgkmcnt(0)
	v_mfma_f32_16x16x32_bf16 v[106:109], v[236:239], v[106:109], 0
	s_nop 4
	v_max_f32_e32 v56, 0, v52
	v_max_f32_e32 v57, 0, v53
	v_max_f32_e32 v23, 0, v54
	v_mfma_f32_16x16x32_bf16 v[106:109], v[240:243], v[110:113], v[106:109]
	v_mul_f32_e32 v52, v49, v23
	s_nop 0
	v_max_f32_e32 v87, 0, v55
	v_pk_mul_f32 v[54:55], v[48:49], v[86:87]
	ds_read2_b32 v[86:87], v137 offset0:176 offset1:192
	s_nop 2
	v_max_f32_e32 v110, 0, v106
	v_max_f32_e32 v111, 0, v107
	v_max_f32_e32 v23, 0, v108
	s_waitcnt lgkmcnt(0)
	v_mul_f32_e32 v112, v86, v23
	v_max_f32_e32 v23, v109, v109
	ds_read_b128 v[106:109], v103
	s_waitcnt lgkmcnt(0)
	v_mfma_f32_16x16x32_bf16 v[14:17], v[236:239], v[106:109], 0
	ds_read_b128 v[106:109], v104
	v_max_f32_e32 v114, 0, v23
	v_mov_b32_e32 v47, v54
	s_waitcnt lgkmcnt(0)
	v_mfma_f32_16x16x32_bf16 v[10:13], v[240:243], v[106:109], v[14:17]
	v_mov_b32_e32 v53, v55
	s_nop 1
	v_pk_fma_f32 v[16:17], v[24:25], v[26:27], 0 op_sel_hi:[0,1,0]
	v_mov_b32_e32 v24, v25
	v_pk_fma_f32 v[16:17], v[24:25], v[32:33], v[16:17] op_sel_hi:[0,1,1]
	v_pk_fma_f32 v[16:17], v[36:37], v[38:39], v[16:17] op_sel_hi:[0,1,1]
	v_mov_b32_e32 v24, v37
	v_pk_fma_f32 v[16:17], v[24:25], v[44:45], v[16:17] op_sel_hi:[0,1,1]
	v_pk_fma_f32 v[16:17], v[48:49], v[50:51], v[16:17] op_sel_hi:[0,1,1]
	v_mov_b32_e32 v24, v49
	v_pk_fma_f32 v[16:17], v[24:25], v[56:57], v[16:17] op_sel_hi:[0,1,1]
	v_max_f32_e32 v10, 0, v10
	v_max_f32_e32 v11, 0, v11
	v_pk_fma_f32 v[16:17], v[86:87], v[110:111], v[16:17] op_sel_hi:[0,1,1]
	v_mov_b32_e32 v24, v87
	v_pk_fma_f32 v[10:11], v[24:25], v[10:11], v[16:17] op_sel_hi:[0,1,1]
	v_and_b32_e32 v17, 0x7fffffff, v11
	v_and_b32_e32 v16, 0x7fffffff, v10
	v_max_f32_e32 v115, 0, v13
	v_xor_b32_e32 v23, -1, v10
	v_pk_add_f32 v[16:17], v[16:17], 0 neg_lo:[1,1] neg_hi:[1,1]
	v_cmp_gt_i32_e32 vcc, 0, v10
	v_pk_mul_f32 v[14:15], v[86:87], v[114:115]
	v_xor_b32_e32 v13, -1, v11
	v_cndmask_b32_e32 v86, v16, v23, vcc
	v_mov_b32_e32 v23, v30
	v_cmp_gt_i32_e64 s[2:3], 0, v11
	v_pk_add_f32 v[10:11], v[22:23], 0 op_sel_hi:[1,0]
	v_pk_add_f32 v[10:11], v[10:11], v[28:29]
	v_max_f32_e32 v12, 0, v12
	v_pk_add_f32 v[10:11], v[10:11], v[34:35]
	v_mov_b32_e32 v113, v14
	v_pk_add_f32 v[10:11], v[10:11], v[40:41]
	v_mul_f32_e32 v12, v87, v12
	v_pk_add_f32 v[10:11], v[10:11], v[46:47]
	v_cndmask_b32_e64 v85, v17, v13, s[2:3]
	v_pk_add_f32 v[10:11], v[10:11], v[52:53]
	v_mov_b32_e32 v13, v15
	v_pk_add_f32 v[10:11], v[10:11], v[112:113]
	s_nop 0
	v_pk_add_f32 v[10:11], v[10:11], v[12:13]
	s_nop 0
	v_xor_b32_e32 v15, -1, v10
	v_and_b32_e32 v12, 0x7fffffff, v10
	v_cmp_gt_i32_e32 vcc, 0, v10
	v_lshrrev_b32_e32 v10, 24, v86
	v_and_b32_e32 v13, 0x7fffffff, v11
	v_lshl_add_u32 v10, v10, 6, v0
	v_pk_add_f32 v[12:13], v[12:13], 0 neg_lo:[1,1] neg_hi:[1,1]
	ds_add_u32 v10, v205 offset:16384
	v_lshrrev_b32_e32 v10, 24, v85
	v_cndmask_b32_e32 v88, v12, v15, vcc
	v_lshl_add_u32 v10, v10, 6, v0
	v_xor_b32_e32 v14, -1, v11
	v_cmp_gt_i32_e64 s[2:3], 0, v11
	ds_add_u32 v10, v205 offset:16384
	v_lshrrev_b32_e32 v10, 24, v88
	v_cndmask_b32_e64 v87, v13, v14, s[2:3]
	v_lshl_add_u32 v10, v10, 6, v0
	ds_add_u32 v10, v205 offset:16384
	v_lshrrev_b32_e32 v10, 24, v87
	v_lshl_add_u32 v10, v10, 6, v0
	ds_add_u32 v10, v205 offset:16384
	ds_read_b128 v[10:13], v95
	ds_read_b128 v[14:17], v96
	ds_read_b128 v[22:25], v92
	ds_read_b128 v[26:29], v93
	ds_read2_b32 v[30:31], v137 offset0:80 offset1:96
	ds_read2_b32 v[38:39], v137 offset0:112 offset1:128
	s_waitcnt vmcnt(1) lgkmcnt(5)
	v_mfma_f32_16x16x32_bf16 v[10:13], v[244:247], v[10:13], 0
	ds_read2_b32 v[50:51], v137 offset0:144 offset1:160
	s_waitcnt vmcnt(0) lgkmcnt(5)
	v_mfma_f32_16x16x32_bf16 v[10:13], v[248:251], v[14:17], v[10:13]
	ds_read_b128 v[14:17], v90
	s_waitcnt lgkmcnt(5)
	v_mfma_f32_16x16x32_bf16 v[22:25], v[244:247], v[22:25], 0
	s_nop 4
	v_max_f32_e32 v32, 0, v10
	v_max_f32_e32 v10, 0, v12
	v_max_f32_e32 v33, 0, v11
	s_waitcnt lgkmcnt(3)
	v_mul_f32_e32 v34, v30, v10
	v_max_f32_e32 v36, 0, v13
	v_mfma_f32_16x16x32_bf16 v[10:13], v[248:251], v[26:29], v[22:25]
	s_nop 2
	ds_read_b128 v[22:25], v89
	s_waitcnt lgkmcnt(1)
	v_mfma_f32_16x16x32_bf16 v[14:17], v[244:247], v[14:17], 0
	s_nop 1
	v_max_f32_e32 v26, 0, v10
	v_max_f32_e32 v27, 0, v11
	v_max_f32_e32 v10, 0, v12
	v_mul_f32_e32 v28, v31, v10
	v_max_f32_e32 v37, 0, v13
	s_waitcnt lgkmcnt(0)
	v_mfma_f32_16x16x32_bf16 v[10:13], v[248:251], v[22:25], v[14:17]
	ds_read_b128 v[22:25], v94
	ds_read2_b32 v[94:95], v137 offset0:176 offset1:192
	v_pk_mul_f32 v[36:37], v[30:31], v[36:37]
	ds_read_b128 v[14:17], v91
	s_waitcnt lgkmcnt(0)
	v_mfma_f32_16x16x32_bf16 v[14:17], v[244:247], v[14:17], 0
	s_nop 1
	v_max_f32_e32 v40, 0, v10
	v_max_f32_e32 v41, 0, v11
	v_max_f32_e32 v10, 0, v12
	v_mul_f32_e32 v42, v38, v10
	s_nop 0
	v_max_f32_e32 v44, 0, v13
	v_mfma_f32_16x16x32_bf16 v[10:13], v[248:251], v[22:25], v[14:17]
	ds_read_b128 v[22:25], v98
	v_mov_b32_e32 v35, v36
	v_mov_b32_e32 v29, v37
	ds_read_b128 v[14:17], v97
	s_waitcnt lgkmcnt(0)
; #define LAS __attribute__((address_space(3)))
; __device__ __forceinline__ unsigned fkey(float f) { const unsigned u = __float_as_uint(f); return (u & 0x80000000u) ? ~u : (u | 0x80000000u); }
; #define SEL_HADD(idx_) __hip_atomic_fetch_add(&hist[(idx_)], 1u, __ATOMIC_RELAXED, __HIP_MEMORY_SCOPE_WORKGROUP)
; __device__ __forceinline__ void sel_unit(LAS char* lds, int b, int u, const bf16_t* QI, const bf16_t* KIDX, const float* WIDX, unsigned long long* MASK) {
;     ...
;     for (int j = 0; j < 8; ++j) {
;         if (j < nj) {
;             int t = wid + 8 * j; asm volatile("" : "+s"(t));
; #pragma unroll
;             for (int kh = 0; kh < 2; ++kh) {
;             bf16x8 kf[2][2];
; #pragma unroll
;             for (int kb = 0; kb < 2; ++kb)
; #pragma unroll
;                 for (int ks = 0; ks < 2; ++ks) kf[kb][ks] = *(const bf16x8*)(KIDX + (rowbase + 64 * t + 32 * kh + 16 * kb + q16) * 64 + 32 * ks + 8 * kg);
; #pragma unroll
;             for (int kb = 0; kb < 2; ++kb) {
;                 f32x4 s = (f32x4){0.f, 0.f, 0.f, 0.f};
; #pragma unroll
;                 for (int hh = 0; hh < 8; ++hh) {
;                     f32x4 a = (f32x4){0.f, 0.f, 0.f, 0.f};
; #pragma unroll
;                     for (int ks = 0; ks < 2; ++ks) {
;                         const bf16x8 qv = *(const LAS bf16x8*)(lds + L_QI + q16 * 1024 + (((hh * 8 + 4 * ks + kg) ^ q16) << 4));
;                         a = __builtin_amdgcn_mfma_f32_16x16x32_bf16(kf[kb][ks], qv, a, 0, 0, 0);
;                     }
;                     const float wh = wl[hh * 16];
; #pragma unroll
;                     for (int i = 0; i < 4; ++i) s[i] += wh * fmaxf(a[i], 0.f);
;                 }
;                 u32x4 kk; kk.x = fkey(s[0]); kk.y = fkey(s[1]); kk.z = fkey(s[2]); kk.w = fkey(s[3]);
;                 sc[j][2 * kh + kb] = kk;
; #pragma unroll
;                 for (int i = 0; i < 4; ++i) SEL_HADD((kk[i] >> 24) * 16 + q16);
;                 __builtin_amdgcn_sched_barrier(0);
	v_mfma_f32_16x16x32_bf16 v[14:17], v[244:247], v[14:17], 0
	s_nop 1
	v_max_f32_e32 v46, 0, v10
	v_max_f32_e32 v47, 0, v11
	v_max_f32_e32 v10, 0, v12
	v_mul_f32_e32 v48, v39, v10
	s_nop 0
	v_max_f32_e32 v45, 0, v13
	v_mfma_f32_16x16x32_bf16 v[10:13], v[248:251], v[22:25], v[14:17]
	ds_read_b128 v[22:25], v100
	v_pk_mul_f32 v[44:45], v[38:39], v[44:45]
	s_nop 0
	ds_read_b128 v[14:17], v99
	s_waitcnt lgkmcnt(0)
	v_mfma_f32_16x16x32_bf16 v[14:17], v[244:247], v[14:17], 0
	s_nop 1
	v_max_f32_e32 v52, 0, v10
	v_max_f32_e32 v53, 0, v11
	v_max_f32_e32 v10, 0, v12
	v_mul_f32_e32 v54, v50, v10
	s_nop 0
	v_max_f32_e32 v56, 0, v13
	v_mfma_f32_16x16x32_bf16 v[10:13], v[248:251], v[22:25], v[14:17]
	ds_read_b128 v[22:25], v102
	v_mov_b32_e32 v43, v44
	v_mov_b32_e32 v49, v45
	ds_read_b128 v[14:17], v101
	s_waitcnt lgkmcnt(0)
	v_mfma_f32_16x16x32_bf16 v[14:17], v[244:247], v[14:17], 0
	s_nop 1
	v_max_f32_e32 v90, 0, v10
	v_max_f32_e32 v91, 0, v11
	v_max_f32_e32 v10, 0, v12
	v_mul_f32_e32 v92, v51, v10
	s_nop 0
	v_max_f32_e32 v57, 0, v13
	v_mfma_f32_16x16x32_bf16 v[10:13], v[248:251], v[22:25], v[14:17]
	ds_read_b128 v[22:25], v104
	v_pk_mul_f32 v[56:57], v[50:51], v[56:57]
	s_nop 0
	ds_read_b128 v[14:17], v103
	s_waitcnt lgkmcnt(0)
	v_mfma_f32_16x16x32_bf16 v[6:9], v[244:247], v[14:17], 0
	s_nop 1
	s_nop 0
	v_max_f32_e32 v14, 0, v13
	s_nop 0
	v_mfma_f32_16x16x32_bf16 v[2:5], v[248:251], v[22:25], v[6:9]
	s_nop 0
	v_max_f32_e32 v10, 0, v10
	v_max_f32_e32 v11, 0, v11
	v_pk_fma_f32 v[8:9], v[30:31], v[32:33], 0 op_sel_hi:[0,1,0]
	s_nop 0
	s_nop 2
	v_max_f32_e32 v15, 0, v5
	v_pk_mul_f32 v[6:7], v[94:95], v[14:15]
	v_mov_b32_e32 v14, v31
	v_pk_fma_f32 v[8:9], v[14:15], v[26:27], v[8:9] op_sel_hi:[0,1,1]
	v_pk_fma_f32 v[8:9], v[38:39], v[40:41], v[8:9] op_sel_hi:[0,1,1]
	v_mov_b32_e32 v14, v39
	v_pk_fma_f32 v[8:9], v[14:15], v[46:47], v[8:9] op_sel_hi:[0,1,1]
	v_pk_fma_f32 v[8:9], v[50:51], v[52:53], v[8:9] op_sel_hi:[0,1,1]
	v_mov_b32_e32 v14, v51
	v_pk_fma_f32 v[8:9], v[14:15], v[90:91], v[8:9] op_sel_hi:[0,1,1]
	v_max_f32_e32 v2, 0, v2
	v_max_f32_e32 v3, 0, v3
	v_pk_fma_f32 v[8:9], v[94:95], v[10:11], v[8:9] op_sel_hi:[0,1,1]
	v_mov_b32_e32 v10, v95
	v_pk_fma_f32 v[2:3], v[10:11], v[2:3], v[8:9] op_sel_hi:[0,1,1]
	v_and_b32_e32 v9, 0x7fffffff, v3
	v_and_b32_e32 v8, 0x7fffffff, v2
	v_xor_b32_e32 v5, -1, v3
	v_pk_add_f32 v[8:9], v[8:9], 0 neg_lo:[1,1] neg_hi:[1,1]
	v_cmp_gt_i32_e32 vcc, 0, v3
	v_xor_b32_e32 v10, -1, v2
	v_mov_b32_e32 v55, v56
	v_cndmask_b32_e32 v89, v9, v5, vcc
	v_cmp_gt_i32_e32 vcc, 0, v2
	v_pk_add_f32 v[2:3], v[34:35], 0 op_sel_hi:[1,0]
	v_max_f32_e32 v12, 0, v12
	v_pk_add_f32 v[2:3], v[2:3], v[28:29]
	v_pk_add_f32 v[2:3], v[2:3], v[42:43]
	v_mov_b32_e32 v93, v57
	v_pk_add_f32 v[2:3], v[2:3], v[48:49]
	v_mul_f32_e32 v12, v94, v12
	v_pk_add_f32 v[2:3], v[2:3], v[54:55]
	v_max_f32_e32 v4, 0, v4
	v_pk_add_f32 v[2:3], v[2:3], v[92:93]
	v_mov_b32_e32 v13, v6
	v_mul_f32_e32 v4, v95, v4
	v_pk_add_f32 v[2:3], v[2:3], v[12:13]
	v_mov_b32_e32 v5, v7
	v_pk_add_f32 v[2:3], v[2:3], v[4:5]
	v_cndmask_b32_e32 v90, v8, v10, vcc
	v_and_b32_e32 v5, 0x7fffffff, v3
	v_and_b32_e32 v4, 0x7fffffff, v2
	v_xor_b32_e32 v6, -1, v3
	v_pk_add_f32 v[4:5], v[4:5], 0 neg_lo:[1,1] neg_hi:[1,1]
	v_cmp_gt_i32_e32 vcc, 0, v3
	v_xor_b32_e32 v7, -1, v2
	s_nop 0
	v_cndmask_b32_e32 v91, v5, v6, vcc
	v_cmp_gt_i32_e32 vcc, 0, v2
	v_lshrrev_b32_e32 v2, 24, v90
	v_lshl_add_u32 v2, v2, 6, v0
	ds_add_u32 v2, v205 offset:16384
	v_lshrrev_b32_e32 v2, 24, v89
	v_cndmask_b32_e32 v92, v4, v7, vcc
	v_lshl_add_u32 v2, v2, 6, v0
	ds_add_u32 v2, v205 offset:16384
	v_lshrrev_b32_e32 v2, 24, v92
	v_lshl_add_u32 v2, v2, 6, v0
	ds_add_u32 v2, v205 offset:16384
	v_lshrrev_b32_e32 v2, 24, v91
	v_lshl_add_u32 v2, v2, 6, v0
	ds_add_u32 v2, v205 offset:16384
.LBB0_660:
	s_cmp_gt_i32 s4, 2
	s_cselect_b64 s[54:55], -1, 0
	s_cmp_lt_i32 s4, 3
	s_cbranch_scc1 .LBB0_662
	s_add_i32 s0, s46, 16
	s_lshl_b32 s0, s0, 6
	s_ashr_i32 s1, s0, 31
	v_lshl_add_u64 v[2:3], v[18:19], 0, s[0:1]
	v_lshlrev_b64 v[2:3], 7, v[2:3]
	v_lshl_add_u64 v[22:23], v[20:21], 0, v[2:3]
	global_load_dwordx4 v[14:17], v[22:23], off
	global_load_dwordx4 v[10:13], v[22:23], off offset:64
	v_lshl_add_u32 v111, v182, 4, v150
	v_lshl_add_u32 v112, v183, 4, v150
	v_lshl_add_u32 v109, v185, 4, v150
	v_lshl_add_u32 v105, v180, 4, v150
	v_lshl_add_u32 v110, v159, 4, v150
	v_lshl_add_u32 v108, v184, 4, v150
	ds_read_b128 v[2:5], v111
	v_lshl_add_u32 v106, v179, 4, v150
	ds_read_b128 v[6:9], v112
	ds_read_b128 v[24:27], v108
	v_lshl_add_u32 v107, v176, 4, v150
	ds_read_b128 v[28:31], v109
	ds_read_b128 v[32:35], v106
	ds_read_b128 v[36:39], v105
	ds_read_b128 v[40:43], v107
	v_lshl_add_u32 v113, v158, 4, v150
	ds_read_b128 v[44:47], v110
	ds_read_b128 v[48:51], v113
	v_lshl_add_u32 v114, v157, 4, v150
	ds_read_b128 v[52:55], v114
	v_lshl_add_u32 v115, v156, 4, v150
	v_lshl_add_u32 v116, v155, 4, v150
	ds_read_b128 v[94:97], v115
	ds_read_b128 v[98:101], v116
	v_lshl_add_u32 v117, v154, 4, v150
	s_waitcnt vmcnt(1) lgkmcnt(11)
	v_mfma_f32_16x16x32_bf16 v[2:5], v[14:17], v[2:5], 0
	s_waitcnt lgkmcnt(9)
	v_mfma_f32_16x16x32_bf16 v[24:27], v[14:17], v[24:27], 0
	s_waitcnt lgkmcnt(7)
	v_mfma_f32_16x16x32_bf16 v[32:35], v[14:17], v[32:35], 0
	s_waitcnt lgkmcnt(5)
	v_mfma_f32_16x16x32_bf16 v[40:43], v[14:17], v[40:43], 0
	s_waitcnt lgkmcnt(3)
	v_mfma_f32_16x16x32_bf16 v[48:51], v[14:17], v[48:51], 0
	s_waitcnt vmcnt(0)
	v_mfma_f32_16x16x32_bf16 v[118:121], v[10:13], v[6:9], v[2:5]
	v_mfma_f32_16x16x32_bf16 v[24:27], v[10:13], v[28:31], v[24:27]
	v_mfma_f32_16x16x32_bf16 v[28:31], v[10:13], v[36:39], v[32:35]
	v_mfma_f32_16x16x32_bf16 v[32:35], v[10:13], v[44:47], v[40:43]
	ds_read2_b32 v[44:45], v137 offset0:80 offset1:96
	ds_read2_b32 v[46:47], v137 offset0:112 offset1:128
	s_nop 3
	s_waitcnt lgkmcnt(4)
; #define LAS __attribute__((address_space(3)))
; __device__ __forceinline__ unsigned fkey(float f) { const unsigned u = __float_as_uint(f); return (u & 0x80000000u) ? ~u : (u | 0x80000000u); }
; #define SEL_HADD(idx_) __hip_atomic_fetch_add(&hist[(idx_)], 1u, __ATOMIC_RELAXED, __HIP_MEMORY_SCOPE_WORKGROUP)
; __device__ __forceinline__ void sel_unit(LAS char* lds, int b, int u, const bf16_t* QI, const bf16_t* KIDX, const float* WIDX, unsigned long long* MASK) {
;     ...
;     for (int j = 0; j < 8; ++j) {
;         if (j < nj) {
;             int t = wid + 8 * j; asm volatile("" : "+s"(t));
; #pragma unroll
;             for (int kh = 0; kh < 2; ++kh) {
;             bf16x8 kf[2][2];
; #pragma unroll
;             for (int kb = 0; kb < 2; ++kb)
; #pragma unroll
;                 for (int ks = 0; ks < 2; ++ks) kf[kb][ks] = *(const bf16x8*)(KIDX + (rowbase + 64 * t + 32 * kh + 16 * kb + q16) * 64 + 32 * ks + 8 * kg);
; #pragma unroll
;             for (int kb = 0; kb < 2; ++kb) {
;                 f32x4 s = (f32x4){0.f, 0.f, 0.f, 0.f};
; #pragma unroll
;                 for (int hh = 0; hh < 8; ++hh) {
;                     f32x4 a = (f32x4){0.f, 0.f, 0.f, 0.f};
; #pragma unroll
;                     for (int ks = 0; ks < 2; ++ks) {
;                         const bf16x8 qv = *(const LAS bf16x8*)(lds + L_QI + q16 * 1024 + (((hh * 8 + 4 * ks + kg) ^ q16) << 4));
;                         a = __builtin_amdgcn_mfma_f32_16x16x32_bf16(kf[kb][ks], qv, a, 0, 0, 0);
;                     }
;                     const float wh = wl[hh * 16];
; #pragma unroll
;                     for (int i = 0; i < 4; ++i) s[i] += wh * fmaxf(a[i], 0.f);
;                 }
;                 u32x4 kk; kk.x = fkey(s[0]); kk.y = fkey(s[1]); kk.z = fkey(s[2]); kk.w = fkey(s[3]);
;                 sc[j][2 * kh + kb] = kk;
; #pragma unroll
;                 for (int i = 0; i < 4; ++i) SEL_HADD((kk[i] >> 24) * 16 + q16);
;                 __builtin_amdgcn_sched_barrier(0);
	v_mfma_f32_16x16x32_bf16 v[36:39], v[10:13], v[52:55], v[48:51]
	s_nop 0
	ds_read2_b32 v[48:49], v137 offset0:144 offset1:160
	global_load_dwordx4 v[6:9], v[22:23], off offset:2048
	global_load_dwordx4 v[2:5], v[22:23], off offset:2112
	v_mov_b32_e32 v252, 0x1000
	v_mov_b32_e32 v253, 0
	v_lshl_add_u64 v[252:253], v[252:253], 0, v[22:23]
	global_load_dwordx4 v[236:239], v[252:253], off
	global_load_dwordx4 v[240:243], v[252:253], off offset:64
	global_load_dwordx4 v[244:247], v[252:253], off offset:2048
	global_load_dwordx4 v[248:251], v[252:253], off offset:2112
	s_waitcnt lgkmcnt(4)
	v_mfma_f32_16x16x32_bf16 v[94:97], v[14:17], v[94:97], 0
	s_nop 0
	v_max_f32_e32 v54, v24, v24
	s_nop 0
	s_waitcnt lgkmcnt(3)
	v_mfma_f32_16x16x32_bf16 v[40:43], v[10:13], v[98:101], v[94:97]
	v_max_f32_e32 v93, v39, v39
	v_max_f32_e32 v24, 0, v121
	v_max_f32_e32 v39, 0, v25
	v_max_f32_e32 v96, 0, v26
	v_max_f32_e32 v25, 0, v27
	v_max_f32_e32 v26, 0, v31
	v_max_f32_e32 v27, 0, v35
	v_max_f32_e32 v53, 0, v37
	s_waitcnt lgkmcnt(2)
	v_mul_f32_e32 v56, v45, v96
	v_pk_mul_f32 v[96:97], v[44:45], v[24:25]
	s_waitcnt lgkmcnt(1)
	v_pk_mul_f32 v[102:103], v[46:47], v[26:27]
	ds_read_b128 v[24:27], v117
	v_max_f32_e32 v94, v40, v40
	v_max_f32_e32 v40, 0, v28
	v_max_f32_e32 v28, 0, v30
	v_max_f32_e32 v50, v118, v118
	v_max_f32_e32 v95, v41, v41
	v_max_f32_e32 v41, 0, v29
	v_max_f32_e32 v29, 0, v34
	v_max_f32_e32 v30, 0, v38
	v_mul_f32_e32 v98, v46, v28
	v_max_f32_e32 v28, 0, v42
	v_lshl_add_u32 v118, v153, 4, v150
	v_mul_f32_e32 v100, v47, v29
	s_waitcnt lgkmcnt(1)
	v_mul_f32_e32 v122, v48, v30
	v_mul_f32_e32 v124, v49, v28
	ds_read_b128 v[28:31], v118
	s_waitcnt lgkmcnt(1)
	v_mfma_f32_16x16x32_bf16 v[24:27], v[14:17], v[24:27], 0
	v_max_f32_e32 v51, v119, v119
	v_lshl_add_u32 v119, v152, 4, v150
	s_waitcnt lgkmcnt(0)
	v_mfma_f32_16x16x32_bf16 v[24:27], v[10:13], v[28:31], v[24:27]
	ds_read_b128 v[28:31], v119
	v_max_f32_e32 v37, 0, v51
	v_max_f32_e32 v51, 0, v33
	v_max_f32_e32 v52, v120, v120
	v_max_f32_e32 v55, v36, v36
	v_max_f32_e32 v36, 0, v50
	v_max_f32_e32 v50, 0, v32
	v_max_f32_e32 v32, 0, v93
	v_max_f32_e32 v33, 0, v43
	v_lshl_add_u32 v120, v151, 4, v150
	v_pk_mul_f32 v[126:127], v[48:49], v[32:33]
	ds_read_b128 v[32:35], v120
	s_waitcnt lgkmcnt(1)
	v_mfma_f32_16x16x32_bf16 v[14:17], v[14:17], v[28:31], 0
	v_max_f32_e32 v42, 0, v52
	v_max_f32_e32 v38, 0, v54
	v_max_f32_e32 v52, 0, v55
	s_waitcnt lgkmcnt(0)
	v_mfma_f32_16x16x32_bf16 v[10:13], v[10:13], v[32:35], v[14:17]
	v_max_f32_e32 v54, 0, v94
	v_max_f32_e32 v55, 0, v95
	ds_read2_b32 v[94:95], v137 offset0:176 offset1:192
	s_nop 0
	v_max_f32_e32 v28, 0, v27
	s_nop 2
	v_max_f32_e32 v29, 0, v13
	s_waitcnt lgkmcnt(0)
	v_pk_mul_f32 v[14:15], v[94:95], v[28:29]
	v_pk_fma_f32 v[16:17], v[44:45], v[36:37], 0 op_sel_hi:[0,1,0]
	v_mov_b32_e32 v28, v45
	v_pk_fma_f32 v[16:17], v[28:29], v[38:39], v[16:17] op_sel_hi:[0,1,1]
	v_pk_fma_f32 v[16:17], v[46:47], v[40:41], v[16:17] op_sel_hi:[0,1,1]
	v_mov_b32_e32 v28, v47
	v_pk_fma_f32 v[16:17], v[28:29], v[50:51], v[16:17] op_sel_hi:[0,1,1]
	v_pk_fma_f32 v[16:17], v[48:49], v[52:53], v[16:17] op_sel_hi:[0,1,1]
	v_mov_b32_e32 v28, v49
	v_max_f32_e32 v24, 0, v24
	v_max_f32_e32 v25, 0, v25
	v_pk_fma_f32 v[16:17], v[28:29], v[54:55], v[16:17] op_sel_hi:[0,1,1]
	v_max_f32_e32 v10, 0, v10
	v_max_f32_e32 v11, 0, v11
	v_pk_fma_f32 v[16:17], v[94:95], v[24:25], v[16:17] op_sel_hi:[0,1,1]
	v_mov_b32_e32 v24, v95
	v_pk_fma_f32 v[10:11], v[24:25], v[10:11], v[16:17] op_sel_hi:[0,1,1]
	v_and_b32_e32 v17, 0x7fffffff, v11
	v_and_b32_e32 v16, 0x7fffffff, v10
	v_mul_f32_e32 v42, v44, v42
	v_xor_b32_e32 v13, -1, v11
	v_pk_add_f32 v[16:17], v[16:17], 0 neg_lo:[1,1] neg_hi:[1,1]
	v_cmp_gt_i32_e32 vcc, 0, v11
	v_mov_b32_e32 v43, v96
	v_xor_b32_e32 v24, -1, v10
	v_cndmask_b32_e32 v93, v17, v13, vcc
	v_cmp_gt_i32_e32 vcc, 0, v10
	v_pk_add_f32 v[10:11], v[42:43], 0 op_sel_hi:[1,0]
	v_mov_b32_e32 v57, v97
	v_pk_add_f32 v[10:11], v[10:11], v[56:57]
	v_mov_b32_e32 v99, v102
	v_pk_add_f32 v[10:11], v[10:11], v[98:99]
	v_mov_b32_e32 v101, v103
	v_pk_add_f32 v[10:11], v[10:11], v[100:101]
	v_mov_b32_e32 v123, v126
	v_max_f32_e32 v26, 0, v26
	v_pk_add_f32 v[10:11], v[10:11], v[122:123]
	v_mov_b32_e32 v125, v127
	v_mul_f32_e32 v26, v94, v26
	v_max_f32_e32 v12, 0, v12
	v_pk_add_f32 v[10:11], v[10:11], v[124:125]
	v_mov_b32_e32 v27, v14
	v_mul_f32_e32 v12, v95, v12
	v_pk_add_f32 v[10:11], v[10:11], v[26:27]
	v_mov_b32_e32 v13, v15
	v_pk_add_f32 v[10:11], v[10:11], v[12:13]
	v_cndmask_b32_e32 v94, v16, v24, vcc
	v_and_b32_e32 v13, 0x7fffffff, v11
	v_and_b32_e32 v12, 0x7fffffff, v10
	v_xor_b32_e32 v14, -1, v11
	v_pk_add_f32 v[12:13], v[12:13], 0 neg_lo:[1,1] neg_hi:[1,1]
	v_cmp_gt_i32_e32 vcc, 0, v11
	v_xor_b32_e32 v15, -1, v10
	s_nop 0
	v_cndmask_b32_e32 v95, v13, v14, vcc
	v_cmp_gt_i32_e32 vcc, 0, v10
	v_lshrrev_b32_e32 v10, 24, v94
	v_lshl_add_u32 v10, v10, 6, v0
	ds_add_u32 v10, v205 offset:16384
	v_lshrrev_b32_e32 v10, 24, v93
	v_cndmask_b32_e32 v96, v12, v15, vcc
	v_lshl_add_u32 v10, v10, 6, v0
	ds_add_u32 v10, v205 offset:16384
	v_lshrrev_b32_e32 v10, 24, v96
	v_lshl_add_u32 v10, v10, 6, v0
	ds_add_u32 v10, v205 offset:16384
	v_lshrrev_b32_e32 v10, 24, v95
	v_lshl_add_u32 v10, v10, 6, v0
	ds_add_u32 v10, v205 offset:16384
	ds_read_b128 v[10:13], v111
	ds_read_b128 v[14:17], v112
	ds_read_b128 v[24:27], v108
	ds_read_b128 v[28:31], v109
	ds_read2_b32 v[50:51], v137 offset0:144 offset1:160
	s_waitcnt vmcnt(5) lgkmcnt(4)
	v_mfma_f32_16x16x32_bf16 v[10:13], v[6:9], v[10:13], 0
	ds_read_b128 v[38:41], v110
	ds_read_b128 v[44:47], v114
	s_waitcnt lgkmcnt(4)
	v_mfma_f32_16x16x32_bf16 v[24:27], v[6:9], v[24:27], 0
	s_waitcnt vmcnt(4)
; #define LAS __attribute__((address_space(3)))
; __device__ __forceinline__ unsigned fkey(float f) { const unsigned u = __float_as_uint(f); return (u & 0x80000000u) ? ~u : (u | 0x80000000u); }
; #define SEL_HADD(idx_) __hip_atomic_fetch_add(&hist[(idx_)], 1u, __ATOMIC_RELAXED, __HIP_MEMORY_SCOPE_WORKGROUP)
; __device__ __forceinline__ void sel_unit(LAS char* lds, int b, int u, const bf16_t* QI, const bf16_t* KIDX, const float* WIDX, unsigned long long* MASK) {
;     ...
;     for (int j = 0; j < 8; ++j) {
;         if (j < nj) {
;             int t = wid + 8 * j; asm volatile("" : "+s"(t));
; #pragma unroll
;             for (int kh = 0; kh < 2; ++kh) {
;             bf16x8 kf[2][2];
; #pragma unroll
;             for (int kb = 0; kb < 2; ++kb)
; #pragma unroll
;                 for (int ks = 0; ks < 2; ++ks) kf[kb][ks] = *(const bf16x8*)(KIDX + (rowbase + 64 * t + 32 * kh + 16 * kb + q16) * 64 + 32 * ks + 8 * kg);
; #pragma unroll
;             for (int kb = 0; kb < 2; ++kb) {
;                 f32x4 s = (f32x4){0.f, 0.f, 0.f, 0.f};
; #pragma unroll
;                 for (int hh = 0; hh < 8; ++hh) {
;                     f32x4 a = (f32x4){0.f, 0.f, 0.f, 0.f};
; #pragma unroll
;                     for (int ks = 0; ks < 2; ++ks) {
;                         const bf16x8 qv = *(const LAS bf16x8*)(lds + L_QI + q16 * 1024 + (((hh * 8 + 4 * ks + kg) ^ q16) << 4));
;                         a = __builtin_amdgcn_mfma_f32_16x16x32_bf16(kf[kb][ks], qv, a, 0, 0, 0);
;                     }
;                     const float wh = wl[hh * 16];
; #pragma unroll
;                     for (int i = 0; i < 4; ++i) s[i] += wh * fmaxf(a[i], 0.f);
;                 }
;                 u32x4 kk; kk.x = fkey(s[0]); kk.y = fkey(s[1]); kk.z = fkey(s[2]); kk.w = fkey(s[3]);
;                 sc[j][2 * kh + kb] = kk;
; #pragma unroll
;                 for (int i = 0; i < 4; ++i) SEL_HADD((kk[i] >> 24) * 16 + q16);
;                 __builtin_amdgcn_sched_barrier(0);
	v_mfma_f32_16x16x32_bf16 v[14:17], v[2:5], v[14:17], v[10:13]
	s_waitcnt lgkmcnt(3)
	v_mfma_f32_16x16x32_bf16 v[26:29], v[2:5], v[28:31], v[24:27]
	s_nop 0
	ds_read2_b32 v[12:13], v137 offset0:80 offset1:96
	s_nop 3
	v_max_f32_e32 v32, 0, v17
	v_max_f32_e32 v14, 0, v14
	v_max_f32_e32 v26, 0, v26
	v_max_f32_e32 v27, 0, v27
	v_max_f32_e32 v11, 0, v28
	v_max_f32_e32 v15, 0, v15
	v_max_f32_e32 v10, v16, v16
	s_waitcnt lgkmcnt(0)
	v_mul_f32_e32 v16, v13, v11
	v_max_f32_e32 v11, v29, v29
	ds_read_b128 v[28:31], v106
	v_max_f32_e32 v33, 0, v11
	v_pk_mul_f32 v[24:25], v[12:13], v[32:33]
	ds_read_b128 v[32:35], v105
	s_waitcnt lgkmcnt(1)
	v_mfma_f32_16x16x32_bf16 v[28:31], v[6:9], v[28:31], 0
	v_max_f32_e32 v10, 0, v10
	v_mul_f32_e32 v10, v12, v10
	v_mov_b32_e32 v17, v25
	s_waitcnt lgkmcnt(0)
	v_mfma_f32_16x16x32_bf16 v[32:35], v[2:5], v[32:35], v[28:31]
	s_nop 2
	ds_read2_b32 v[30:31], v137 offset0:112 offset1:128
	s_nop 3
	v_max_f32_e32 v32, 0, v32
	v_max_f32_e32 v33, 0, v33
	v_max_f32_e32 v11, 0, v34
	s_waitcnt lgkmcnt(0)
	v_mul_f32_e32 v28, v30, v11
	v_max_f32_e32 v11, v35, v35
	ds_read_b128 v[34:37], v107
	s_waitcnt lgkmcnt(0)
	v_mfma_f32_16x16x32_bf16 v[34:37], v[6:9], v[34:37], 0
	v_max_f32_e32 v42, 0, v11
	v_mfma_f32_16x16x32_bf16 v[34:37], v[2:5], v[38:41], v[34:37]
	s_nop 7
	v_max_f32_e32 v38, 0, v34
	v_max_f32_e32 v39, 0, v35
	v_max_f32_e32 v11, 0, v36
	v_mul_f32_e32 v34, v31, v11
	v_max_f32_e32 v43, 0, v37
	v_pk_mul_f32 v[36:37], v[30:31], v[42:43]
	ds_read_b128 v[40:43], v113
	s_waitcnt lgkmcnt(0)
	v_mfma_f32_16x16x32_bf16 v[40:43], v[6:9], v[40:43], 0
	v_mov_b32_e32 v29, v36
	v_mov_b32_e32 v35, v37
	v_mfma_f32_16x16x32_bf16 v[40:43], v[2:5], v[44:47], v[40:43]
	ds_read_b128 v[46:49], v116
	s_nop 6
	v_max_f32_e32 v52, 0, v40
	v_max_f32_e32 v53, 0, v41
	v_max_f32_e32 v11, 0, v42
	v_mul_f32_e32 v40, v50, v11
	v_max_f32_e32 v11, v43, v43
	ds_read_b128 v[42:45], v115
	s_waitcnt lgkmcnt(0)
	v_mfma_f32_16x16x32_bf16 v[42:45], v[6:9], v[42:45], 0
	v_max_f32_e32 v54, 0, v11
	v_mfma_f32_16x16x32_bf16 v[42:45], v[2:5], v[46:49], v[42:45]
	ds_read_b128 v[46:49], v118
	s_nop 6
	v_max_f32_e32 v56, 0, v42
	v_max_f32_e32 v57, 0, v43
	v_max_f32_e32 v11, 0, v44
	v_mul_f32_e32 v100, v51, v11
	v_max_f32_e32 v11, v45, v45
	ds_read_b128 v[42:45], v117
	s_waitcnt lgkmcnt(0)
	v_mfma_f32_16x16x32_bf16 v[42:45], v[6:9], v[42:45], 0
	v_max_f32_e32 v55, 0, v11
	v_pk_mul_f32 v[54:55], v[50:51], v[54:55]
	v_mfma_f32_16x16x32_bf16 v[42:45], v[2:5], v[46:49], v[42:45]
	ds_read2_b32 v[46:47], v137 offset0:176 offset1:192
	v_mov_b32_e32 v41, v54
	v_mov_b32_e32 v101, v55
	s_nop 4
	v_max_f32_e32 v48, 0, v42
	v_max_f32_e32 v49, 0, v43
	v_max_f32_e32 v11, 0, v44
	s_waitcnt lgkmcnt(0)
	v_mul_f32_e32 v102, v46, v11
	v_max_f32_e32 v11, v45, v45
	ds_read_b128 v[42:45], v119
	s_waitcnt lgkmcnt(0)
	v_mfma_f32_16x16x32_bf16 v[6:9], v[6:9], v[42:45], 0
	ds_read_b128 v[42:45], v120
	v_max_f32_e32 v98, 0, v11
	s_waitcnt lgkmcnt(0)
	v_mfma_f32_16x16x32_bf16 v[2:5], v[2:5], v[42:45], v[6:9]
	s_nop 3
	v_fma_f32 v8, v12, v14, 0
	v_fma_f32 v9, v12, v15, 0
	v_mov_b32_e32 v12, v13
	v_pk_fma_f32 v[8:9], v[12:13], v[26:27], v[8:9] op_sel_hi:[0,1,1]
	v_pk_fma_f32 v[8:9], v[30:31], v[32:33], v[8:9] op_sel_hi:[0,1,1]
	v_mov_b32_e32 v12, v31
	v_pk_fma_f32 v[8:9], v[12:13], v[38:39], v[8:9] op_sel_hi:[0,1,1]
	v_pk_fma_f32 v[8:9], v[50:51], v[52:53], v[8:9] op_sel_hi:[0,1,1]
	v_mov_b32_e32 v12, v51
	v_pk_fma_f32 v[8:9], v[12:13], v[56:57], v[8:9] op_sel_hi:[0,1,1]
	v_max_f32_e32 v2, 0, v2
	v_max_f32_e32 v3, 0, v3
	v_pk_fma_f32 v[8:9], v[46:47], v[48:49], v[8:9] op_sel_hi:[0,1,1]
	v_mov_b32_e32 v12, v47
	v_pk_fma_f32 v[2:3], v[12:13], v[2:3], v[8:9] op_sel_hi:[0,1,1]
	v_and_b32_e32 v9, 0x7fffffff, v3
	v_and_b32_e32 v8, 0x7fffffff, v2
	v_max_f32_e32 v99, 0, v5
	v_xor_b32_e32 v11, -1, v2
	v_pk_add_f32 v[8:9], v[8:9], 0 neg_lo:[1,1] neg_hi:[1,1]
	v_cmp_gt_i32_e32 vcc, 0, v2
	v_pk_mul_f32 v[6:7], v[46:47], v[98:99]
	v_xor_b32_e32 v5, -1, v3
	v_cndmask_b32_e32 v98, v8, v11, vcc
	v_mov_b32_e32 v11, v24
	v_cmp_gt_i32_e64 s[2:3], 0, v3
	v_pk_add_f32 v[2:3], v[10:11], 0 op_sel_hi:[1,0]
	v_pk_add_f32 v[2:3], v[2:3], v[16:17]
	v_max_f32_e32 v4, 0, v4
	v_pk_add_f32 v[2:3], v[2:3], v[28:29]
	v_mov_b32_e32 v103, v6
	v_pk_add_f32 v[2:3], v[2:3], v[34:35]
	v_mul_f32_e32 v4, v47, v4
	v_pk_add_f32 v[2:3], v[2:3], v[40:41]
	v_cndmask_b32_e64 v97, v9, v5, s[2:3]
	v_pk_add_f32 v[2:3], v[2:3], v[100:101]
	v_mov_b32_e32 v5, v7
	v_pk_add_f32 v[2:3], v[2:3], v[102:103]
	s_nop 0
	v_pk_add_f32 v[2:3], v[2:3], v[4:5]
	s_nop 0
	v_xor_b32_e32 v7, -1, v2
	v_and_b32_e32 v4, 0x7fffffff, v2
	v_cmp_gt_i32_e32 vcc, 0, v2
	v_lshrrev_b32_e32 v2, 24, v98
	v_and_b32_e32 v5, 0x7fffffff, v3
	v_lshl_add_u32 v2, v2, 6, v0
	v_pk_add_f32 v[4:5], v[4:5], 0 neg_lo:[1,1] neg_hi:[1,1]
	ds_add_u32 v2, v205 offset:16384
	v_lshrrev_b32_e32 v2, 24, v97
	v_cndmask_b32_e32 v100, v4, v7, vcc
	v_lshl_add_u32 v2, v2, 6, v0
	v_xor_b32_e32 v6, -1, v3
	v_cmp_gt_i32_e64 s[2:3], 0, v3
	ds_add_u32 v2, v205 offset:16384
	v_lshrrev_b32_e32 v2, 24, v100
	v_cndmask_b32_e64 v99, v5, v6, s[2:3]
	v_lshl_add_u32 v2, v2, 6, v0
	ds_add_u32 v2, v205 offset:16384
	v_lshrrev_b32_e32 v2, 24, v99
	v_lshl_add_u32 v2, v2, 6, v0
	ds_add_u32 v2, v205 offset:16384
	ds_read_b128 v[22:25], v111
	ds_read_b128 v[26:29], v112
	s_waitcnt vmcnt(3) lgkmcnt(1)
	v_mfma_f32_16x16x32_bf16 v[22:25], v[236:239], v[22:25], 0
	ds_read_b128 v[32:35], v109
	ds_read_b128 v[38:41], v105
	ds_read_b128 v[44:47], v110
	s_waitcnt vmcnt(2) lgkmcnt(3)
; #define LAS __attribute__((address_space(3)))
; __device__ __forceinline__ unsigned fkey(float f) { const unsigned u = __float_as_uint(f); return (u & 0x80000000u) ? ~u : (u | 0x80000000u); }
; #define SEL_HADD(idx_) __hip_atomic_fetch_add(&hist[(idx_)], 1u, __ATOMIC_RELAXED, __HIP_MEMORY_SCOPE_WORKGROUP)
; __device__ __forceinline__ void sel_unit(LAS char* lds, int b, int u, const bf16_t* QI, const bf16_t* KIDX, const float* WIDX, unsigned long long* MASK) {
;     ...
;     for (int j = 0; j < 8; ++j) {
;         if (j < nj) {
;             int t = wid + 8 * j; asm volatile("" : "+s"(t));
; #pragma unroll
;             for (int kh = 0; kh < 2; ++kh) {
;             bf16x8 kf[2][2];
; #pragma unroll
;             for (int kb = 0; kb < 2; ++kb)
; #pragma unroll
;                 for (int ks = 0; ks < 2; ++ks) kf[kb][ks] = *(const bf16x8*)(KIDX + (rowbase + 64 * t + 32 * kh + 16 * kb + q16) * 64 + 32 * ks + 8 * kg);
; #pragma unroll
;             for (int kb = 0; kb < 2; ++kb) {
;                 f32x4 s = (f32x4){0.f, 0.f, 0.f, 0.f};
; #pragma unroll
;                 for (int hh = 0; hh < 8; ++hh) {
;                     f32x4 a = (f32x4){0.f, 0.f, 0.f, 0.f};
; #pragma unroll
;                     for (int ks = 0; ks < 2; ++ks) {
;                         const bf16x8 qv = *(const LAS bf16x8*)(lds + L_QI + q16 * 1024 + (((hh * 8 + 4 * ks + kg) ^ q16) << 4));
;                         a = __builtin_amdgcn_mfma_f32_16x16x32_bf16(kf[kb][ks], qv, a, 0, 0, 0);
;                     }
;                     const float wh = wl[hh * 16];
; #pragma unroll
;                     for (int i = 0; i < 4; ++i) s[i] += wh * fmaxf(a[i], 0.f);
;                 }
;                 u32x4 kk; kk.x = fkey(s[0]); kk.y = fkey(s[1]); kk.z = fkey(s[2]); kk.w = fkey(s[3]);
;                 sc[j][2 * kh + kb] = kk;
; #pragma unroll
;                 for (int i = 0; i < 4; ++i) SEL_HADD((kk[i] >> 24) * 16 + q16);
;                 __builtin_amdgcn_sched_barrier(0);
	v_mfma_f32_16x16x32_bf16 v[26:29], v[240:243], v[26:29], v[22:25]
	ds_read_b128 v[50:53], v114
	ds_read_b128 v[122:125], v116
	ds_read_b128 v[126:129], v118
	ds_read2_b32 v[24:25], v137 offset0:80 offset1:96
	s_nop 3
	v_max_f32_e32 v26, 0, v26
	v_max_f32_e32 v27, 0, v27
	v_max_f32_e32 v22, v28, v28
	v_max_f32_e32 v23, v29, v29
	ds_read_b128 v[28:31], v108
	s_waitcnt lgkmcnt(0)
	v_mfma_f32_16x16x32_bf16 v[28:31], v[236:239], v[28:31], 0
	v_max_f32_e32 v36, 0, v23
	v_max_f32_e32 v22, 0, v22
	v_mul_f32_e32 v22, v24, v22
	v_mfma_f32_16x16x32_bf16 v[28:31], v[240:243], v[32:35], v[28:31]
	s_nop 7
	v_max_f32_e32 v32, 0, v28
	v_max_f32_e32 v33, 0, v29
	v_max_f32_e32 v23, 0, v30
	v_mul_f32_e32 v28, v25, v23
	v_max_f32_e32 v37, 0, v31
	v_pk_mul_f32 v[30:31], v[24:25], v[36:37]
	ds_read_b128 v[34:37], v106
	s_waitcnt lgkmcnt(0)
	v_mfma_f32_16x16x32_bf16 v[34:37], v[236:239], v[34:37], 0
	v_mov_b32_e32 v29, v31
	v_mfma_f32_16x16x32_bf16 v[38:41], v[240:243], v[38:41], v[34:37]
	s_nop 5
	ds_read2_b32 v[36:37], v137 offset0:112 offset1:128
	s_nop 0
	v_max_f32_e32 v38, 0, v38
	v_max_f32_e32 v39, 0, v39
	v_max_f32_e32 v23, 0, v40
	s_waitcnt lgkmcnt(0)
	v_mul_f32_e32 v34, v36, v23
	v_max_f32_e32 v23, v41, v41
	ds_read_b128 v[40:43], v107
	s_waitcnt lgkmcnt(0)
	v_mfma_f32_16x16x32_bf16 v[40:43], v[236:239], v[40:43], 0
	v_max_f32_e32 v48, 0, v23
	v_mfma_f32_16x16x32_bf16 v[40:43], v[240:243], v[44:47], v[40:43]
	s_nop 7
	v_max_f32_e32 v44, 0, v40
	v_max_f32_e32 v45, 0, v41
	v_max_f32_e32 v23, 0, v42
	v_mul_f32_e32 v40, v37, v23
	v_max_f32_e32 v49, 0, v43
	v_pk_mul_f32 v[42:43], v[36:37], v[48:49]
	ds_read_b128 v[46:49], v113
	s_waitcnt lgkmcnt(0)
	v_mfma_f32_16x16x32_bf16 v[46:49], v[236:239], v[46:49], 0
	v_mov_b32_e32 v35, v42
	v_mov_b32_e32 v41, v43
	v_mfma_f32_16x16x32_bf16 v[50:53], v[240:243], v[50:53], v[46:49]
	s_nop 4
	ds_read2_b32 v[48:49], v137 offset0:144 offset1:160
	s_nop 1
	v_max_f32_e32 v50, 0, v50
	v_max_f32_e32 v51, 0, v51
	v_max_f32_e32 v23, 0, v52
	s_waitcnt lgkmcnt(0)
	v_mul_f32_e32 v46, v48, v23
	v_max_f32_e32 v23, v53, v53
	ds_read_b128 v[52:55], v115
	s_waitcnt lgkmcnt(0)
	v_mfma_f32_16x16x32_bf16 v[52:55], v[236:239], v[52:55], 0
	v_max_f32_e32 v102, 0, v23
	v_mfma_f32_16x16x32_bf16 v[52:55], v[240:243], v[122:125], v[52:55]
	ds_read_b128 v[122:125], v117
	s_waitcnt lgkmcnt(0)
	v_mfma_f32_16x16x32_bf16 v[122:125], v[236:239], v[122:125], 0
	s_nop 4
	v_max_f32_e32 v56, 0, v52
	v_max_f32_e32 v57, 0, v53
	v_max_f32_e32 v23, 0, v54
	v_mfma_f32_16x16x32_bf16 v[122:125], v[240:243], v[126:129], v[122:125]
	v_mul_f32_e32 v52, v49, v23
	s_nop 0
	v_max_f32_e32 v103, 0, v55
	v_pk_mul_f32 v[54:55], v[48:49], v[102:103]
	ds_read2_b32 v[102:103], v137 offset0:176 offset1:192
	s_nop 2
	v_max_f32_e32 v126, 0, v122
	v_max_f32_e32 v127, 0, v123
	v_max_f32_e32 v23, 0, v124
	s_waitcnt lgkmcnt(0)
	v_mul_f32_e32 v128, v102, v23
	v_max_f32_e32 v23, v125, v125
	ds_read_b128 v[122:125], v119
	s_waitcnt lgkmcnt(0)
	v_mfma_f32_16x16x32_bf16 v[14:17], v[236:239], v[122:125], 0
	ds_read_b128 v[122:125], v120
	v_max_f32_e32 v130, 0, v23
	v_mov_b32_e32 v47, v54
	s_waitcnt lgkmcnt(0)
	v_mfma_f32_16x16x32_bf16 v[10:13], v[240:243], v[122:125], v[14:17]
	v_mov_b32_e32 v53, v55
	s_nop 1
	v_pk_fma_f32 v[16:17], v[24:25], v[26:27], 0 op_sel_hi:[0,1,0]
	v_mov_b32_e32 v24, v25
	v_pk_fma_f32 v[16:17], v[24:25], v[32:33], v[16:17] op_sel_hi:[0,1,1]
	v_pk_fma_f32 v[16:17], v[36:37], v[38:39], v[16:17] op_sel_hi:[0,1,1]
	v_mov_b32_e32 v24, v37
	v_pk_fma_f32 v[16:17], v[24:25], v[44:45], v[16:17] op_sel_hi:[0,1,1]
	v_pk_fma_f32 v[16:17], v[48:49], v[50:51], v[16:17] op_sel_hi:[0,1,1]
	v_mov_b32_e32 v24, v49
	v_pk_fma_f32 v[16:17], v[24:25], v[56:57], v[16:17] op_sel_hi:[0,1,1]
	v_max_f32_e32 v10, 0, v10
	v_max_f32_e32 v11, 0, v11
	v_pk_fma_f32 v[16:17], v[102:103], v[126:127], v[16:17] op_sel_hi:[0,1,1]
	v_mov_b32_e32 v24, v103
	v_pk_fma_f32 v[10:11], v[24:25], v[10:11], v[16:17] op_sel_hi:[0,1,1]
	v_and_b32_e32 v17, 0x7fffffff, v11
	v_and_b32_e32 v16, 0x7fffffff, v10
	v_max_f32_e32 v131, 0, v13
	v_xor_b32_e32 v23, -1, v10
	v_pk_add_f32 v[16:17], v[16:17], 0 neg_lo:[1,1] neg_hi:[1,1]
	v_cmp_gt_i32_e32 vcc, 0, v10
	v_pk_mul_f32 v[14:15], v[102:103], v[130:131]
	v_xor_b32_e32 v13, -1, v11
	v_cndmask_b32_e32 v102, v16, v23, vcc
	v_mov_b32_e32 v23, v30
	v_cmp_gt_i32_e64 s[2:3], 0, v11
	v_pk_add_f32 v[10:11], v[22:23], 0 op_sel_hi:[1,0]
	v_pk_add_f32 v[10:11], v[10:11], v[28:29]
	v_max_f32_e32 v12, 0, v12
	v_pk_add_f32 v[10:11], v[10:11], v[34:35]
	v_mov_b32_e32 v129, v14
	v_pk_add_f32 v[10:11], v[10:11], v[40:41]
	v_mul_f32_e32 v12, v103, v12
	v_pk_add_f32 v[10:11], v[10:11], v[46:47]
	v_cndmask_b32_e64 v101, v17, v13, s[2:3]
	v_pk_add_f32 v[10:11], v[10:11], v[52:53]
	v_mov_b32_e32 v13, v15
	v_pk_add_f32 v[10:11], v[10:11], v[128:129]
	s_nop 0
	v_pk_add_f32 v[10:11], v[10:11], v[12:13]
	s_nop 0
	v_xor_b32_e32 v15, -1, v10
	v_and_b32_e32 v12, 0x7fffffff, v10
	v_cmp_gt_i32_e32 vcc, 0, v10
	v_lshrrev_b32_e32 v10, 24, v102
	v_and_b32_e32 v13, 0x7fffffff, v11
	v_lshl_add_u32 v10, v10, 6, v0
	v_pk_add_f32 v[12:13], v[12:13], 0 neg_lo:[1,1] neg_hi:[1,1]
	ds_add_u32 v10, v205 offset:16384
	v_lshrrev_b32_e32 v10, 24, v101
	v_cndmask_b32_e32 v104, v12, v15, vcc
	v_lshl_add_u32 v10, v10, 6, v0
	v_xor_b32_e32 v14, -1, v11
	v_cmp_gt_i32_e64 s[2:3], 0, v11
	ds_add_u32 v10, v205 offset:16384
	v_lshrrev_b32_e32 v10, 24, v104
	v_cndmask_b32_e64 v103, v13, v14, s[2:3]
	v_lshl_add_u32 v10, v10, 6, v0
	ds_add_u32 v10, v205 offset:16384
	v_lshrrev_b32_e32 v10, 24, v103
	v_lshl_add_u32 v10, v10, 6, v0
	ds_add_u32 v10, v205 offset:16384
	ds_read_b128 v[10:13], v111
	ds_read_b128 v[14:17], v112
	ds_read_b128 v[22:25], v108
	ds_read_b128 v[26:29], v109
	ds_read2_b32 v[30:31], v137 offset0:80 offset1:96
	ds_read2_b32 v[38:39], v137 offset0:112 offset1:128
	s_waitcnt vmcnt(1) lgkmcnt(5)
; #define LAS __attribute__((address_space(3)))
; __device__ __forceinline__ unsigned fkey(float f) { const unsigned u = __float_as_uint(f); return (u & 0x80000000u) ? ~u : (u | 0x80000000u); }
; #define SEL_HADD(idx_) __hip_atomic_fetch_add(&hist[(idx_)], 1u, __ATOMIC_RELAXED, __HIP_MEMORY_SCOPE_WORKGROUP)
; __device__ __forceinline__ void sel_unit(LAS char* lds, int b, int u, const bf16_t* QI, const bf16_t* KIDX, const float* WIDX, unsigned long long* MASK) {
;     ...
;     for (int j = 0; j < 8; ++j) {
;         if (j < nj) {
;             int t = wid + 8 * j; asm volatile("" : "+s"(t));
; #pragma unroll
;             for (int kh = 0; kh < 2; ++kh) {
;             bf16x8 kf[2][2];
; #pragma unroll
;             for (int kb = 0; kb < 2; ++kb)
; #pragma unroll
;                 for (int ks = 0; ks < 2; ++ks) kf[kb][ks] = *(const bf16x8*)(KIDX + (rowbase + 64 * t + 32 * kh + 16 * kb + q16) * 64 + 32 * ks + 8 * kg);
; #pragma unroll
;             for (int kb = 0; kb < 2; ++kb) {
;                 f32x4 s = (f32x4){0.f, 0.f, 0.f, 0.f};
; #pragma unroll
;                 for (int hh = 0; hh < 8; ++hh) {
;                     f32x4 a = (f32x4){0.f, 0.f, 0.f, 0.f};
; #pragma unroll
;                     for (int ks = 0; ks < 2; ++ks) {
;                         const bf16x8 qv = *(const LAS bf16x8*)(lds + L_QI + q16 * 1024 + (((hh * 8 + 4 * ks + kg) ^ q16) << 4));
;                         a = __builtin_amdgcn_mfma_f32_16x16x32_bf16(kf[kb][ks], qv, a, 0, 0, 0);
;                     }
;                     const float wh = wl[hh * 16];
; #pragma unroll
;                     for (int i = 0; i < 4; ++i) s[i] += wh * fmaxf(a[i], 0.f);
;                 }
;                 u32x4 kk; kk.x = fkey(s[0]); kk.y = fkey(s[1]); kk.z = fkey(s[2]); kk.w = fkey(s[3]);
;                 sc[j][2 * kh + kb] = kk;
; #pragma unroll
;                 for (int i = 0; i < 4; ++i) SEL_HADD((kk[i] >> 24) * 16 + q16);
;                 __builtin_amdgcn_sched_barrier(0);
	v_mfma_f32_16x16x32_bf16 v[10:13], v[244:247], v[10:13], 0
	ds_read2_b32 v[50:51], v137 offset0:144 offset1:160
	s_waitcnt vmcnt(0) lgkmcnt(5)
	v_mfma_f32_16x16x32_bf16 v[10:13], v[248:251], v[14:17], v[10:13]
	ds_read_b128 v[14:17], v106
	s_waitcnt lgkmcnt(5)
	v_mfma_f32_16x16x32_bf16 v[22:25], v[244:247], v[22:25], 0
	s_nop 4
	v_max_f32_e32 v32, 0, v10
	v_max_f32_e32 v10, 0, v12
	v_max_f32_e32 v33, 0, v11
	s_waitcnt lgkmcnt(3)
	v_mul_f32_e32 v34, v30, v10
	v_max_f32_e32 v36, 0, v13
	v_mfma_f32_16x16x32_bf16 v[10:13], v[248:251], v[26:29], v[22:25]
	s_nop 2
	ds_read_b128 v[22:25], v105
	s_waitcnt lgkmcnt(1)
	v_mfma_f32_16x16x32_bf16 v[14:17], v[244:247], v[14:17], 0
	s_nop 1
	v_max_f32_e32 v26, 0, v10
	v_max_f32_e32 v27, 0, v11
	v_max_f32_e32 v10, 0, v12
	v_mul_f32_e32 v28, v31, v10
	v_max_f32_e32 v37, 0, v13
	s_waitcnt lgkmcnt(0)
	v_mfma_f32_16x16x32_bf16 v[10:13], v[248:251], v[22:25], v[14:17]
	ds_read_b128 v[22:25], v110
	ds_read2_b32 v[110:111], v137 offset0:176 offset1:192
	v_pk_mul_f32 v[36:37], v[30:31], v[36:37]
	ds_read_b128 v[14:17], v107
	s_waitcnt lgkmcnt(0)
	v_mfma_f32_16x16x32_bf16 v[14:17], v[244:247], v[14:17], 0
	s_nop 1
	v_max_f32_e32 v40, 0, v10
	v_max_f32_e32 v41, 0, v11
	v_max_f32_e32 v10, 0, v12
	v_mul_f32_e32 v42, v38, v10
	s_nop 0
	v_max_f32_e32 v44, 0, v13
	v_mfma_f32_16x16x32_bf16 v[10:13], v[248:251], v[22:25], v[14:17]
	ds_read_b128 v[22:25], v114
	v_mov_b32_e32 v35, v36
	v_mov_b32_e32 v29, v37
	ds_read_b128 v[14:17], v113
	s_waitcnt lgkmcnt(0)
	v_mfma_f32_16x16x32_bf16 v[14:17], v[244:247], v[14:17], 0
	s_nop 1
	v_max_f32_e32 v46, 0, v10
	v_max_f32_e32 v47, 0, v11
	v_max_f32_e32 v10, 0, v12
	v_mul_f32_e32 v48, v39, v10
	s_nop 0
	v_max_f32_e32 v45, 0, v13
	v_mfma_f32_16x16x32_bf16 v[10:13], v[248:251], v[22:25], v[14:17]
	ds_read_b128 v[22:25], v116
	v_pk_mul_f32 v[44:45], v[38:39], v[44:45]
	s_nop 0
	ds_read_b128 v[14:17], v115
	s_waitcnt lgkmcnt(0)
	v_mfma_f32_16x16x32_bf16 v[14:17], v[244:247], v[14:17], 0
	s_nop 1
	v_max_f32_e32 v52, 0, v10
	v_max_f32_e32 v53, 0, v11
	v_max_f32_e32 v10, 0, v12
	v_mul_f32_e32 v54, v50, v10
	s_nop 0
	v_max_f32_e32 v56, 0, v13
	v_mfma_f32_16x16x32_bf16 v[10:13], v[248:251], v[22:25], v[14:17]
	ds_read_b128 v[22:25], v118
	v_mov_b32_e32 v43, v44
	v_mov_b32_e32 v49, v45
	ds_read_b128 v[14:17], v117
	s_waitcnt lgkmcnt(0)
	v_mfma_f32_16x16x32_bf16 v[14:17], v[244:247], v[14:17], 0
	s_nop 1
	v_max_f32_e32 v106, 0, v10
	v_max_f32_e32 v107, 0, v11
	v_max_f32_e32 v10, 0, v12
	v_mul_f32_e32 v108, v51, v10
	s_nop 0
	v_max_f32_e32 v57, 0, v13
	v_mfma_f32_16x16x32_bf16 v[10:13], v[248:251], v[22:25], v[14:17]
	ds_read_b128 v[22:25], v120
	v_pk_mul_f32 v[56:57], v[50:51], v[56:57]
	s_nop 0
	ds_read_b128 v[14:17], v119
	s_waitcnt lgkmcnt(0)
	v_mfma_f32_16x16x32_bf16 v[6:9], v[244:247], v[14:17], 0
	s_nop 1
	s_nop 0
	v_max_f32_e32 v14, 0, v13
	s_nop 0
	v_mfma_f32_16x16x32_bf16 v[2:5], v[248:251], v[22:25], v[6:9]
	s_nop 0
	v_max_f32_e32 v10, 0, v10
	v_max_f32_e32 v11, 0, v11
	v_pk_fma_f32 v[8:9], v[30:31], v[32:33], 0 op_sel_hi:[0,1,0]
	s_nop 0
	s_nop 2
	v_max_f32_e32 v15, 0, v5
	v_pk_mul_f32 v[6:7], v[110:111], v[14:15]
	v_mov_b32_e32 v14, v31
	v_pk_fma_f32 v[8:9], v[14:15], v[26:27], v[8:9] op_sel_hi:[0,1,1]
	v_pk_fma_f32 v[8:9], v[38:39], v[40:41], v[8:9] op_sel_hi:[0,1,1]
	v_mov_b32_e32 v14, v39
	v_pk_fma_f32 v[8:9], v[14:15], v[46:47], v[8:9] op_sel_hi:[0,1,1]
	v_pk_fma_f32 v[8:9], v[50:51], v[52:53], v[8:9] op_sel_hi:[0,1,1]
	v_mov_b32_e32 v14, v51
	v_pk_fma_f32 v[8:9], v[14:15], v[106:107], v[8:9] op_sel_hi:[0,1,1]
	v_max_f32_e32 v2, 0, v2
	v_max_f32_e32 v3, 0, v3
	v_pk_fma_f32 v[8:9], v[110:111], v[10:11], v[8:9] op_sel_hi:[0,1,1]
	v_mov_b32_e32 v10, v111
	v_pk_fma_f32 v[2:3], v[10:11], v[2:3], v[8:9] op_sel_hi:[0,1,1]
	v_and_b32_e32 v9, 0x7fffffff, v3
	v_and_b32_e32 v8, 0x7fffffff, v2
	v_xor_b32_e32 v5, -1, v3
	v_pk_add_f32 v[8:9], v[8:9], 0 neg_lo:[1,1] neg_hi:[1,1]
	v_cmp_gt_i32_e32 vcc, 0, v3
	v_xor_b32_e32 v10, -1, v2
	v_mov_b32_e32 v55, v56
	v_cndmask_b32_e32 v105, v9, v5, vcc
	v_cmp_gt_i32_e32 vcc, 0, v2
	v_pk_add_f32 v[2:3], v[34:35], 0 op_sel_hi:[1,0]
	v_max_f32_e32 v12, 0, v12
	v_pk_add_f32 v[2:3], v[2:3], v[28:29]
	v_pk_add_f32 v[2:3], v[2:3], v[42:43]
	v_mov_b32_e32 v109, v57
	v_pk_add_f32 v[2:3], v[2:3], v[48:49]
	v_mul_f32_e32 v12, v110, v12
	v_pk_add_f32 v[2:3], v[2:3], v[54:55]
	v_max_f32_e32 v4, 0, v4
	v_pk_add_f32 v[2:3], v[2:3], v[108:109]
	v_mov_b32_e32 v13, v6
	v_mul_f32_e32 v4, v111, v4
	v_pk_add_f32 v[2:3], v[2:3], v[12:13]
	v_mov_b32_e32 v5, v7
	v_pk_add_f32 v[2:3], v[2:3], v[4:5]
	v_cndmask_b32_e32 v106, v8, v10, vcc
	v_and_b32_e32 v5, 0x7fffffff, v3
	v_and_b32_e32 v4, 0x7fffffff, v2
	v_xor_b32_e32 v6, -1, v3
	v_pk_add_f32 v[4:5], v[4:5], 0 neg_lo:[1,1] neg_hi:[1,1]
	v_cmp_gt_i32_e32 vcc, 0, v3
	v_xor_b32_e32 v7, -1, v2
	s_nop 0
	v_cndmask_b32_e32 v107, v5, v6, vcc
	v_cmp_gt_i32_e32 vcc, 0, v2
	v_lshrrev_b32_e32 v2, 24, v106
	v_lshl_add_u32 v2, v2, 6, v0
	ds_add_u32 v2, v205 offset:16384
	v_lshrrev_b32_e32 v2, 24, v105
	v_cndmask_b32_e32 v108, v4, v7, vcc
	v_lshl_add_u32 v2, v2, 6, v0
	ds_add_u32 v2, v205 offset:16384
	v_lshrrev_b32_e32 v2, 24, v108
	v_lshl_add_u32 v2, v2, 6, v0
	ds_add_u32 v2, v205 offset:16384
	v_lshrrev_b32_e32 v2, 24, v107
	v_lshl_add_u32 v2, v2, 6, v0
	ds_add_u32 v2, v205 offset:16384
; #define LAS __attribute__((address_space(3)))
; __device__ __forceinline__ unsigned fkey(float f) { const unsigned u = __float_as_uint(f); return (u & 0x80000000u) ? ~u : (u | 0x80000000u); }
; #define SEL_HADD(idx_) __hip_atomic_fetch_add(&hist[(idx_)], 1u, __ATOMIC_RELAXED, __HIP_MEMORY_SCOPE_WORKGROUP)
; __device__ __forceinline__ void sel_unit(LAS char* lds, int b, int u, const bf16_t* QI, const bf16_t* KIDX, const float* WIDX, unsigned long long* MASK) {
;     ...
;     for (int j = 0; j < 8; ++j) {
;         if (j < nj) {
;             int t = wid + 8 * j; asm volatile("" : "+s"(t));
; #pragma unroll
;             for (int kh = 0; kh < 2; ++kh) {
;             bf16x8 kf[2][2];
; #pragma unroll
;             for (int kb = 0; kb < 2; ++kb)
; #pragma unroll
;                 for (int ks = 0; ks < 2; ++ks) kf[kb][ks] = *(const bf16x8*)(KIDX + (rowbase + 64 * t + 32 * kh + 16 * kb + q16) * 64 + 32 * ks + 8 * kg);
; #pragma unroll
;             for (int kb = 0; kb < 2; ++kb) {
;                 f32x4 s = (f32x4){0.f, 0.f, 0.f, 0.f};
; #pragma unroll
;                 for (int hh = 0; hh < 8; ++hh) {
;                     f32x4 a = (f32x4){0.f, 0.f, 0.f, 0.f};
; #pragma unroll
;                     for (int ks = 0; ks < 2; ++ks) {
;                         const bf16x8 qv = *(const LAS bf16x8*)(lds + L_QI + q16 * 1024 + (((hh * 8 + 4 * ks + kg) ^ q16) << 4));
;                         a = __builtin_amdgcn_mfma_f32_16x16x32_bf16(kf[kb][ks], qv, a, 0, 0, 0);
;                     }
;                     const float wh = wl[hh * 16];
; #pragma unroll
;                     for (int i = 0; i < 4; ++i) s[i] += wh * fmaxf(a[i], 0.f);
;                 }
;                 u32x4 kk; kk.x = fkey(s[0]); kk.y = fkey(s[1]); kk.z = fkey(s[2]); kk.w = fkey(s[3]);
;                 sc[j][2 * kh + kb] = kk;
; #pragma unroll
;                 for (int i = 0; i < 4; ++i) SEL_HADD((kk[i] >> 24) * 16 + q16);
;                 __builtin_amdgcn_sched_barrier(0);
.LBB0_662:
	s_cmp_gt_i32 s4, 3
	s_cselect_b64 s[56:57], -1, 0
	s_cmp_lt_i32 s4, 4
	s_cbranch_scc1 .LBB0_664
	s_add_i32 s0, s46, 24
	s_lshl_b32 s0, s0, 6
	s_ashr_i32 s1, s0, 31
	v_lshl_add_u64 v[2:3], v[18:19], 0, s[0:1]
	v_lshlrev_b64 v[2:3], 7, v[2:3]
	v_lshl_add_u64 v[22:23], v[20:21], 0, v[2:3]
	global_load_dwordx4 v[14:17], v[22:23], off
	global_load_dwordx4 v[10:13], v[22:23], off offset:64
	v_lshl_add_u32 v127, v182, 4, v150
	v_lshl_add_u32 v128, v183, 4, v150
	v_lshl_add_u32 v125, v185, 4, v150
	v_lshl_add_u32 v121, v180, 4, v150
	v_lshl_add_u32 v126, v159, 4, v150
	v_lshl_add_u32 v124, v184, 4, v150
	ds_read_b128 v[2:5], v127
	v_lshl_add_u32 v122, v179, 4, v150
	ds_read_b128 v[6:9], v128
	ds_read_b128 v[24:27], v124
	v_lshl_add_u32 v123, v176, 4, v150
	ds_read_b128 v[28:31], v125
	ds_read_b128 v[32:35], v122
	ds_read_b128 v[36:39], v121
	ds_read_b128 v[40:43], v123
	v_lshl_add_u32 v129, v158, 4, v150
	ds_read_b128 v[44:47], v126
	ds_read_b128 v[48:51], v129
	v_lshl_add_u32 v130, v157, 4, v150
	ds_read_b128 v[52:55], v130
	v_lshl_add_u32 v131, v156, 4, v150
	v_lshl_add_u32 v132, v155, 4, v150
	ds_read_b128 v[110:113], v131
	ds_read_b128 v[114:117], v132
	v_lshl_add_u32 v133, v154, 4, v150
	v_lshl_add_u32 v134, v153, 4, v150
	v_lshl_add_u32 v135, v152, 4, v150
	v_lshl_add_u32 v136, v151, 4, v150
	s_waitcnt vmcnt(1) lgkmcnt(11)
	v_mfma_f32_16x16x32_bf16 v[2:5], v[14:17], v[2:5], 0
	s_waitcnt lgkmcnt(9)
	v_mfma_f32_16x16x32_bf16 v[24:27], v[14:17], v[24:27], 0
	s_waitcnt lgkmcnt(7)
	v_mfma_f32_16x16x32_bf16 v[32:35], v[14:17], v[32:35], 0
	s_waitcnt lgkmcnt(5)
	v_mfma_f32_16x16x32_bf16 v[40:43], v[14:17], v[40:43], 0
	s_waitcnt lgkmcnt(3)
	v_mfma_f32_16x16x32_bf16 v[48:51], v[14:17], v[48:51], 0
	s_waitcnt vmcnt(0)
	v_mfma_f32_16x16x32_bf16 v[138:141], v[10:13], v[6:9], v[2:5]
	v_mfma_f32_16x16x32_bf16 v[24:27], v[10:13], v[28:31], v[24:27]
	v_mfma_f32_16x16x32_bf16 v[28:31], v[10:13], v[36:39], v[32:35]
	v_mfma_f32_16x16x32_bf16 v[32:35], v[10:13], v[44:47], v[40:43]
	ds_read2_b32 v[44:45], v137 offset0:80 offset1:96
	ds_read2_b32 v[46:47], v137 offset0:112 offset1:128
	s_nop 3
	s_waitcnt lgkmcnt(4)
	v_mfma_f32_16x16x32_bf16 v[36:39], v[10:13], v[52:55], v[48:51]
	s_nop 0
	ds_read2_b32 v[48:49], v137 offset0:144 offset1:160
	global_load_dwordx4 v[6:9], v[22:23], off offset:2048
	global_load_dwordx4 v[2:5], v[22:23], off offset:2112
	v_mov_b32_e32 v252, 0x1000
	v_mov_b32_e32 v253, 0
	v_lshl_add_u64 v[252:253], v[252:253], 0, v[22:23]
	global_load_dwordx4 v[236:239], v[252:253], off
	global_load_dwordx4 v[240:243], v[252:253], off offset:64
	global_load_dwordx4 v[244:247], v[252:253], off offset:2048
	global_load_dwordx4 v[248:251], v[252:253], off offset:2112
	s_waitcnt lgkmcnt(4)
	v_mfma_f32_16x16x32_bf16 v[110:113], v[14:17], v[110:113], 0
	s_nop 0
	v_max_f32_e32 v54, v24, v24
	s_nop 0
	s_waitcnt lgkmcnt(3)
	v_mfma_f32_16x16x32_bf16 v[40:43], v[10:13], v[114:117], v[110:113]
	v_max_f32_e32 v109, v39, v39
	v_max_f32_e32 v24, 0, v141
	v_max_f32_e32 v39, 0, v25
	v_max_f32_e32 v112, 0, v26
	v_max_f32_e32 v25, 0, v27
	v_max_f32_e32 v26, 0, v31
	v_max_f32_e32 v27, 0, v35
	v_max_f32_e32 v53, 0, v37
	s_waitcnt lgkmcnt(2)
	v_mul_f32_e32 v56, v45, v112
	v_pk_mul_f32 v[112:113], v[44:45], v[24:25]
	s_waitcnt lgkmcnt(1)
	v_pk_mul_f32 v[118:119], v[46:47], v[26:27]
	ds_read_b128 v[24:27], v133
	v_max_f32_e32 v110, v40, v40
	v_max_f32_e32 v40, 0, v28
	v_max_f32_e32 v28, 0, v30
	v_max_f32_e32 v111, v41, v41
	v_max_f32_e32 v41, 0, v29
	v_max_f32_e32 v29, 0, v34
	v_max_f32_e32 v30, 0, v38
	v_mul_f32_e32 v114, v46, v28
	v_max_f32_e32 v28, 0, v42
	v_max_f32_e32 v50, v138, v138
	v_max_f32_e32 v52, v140, v140
	v_mul_f32_e32 v116, v47, v29
	s_waitcnt lgkmcnt(1)
	v_mul_f32_e32 v138, v48, v30
	v_mul_f32_e32 v140, v49, v28
	ds_read_b128 v[28:31], v134
	s_waitcnt lgkmcnt(1)
	v_mfma_f32_16x16x32_bf16 v[24:27], v[14:17], v[24:27], 0
	s_waitcnt lgkmcnt(0)
	v_mfma_f32_16x16x32_bf16 v[24:27], v[10:13], v[28:31], v[24:27]
	ds_read_b128 v[28:31], v135
	v_max_f32_e32 v37, 0, v139
	v_max_f32_e32 v51, 0, v33
	v_max_f32_e32 v55, v36, v36
	v_max_f32_e32 v36, 0, v50
	v_max_f32_e32 v50, 0, v32
	v_max_f32_e32 v32, 0, v109
	v_max_f32_e32 v33, 0, v43
	v_pk_mul_f32 v[142:143], v[48:49], v[32:33]
	ds_read_b128 v[32:35], v136
	s_waitcnt lgkmcnt(1)
	v_mfma_f32_16x16x32_bf16 v[14:17], v[14:17], v[28:31], 0
	v_max_f32_e32 v42, 0, v52
	v_max_f32_e32 v38, 0, v54
	v_max_f32_e32 v52, 0, v55
	s_waitcnt lgkmcnt(0)
	v_mfma_f32_16x16x32_bf16 v[10:13], v[10:13], v[32:35], v[14:17]
	v_max_f32_e32 v54, 0, v110
	v_max_f32_e32 v55, 0, v111
	ds_read2_b32 v[110:111], v137 offset0:176 offset1:192
	s_nop 0
	v_max_f32_e32 v28, 0, v27
	s_nop 2
	v_max_f32_e32 v29, 0, v13
	s_waitcnt lgkmcnt(0)
; #define LAS __attribute__((address_space(3)))
; __device__ __forceinline__ unsigned fkey(float f) { const unsigned u = __float_as_uint(f); return (u & 0x80000000u) ? ~u : (u | 0x80000000u); }
; #define SEL_HADD(idx_) __hip_atomic_fetch_add(&hist[(idx_)], 1u, __ATOMIC_RELAXED, __HIP_MEMORY_SCOPE_WORKGROUP)
; __device__ __forceinline__ void sel_unit(LAS char* lds, int b, int u, const bf16_t* QI, const bf16_t* KIDX, const float* WIDX, unsigned long long* MASK) {
;     ...
;     for (int j = 0; j < 8; ++j) {
;         if (j < nj) {
;             int t = wid + 8 * j; asm volatile("" : "+s"(t));
; #pragma unroll
;             for (int kh = 0; kh < 2; ++kh) {
;             bf16x8 kf[2][2];
; #pragma unroll
;             for (int kb = 0; kb < 2; ++kb)
; #pragma unroll
;                 for (int ks = 0; ks < 2; ++ks) kf[kb][ks] = *(const bf16x8*)(KIDX + (rowbase + 64 * t + 32 * kh + 16 * kb + q16) * 64 + 32 * ks + 8 * kg);
; #pragma unroll
;             for (int kb = 0; kb < 2; ++kb) {
;                 f32x4 s = (f32x4){0.f, 0.f, 0.f, 0.f};
; #pragma unroll
;                 for (int hh = 0; hh < 8; ++hh) {
;                     f32x4 a = (f32x4){0.f, 0.f, 0.f, 0.f};
; #pragma unroll
;                     for (int ks = 0; ks < 2; ++ks) {
;                         const bf16x8 qv = *(const LAS bf16x8*)(lds + L_QI + q16 * 1024 + (((hh * 8 + 4 * ks + kg) ^ q16) << 4));
;                         a = __builtin_amdgcn_mfma_f32_16x16x32_bf16(kf[kb][ks], qv, a, 0, 0, 0);
;                     }
;                     const float wh = wl[hh * 16];
; #pragma unroll
;                     for (int i = 0; i < 4; ++i) s[i] += wh * fmaxf(a[i], 0.f);
;                 }
;                 u32x4 kk; kk.x = fkey(s[0]); kk.y = fkey(s[1]); kk.z = fkey(s[2]); kk.w = fkey(s[3]);
;                 sc[j][2 * kh + kb] = kk;
; #pragma unroll
;                 for (int i = 0; i < 4; ++i) SEL_HADD((kk[i] >> 24) * 16 + q16);
;                 __builtin_amdgcn_sched_barrier(0);
	v_pk_mul_f32 v[14:15], v[110:111], v[28:29]
	v_pk_fma_f32 v[16:17], v[44:45], v[36:37], 0 op_sel_hi:[0,1,0]
	v_mov_b32_e32 v28, v45
	v_pk_fma_f32 v[16:17], v[28:29], v[38:39], v[16:17] op_sel_hi:[0,1,1]
	v_pk_fma_f32 v[16:17], v[46:47], v[40:41], v[16:17] op_sel_hi:[0,1,1]
	v_mov_b32_e32 v28, v47
	v_pk_fma_f32 v[16:17], v[28:29], v[50:51], v[16:17] op_sel_hi:[0,1,1]
	v_pk_fma_f32 v[16:17], v[48:49], v[52:53], v[16:17] op_sel_hi:[0,1,1]
	v_mov_b32_e32 v28, v49
	v_max_f32_e32 v24, 0, v24
	v_max_f32_e32 v25, 0, v25
	v_pk_fma_f32 v[16:17], v[28:29], v[54:55], v[16:17] op_sel_hi:[0,1,1]
	v_max_f32_e32 v10, 0, v10
	v_max_f32_e32 v11, 0, v11
	v_pk_fma_f32 v[16:17], v[110:111], v[24:25], v[16:17] op_sel_hi:[0,1,1]
	v_mov_b32_e32 v24, v111
	v_pk_fma_f32 v[10:11], v[24:25], v[10:11], v[16:17] op_sel_hi:[0,1,1]
	v_and_b32_e32 v17, 0x7fffffff, v11
	v_and_b32_e32 v16, 0x7fffffff, v10
	v_mul_f32_e32 v42, v44, v42
	v_xor_b32_e32 v13, -1, v11
	v_pk_add_f32 v[16:17], v[16:17], 0 neg_lo:[1,1] neg_hi:[1,1]
	v_cmp_gt_i32_e32 vcc, 0, v11
	v_mov_b32_e32 v43, v112
	v_xor_b32_e32 v24, -1, v10
	v_cndmask_b32_e32 v109, v17, v13, vcc
	v_cmp_gt_i32_e32 vcc, 0, v10
	v_pk_add_f32 v[10:11], v[42:43], 0 op_sel_hi:[1,0]
	v_mov_b32_e32 v57, v113
	v_pk_add_f32 v[10:11], v[10:11], v[56:57]
	v_mov_b32_e32 v115, v118
	v_pk_add_f32 v[10:11], v[10:11], v[114:115]
	v_mov_b32_e32 v117, v119
	v_pk_add_f32 v[10:11], v[10:11], v[116:117]
	v_mov_b32_e32 v139, v142
	v_max_f32_e32 v26, 0, v26
	v_pk_add_f32 v[10:11], v[10:11], v[138:139]
	v_mov_b32_e32 v141, v143
	v_mul_f32_e32 v26, v110, v26
	v_max_f32_e32 v12, 0, v12
	v_pk_add_f32 v[10:11], v[10:11], v[140:141]
	v_mov_b32_e32 v27, v14
	v_mul_f32_e32 v12, v111, v12
	v_pk_add_f32 v[10:11], v[10:11], v[26:27]
	v_mov_b32_e32 v13, v15
	v_pk_add_f32 v[10:11], v[10:11], v[12:13]
	v_cndmask_b32_e32 v110, v16, v24, vcc
	v_and_b32_e32 v13, 0x7fffffff, v11
	v_and_b32_e32 v12, 0x7fffffff, v10
	v_xor_b32_e32 v14, -1, v11
	v_pk_add_f32 v[12:13], v[12:13], 0 neg_lo:[1,1] neg_hi:[1,1]
	v_cmp_gt_i32_e32 vcc, 0, v11
	v_xor_b32_e32 v15, -1, v10
	s_nop 0
	v_cndmask_b32_e32 v111, v13, v14, vcc
	v_cmp_gt_i32_e32 vcc, 0, v10
	v_lshrrev_b32_e32 v10, 24, v110
	v_lshl_add_u32 v10, v10, 6, v0
	ds_add_u32 v10, v205 offset:16384
	v_lshrrev_b32_e32 v10, 24, v109
	v_cndmask_b32_e32 v112, v12, v15, vcc
	v_lshl_add_u32 v10, v10, 6, v0
	ds_add_u32 v10, v205 offset:16384
	v_lshrrev_b32_e32 v10, 24, v112
	v_lshl_add_u32 v10, v10, 6, v0
	ds_add_u32 v10, v205 offset:16384
	v_lshrrev_b32_e32 v10, 24, v111
	v_lshl_add_u32 v10, v10, 6, v0
	ds_add_u32 v10, v205 offset:16384
	ds_read_b128 v[10:13], v127
	ds_read_b128 v[14:17], v128
	ds_read_b128 v[24:27], v124
	ds_read_b128 v[28:31], v125
	ds_read2_b32 v[32:33], v137 offset0:80 offset1:96
	ds_read2_b32 v[40:41], v137 offset0:112 offset1:128
	s_waitcnt vmcnt(5) lgkmcnt(5)
	v_mfma_f32_16x16x32_bf16 v[10:13], v[6:9], v[10:13], 0
	ds_read2_b32 v[52:53], v137 offset0:144 offset1:160
	s_waitcnt vmcnt(4) lgkmcnt(5)
	v_mfma_f32_16x16x32_bf16 v[10:13], v[2:5], v[14:17], v[10:13]
	ds_read_b128 v[14:17], v122
	s_waitcnt lgkmcnt(5)
	v_mfma_f32_16x16x32_bf16 v[24:27], v[6:9], v[24:27], 0
	s_nop 4
	v_max_f32_e32 v34, 0, v10
	v_max_f32_e32 v10, 0, v12
	v_max_f32_e32 v35, 0, v11
	s_waitcnt lgkmcnt(3)
	v_mul_f32_e32 v36, v32, v10
	v_max_f32_e32 v38, 0, v13
	v_mfma_f32_16x16x32_bf16 v[10:13], v[2:5], v[28:31], v[24:27]
	s_nop 2
	ds_read_b128 v[24:27], v121
	s_waitcnt lgkmcnt(1)
	v_mfma_f32_16x16x32_bf16 v[14:17], v[6:9], v[14:17], 0
	s_nop 1
	v_max_f32_e32 v28, 0, v10
	v_max_f32_e32 v29, 0, v11
	v_max_f32_e32 v10, 0, v12
	v_mul_f32_e32 v30, v33, v10
	v_max_f32_e32 v39, 0, v13
	s_waitcnt lgkmcnt(0)
	v_mfma_f32_16x16x32_bf16 v[10:13], v[2:5], v[24:27], v[14:17]
	ds_read_b128 v[24:27], v126
	v_pk_mul_f32 v[38:39], v[32:33], v[38:39]
	s_nop 0
	ds_read_b128 v[14:17], v123
	s_waitcnt lgkmcnt(0)
	v_mfma_f32_16x16x32_bf16 v[14:17], v[6:9], v[14:17], 0
	s_nop 1
	v_max_f32_e32 v42, 0, v10
	v_max_f32_e32 v43, 0, v11
	v_max_f32_e32 v10, 0, v12
	v_mul_f32_e32 v44, v40, v10
	s_nop 0
	v_max_f32_e32 v46, 0, v13
	v_mfma_f32_16x16x32_bf16 v[10:13], v[2:5], v[24:27], v[14:17]
	ds_read_b128 v[24:27], v130
	v_mov_b32_e32 v37, v38
	v_mov_b32_e32 v31, v39
	ds_read_b128 v[14:17], v129
	s_waitcnt lgkmcnt(0)
	v_mfma_f32_16x16x32_bf16 v[14:17], v[6:9], v[14:17], 0
	s_nop 1
	v_max_f32_e32 v48, 0, v10
	v_max_f32_e32 v49, 0, v11
	v_max_f32_e32 v10, 0, v12
	v_mul_f32_e32 v50, v41, v10
	s_nop 0
	v_max_f32_e32 v47, 0, v13
	v_mfma_f32_16x16x32_bf16 v[10:13], v[2:5], v[24:27], v[14:17]
	ds_read_b128 v[24:27], v132
	v_pk_mul_f32 v[46:47], v[40:41], v[46:47]
	s_nop 0
	ds_read_b128 v[14:17], v131
	s_waitcnt lgkmcnt(0)
	v_mfma_f32_16x16x32_bf16 v[14:17], v[6:9], v[14:17], 0
	s_nop 1
	v_max_f32_e32 v54, 0, v10
	v_max_f32_e32 v55, 0, v11
	v_max_f32_e32 v10, 0, v12
	v_mul_f32_e32 v56, v52, v10
	s_nop 0
	v_max_f32_e32 v114, 0, v13
	v_mfma_f32_16x16x32_bf16 v[10:13], v[2:5], v[24:27], v[14:17]
	ds_read_b128 v[24:27], v134
	v_mov_b32_e32 v45, v46
	v_mov_b32_e32 v51, v47
	ds_read_b128 v[14:17], v133
	s_waitcnt lgkmcnt(0)
	v_mfma_f32_16x16x32_bf16 v[14:17], v[6:9], v[14:17], 0
	s_nop 1
	v_max_f32_e32 v116, 0, v10
	v_max_f32_e32 v117, 0, v11
	v_max_f32_e32 v10, 0, v12
	v_mul_f32_e32 v118, v53, v10
	s_nop 0
	v_max_f32_e32 v115, 0, v13
	v_mfma_f32_16x16x32_bf16 v[10:13], v[2:5], v[24:27], v[14:17]
	ds_read_b128 v[24:27], v136
	v_pk_mul_f32 v[138:139], v[52:53], v[114:115]
	ds_read2_b32 v[114:115], v137 offset0:176 offset1:192
	ds_read_b128 v[14:17], v135
	s_waitcnt lgkmcnt(0)
; #define LAS __attribute__((address_space(3)))
; __device__ __forceinline__ unsigned fkey(float f) { const unsigned u = __float_as_uint(f); return (u & 0x80000000u) ? ~u : (u | 0x80000000u); }
; #define SEL_HADD(idx_) __hip_atomic_fetch_add(&hist[(idx_)], 1u, __ATOMIC_RELAXED, __HIP_MEMORY_SCOPE_WORKGROUP)
; __device__ __forceinline__ void sel_unit(LAS char* lds, int b, int u, const bf16_t* QI, const bf16_t* KIDX, const float* WIDX, unsigned long long* MASK) {
;     ...
;     for (int j = 0; j < 8; ++j) {
;         if (j < nj) {
;             int t = wid + 8 * j; asm volatile("" : "+s"(t));
; #pragma unroll
;             for (int kh = 0; kh < 2; ++kh) {
;             bf16x8 kf[2][2];
; #pragma unroll
;             for (int kb = 0; kb < 2; ++kb)
; #pragma unroll
;                 for (int ks = 0; ks < 2; ++ks) kf[kb][ks] = *(const bf16x8*)(KIDX + (rowbase + 64 * t + 32 * kh + 16 * kb + q16) * 64 + 32 * ks + 8 * kg);
; #pragma unroll
;             for (int kb = 0; kb < 2; ++kb) {
;                 f32x4 s = (f32x4){0.f, 0.f, 0.f, 0.f};
; #pragma unroll
;                 for (int hh = 0; hh < 8; ++hh) {
;                     f32x4 a = (f32x4){0.f, 0.f, 0.f, 0.f};
; #pragma unroll
;                     for (int ks = 0; ks < 2; ++ks) {
;                         const bf16x8 qv = *(const LAS bf16x8*)(lds + L_QI + q16 * 1024 + (((hh * 8 + 4 * ks + kg) ^ q16) << 4));
;                         a = __builtin_amdgcn_mfma_f32_16x16x32_bf16(kf[kb][ks], qv, a, 0, 0, 0);
;                     }
;                     const float wh = wl[hh * 16];
; #pragma unroll
;                     for (int i = 0; i < 4; ++i) s[i] += wh * fmaxf(a[i], 0.f);
;                 }
;                 u32x4 kk; kk.x = fkey(s[0]); kk.y = fkey(s[1]); kk.z = fkey(s[2]); kk.w = fkey(s[3]);
;                 sc[j][2 * kh + kb] = kk;
; #pragma unroll
;                 for (int i = 0; i < 4; ++i) SEL_HADD((kk[i] >> 24) * 16 + q16);
;                 __builtin_amdgcn_sched_barrier(0);
	v_mfma_f32_16x16x32_bf16 v[6:9], v[6:9], v[14:17], 0
	s_nop 1
	s_nop 0
	v_max_f32_e32 v14, 0, v13
	s_nop 0
	v_mfma_f32_16x16x32_bf16 v[2:5], v[2:5], v[24:27], v[6:9]
	s_nop 0
	v_max_f32_e32 v10, 0, v10
	v_max_f32_e32 v11, 0, v11
	v_pk_fma_f32 v[8:9], v[32:33], v[34:35], 0 op_sel_hi:[0,1,0]
	s_nop 0
	s_nop 2
	v_max_f32_e32 v15, 0, v5
	v_pk_mul_f32 v[6:7], v[114:115], v[14:15]
	v_mov_b32_e32 v14, v33
	v_pk_fma_f32 v[8:9], v[14:15], v[28:29], v[8:9] op_sel_hi:[0,1,1]
	v_pk_fma_f32 v[8:9], v[40:41], v[42:43], v[8:9] op_sel_hi:[0,1,1]
	v_mov_b32_e32 v14, v41
	v_pk_fma_f32 v[8:9], v[14:15], v[48:49], v[8:9] op_sel_hi:[0,1,1]
	v_pk_fma_f32 v[8:9], v[52:53], v[54:55], v[8:9] op_sel_hi:[0,1,1]
	v_mov_b32_e32 v14, v53
	v_pk_fma_f32 v[8:9], v[14:15], v[116:117], v[8:9] op_sel_hi:[0,1,1]
	v_max_f32_e32 v2, 0, v2
	v_max_f32_e32 v3, 0, v3
	v_pk_fma_f32 v[8:9], v[114:115], v[10:11], v[8:9] op_sel_hi:[0,1,1]
	v_mov_b32_e32 v10, v115
	v_pk_fma_f32 v[2:3], v[10:11], v[2:3], v[8:9] op_sel_hi:[0,1,1]
	v_and_b32_e32 v9, 0x7fffffff, v3
	v_and_b32_e32 v8, 0x7fffffff, v2
	v_xor_b32_e32 v5, -1, v3
	v_pk_add_f32 v[8:9], v[8:9], 0 neg_lo:[1,1] neg_hi:[1,1]
	v_cmp_gt_i32_e32 vcc, 0, v3
	v_xor_b32_e32 v10, -1, v2
	v_mov_b32_e32 v57, v138
	v_cndmask_b32_e32 v113, v9, v5, vcc
	v_cmp_gt_i32_e32 vcc, 0, v2
	v_pk_add_f32 v[2:3], v[36:37], 0 op_sel_hi:[1,0]
	v_max_f32_e32 v12, 0, v12
	v_pk_add_f32 v[2:3], v[2:3], v[30:31]
	v_pk_add_f32 v[2:3], v[2:3], v[44:45]
	v_mov_b32_e32 v119, v139
	v_pk_add_f32 v[2:3], v[2:3], v[50:51]
	v_mul_f32_e32 v12, v114, v12
	v_pk_add_f32 v[2:3], v[2:3], v[56:57]
	v_max_f32_e32 v4, 0, v4
	v_pk_add_f32 v[2:3], v[2:3], v[118:119]
	v_mov_b32_e32 v13, v6
	v_mul_f32_e32 v4, v115, v4
	v_pk_add_f32 v[2:3], v[2:3], v[12:13]
	v_mov_b32_e32 v5, v7
	v_pk_add_f32 v[2:3], v[2:3], v[4:5]
	v_cndmask_b32_e32 v114, v8, v10, vcc
	v_and_b32_e32 v5, 0x7fffffff, v3
	v_and_b32_e32 v4, 0x7fffffff, v2
	v_xor_b32_e32 v6, -1, v3
	v_pk_add_f32 v[4:5], v[4:5], 0 neg_lo:[1,1] neg_hi:[1,1]
	v_cmp_gt_i32_e32 vcc, 0, v3
	v_xor_b32_e32 v7, -1, v2
	s_nop 0
	v_cndmask_b32_e32 v115, v5, v6, vcc
	v_cmp_gt_i32_e32 vcc, 0, v2
	v_lshrrev_b32_e32 v2, 24, v114
	v_lshl_add_u32 v2, v2, 6, v0
	ds_add_u32 v2, v205 offset:16384
	v_lshrrev_b32_e32 v2, 24, v113
	v_cndmask_b32_e32 v116, v4, v7, vcc
	v_lshl_add_u32 v2, v2, 6, v0
	ds_add_u32 v2, v205 offset:16384
	v_lshrrev_b32_e32 v2, 24, v116
	v_lshl_add_u32 v2, v2, 6, v0
	ds_add_u32 v2, v205 offset:16384
	v_lshrrev_b32_e32 v2, 24, v115
	v_lshl_add_u32 v2, v2, 6, v0
	ds_add_u32 v2, v205 offset:16384
	ds_read_b128 v[22:25], v127
	ds_read_b128 v[26:29], v128
	s_waitcnt vmcnt(3) lgkmcnt(1)
	v_mfma_f32_16x16x32_bf16 v[22:25], v[236:239], v[22:25], 0
	ds_read_b128 v[32:35], v125
	ds_read_b128 v[38:41], v121
	ds_read_b128 v[44:47], v126
	s_waitcnt vmcnt(2) lgkmcnt(3)
	v_mfma_f32_16x16x32_bf16 v[26:29], v[240:243], v[26:29], v[22:25]
	ds_read_b128 v[50:53], v130
	ds_read_b128 v[138:141], v132
	ds_read_b128 v[142:145], v134
	ds_read2_b32 v[24:25], v137 offset0:80 offset1:96
	s_nop 3
	v_max_f32_e32 v26, 0, v26
	v_max_f32_e32 v27, 0, v27
	v_max_f32_e32 v22, v28, v28
	v_max_f32_e32 v23, v29, v29
	ds_read_b128 v[28:31], v124
	s_waitcnt lgkmcnt(0)
	v_mfma_f32_16x16x32_bf16 v[28:31], v[236:239], v[28:31], 0
	v_max_f32_e32 v36, 0, v23
	v_max_f32_e32 v22, 0, v22
	v_mul_f32_e32 v22, v24, v22
	v_mfma_f32_16x16x32_bf16 v[28:31], v[240:243], v[32:35], v[28:31]
	s_nop 7
	v_max_f32_e32 v32, 0, v28
	v_max_f32_e32 v33, 0, v29
	v_max_f32_e32 v23, 0, v30
	v_mul_f32_e32 v28, v25, v23
	v_max_f32_e32 v37, 0, v31
	v_pk_mul_f32 v[30:31], v[24:25], v[36:37]
	ds_read_b128 v[34:37], v122
	s_waitcnt lgkmcnt(0)
	v_mfma_f32_16x16x32_bf16 v[34:37], v[236:239], v[34:37], 0
	v_mov_b32_e32 v29, v31
	v_mfma_f32_16x16x32_bf16 v[38:41], v[240:243], v[38:41], v[34:37]
	s_nop 5
	ds_read2_b32 v[36:37], v137 offset0:112 offset1:128
	s_nop 0
	v_max_f32_e32 v38, 0, v38
	v_max_f32_e32 v39, 0, v39
	v_max_f32_e32 v23, 0, v40
	s_waitcnt lgkmcnt(0)
	v_mul_f32_e32 v34, v36, v23
	v_max_f32_e32 v23, v41, v41
	ds_read_b128 v[40:43], v123
	s_waitcnt lgkmcnt(0)
	v_mfma_f32_16x16x32_bf16 v[40:43], v[236:239], v[40:43], 0
	v_max_f32_e32 v48, 0, v23
	v_mfma_f32_16x16x32_bf16 v[40:43], v[240:243], v[44:47], v[40:43]
	s_nop 7
	v_max_f32_e32 v44, 0, v40
	v_max_f32_e32 v45, 0, v41
	v_max_f32_e32 v23, 0, v42
	v_mul_f32_e32 v40, v37, v23
	v_max_f32_e32 v49, 0, v43
	v_pk_mul_f32 v[42:43], v[36:37], v[48:49]
	ds_read_b128 v[46:49], v129
	s_waitcnt lgkmcnt(0)
	v_mfma_f32_16x16x32_bf16 v[46:49], v[236:239], v[46:49], 0
	v_mov_b32_e32 v35, v42
	v_mov_b32_e32 v41, v43
	v_mfma_f32_16x16x32_bf16 v[50:53], v[240:243], v[50:53], v[46:49]
	s_nop 4
	ds_read2_b32 v[48:49], v137 offset0:144 offset1:160
	s_nop 1
	v_max_f32_e32 v50, 0, v50
	v_max_f32_e32 v51, 0, v51
	v_max_f32_e32 v23, 0, v52
	s_waitcnt lgkmcnt(0)
	v_mul_f32_e32 v46, v48, v23
	v_max_f32_e32 v23, v53, v53
	ds_read_b128 v[52:55], v131
	s_waitcnt lgkmcnt(0)
	v_mfma_f32_16x16x32_bf16 v[52:55], v[236:239], v[52:55], 0
	v_max_f32_e32 v118, 0, v23
	v_mfma_f32_16x16x32_bf16 v[52:55], v[240:243], v[138:141], v[52:55]
	ds_read_b128 v[138:141], v133
	s_waitcnt lgkmcnt(0)
	v_mfma_f32_16x16x32_bf16 v[138:141], v[236:239], v[138:141], 0
	s_nop 4
	v_max_f32_e32 v56, 0, v52
	v_max_f32_e32 v57, 0, v53
	v_max_f32_e32 v23, 0, v54
	v_mfma_f32_16x16x32_bf16 v[138:141], v[240:243], v[142:145], v[138:141]
	v_mul_f32_e32 v52, v49, v23
	s_nop 0
	v_max_f32_e32 v119, 0, v55
	v_pk_mul_f32 v[54:55], v[48:49], v[118:119]
	ds_read2_b32 v[118:119], v137 offset0:176 offset1:192
	s_nop 2
	v_max_f32_e32 v142, 0, v138
	v_max_f32_e32 v143, 0, v139
	v_max_f32_e32 v23, 0, v140
	s_waitcnt lgkmcnt(0)
; #define LAS __attribute__((address_space(3)))
; __device__ __forceinline__ unsigned fkey(float f) { const unsigned u = __float_as_uint(f); return (u & 0x80000000u) ? ~u : (u | 0x80000000u); }
; #define SEL_HADD(idx_) __hip_atomic_fetch_add(&hist[(idx_)], 1u, __ATOMIC_RELAXED, __HIP_MEMORY_SCOPE_WORKGROUP)
; __device__ __forceinline__ void sel_unit(LAS char* lds, int b, int u, const bf16_t* QI, const bf16_t* KIDX, const float* WIDX, unsigned long long* MASK) {
;     ...
;     for (int j = 0; j < 8; ++j) {
;         if (j < nj) {
;             int t = wid + 8 * j; asm volatile("" : "+s"(t));
; #pragma unroll
;             for (int kh = 0; kh < 2; ++kh) {
;             bf16x8 kf[2][2];
; #pragma unroll
;             for (int kb = 0; kb < 2; ++kb)
; #pragma unroll
;                 for (int ks = 0; ks < 2; ++ks) kf[kb][ks] = *(const bf16x8*)(KIDX + (rowbase + 64 * t + 32 * kh + 16 * kb + q16) * 64 + 32 * ks + 8 * kg);
; #pragma unroll
;             for (int kb = 0; kb < 2; ++kb) {
;                 f32x4 s = (f32x4){0.f, 0.f, 0.f, 0.f};
; #pragma unroll
;                 for (int hh = 0; hh < 8; ++hh) {
;                     f32x4 a = (f32x4){0.f, 0.f, 0.f, 0.f};
; #pragma unroll
;                     for (int ks = 0; ks < 2; ++ks) {
;                         const bf16x8 qv = *(const LAS bf16x8*)(lds + L_QI + q16 * 1024 + (((hh * 8 + 4 * ks + kg) ^ q16) << 4));
;                         a = __builtin_amdgcn_mfma_f32_16x16x32_bf16(kf[kb][ks], qv, a, 0, 0, 0);
;                     }
;                     const float wh = wl[hh * 16];
; #pragma unroll
;                     for (int i = 0; i < 4; ++i) s[i] += wh * fmaxf(a[i], 0.f);
;                 }
;                 u32x4 kk; kk.x = fkey(s[0]); kk.y = fkey(s[1]); kk.z = fkey(s[2]); kk.w = fkey(s[3]);
;                 sc[j][2 * kh + kb] = kk;
; #pragma unroll
;                 for (int i = 0; i < 4; ++i) SEL_HADD((kk[i] >> 24) * 16 + q16);
;                 __builtin_amdgcn_sched_barrier(0);
	v_mul_f32_e32 v144, v118, v23
	v_max_f32_e32 v23, v141, v141
	ds_read_b128 v[138:141], v135
	s_waitcnt lgkmcnt(0)
	v_mfma_f32_16x16x32_bf16 v[14:17], v[236:239], v[138:141], 0
	ds_read_b128 v[138:141], v136
	v_max_f32_e32 v146, 0, v23
	v_mov_b32_e32 v47, v54
	s_waitcnt lgkmcnt(0)
	v_mfma_f32_16x16x32_bf16 v[10:13], v[240:243], v[138:141], v[14:17]
	v_mov_b32_e32 v53, v55
	s_nop 1
	v_pk_fma_f32 v[16:17], v[24:25], v[26:27], 0 op_sel_hi:[0,1,0]
	v_mov_b32_e32 v24, v25
	v_pk_fma_f32 v[16:17], v[24:25], v[32:33], v[16:17] op_sel_hi:[0,1,1]
	v_pk_fma_f32 v[16:17], v[36:37], v[38:39], v[16:17] op_sel_hi:[0,1,1]
	v_mov_b32_e32 v24, v37
	v_pk_fma_f32 v[16:17], v[24:25], v[44:45], v[16:17] op_sel_hi:[0,1,1]
	v_pk_fma_f32 v[16:17], v[48:49], v[50:51], v[16:17] op_sel_hi:[0,1,1]
	v_mov_b32_e32 v24, v49
	v_pk_fma_f32 v[16:17], v[24:25], v[56:57], v[16:17] op_sel_hi:[0,1,1]
	v_max_f32_e32 v10, 0, v10
	v_max_f32_e32 v11, 0, v11
	v_pk_fma_f32 v[16:17], v[118:119], v[142:143], v[16:17] op_sel_hi:[0,1,1]
	v_mov_b32_e32 v24, v119
	v_pk_fma_f32 v[10:11], v[24:25], v[10:11], v[16:17] op_sel_hi:[0,1,1]
	v_and_b32_e32 v17, 0x7fffffff, v11
	v_and_b32_e32 v16, 0x7fffffff, v10
	v_max_f32_e32 v147, 0, v13
	v_xor_b32_e32 v23, -1, v10
	v_pk_add_f32 v[16:17], v[16:17], 0 neg_lo:[1,1] neg_hi:[1,1]
	v_cmp_gt_i32_e32 vcc, 0, v10
	v_pk_mul_f32 v[14:15], v[118:119], v[146:147]
	v_xor_b32_e32 v13, -1, v11
	v_cndmask_b32_e32 v118, v16, v23, vcc
	v_mov_b32_e32 v23, v30
	v_cmp_gt_i32_e64 s[2:3], 0, v11
	v_pk_add_f32 v[10:11], v[22:23], 0 op_sel_hi:[1,0]
	v_pk_add_f32 v[10:11], v[10:11], v[28:29]
	v_max_f32_e32 v12, 0, v12
	v_pk_add_f32 v[10:11], v[10:11], v[34:35]
	v_mov_b32_e32 v145, v14
	v_pk_add_f32 v[10:11], v[10:11], v[40:41]
	v_mul_f32_e32 v12, v119, v12
	v_pk_add_f32 v[10:11], v[10:11], v[46:47]
	v_cndmask_b32_e64 v117, v17, v13, s[2:3]
	v_pk_add_f32 v[10:11], v[10:11], v[52:53]
	v_mov_b32_e32 v13, v15
	v_pk_add_f32 v[10:11], v[10:11], v[144:145]
	s_nop 0
	v_pk_add_f32 v[10:11], v[10:11], v[12:13]
	s_nop 0
	v_xor_b32_e32 v15, -1, v10
	v_and_b32_e32 v12, 0x7fffffff, v10
	v_cmp_gt_i32_e32 vcc, 0, v10
	v_lshrrev_b32_e32 v10, 24, v118
	v_and_b32_e32 v13, 0x7fffffff, v11
	v_lshl_add_u32 v10, v10, 6, v0
	v_pk_add_f32 v[12:13], v[12:13], 0 neg_lo:[1,1] neg_hi:[1,1]
	ds_add_u32 v10, v205 offset:16384
	v_lshrrev_b32_e32 v10, 24, v117
	v_cndmask_b32_e32 v120, v12, v15, vcc
	v_lshl_add_u32 v10, v10, 6, v0
	v_xor_b32_e32 v14, -1, v11
	v_cmp_gt_i32_e64 s[2:3], 0, v11
	ds_add_u32 v10, v205 offset:16384
	v_lshrrev_b32_e32 v10, 24, v120
	v_cndmask_b32_e64 v119, v13, v14, s[2:3]
	v_lshl_add_u32 v10, v10, 6, v0
	ds_add_u32 v10, v205 offset:16384
	v_lshrrev_b32_e32 v10, 24, v119
	v_lshl_add_u32 v10, v10, 6, v0
	ds_add_u32 v10, v205 offset:16384
	ds_read_b128 v[10:13], v127
	ds_read_b128 v[14:17], v128
	ds_read_b128 v[22:25], v124
	ds_read_b128 v[26:29], v125
	ds_read2_b32 v[30:31], v137 offset0:80 offset1:96
	ds_read2_b32 v[38:39], v137 offset0:112 offset1:128
	s_waitcnt vmcnt(1) lgkmcnt(5)
	v_mfma_f32_16x16x32_bf16 v[10:13], v[244:247], v[10:13], 0
	ds_read2_b32 v[50:51], v137 offset0:144 offset1:160
	s_waitcnt vmcnt(0) lgkmcnt(5)
	v_mfma_f32_16x16x32_bf16 v[10:13], v[248:251], v[14:17], v[10:13]
	ds_read_b128 v[14:17], v122
	s_waitcnt lgkmcnt(5)
	v_mfma_f32_16x16x32_bf16 v[22:25], v[244:247], v[22:25], 0
	s_nop 4
	v_max_f32_e32 v32, 0, v10
	v_max_f32_e32 v10, 0, v12
	v_max_f32_e32 v33, 0, v11
	s_waitcnt lgkmcnt(3)
	v_mul_f32_e32 v34, v30, v10
	v_max_f32_e32 v36, 0, v13
	v_mfma_f32_16x16x32_bf16 v[10:13], v[248:251], v[26:29], v[22:25]
	s_nop 2
	ds_read_b128 v[22:25], v121
	s_waitcnt lgkmcnt(1)
	v_mfma_f32_16x16x32_bf16 v[14:17], v[244:247], v[14:17], 0
	s_nop 1
	v_max_f32_e32 v26, 0, v10
	v_max_f32_e32 v27, 0, v11
	v_max_f32_e32 v10, 0, v12
	v_mul_f32_e32 v28, v31, v10
	v_max_f32_e32 v37, 0, v13
	s_waitcnt lgkmcnt(0)
	v_mfma_f32_16x16x32_bf16 v[10:13], v[248:251], v[22:25], v[14:17]
	ds_read_b128 v[22:25], v126
	ds_read2_b32 v[126:127], v137 offset0:176 offset1:192
	v_pk_mul_f32 v[36:37], v[30:31], v[36:37]
	ds_read_b128 v[14:17], v123
	s_waitcnt lgkmcnt(0)
	v_mfma_f32_16x16x32_bf16 v[14:17], v[244:247], v[14:17], 0
	s_nop 1
	v_max_f32_e32 v40, 0, v10
	v_max_f32_e32 v41, 0, v11
	v_max_f32_e32 v10, 0, v12
	v_mul_f32_e32 v42, v38, v10
	s_nop 0
	v_max_f32_e32 v44, 0, v13
	v_mfma_f32_16x16x32_bf16 v[10:13], v[248:251], v[22:25], v[14:17]
	ds_read_b128 v[22:25], v130
	v_mov_b32_e32 v35, v36
	v_mov_b32_e32 v29, v37
	ds_read_b128 v[14:17], v129
	s_waitcnt lgkmcnt(0)
	v_mfma_f32_16x16x32_bf16 v[14:17], v[244:247], v[14:17], 0
	s_nop 1
	v_max_f32_e32 v46, 0, v10
	v_max_f32_e32 v47, 0, v11
	v_max_f32_e32 v10, 0, v12
	v_mul_f32_e32 v48, v39, v10
	s_nop 0
	v_max_f32_e32 v45, 0, v13
	v_mfma_f32_16x16x32_bf16 v[10:13], v[248:251], v[22:25], v[14:17]
	ds_read_b128 v[22:25], v132
	v_pk_mul_f32 v[44:45], v[38:39], v[44:45]
	s_nop 0
	ds_read_b128 v[14:17], v131
	s_waitcnt lgkmcnt(0)
	v_mfma_f32_16x16x32_bf16 v[14:17], v[244:247], v[14:17], 0
	s_nop 1
	v_max_f32_e32 v52, 0, v10
	v_max_f32_e32 v53, 0, v11
	v_max_f32_e32 v10, 0, v12
	v_mul_f32_e32 v54, v50, v10
	s_nop 0
	v_max_f32_e32 v56, 0, v13
	v_mfma_f32_16x16x32_bf16 v[10:13], v[248:251], v[22:25], v[14:17]
	ds_read_b128 v[22:25], v134
	v_mov_b32_e32 v43, v44
	v_mov_b32_e32 v49, v45
	ds_read_b128 v[14:17], v133
	s_waitcnt lgkmcnt(0)
	v_mfma_f32_16x16x32_bf16 v[14:17], v[244:247], v[14:17], 0
	s_nop 1
	v_max_f32_e32 v122, 0, v10
	v_max_f32_e32 v123, 0, v11
	v_max_f32_e32 v10, 0, v12
	v_mul_f32_e32 v124, v51, v10
	s_nop 0
	v_max_f32_e32 v57, 0, v13
	v_mfma_f32_16x16x32_bf16 v[10:13], v[248:251], v[22:25], v[14:17]
	ds_read_b128 v[22:25], v136
	v_pk_mul_f32 v[56:57], v[50:51], v[56:57]
	s_nop 0
	ds_read_b128 v[14:17], v135
	s_waitcnt lgkmcnt(0)
; #define LAS __attribute__((address_space(3)))
; __device__ __forceinline__ unsigned fkey(float f) { const unsigned u = __float_as_uint(f); return (u & 0x80000000u) ? ~u : (u | 0x80000000u); }
; #define SEL_HADD(idx_) __hip_atomic_fetch_add(&hist[(idx_)], 1u, __ATOMIC_RELAXED, __HIP_MEMORY_SCOPE_WORKGROUP)
; __device__ __forceinline__ void sel_unit(LAS char* lds, int b, int u, const bf16_t* QI, const bf16_t* KIDX, const float* WIDX, unsigned long long* MASK) {
;     ...
;     for (int j = 0; j < 8; ++j) {
;         if (j < nj) {
;             int t = wid + 8 * j; asm volatile("" : "+s"(t));
; #pragma unroll
;             for (int kh = 0; kh < 2; ++kh) {
;             bf16x8 kf[2][2];
; #pragma unroll
;             for (int kb = 0; kb < 2; ++kb)
; #pragma unroll
;                 for (int ks = 0; ks < 2; ++ks) kf[kb][ks] = *(const bf16x8*)(KIDX + (rowbase + 64 * t + 32 * kh + 16 * kb + q16) * 64 + 32 * ks + 8 * kg);
; #pragma unroll
;             for (int kb = 0; kb < 2; ++kb) {
;                 f32x4 s = (f32x4){0.f, 0.f, 0.f, 0.f};
; #pragma unroll
;                 for (int hh = 0; hh < 8; ++hh) {
;                     f32x4 a = (f32x4){0.f, 0.f, 0.f, 0.f};
; #pragma unroll
;                     for (int ks = 0; ks < 2; ++ks) {
;                         const bf16x8 qv = *(const LAS bf16x8*)(lds + L_QI + q16 * 1024 + (((hh * 8 + 4 * ks + kg) ^ q16) << 4));
;                         a = __builtin_amdgcn_mfma_f32_16x16x32_bf16(kf[kb][ks], qv, a, 0, 0, 0);
;                     }
;                     const float wh = wl[hh * 16];
; #pragma unroll
;                     for (int i = 0; i < 4; ++i) s[i] += wh * fmaxf(a[i], 0.f);
;                 }
;                 u32x4 kk; kk.x = fkey(s[0]); kk.y = fkey(s[1]); kk.z = fkey(s[2]); kk.w = fkey(s[3]);
;                 sc[j][2 * kh + kb] = kk;
; #pragma unroll
;                 for (int i = 0; i < 4; ++i) SEL_HADD((kk[i] >> 24) * 16 + q16);
;                 __builtin_amdgcn_sched_barrier(0);
	v_mfma_f32_16x16x32_bf16 v[6:9], v[244:247], v[14:17], 0
	s_nop 1
	s_nop 0
	v_max_f32_e32 v14, 0, v13
	s_nop 0
	v_mfma_f32_16x16x32_bf16 v[2:5], v[248:251], v[22:25], v[6:9]
	s_nop 0
	v_max_f32_e32 v10, 0, v10
	v_max_f32_e32 v11, 0, v11
	v_pk_fma_f32 v[8:9], v[30:31], v[32:33], 0 op_sel_hi:[0,1,0]
	s_nop 0
	s_nop 2
	v_max_f32_e32 v15, 0, v5
	v_pk_mul_f32 v[6:7], v[126:127], v[14:15]
	v_mov_b32_e32 v14, v31
	v_pk_fma_f32 v[8:9], v[14:15], v[26:27], v[8:9] op_sel_hi:[0,1,1]
	v_pk_fma_f32 v[8:9], v[38:39], v[40:41], v[8:9] op_sel_hi:[0,1,1]
	v_mov_b32_e32 v14, v39
	v_pk_fma_f32 v[8:9], v[14:15], v[46:47], v[8:9] op_sel_hi:[0,1,1]
	v_pk_fma_f32 v[8:9], v[50:51], v[52:53], v[8:9] op_sel_hi:[0,1,1]
	v_mov_b32_e32 v14, v51
	v_pk_fma_f32 v[8:9], v[14:15], v[122:123], v[8:9] op_sel_hi:[0,1,1]
	v_max_f32_e32 v2, 0, v2
	v_max_f32_e32 v3, 0, v3
	v_pk_fma_f32 v[8:9], v[126:127], v[10:11], v[8:9] op_sel_hi:[0,1,1]
	v_mov_b32_e32 v10, v127
	v_pk_fma_f32 v[2:3], v[10:11], v[2:3], v[8:9] op_sel_hi:[0,1,1]
	v_and_b32_e32 v9, 0x7fffffff, v3
	v_and_b32_e32 v8, 0x7fffffff, v2
	v_xor_b32_e32 v5, -1, v3
	v_pk_add_f32 v[8:9], v[8:9], 0 neg_lo:[1,1] neg_hi:[1,1]
	v_cmp_gt_i32_e32 vcc, 0, v3
	v_xor_b32_e32 v10, -1, v2
	v_mov_b32_e32 v55, v56
	v_cndmask_b32_e32 v121, v9, v5, vcc
	v_cmp_gt_i32_e32 vcc, 0, v2
	v_pk_add_f32 v[2:3], v[34:35], 0 op_sel_hi:[1,0]
	v_max_f32_e32 v12, 0, v12
	v_pk_add_f32 v[2:3], v[2:3], v[28:29]
	v_pk_add_f32 v[2:3], v[2:3], v[42:43]
	v_mov_b32_e32 v125, v57
	v_pk_add_f32 v[2:3], v[2:3], v[48:49]
	v_mul_f32_e32 v12, v126, v12
	v_pk_add_f32 v[2:3], v[2:3], v[54:55]
	v_max_f32_e32 v4, 0, v4
	v_pk_add_f32 v[2:3], v[2:3], v[124:125]
	v_mov_b32_e32 v13, v6
	v_mul_f32_e32 v4, v127, v4
	v_pk_add_f32 v[2:3], v[2:3], v[12:13]
	v_mov_b32_e32 v5, v7
	v_pk_add_f32 v[2:3], v[2:3], v[4:5]
	v_cndmask_b32_e32 v122, v8, v10, vcc
	v_and_b32_e32 v5, 0x7fffffff, v3
	v_and_b32_e32 v4, 0x7fffffff, v2
	v_xor_b32_e32 v6, -1, v3
	v_pk_add_f32 v[4:5], v[4:5], 0 neg_lo:[1,1] neg_hi:[1,1]
	v_cmp_gt_i32_e32 vcc, 0, v3
	v_xor_b32_e32 v7, -1, v2
	s_nop 0
	v_cndmask_b32_e32 v123, v5, v6, vcc
	v_cmp_gt_i32_e32 vcc, 0, v2
	v_lshrrev_b32_e32 v2, 24, v122
	v_lshl_add_u32 v2, v2, 6, v0
	ds_add_u32 v2, v205 offset:16384
	v_lshrrev_b32_e32 v2, 24, v121
	v_cndmask_b32_e32 v124, v4, v7, vcc
	v_lshl_add_u32 v2, v2, 6, v0
	ds_add_u32 v2, v205 offset:16384
	v_lshrrev_b32_e32 v2, 24, v124
	v_lshl_add_u32 v2, v2, 6, v0
	ds_add_u32 v2, v205 offset:16384
	v_lshrrev_b32_e32 v2, 24, v123
	v_lshl_add_u32 v2, v2, 6, v0
	ds_add_u32 v2, v205 offset:16384
.LBB0_664:
	s_cmp_gt_i32 s4, 4
	s_cselect_b64 s[24:25], -1, 0
	s_cmp_lt_i32 s4, 5
	s_cbranch_scc1 .LBB0_666
	s_add_i32 s0, s46, 32
	s_lshl_b32 s0, s0, 6
	s_ashr_i32 s1, s0, 31
	v_lshl_add_u64 v[2:3], v[18:19], 0, s[0:1]
	v_lshlrev_b64 v[2:3], 7, v[2:3]
	v_lshl_add_u64 v[22:23], v[20:21], 0, v[2:3]
	global_load_dwordx4 v[14:17], v[22:23], off
	global_load_dwordx4 v[10:13], v[22:23], off offset:64
	v_lshl_add_u32 v144, v182, 4, v150
	v_lshl_add_u32 v145, v183, 4, v150
	v_lshl_add_u32 v142, v185, 4, v150
	v_lshl_add_u32 v138, v180, 4, v150
	v_lshl_add_u32 v143, v159, 4, v150
	v_lshl_add_u32 v141, v184, 4, v150
	ds_read_b128 v[2:5], v144
	v_lshl_add_u32 v139, v179, 4, v150
	ds_read_b128 v[6:9], v145
	ds_read_b128 v[24:27], v141
	v_lshl_add_u32 v140, v176, 4, v150
	ds_read_b128 v[28:31], v142
	ds_read_b128 v[32:35], v139
	ds_read_b128 v[36:39], v138
	ds_read_b128 v[40:43], v140
	v_lshl_add_u32 v146, v158, 4, v150
	ds_read_b128 v[44:47], v143
	ds_read_b128 v[48:51], v146
	v_lshl_add_u32 v147, v157, 4, v150
	ds_read_b128 v[52:55], v147
	v_lshl_add_u32 v148, v156, 4, v150
	v_lshl_add_u32 v149, v155, 4, v150
	ds_read_b128 v[126:129], v148
	ds_read_b128 v[130:133], v149
	v_lshl_add_u32 v177, v154, 4, v150
	v_lshl_add_u32 v178, v153, 4, v150
	v_lshl_add_u32 v181, v152, 4, v150
	v_lshl_add_u32 v186, v151, 4, v150
	s_waitcnt vmcnt(1) lgkmcnt(11)
	v_mfma_f32_16x16x32_bf16 v[2:5], v[14:17], v[2:5], 0
	s_waitcnt lgkmcnt(9)
	v_mfma_f32_16x16x32_bf16 v[24:27], v[14:17], v[24:27], 0
	s_waitcnt lgkmcnt(7)
	v_mfma_f32_16x16x32_bf16 v[32:35], v[14:17], v[32:35], 0
	s_waitcnt lgkmcnt(5)
	v_mfma_f32_16x16x32_bf16 v[40:43], v[14:17], v[40:43], 0
	s_waitcnt lgkmcnt(3)
	v_mfma_f32_16x16x32_bf16 v[48:51], v[14:17], v[48:51], 0
	s_waitcnt vmcnt(0)
	v_mfma_f32_16x16x32_bf16 v[160:163], v[10:13], v[6:9], v[2:5]
	v_mfma_f32_16x16x32_bf16 v[24:27], v[10:13], v[28:31], v[24:27]
	v_mfma_f32_16x16x32_bf16 v[28:31], v[10:13], v[36:39], v[32:35]
	v_mfma_f32_16x16x32_bf16 v[32:35], v[10:13], v[44:47], v[40:43]
	ds_read2_b32 v[44:45], v137 offset0:80 offset1:96
	ds_read2_b32 v[46:47], v137 offset0:112 offset1:128
	s_nop 3
	s_waitcnt lgkmcnt(4)
	v_mfma_f32_16x16x32_bf16 v[36:39], v[10:13], v[52:55], v[48:51]
	s_nop 0
	ds_read2_b32 v[48:49], v137 offset0:144 offset1:160
	global_load_dwordx4 v[6:9], v[22:23], off offset:2048
	global_load_dwordx4 v[2:5], v[22:23], off offset:2112
	v_mov_b32_e32 v252, 0x1000
	v_mov_b32_e32 v253, 0
	v_lshl_add_u64 v[252:253], v[252:253], 0, v[22:23]
	global_load_dwordx4 v[236:239], v[252:253], off
	global_load_dwordx4 v[240:243], v[252:253], off offset:64
	global_load_dwordx4 v[244:247], v[252:253], off offset:2048
	global_load_dwordx4 v[248:251], v[252:253], off offset:2112
	s_waitcnt lgkmcnt(4)
	v_mfma_f32_16x16x32_bf16 v[126:129], v[14:17], v[126:129], 0
	s_nop 0
	v_max_f32_e32 v54, v24, v24
	s_nop 0
	s_waitcnt lgkmcnt(3)
	v_mfma_f32_16x16x32_bf16 v[40:43], v[10:13], v[130:133], v[126:129]
	v_max_f32_e32 v125, v39, v39
	v_max_f32_e32 v24, 0, v163
	v_max_f32_e32 v39, 0, v25
	v_max_f32_e32 v128, 0, v26
	v_max_f32_e32 v25, 0, v27
	v_max_f32_e32 v26, 0, v31
	v_max_f32_e32 v27, 0, v35
	v_max_f32_e32 v53, 0, v37
	s_waitcnt lgkmcnt(2)
; #define LAS __attribute__((address_space(3)))
; __device__ __forceinline__ unsigned fkey(float f) { const unsigned u = __float_as_uint(f); return (u & 0x80000000u) ? ~u : (u | 0x80000000u); }
; #define SEL_HADD(idx_) __hip_atomic_fetch_add(&hist[(idx_)], 1u, __ATOMIC_RELAXED, __HIP_MEMORY_SCOPE_WORKGROUP)
; __device__ __forceinline__ void sel_unit(LAS char* lds, int b, int u, const bf16_t* QI, const bf16_t* KIDX, const float* WIDX, unsigned long long* MASK) {
;     ...
;     for (int j = 0; j < 8; ++j) {
;         if (j < nj) {
;             int t = wid + 8 * j; asm volatile("" : "+s"(t));
; #pragma unroll
;             for (int kh = 0; kh < 2; ++kh) {
;             bf16x8 kf[2][2];
; #pragma unroll
;             for (int kb = 0; kb < 2; ++kb)
; #pragma unroll
;                 for (int ks = 0; ks < 2; ++ks) kf[kb][ks] = *(const bf16x8*)(KIDX + (rowbase + 64 * t + 32 * kh + 16 * kb + q16) * 64 + 32 * ks + 8 * kg);
; #pragma unroll
;             for (int kb = 0; kb < 2; ++kb) {
;                 f32x4 s = (f32x4){0.f, 0.f, 0.f, 0.f};
; #pragma unroll
;                 for (int hh = 0; hh < 8; ++hh) {
;                     f32x4 a = (f32x4){0.f, 0.f, 0.f, 0.f};
; #pragma unroll
;                     for (int ks = 0; ks < 2; ++ks) {
;                         const bf16x8 qv = *(const LAS bf16x8*)(lds + L_QI + q16 * 1024 + (((hh * 8 + 4 * ks + kg) ^ q16) << 4));
;                         a = __builtin_amdgcn_mfma_f32_16x16x32_bf16(kf[kb][ks], qv, a, 0, 0, 0);
;                     }
;                     const float wh = wl[hh * 16];
; #pragma unroll
;                     for (int i = 0; i < 4; ++i) s[i] += wh * fmaxf(a[i], 0.f);
;                 }
;                 u32x4 kk; kk.x = fkey(s[0]); kk.y = fkey(s[1]); kk.z = fkey(s[2]); kk.w = fkey(s[3]);
;                 sc[j][2 * kh + kb] = kk;
; #pragma unroll
;                 for (int i = 0; i < 4; ++i) SEL_HADD((kk[i] >> 24) * 16 + q16);
;                 __builtin_amdgcn_sched_barrier(0);
	v_mul_f32_e32 v56, v45, v128
	v_pk_mul_f32 v[128:129], v[44:45], v[24:25]
	s_waitcnt lgkmcnt(1)
	v_pk_mul_f32 v[134:135], v[46:47], v[26:27]
	ds_read_b128 v[24:27], v177
	v_max_f32_e32 v126, v40, v40
	v_max_f32_e32 v40, 0, v28
	v_max_f32_e32 v28, 0, v30
	v_max_f32_e32 v127, v41, v41
	v_max_f32_e32 v41, 0, v29
	v_max_f32_e32 v29, 0, v34
	v_max_f32_e32 v30, 0, v38
	v_mul_f32_e32 v130, v46, v28
	v_max_f32_e32 v28, 0, v42
	v_max_f32_e32 v50, v160, v160
	v_max_f32_e32 v52, v162, v162
	v_mul_f32_e32 v132, v47, v29
	s_waitcnt lgkmcnt(1)
	v_mul_f32_e32 v160, v48, v30
	v_mul_f32_e32 v162, v49, v28
	ds_read_b128 v[28:31], v178
	s_waitcnt lgkmcnt(1)
	v_mfma_f32_16x16x32_bf16 v[24:27], v[14:17], v[24:27], 0
	s_waitcnt lgkmcnt(0)
	v_mfma_f32_16x16x32_bf16 v[24:27], v[10:13], v[28:31], v[24:27]
	ds_read_b128 v[28:31], v181
	v_max_f32_e32 v37, 0, v161
	v_max_f32_e32 v51, 0, v33
	v_max_f32_e32 v55, v36, v36
	v_max_f32_e32 v36, 0, v50
	v_max_f32_e32 v50, 0, v32
	v_max_f32_e32 v32, 0, v125
	v_max_f32_e32 v33, 0, v43
	v_pk_mul_f32 v[164:165], v[48:49], v[32:33]
	ds_read_b128 v[32:35], v186
	s_waitcnt lgkmcnt(1)
	v_mfma_f32_16x16x32_bf16 v[14:17], v[14:17], v[28:31], 0
	v_max_f32_e32 v42, 0, v52
	v_max_f32_e32 v38, 0, v54
	v_max_f32_e32 v52, 0, v55
	s_waitcnt lgkmcnt(0)
	v_mfma_f32_16x16x32_bf16 v[10:13], v[10:13], v[32:35], v[14:17]
	v_max_f32_e32 v54, 0, v126
	v_max_f32_e32 v55, 0, v127
	ds_read2_b32 v[126:127], v137 offset0:176 offset1:192
	s_nop 0
	v_max_f32_e32 v28, 0, v27
	s_nop 2
	v_max_f32_e32 v29, 0, v13
	s_waitcnt lgkmcnt(0)
	v_pk_mul_f32 v[14:15], v[126:127], v[28:29]
	v_pk_fma_f32 v[16:17], v[44:45], v[36:37], 0 op_sel_hi:[0,1,0]
	v_mov_b32_e32 v28, v45
	v_pk_fma_f32 v[16:17], v[28:29], v[38:39], v[16:17] op_sel_hi:[0,1,1]
	v_pk_fma_f32 v[16:17], v[46:47], v[40:41], v[16:17] op_sel_hi:[0,1,1]
	v_mov_b32_e32 v28, v47
	v_pk_fma_f32 v[16:17], v[28:29], v[50:51], v[16:17] op_sel_hi:[0,1,1]
	v_pk_fma_f32 v[16:17], v[48:49], v[52:53], v[16:17] op_sel_hi:[0,1,1]
	v_mov_b32_e32 v28, v49
	v_max_f32_e32 v24, 0, v24
	v_max_f32_e32 v25, 0, v25
	v_pk_fma_f32 v[16:17], v[28:29], v[54:55], v[16:17] op_sel_hi:[0,1,1]
	v_max_f32_e32 v10, 0, v10
	v_max_f32_e32 v11, 0, v11
	v_pk_fma_f32 v[16:17], v[126:127], v[24:25], v[16:17] op_sel_hi:[0,1,1]
	v_mov_b32_e32 v24, v127
	v_pk_fma_f32 v[10:11], v[24:25], v[10:11], v[16:17] op_sel_hi:[0,1,1]
	v_and_b32_e32 v17, 0x7fffffff, v11
	v_and_b32_e32 v16, 0x7fffffff, v10
	v_mul_f32_e32 v42, v44, v42
	v_xor_b32_e32 v13, -1, v11
	v_pk_add_f32 v[16:17], v[16:17], 0 neg_lo:[1,1] neg_hi:[1,1]
	v_cmp_gt_i32_e32 vcc, 0, v11
	v_mov_b32_e32 v43, v128
	v_xor_b32_e32 v24, -1, v10
	v_cndmask_b32_e32 v125, v17, v13, vcc
	v_cmp_gt_i32_e32 vcc, 0, v10
	v_pk_add_f32 v[10:11], v[42:43], 0 op_sel_hi:[1,0]
	v_mov_b32_e32 v57, v129
	v_pk_add_f32 v[10:11], v[10:11], v[56:57]
	v_mov_b32_e32 v131, v134
	v_pk_add_f32 v[10:11], v[10:11], v[130:131]
	v_mov_b32_e32 v133, v135
	v_pk_add_f32 v[10:11], v[10:11], v[132:133]
	v_mov_b32_e32 v161, v164
	v_max_f32_e32 v26, 0, v26
	v_pk_add_f32 v[10:11], v[10:11], v[160:161]
	v_mov_b32_e32 v163, v165
	v_mul_f32_e32 v26, v126, v26
	v_max_f32_e32 v12, 0, v12
	v_pk_add_f32 v[10:11], v[10:11], v[162:163]
	v_mov_b32_e32 v27, v14
	v_mul_f32_e32 v12, v127, v12
	v_pk_add_f32 v[10:11], v[10:11], v[26:27]
	v_mov_b32_e32 v13, v15
	v_pk_add_f32 v[10:11], v[10:11], v[12:13]
	v_cndmask_b32_e32 v126, v16, v24, vcc
	v_and_b32_e32 v13, 0x7fffffff, v11
	v_and_b32_e32 v12, 0x7fffffff, v10
	v_xor_b32_e32 v14, -1, v11
	v_pk_add_f32 v[12:13], v[12:13], 0 neg_lo:[1,1] neg_hi:[1,1]
	v_cmp_gt_i32_e32 vcc, 0, v11
	v_xor_b32_e32 v15, -1, v10
	s_nop 0
	v_cndmask_b32_e32 v127, v13, v14, vcc
	v_cmp_gt_i32_e32 vcc, 0, v10
	v_lshrrev_b32_e32 v10, 24, v126
	v_lshl_add_u32 v10, v10, 6, v0
	ds_add_u32 v10, v205 offset:16384
	v_lshrrev_b32_e32 v10, 24, v125
	v_cndmask_b32_e32 v128, v12, v15, vcc
	v_lshl_add_u32 v10, v10, 6, v0
	ds_add_u32 v10, v205 offset:16384
	v_lshrrev_b32_e32 v10, 24, v128
	v_lshl_add_u32 v10, v10, 6, v0
	ds_add_u32 v10, v205 offset:16384
	v_lshrrev_b32_e32 v10, 24, v127
	v_lshl_add_u32 v10, v10, 6, v0
	ds_add_u32 v10, v205 offset:16384
	ds_read_b128 v[10:13], v144
	ds_read_b128 v[14:17], v145
	ds_read_b128 v[24:27], v141
	ds_read_b128 v[28:31], v142
	ds_read2_b32 v[32:33], v137 offset0:80 offset1:96
	ds_read2_b32 v[40:41], v137 offset0:112 offset1:128
	s_waitcnt vmcnt(5) lgkmcnt(5)
	v_mfma_f32_16x16x32_bf16 v[10:13], v[6:9], v[10:13], 0
	ds_read2_b32 v[52:53], v137 offset0:144 offset1:160
	s_waitcnt vmcnt(4) lgkmcnt(5)
	v_mfma_f32_16x16x32_bf16 v[10:13], v[2:5], v[14:17], v[10:13]
	ds_read_b128 v[14:17], v139
	s_waitcnt lgkmcnt(5)
	v_mfma_f32_16x16x32_bf16 v[24:27], v[6:9], v[24:27], 0
	s_nop 4
	v_max_f32_e32 v34, 0, v10
	v_max_f32_e32 v10, 0, v12
	v_max_f32_e32 v35, 0, v11
	s_waitcnt lgkmcnt(3)
	v_mul_f32_e32 v36, v32, v10
	v_max_f32_e32 v38, 0, v13
	v_mfma_f32_16x16x32_bf16 v[10:13], v[2:5], v[28:31], v[24:27]
	s_nop 2
	ds_read_b128 v[24:27], v138
	s_waitcnt lgkmcnt(1)
	v_mfma_f32_16x16x32_bf16 v[14:17], v[6:9], v[14:17], 0
	s_nop 1
	v_max_f32_e32 v28, 0, v10
	v_max_f32_e32 v29, 0, v11
	v_max_f32_e32 v10, 0, v12
	v_mul_f32_e32 v30, v33, v10
	v_max_f32_e32 v39, 0, v13
	s_waitcnt lgkmcnt(0)
	v_mfma_f32_16x16x32_bf16 v[10:13], v[2:5], v[24:27], v[14:17]
	ds_read_b128 v[24:27], v143
	v_pk_mul_f32 v[38:39], v[32:33], v[38:39]
	s_nop 0
	ds_read_b128 v[14:17], v140
	s_waitcnt lgkmcnt(0)
	v_mfma_f32_16x16x32_bf16 v[14:17], v[6:9], v[14:17], 0
	s_nop 1
	v_max_f32_e32 v42, 0, v10
	v_max_f32_e32 v43, 0, v11
	v_max_f32_e32 v10, 0, v12
	v_mul_f32_e32 v44, v40, v10
	s_nop 0
	v_max_f32_e32 v46, 0, v13
	v_mfma_f32_16x16x32_bf16 v[10:13], v[2:5], v[24:27], v[14:17]
	ds_read_b128 v[24:27], v147
	v_mov_b32_e32 v37, v38
	v_mov_b32_e32 v31, v39
	ds_read_b128 v[14:17], v146
	s_waitcnt lgkmcnt(0)
; #define LAS __attribute__((address_space(3)))
; __device__ __forceinline__ unsigned fkey(float f) { const unsigned u = __float_as_uint(f); return (u & 0x80000000u) ? ~u : (u | 0x80000000u); }
; #define SEL_HADD(idx_) __hip_atomic_fetch_add(&hist[(idx_)], 1u, __ATOMIC_RELAXED, __HIP_MEMORY_SCOPE_WORKGROUP)
; __device__ __forceinline__ void sel_unit(LAS char* lds, int b, int u, const bf16_t* QI, const bf16_t* KIDX, const float* WIDX, unsigned long long* MASK) {
;     ...
;     for (int j = 0; j < 8; ++j) {
;         if (j < nj) {
;             int t = wid + 8 * j; asm volatile("" : "+s"(t));
; #pragma unroll
;             for (int kh = 0; kh < 2; ++kh) {
;             bf16x8 kf[2][2];
; #pragma unroll
;             for (int kb = 0; kb < 2; ++kb)
; #pragma unroll
;                 for (int ks = 0; ks < 2; ++ks) kf[kb][ks] = *(const bf16x8*)(KIDX + (rowbase + 64 * t + 32 * kh + 16 * kb + q16) * 64 + 32 * ks + 8 * kg);
; #pragma unroll
;             for (int kb = 0; kb < 2; ++kb) {
;                 f32x4 s = (f32x4){0.f, 0.f, 0.f, 0.f};
; #pragma unroll
;                 for (int hh = 0; hh < 8; ++hh) {
;                     f32x4 a = (f32x4){0.f, 0.f, 0.f, 0.f};
; #pragma unroll
;                     for (int ks = 0; ks < 2; ++ks) {
;                         const bf16x8 qv = *(const LAS bf16x8*)(lds + L_QI + q16 * 1024 + (((hh * 8 + 4 * ks + kg) ^ q16) << 4));
;                         a = __builtin_amdgcn_mfma_f32_16x16x32_bf16(kf[kb][ks], qv, a, 0, 0, 0);
;                     }
;                     const float wh = wl[hh * 16];
; #pragma unroll
;                     for (int i = 0; i < 4; ++i) s[i] += wh * fmaxf(a[i], 0.f);
;                 }
;                 u32x4 kk; kk.x = fkey(s[0]); kk.y = fkey(s[1]); kk.z = fkey(s[2]); kk.w = fkey(s[3]);
;                 sc[j][2 * kh + kb] = kk;
; #pragma unroll
;                 for (int i = 0; i < 4; ++i) SEL_HADD((kk[i] >> 24) * 16 + q16);
;                 __builtin_amdgcn_sched_barrier(0);
	v_mfma_f32_16x16x32_bf16 v[14:17], v[6:9], v[14:17], 0
	s_nop 1
	v_max_f32_e32 v48, 0, v10
	v_max_f32_e32 v49, 0, v11
	v_max_f32_e32 v10, 0, v12
	v_mul_f32_e32 v50, v41, v10
	s_nop 0
	v_max_f32_e32 v47, 0, v13
	v_mfma_f32_16x16x32_bf16 v[10:13], v[2:5], v[24:27], v[14:17]
	ds_read_b128 v[24:27], v149
	v_pk_mul_f32 v[46:47], v[40:41], v[46:47]
	s_nop 0
	ds_read_b128 v[14:17], v148
	s_waitcnt lgkmcnt(0)
	v_mfma_f32_16x16x32_bf16 v[14:17], v[6:9], v[14:17], 0
	s_nop 1
	v_max_f32_e32 v54, 0, v10
	v_max_f32_e32 v55, 0, v11
	v_max_f32_e32 v10, 0, v12
	v_mul_f32_e32 v56, v52, v10
	s_nop 0
	v_max_f32_e32 v130, 0, v13
	v_mfma_f32_16x16x32_bf16 v[10:13], v[2:5], v[24:27], v[14:17]
	ds_read_b128 v[24:27], v178
	v_mov_b32_e32 v45, v46
	v_mov_b32_e32 v51, v47
	ds_read_b128 v[14:17], v177
	s_waitcnt lgkmcnt(0)
	v_mfma_f32_16x16x32_bf16 v[14:17], v[6:9], v[14:17], 0
	s_nop 1
	v_max_f32_e32 v132, 0, v10
	v_max_f32_e32 v133, 0, v11
	v_max_f32_e32 v10, 0, v12
	v_mul_f32_e32 v134, v53, v10
	s_nop 0
	v_max_f32_e32 v131, 0, v13
	v_mfma_f32_16x16x32_bf16 v[10:13], v[2:5], v[24:27], v[14:17]
	ds_read_b128 v[24:27], v186
	v_pk_mul_f32 v[160:161], v[52:53], v[130:131]
	ds_read2_b32 v[130:131], v137 offset0:176 offset1:192
	ds_read_b128 v[14:17], v181
	s_waitcnt lgkmcnt(0)
	v_mfma_f32_16x16x32_bf16 v[6:9], v[6:9], v[14:17], 0
	s_nop 1
	s_nop 0
	v_max_f32_e32 v14, 0, v13
	s_nop 0
	v_mfma_f32_16x16x32_bf16 v[2:5], v[2:5], v[24:27], v[6:9]
	s_nop 0
	v_max_f32_e32 v10, 0, v10
	v_max_f32_e32 v11, 0, v11
	v_pk_fma_f32 v[8:9], v[32:33], v[34:35], 0 op_sel_hi:[0,1,0]
	s_nop 0
	s_nop 2
	v_max_f32_e32 v15, 0, v5
	v_pk_mul_f32 v[6:7], v[130:131], v[14:15]
	v_mov_b32_e32 v14, v33
	v_pk_fma_f32 v[8:9], v[14:15], v[28:29], v[8:9] op_sel_hi:[0,1,1]
	v_pk_fma_f32 v[8:9], v[40:41], v[42:43], v[8:9] op_sel_hi:[0,1,1]
	v_mov_b32_e32 v14, v41
	v_pk_fma_f32 v[8:9], v[14:15], v[48:49], v[8:9] op_sel_hi:[0,1,1]
	v_pk_fma_f32 v[8:9], v[52:53], v[54:55], v[8:9] op_sel_hi:[0,1,1]
	v_mov_b32_e32 v14, v53
	v_pk_fma_f32 v[8:9], v[14:15], v[132:133], v[8:9] op_sel_hi:[0,1,1]
	v_max_f32_e32 v2, 0, v2
	v_max_f32_e32 v3, 0, v3
	v_pk_fma_f32 v[8:9], v[130:131], v[10:11], v[8:9] op_sel_hi:[0,1,1]
	v_mov_b32_e32 v10, v131
	v_pk_fma_f32 v[2:3], v[10:11], v[2:3], v[8:9] op_sel_hi:[0,1,1]
	v_and_b32_e32 v9, 0x7fffffff, v3
	v_and_b32_e32 v8, 0x7fffffff, v2
	v_xor_b32_e32 v5, -1, v3
	v_pk_add_f32 v[8:9], v[8:9], 0 neg_lo:[1,1] neg_hi:[1,1]
	v_cmp_gt_i32_e32 vcc, 0, v3
	v_xor_b32_e32 v10, -1, v2
	v_mov_b32_e32 v57, v160
	v_cndmask_b32_e32 v129, v9, v5, vcc
	v_cmp_gt_i32_e32 vcc, 0, v2
	v_pk_add_f32 v[2:3], v[36:37], 0 op_sel_hi:[1,0]
	v_max_f32_e32 v12, 0, v12
	v_pk_add_f32 v[2:3], v[2:3], v[30:31]
	v_pk_add_f32 v[2:3], v[2:3], v[44:45]
	v_mov_b32_e32 v135, v161
	v_pk_add_f32 v[2:3], v[2:3], v[50:51]
	v_mul_f32_e32 v12, v130, v12
	v_pk_add_f32 v[2:3], v[2:3], v[56:57]
	v_max_f32_e32 v4, 0, v4
	v_pk_add_f32 v[2:3], v[2:3], v[134:135]
	v_mov_b32_e32 v13, v6
	v_mul_f32_e32 v4, v131, v4
	v_pk_add_f32 v[2:3], v[2:3], v[12:13]
	v_mov_b32_e32 v5, v7
	v_pk_add_f32 v[2:3], v[2:3], v[4:5]
	v_cndmask_b32_e32 v130, v8, v10, vcc
	v_and_b32_e32 v5, 0x7fffffff, v3
	v_and_b32_e32 v4, 0x7fffffff, v2
	v_xor_b32_e32 v6, -1, v3
	v_pk_add_f32 v[4:5], v[4:5], 0 neg_lo:[1,1] neg_hi:[1,1]
	v_cmp_gt_i32_e32 vcc, 0, v3
	v_xor_b32_e32 v7, -1, v2
	s_nop 0
	v_cndmask_b32_e32 v131, v5, v6, vcc
	v_cmp_gt_i32_e32 vcc, 0, v2
	v_lshrrev_b32_e32 v2, 24, v130
	v_lshl_add_u32 v2, v2, 6, v0
	ds_add_u32 v2, v205 offset:16384
	v_lshrrev_b32_e32 v2, 24, v129
	v_cndmask_b32_e32 v132, v4, v7, vcc
	v_lshl_add_u32 v2, v2, 6, v0
	ds_add_u32 v2, v205 offset:16384
	v_lshrrev_b32_e32 v2, 24, v132
	v_lshl_add_u32 v2, v2, 6, v0
	ds_add_u32 v2, v205 offset:16384
	v_lshrrev_b32_e32 v2, 24, v131
	v_lshl_add_u32 v2, v2, 6, v0
	ds_add_u32 v2, v205 offset:16384
	ds_read_b128 v[22:25], v144
	ds_read_b128 v[26:29], v145
	s_waitcnt vmcnt(3) lgkmcnt(1)
	v_mfma_f32_16x16x32_bf16 v[22:25], v[236:239], v[22:25], 0
	ds_read_b128 v[32:35], v142
	ds_read_b128 v[38:41], v138
	ds_read_b128 v[44:47], v143
	s_waitcnt vmcnt(2) lgkmcnt(3)
	v_mfma_f32_16x16x32_bf16 v[26:29], v[240:243], v[26:29], v[22:25]
	ds_read_b128 v[50:53], v147
	ds_read_b128 v[160:163], v149
	ds_read_b128 v[164:167], v178
	ds_read2_b32 v[24:25], v137 offset0:80 offset1:96
	s_nop 3
	v_max_f32_e32 v26, 0, v26
	v_max_f32_e32 v27, 0, v27
	v_max_f32_e32 v22, v28, v28
	v_max_f32_e32 v23, v29, v29
	ds_read_b128 v[28:31], v141
	s_waitcnt lgkmcnt(0)
	v_mfma_f32_16x16x32_bf16 v[28:31], v[236:239], v[28:31], 0
	v_max_f32_e32 v36, 0, v23
	v_max_f32_e32 v22, 0, v22
	v_mul_f32_e32 v22, v24, v22
	v_mfma_f32_16x16x32_bf16 v[28:31], v[240:243], v[32:35], v[28:31]
	s_nop 7
	v_max_f32_e32 v32, 0, v28
	v_max_f32_e32 v33, 0, v29
	v_max_f32_e32 v23, 0, v30
	v_mul_f32_e32 v28, v25, v23
	v_max_f32_e32 v37, 0, v31
	v_pk_mul_f32 v[30:31], v[24:25], v[36:37]
	ds_read_b128 v[34:37], v139
	s_waitcnt lgkmcnt(0)
	v_mfma_f32_16x16x32_bf16 v[34:37], v[236:239], v[34:37], 0
	v_mov_b32_e32 v29, v31
	v_mfma_f32_16x16x32_bf16 v[38:41], v[240:243], v[38:41], v[34:37]
	s_nop 5
	ds_read2_b32 v[36:37], v137 offset0:112 offset1:128
	s_nop 0
	v_max_f32_e32 v38, 0, v38
	v_max_f32_e32 v39, 0, v39
	v_max_f32_e32 v23, 0, v40
	s_waitcnt lgkmcnt(0)
	v_mul_f32_e32 v34, v36, v23
	v_max_f32_e32 v23, v41, v41
	ds_read_b128 v[40:43], v140
	s_waitcnt lgkmcnt(0)
	v_mfma_f32_16x16x32_bf16 v[40:43], v[236:239], v[40:43], 0
	v_max_f32_e32 v48, 0, v23
	v_mfma_f32_16x16x32_bf16 v[40:43], v[240:243], v[44:47], v[40:43]
	s_nop 7
	v_max_f32_e32 v44, 0, v40
	v_max_f32_e32 v45, 0, v41
	v_max_f32_e32 v23, 0, v42
	v_mul_f32_e32 v40, v37, v23
	v_max_f32_e32 v49, 0, v43
	v_pk_mul_f32 v[42:43], v[36:37], v[48:49]
	ds_read_b128 v[46:49], v146
	s_waitcnt lgkmcnt(0)
; #define LAS __attribute__((address_space(3)))
; __device__ __forceinline__ unsigned fkey(float f) { const unsigned u = __float_as_uint(f); return (u & 0x80000000u) ? ~u : (u | 0x80000000u); }
; #define SEL_HADD(idx_) __hip_atomic_fetch_add(&hist[(idx_)], 1u, __ATOMIC_RELAXED, __HIP_MEMORY_SCOPE_WORKGROUP)
; __device__ __forceinline__ void sel_unit(LAS char* lds, int b, int u, const bf16_t* QI, const bf16_t* KIDX, const float* WIDX, unsigned long long* MASK) {
;     ...
;     for (int j = 0; j < 8; ++j) {
;         if (j < nj) {
;             int t = wid + 8 * j; asm volatile("" : "+s"(t));
; #pragma unroll
;             for (int kh = 0; kh < 2; ++kh) {
;             bf16x8 kf[2][2];
; #pragma unroll
;             for (int kb = 0; kb < 2; ++kb)
; #pragma unroll
;                 for (int ks = 0; ks < 2; ++ks) kf[kb][ks] = *(const bf16x8*)(KIDX + (rowbase + 64 * t + 32 * kh + 16 * kb + q16) * 64 + 32 * ks + 8 * kg);
; #pragma unroll
;             for (int kb = 0; kb < 2; ++kb) {
;                 f32x4 s = (f32x4){0.f, 0.f, 0.f, 0.f};
; #pragma unroll
;                 for (int hh = 0; hh < 8; ++hh) {
;                     f32x4 a = (f32x4){0.f, 0.f, 0.f, 0.f};
; #pragma unroll
;                     for (int ks = 0; ks < 2; ++ks) {
;                         const bf16x8 qv = *(const LAS bf16x8*)(lds + L_QI + q16 * 1024 + (((hh * 8 + 4 * ks + kg) ^ q16) << 4));
;                         a = __builtin_amdgcn_mfma_f32_16x16x32_bf16(kf[kb][ks], qv, a, 0, 0, 0);
;                     }
;                     const float wh = wl[hh * 16];
; #pragma unroll
;                     for (int i = 0; i < 4; ++i) s[i] += wh * fmaxf(a[i], 0.f);
;                 }
;                 u32x4 kk; kk.x = fkey(s[0]); kk.y = fkey(s[1]); kk.z = fkey(s[2]); kk.w = fkey(s[3]);
;                 sc[j][2 * kh + kb] = kk;
; #pragma unroll
;                 for (int i = 0; i < 4; ++i) SEL_HADD((kk[i] >> 24) * 16 + q16);
;                 __builtin_amdgcn_sched_barrier(0);
	v_mfma_f32_16x16x32_bf16 v[46:49], v[236:239], v[46:49], 0
	v_mov_b32_e32 v35, v42
	v_mov_b32_e32 v41, v43
	v_mfma_f32_16x16x32_bf16 v[50:53], v[240:243], v[50:53], v[46:49]
	s_nop 4
	ds_read2_b32 v[48:49], v137 offset0:144 offset1:160
	s_nop 1
	v_max_f32_e32 v50, 0, v50
	v_max_f32_e32 v51, 0, v51
	v_max_f32_e32 v23, 0, v52
	s_waitcnt lgkmcnt(0)
	v_mul_f32_e32 v46, v48, v23
	v_max_f32_e32 v23, v53, v53
	ds_read_b128 v[52:55], v148
	s_waitcnt lgkmcnt(0)
	v_mfma_f32_16x16x32_bf16 v[52:55], v[236:239], v[52:55], 0
	v_max_f32_e32 v134, 0, v23
	v_mfma_f32_16x16x32_bf16 v[52:55], v[240:243], v[160:163], v[52:55]
	ds_read_b128 v[160:163], v177
	s_waitcnt lgkmcnt(0)
	v_mfma_f32_16x16x32_bf16 v[160:163], v[236:239], v[160:163], 0
	s_nop 4
	v_max_f32_e32 v56, 0, v52
	v_max_f32_e32 v57, 0, v53
	v_max_f32_e32 v23, 0, v54
	v_mfma_f32_16x16x32_bf16 v[160:163], v[240:243], v[164:167], v[160:163]
	v_mul_f32_e32 v52, v49, v23
	s_nop 0
	v_max_f32_e32 v135, 0, v55
	v_pk_mul_f32 v[54:55], v[48:49], v[134:135]
	ds_read2_b32 v[134:135], v137 offset0:176 offset1:192
	s_nop 2
	v_max_f32_e32 v164, 0, v160
	v_max_f32_e32 v165, 0, v161
	v_max_f32_e32 v23, 0, v162
	s_waitcnt lgkmcnt(0)
	v_mul_f32_e32 v166, v134, v23
	v_max_f32_e32 v23, v163, v163
	ds_read_b128 v[160:163], v181
	s_waitcnt lgkmcnt(0)
	v_mfma_f32_16x16x32_bf16 v[14:17], v[236:239], v[160:163], 0
	ds_read_b128 v[160:163], v186
	v_max_f32_e32 v168, 0, v23
	v_mov_b32_e32 v47, v54
	s_waitcnt lgkmcnt(0)
	v_mfma_f32_16x16x32_bf16 v[10:13], v[240:243], v[160:163], v[14:17]
	v_mov_b32_e32 v53, v55
	s_nop 1
	v_pk_fma_f32 v[16:17], v[24:25], v[26:27], 0 op_sel_hi:[0,1,0]
	v_mov_b32_e32 v24, v25
	v_pk_fma_f32 v[16:17], v[24:25], v[32:33], v[16:17] op_sel_hi:[0,1,1]
	v_pk_fma_f32 v[16:17], v[36:37], v[38:39], v[16:17] op_sel_hi:[0,1,1]
	v_mov_b32_e32 v24, v37
	v_pk_fma_f32 v[16:17], v[24:25], v[44:45], v[16:17] op_sel_hi:[0,1,1]
	v_pk_fma_f32 v[16:17], v[48:49], v[50:51], v[16:17] op_sel_hi:[0,1,1]
	v_mov_b32_e32 v24, v49
	v_pk_fma_f32 v[16:17], v[24:25], v[56:57], v[16:17] op_sel_hi:[0,1,1]
	v_max_f32_e32 v10, 0, v10
	v_max_f32_e32 v11, 0, v11
	v_pk_fma_f32 v[16:17], v[134:135], v[164:165], v[16:17] op_sel_hi:[0,1,1]
	v_mov_b32_e32 v24, v135
	v_pk_fma_f32 v[10:11], v[24:25], v[10:11], v[16:17] op_sel_hi:[0,1,1]
	v_and_b32_e32 v17, 0x7fffffff, v11
	v_and_b32_e32 v16, 0x7fffffff, v10
	v_max_f32_e32 v169, 0, v13
	v_xor_b32_e32 v23, -1, v10
	v_pk_add_f32 v[16:17], v[16:17], 0 neg_lo:[1,1] neg_hi:[1,1]
	v_cmp_gt_i32_e32 vcc, 0, v10
	v_pk_mul_f32 v[14:15], v[134:135], v[168:169]
	v_xor_b32_e32 v13, -1, v11
	v_cndmask_b32_e32 v134, v16, v23, vcc
	v_mov_b32_e32 v23, v30
	v_cmp_gt_i32_e64 s[2:3], 0, v11
	v_pk_add_f32 v[10:11], v[22:23], 0 op_sel_hi:[1,0]
	v_pk_add_f32 v[10:11], v[10:11], v[28:29]
	v_max_f32_e32 v12, 0, v12
	v_pk_add_f32 v[10:11], v[10:11], v[34:35]
	v_mov_b32_e32 v167, v14
	v_pk_add_f32 v[10:11], v[10:11], v[40:41]
	v_mul_f32_e32 v12, v135, v12
	v_pk_add_f32 v[10:11], v[10:11], v[46:47]
	v_cndmask_b32_e64 v133, v17, v13, s[2:3]
	v_pk_add_f32 v[10:11], v[10:11], v[52:53]
	v_mov_b32_e32 v13, v15
	v_pk_add_f32 v[10:11], v[10:11], v[166:167]
	s_nop 0
	v_pk_add_f32 v[10:11], v[10:11], v[12:13]
	s_nop 0
	v_xor_b32_e32 v15, -1, v10
	v_and_b32_e32 v12, 0x7fffffff, v10
	v_cmp_gt_i32_e32 vcc, 0, v10
	v_lshrrev_b32_e32 v10, 24, v134
	v_and_b32_e32 v13, 0x7fffffff, v11
	v_lshl_add_u32 v10, v10, 6, v0
	v_pk_add_f32 v[12:13], v[12:13], 0 neg_lo:[1,1] neg_hi:[1,1]
	ds_add_u32 v10, v205 offset:16384
	v_lshrrev_b32_e32 v10, 24, v133
	v_cndmask_b32_e32 v136, v12, v15, vcc
	v_lshl_add_u32 v10, v10, 6, v0
	v_xor_b32_e32 v14, -1, v11
	v_cmp_gt_i32_e64 s[2:3], 0, v11
	ds_add_u32 v10, v205 offset:16384
	v_lshrrev_b32_e32 v10, 24, v136
	v_cndmask_b32_e64 v135, v13, v14, s[2:3]
	v_lshl_add_u32 v10, v10, 6, v0
	ds_add_u32 v10, v205 offset:16384
	v_lshrrev_b32_e32 v10, 24, v135
	v_lshl_add_u32 v10, v10, 6, v0
	ds_add_u32 v10, v205 offset:16384
	ds_read_b128 v[10:13], v144
	ds_read_b128 v[14:17], v145
	ds_read_b128 v[22:25], v141
	ds_read_b128 v[26:29], v142
	ds_read2_b32 v[30:31], v137 offset0:80 offset1:96
	ds_read2_b32 v[38:39], v137 offset0:112 offset1:128
	s_waitcnt vmcnt(1) lgkmcnt(5)
	v_mfma_f32_16x16x32_bf16 v[10:13], v[244:247], v[10:13], 0
	ds_read2_b32 v[50:51], v137 offset0:144 offset1:160
	s_waitcnt vmcnt(0) lgkmcnt(5)
	v_mfma_f32_16x16x32_bf16 v[10:13], v[248:251], v[14:17], v[10:13]
	ds_read_b128 v[14:17], v139
	s_waitcnt lgkmcnt(5)
	v_mfma_f32_16x16x32_bf16 v[22:25], v[244:247], v[22:25], 0
	s_nop 4
	v_max_f32_e32 v32, 0, v10
	v_max_f32_e32 v10, 0, v12
	v_max_f32_e32 v33, 0, v11
	s_waitcnt lgkmcnt(3)
	v_mul_f32_e32 v34, v30, v10
	v_max_f32_e32 v36, 0, v13
	v_mfma_f32_16x16x32_bf16 v[10:13], v[248:251], v[26:29], v[22:25]
	s_nop 2
	ds_read_b128 v[22:25], v138
	s_waitcnt lgkmcnt(1)
	v_mfma_f32_16x16x32_bf16 v[14:17], v[244:247], v[14:17], 0
	s_nop 1
	v_max_f32_e32 v26, 0, v10
	v_max_f32_e32 v27, 0, v11
	v_max_f32_e32 v10, 0, v12
	v_mul_f32_e32 v28, v31, v10
	v_max_f32_e32 v37, 0, v13
	s_waitcnt lgkmcnt(0)
	v_mfma_f32_16x16x32_bf16 v[10:13], v[248:251], v[22:25], v[14:17]
	ds_read_b128 v[22:25], v143
	ds_read2_b32 v[142:143], v137 offset0:176 offset1:192
	v_pk_mul_f32 v[36:37], v[30:31], v[36:37]
	ds_read_b128 v[14:17], v140
	s_waitcnt lgkmcnt(0)
	v_mfma_f32_16x16x32_bf16 v[14:17], v[244:247], v[14:17], 0
	s_nop 1
	v_max_f32_e32 v40, 0, v10
	v_max_f32_e32 v41, 0, v11
	v_max_f32_e32 v10, 0, v12
	v_mul_f32_e32 v42, v38, v10
	s_nop 0
	v_max_f32_e32 v44, 0, v13
	v_mfma_f32_16x16x32_bf16 v[10:13], v[248:251], v[22:25], v[14:17]
	ds_read_b128 v[22:25], v147
	v_mov_b32_e32 v35, v36
	v_mov_b32_e32 v29, v37
	ds_read_b128 v[14:17], v146
	s_waitcnt lgkmcnt(0)
; #define LAS __attribute__((address_space(3)))
; __device__ __forceinline__ unsigned fkey(float f) { const unsigned u = __float_as_uint(f); return (u & 0x80000000u) ? ~u : (u | 0x80000000u); }
; #define SEL_HADD(idx_) __hip_atomic_fetch_add(&hist[(idx_)], 1u, __ATOMIC_RELAXED, __HIP_MEMORY_SCOPE_WORKGROUP)
; __device__ __forceinline__ void sel_unit(LAS char* lds, int b, int u, const bf16_t* QI, const bf16_t* KIDX, const float* WIDX, unsigned long long* MASK) {
;     ...
;     for (int j = 0; j < 8; ++j) {
;         if (j < nj) {
;             int t = wid + 8 * j; asm volatile("" : "+s"(t));
; #pragma unroll
;             for (int kh = 0; kh < 2; ++kh) {
;             bf16x8 kf[2][2];
; #pragma unroll
;             for (int kb = 0; kb < 2; ++kb)
; #pragma unroll
;                 for (int ks = 0; ks < 2; ++ks) kf[kb][ks] = *(const bf16x8*)(KIDX + (rowbase + 64 * t + 32 * kh + 16 * kb + q16) * 64 + 32 * ks + 8 * kg);
; #pragma unroll
;             for (int kb = 0; kb < 2; ++kb) {
;                 f32x4 s = (f32x4){0.f, 0.f, 0.f, 0.f};
; #pragma unroll
;                 for (int hh = 0; hh < 8; ++hh) {
;                     f32x4 a = (f32x4){0.f, 0.f, 0.f, 0.f};
; #pragma unroll
;                     for (int ks = 0; ks < 2; ++ks) {
;                         const bf16x8 qv = *(const LAS bf16x8*)(lds + L_QI + q16 * 1024 + (((hh * 8 + 4 * ks + kg) ^ q16) << 4));
;                         a = __builtin_amdgcn_mfma_f32_16x16x32_bf16(kf[kb][ks], qv, a, 0, 0, 0);
;                     }
;                     const float wh = wl[hh * 16];
; #pragma unroll
;                     for (int i = 0; i < 4; ++i) s[i] += wh * fmaxf(a[i], 0.f);
;                 }
;                 u32x4 kk; kk.x = fkey(s[0]); kk.y = fkey(s[1]); kk.z = fkey(s[2]); kk.w = fkey(s[3]);
;                 sc[j][2 * kh + kb] = kk;
; #pragma unroll
;                 for (int i = 0; i < 4; ++i) SEL_HADD((kk[i] >> 24) * 16 + q16);
;                 __builtin_amdgcn_sched_barrier(0);
	v_mfma_f32_16x16x32_bf16 v[14:17], v[244:247], v[14:17], 0
	s_nop 1
	v_max_f32_e32 v46, 0, v10
	v_max_f32_e32 v47, 0, v11
	v_max_f32_e32 v10, 0, v12
	v_mul_f32_e32 v48, v39, v10
	s_nop 0
	v_max_f32_e32 v45, 0, v13
	v_mfma_f32_16x16x32_bf16 v[10:13], v[248:251], v[22:25], v[14:17]
	ds_read_b128 v[22:25], v149
	v_pk_mul_f32 v[44:45], v[38:39], v[44:45]
	s_nop 0
	ds_read_b128 v[14:17], v148
	s_waitcnt lgkmcnt(0)
	v_mfma_f32_16x16x32_bf16 v[14:17], v[244:247], v[14:17], 0
	s_nop 1
	v_max_f32_e32 v52, 0, v10
	v_max_f32_e32 v53, 0, v11
	v_max_f32_e32 v10, 0, v12
	v_mul_f32_e32 v54, v50, v10
	s_nop 0
	v_max_f32_e32 v56, 0, v13
	v_mfma_f32_16x16x32_bf16 v[10:13], v[248:251], v[22:25], v[14:17]
	ds_read_b128 v[22:25], v178
	v_mov_b32_e32 v43, v44
	v_mov_b32_e32 v49, v45
	ds_read_b128 v[14:17], v177
	s_waitcnt lgkmcnt(0)
	v_mfma_f32_16x16x32_bf16 v[14:17], v[244:247], v[14:17], 0
	s_nop 1
	v_max_f32_e32 v138, 0, v10
	v_max_f32_e32 v139, 0, v11
	v_max_f32_e32 v10, 0, v12
	v_mul_f32_e32 v140, v51, v10
	s_nop 0
	v_max_f32_e32 v57, 0, v13
	v_mfma_f32_16x16x32_bf16 v[10:13], v[248:251], v[22:25], v[14:17]
	ds_read_b128 v[22:25], v186
	v_pk_mul_f32 v[56:57], v[50:51], v[56:57]
	s_nop 0
	ds_read_b128 v[14:17], v181
	s_waitcnt lgkmcnt(0)
	v_mfma_f32_16x16x32_bf16 v[6:9], v[244:247], v[14:17], 0
	s_nop 1
	s_nop 0
	v_max_f32_e32 v14, 0, v13
	s_nop 0
	v_mfma_f32_16x16x32_bf16 v[2:5], v[248:251], v[22:25], v[6:9]
	s_nop 0
	v_max_f32_e32 v10, 0, v10
	v_max_f32_e32 v11, 0, v11
	v_pk_fma_f32 v[8:9], v[30:31], v[32:33], 0 op_sel_hi:[0,1,0]
	s_nop 0
	s_nop 2
	v_max_f32_e32 v15, 0, v5
	v_pk_mul_f32 v[6:7], v[142:143], v[14:15]
	v_mov_b32_e32 v14, v31
	v_pk_fma_f32 v[8:9], v[14:15], v[26:27], v[8:9] op_sel_hi:[0,1,1]
	v_pk_fma_f32 v[8:9], v[38:39], v[40:41], v[8:9] op_sel_hi:[0,1,1]
	v_mov_b32_e32 v14, v39
	v_pk_fma_f32 v[8:9], v[14:15], v[46:47], v[8:9] op_sel_hi:[0,1,1]
	v_pk_fma_f32 v[8:9], v[50:51], v[52:53], v[8:9] op_sel_hi:[0,1,1]
	v_mov_b32_e32 v14, v51
	v_pk_fma_f32 v[8:9], v[14:15], v[138:139], v[8:9] op_sel_hi:[0,1,1]
	v_max_f32_e32 v2, 0, v2
	v_max_f32_e32 v3, 0, v3
	v_pk_fma_f32 v[8:9], v[142:143], v[10:11], v[8:9] op_sel_hi:[0,1,1]
	v_mov_b32_e32 v10, v143
	v_pk_fma_f32 v[2:3], v[10:11], v[2:3], v[8:9] op_sel_hi:[0,1,1]
	v_and_b32_e32 v9, 0x7fffffff, v3
	v_and_b32_e32 v8, 0x7fffffff, v2
	v_xor_b32_e32 v5, -1, v3
	v_pk_add_f32 v[8:9], v[8:9], 0 neg_lo:[1,1] neg_hi:[1,1]
	v_cmp_gt_i32_e32 vcc, 0, v3
	v_xor_b32_e32 v10, -1, v2
	v_mov_b32_e32 v55, v56
	v_cndmask_b32_e32 v138, v9, v5, vcc
	v_cmp_gt_i32_e32 vcc, 0, v2
	v_pk_add_f32 v[2:3], v[34:35], 0 op_sel_hi:[1,0]
	v_max_f32_e32 v12, 0, v12
	v_pk_add_f32 v[2:3], v[2:3], v[28:29]
	v_pk_add_f32 v[2:3], v[2:3], v[42:43]
	v_mov_b32_e32 v141, v57
	v_pk_add_f32 v[2:3], v[2:3], v[48:49]
	v_mul_f32_e32 v12, v142, v12
	v_pk_add_f32 v[2:3], v[2:3], v[54:55]
	v_max_f32_e32 v4, 0, v4
	v_pk_add_f32 v[2:3], v[2:3], v[140:141]
	v_mov_b32_e32 v13, v6
	v_mul_f32_e32 v4, v143, v4
	v_pk_add_f32 v[2:3], v[2:3], v[12:13]
	v_mov_b32_e32 v5, v7
	v_pk_add_f32 v[2:3], v[2:3], v[4:5]
	v_cndmask_b32_e32 v139, v8, v10, vcc
	v_and_b32_e32 v5, 0x7fffffff, v3
	v_and_b32_e32 v4, 0x7fffffff, v2
	v_xor_b32_e32 v6, -1, v3
	v_pk_add_f32 v[4:5], v[4:5], 0 neg_lo:[1,1] neg_hi:[1,1]
	v_cmp_gt_i32_e32 vcc, 0, v3
	v_xor_b32_e32 v7, -1, v2
	s_nop 0
	v_cndmask_b32_e32 v140, v5, v6, vcc
	v_cmp_gt_i32_e32 vcc, 0, v2
	v_lshrrev_b32_e32 v2, 24, v139
	v_lshl_add_u32 v2, v2, 6, v0
	ds_add_u32 v2, v205 offset:16384
	v_lshrrev_b32_e32 v2, 24, v138
	v_cndmask_b32_e32 v141, v4, v7, vcc
	v_lshl_add_u32 v2, v2, 6, v0
	ds_add_u32 v2, v205 offset:16384
	v_lshrrev_b32_e32 v2, 24, v141
	v_lshl_add_u32 v2, v2, 6, v0
	ds_add_u32 v2, v205 offset:16384
	v_lshrrev_b32_e32 v2, 24, v140
	v_lshl_add_u32 v2, v2, 6, v0
	ds_add_u32 v2, v205 offset:16384
.LBB0_666:
	s_cmp_gt_i32 s4, 5
	s_cselect_b64 s[48:49], -1, 0
	s_cmp_lt_i32 s4, 6
	s_cbranch_scc1 .LBB0_668
	s_add_i32 s0, s46, 40
	s_lshl_b32 s0, s0, 6
	s_ashr_i32 s1, s0, 31
	v_lshl_add_u64 v[2:3], v[18:19], 0, s[0:1]
	v_lshlrev_b64 v[2:3], 7, v[2:3]
	v_lshl_add_u64 v[22:23], v[20:21], 0, v[2:3]
	global_load_dwordx4 v[14:17], v[22:23], off
	global_load_dwordx4 v[10:13], v[22:23], off offset:64
	v_lshl_add_u32 v193, v182, 4, v150
	v_lshl_add_u32 v194, v183, 4, v150
	v_lshl_add_u32 v191, v185, 4, v150
	v_lshl_add_u32 v187, v180, 4, v150
	v_lshl_add_u32 v192, v159, 4, v150
	v_lshl_add_u32 v190, v184, 4, v150
	ds_read_b128 v[2:5], v193
	v_lshl_add_u32 v188, v179, 4, v150
	ds_read_b128 v[6:9], v194
	ds_read_b128 v[24:27], v190
	v_lshl_add_u32 v189, v176, 4, v150
	ds_read_b128 v[28:31], v191
	ds_read_b128 v[32:35], v188
	ds_read_b128 v[36:39], v187
	ds_read_b128 v[40:43], v189
	v_lshl_add_u32 v195, v158, 4, v150
	ds_read_b128 v[44:47], v192
	ds_read_b128 v[48:51], v195
	v_lshl_add_u32 v196, v157, 4, v150
	ds_read_b128 v[52:55], v196
	v_lshl_add_u32 v197, v156, 4, v150
	v_lshl_add_u32 v198, v155, 4, v150
	ds_read_b128 v[142:145], v197
	ds_read_b128 v[146:149], v198
	v_lshl_add_u32 v199, v154, 4, v150
	v_lshl_add_u32 v218, v153, 4, v150
	v_lshl_add_u32 v219, v152, 4, v150
	v_lshl_add_u32 v220, v151, 4, v150
	s_waitcnt vmcnt(1) lgkmcnt(11)
	v_mfma_f32_16x16x32_bf16 v[2:5], v[14:17], v[2:5], 0
	s_waitcnt lgkmcnt(9)
	v_mfma_f32_16x16x32_bf16 v[24:27], v[14:17], v[24:27], 0
	s_waitcnt lgkmcnt(7)
	v_mfma_f32_16x16x32_bf16 v[32:35], v[14:17], v[32:35], 0
	s_waitcnt lgkmcnt(5)
	v_mfma_f32_16x16x32_bf16 v[40:43], v[14:17], v[40:43], 0
	s_waitcnt lgkmcnt(3)
	v_mfma_f32_16x16x32_bf16 v[48:51], v[14:17], v[48:51], 0
	s_waitcnt vmcnt(0)
; #define LAS __attribute__((address_space(3)))
; __device__ __forceinline__ unsigned fkey(float f) { const unsigned u = __float_as_uint(f); return (u & 0x80000000u) ? ~u : (u | 0x80000000u); }
; #define SEL_HADD(idx_) __hip_atomic_fetch_add(&hist[(idx_)], 1u, __ATOMIC_RELAXED, __HIP_MEMORY_SCOPE_WORKGROUP)
; __device__ __forceinline__ void sel_unit(LAS char* lds, int b, int u, const bf16_t* QI, const bf16_t* KIDX, const float* WIDX, unsigned long long* MASK) {
;     ...
;     for (int j = 0; j < 8; ++j) {
;         if (j < nj) {
;             int t = wid + 8 * j; asm volatile("" : "+s"(t));
; #pragma unroll
;             for (int kh = 0; kh < 2; ++kh) {
;             bf16x8 kf[2][2];
; #pragma unroll
;             for (int kb = 0; kb < 2; ++kb)
; #pragma unroll
;                 for (int ks = 0; ks < 2; ++ks) kf[kb][ks] = *(const bf16x8*)(KIDX + (rowbase + 64 * t + 32 * kh + 16 * kb + q16) * 64 + 32 * ks + 8 * kg);
; #pragma unroll
;             for (int kb = 0; kb < 2; ++kb) {
;                 f32x4 s = (f32x4){0.f, 0.f, 0.f, 0.f};
; #pragma unroll
;                 for (int hh = 0; hh < 8; ++hh) {
;                     f32x4 a = (f32x4){0.f, 0.f, 0.f, 0.f};
; #pragma unroll
;                     for (int ks = 0; ks < 2; ++ks) {
;                         const bf16x8 qv = *(const LAS bf16x8*)(lds + L_QI + q16 * 1024 + (((hh * 8 + 4 * ks + kg) ^ q16) << 4));
;                         a = __builtin_amdgcn_mfma_f32_16x16x32_bf16(kf[kb][ks], qv, a, 0, 0, 0);
;                     }
;                     const float wh = wl[hh * 16];
; #pragma unroll
;                     for (int i = 0; i < 4; ++i) s[i] += wh * fmaxf(a[i], 0.f);
;                 }
;                 u32x4 kk; kk.x = fkey(s[0]); kk.y = fkey(s[1]); kk.z = fkey(s[2]); kk.w = fkey(s[3]);
;                 sc[j][2 * kh + kb] = kk;
; #pragma unroll
;                 for (int i = 0; i < 4; ++i) SEL_HADD((kk[i] >> 24) * 16 + q16);
;                 __builtin_amdgcn_sched_barrier(0);
	v_mfma_f32_16x16x32_bf16 v[160:163], v[10:13], v[6:9], v[2:5]
	v_mfma_f32_16x16x32_bf16 v[24:27], v[10:13], v[28:31], v[24:27]
	v_mfma_f32_16x16x32_bf16 v[28:31], v[10:13], v[36:39], v[32:35]
	v_mfma_f32_16x16x32_bf16 v[32:35], v[10:13], v[44:47], v[40:43]
	ds_read2_b32 v[44:45], v137 offset0:80 offset1:96
	ds_read2_b32 v[46:47], v137 offset0:112 offset1:128
	s_nop 3
	s_waitcnt lgkmcnt(4)
	v_mfma_f32_16x16x32_bf16 v[36:39], v[10:13], v[52:55], v[48:51]
	ds_read2_b32 v[48:49], v137 offset0:144 offset1:160
	global_load_dwordx4 v[6:9], v[22:23], off offset:2048
	global_load_dwordx4 v[2:5], v[22:23], off offset:2112
	v_mov_b32_e32 v252, 0x1000
	v_mov_b32_e32 v253, 0
	v_lshl_add_u64 v[252:253], v[252:253], 0, v[22:23]
	global_load_dwordx4 v[236:239], v[252:253], off
	global_load_dwordx4 v[240:243], v[252:253], off offset:64
	global_load_dwordx4 v[244:247], v[252:253], off offset:2048
	global_load_dwordx4 v[248:251], v[252:253], off offset:2112
	s_waitcnt lgkmcnt(4)
	v_mfma_f32_16x16x32_bf16 v[142:145], v[14:17], v[142:145], 0
	s_nop 0
	s_nop 0
	v_max_f32_e32 v54, v24, v24
	s_waitcnt lgkmcnt(3)
	v_mfma_f32_16x16x32_bf16 v[40:43], v[10:13], v[146:149], v[142:145]
	s_nop 0
	s_nop 0
	v_max_f32_e32 v24, 0, v163
	v_max_f32_e32 v142, v39, v39
	v_max_f32_e32 v39, 0, v25
	s_nop 2
	v_max_f32_e32 v145, 0, v26
	v_max_f32_e32 v25, 0, v27
	v_max_f32_e32 v26, 0, v31
	v_max_f32_e32 v27, 0, v35
	v_max_f32_e32 v50, v160, v160
	v_max_f32_e32 v51, v161, v161
	v_max_f32_e32 v147, v42, v42
	v_max_f32_e32 v42, 0, v162
	v_max_f32_e32 v52, 0, v36
	v_max_f32_e32 v53, 0, v37
	v_max_f32_e32 v55, 0, v41
	s_waitcnt lgkmcnt(2)
	v_mul_f32_e32 v56, v45, v145
	v_pk_mul_f32 v[144:145], v[44:45], v[24:25]
	s_waitcnt lgkmcnt(1)
	v_pk_mul_f32 v[160:161], v[46:47], v[26:27]
	ds_read_b128 v[24:27], v199
	v_max_f32_e32 v143, v40, v40
	v_max_f32_e32 v40, 0, v28
	v_max_f32_e32 v28, 0, v30
	v_max_f32_e32 v41, 0, v29
	v_max_f32_e32 v29, 0, v34
	v_max_f32_e32 v30, 0, v38
	v_mul_f32_e32 v146, v46, v28
	v_max_f32_e32 v28, 0, v147
	v_mul_f32_e32 v148, v47, v29
	s_waitcnt lgkmcnt(1)
	v_mul_f32_e32 v162, v48, v30
	v_mul_f32_e32 v164, v49, v28
	ds_read_b128 v[28:31], v218
	s_waitcnt lgkmcnt(1)
	v_mfma_f32_16x16x32_bf16 v[24:27], v[14:17], v[24:27], 0
	v_max_f32_e32 v37, 0, v51
	s_waitcnt lgkmcnt(0)
	v_mfma_f32_16x16x32_bf16 v[24:27], v[10:13], v[28:31], v[24:27]
	ds_read_b128 v[28:31], v219
	v_max_f32_e32 v51, 0, v33
	v_max_f32_e32 v36, 0, v50
	v_max_f32_e32 v50, 0, v32
	v_max_f32_e32 v32, 0, v142
	v_max_f32_e32 v33, 0, v43
	v_pk_mul_f32 v[166:167], v[48:49], v[32:33]
	ds_read_b128 v[32:35], v220
	s_waitcnt lgkmcnt(1)
	v_mfma_f32_16x16x32_bf16 v[14:17], v[14:17], v[28:31], 0
	v_max_f32_e32 v38, 0, v54
	v_max_f32_e32 v54, 0, v143
	ds_read2_b32 v[142:143], v137 offset0:176 offset1:192
	s_waitcnt lgkmcnt(1)
	v_mfma_f32_16x16x32_bf16 v[10:13], v[10:13], v[32:35], v[14:17]
	s_nop 0
	v_max_f32_e32 v28, 0, v27
	s_nop 0
	v_pk_fma_f32 v[16:17], v[44:45], v[36:37], 0 op_sel_hi:[0,1,0]
	s_nop 0
	s_nop 2
	v_max_f32_e32 v29, 0, v13
	s_waitcnt lgkmcnt(0)
	v_pk_mul_f32 v[14:15], v[142:143], v[28:29]
	v_mov_b32_e32 v28, v45
	v_pk_fma_f32 v[16:17], v[28:29], v[38:39], v[16:17] op_sel_hi:[0,1,1]
	v_pk_fma_f32 v[16:17], v[46:47], v[40:41], v[16:17] op_sel_hi:[0,1,1]
	v_mov_b32_e32 v28, v47
	v_pk_fma_f32 v[16:17], v[28:29], v[50:51], v[16:17] op_sel_hi:[0,1,1]
	v_pk_fma_f32 v[16:17], v[48:49], v[52:53], v[16:17] op_sel_hi:[0,1,1]
	v_mov_b32_e32 v28, v49
	v_max_f32_e32 v24, 0, v24
	v_max_f32_e32 v25, 0, v25
	v_pk_fma_f32 v[16:17], v[28:29], v[54:55], v[16:17] op_sel_hi:[0,1,1]
	v_max_f32_e32 v10, 0, v10
	v_max_f32_e32 v11, 0, v11
	v_pk_fma_f32 v[16:17], v[142:143], v[24:25], v[16:17] op_sel_hi:[0,1,1]
	v_mov_b32_e32 v24, v143
	v_pk_fma_f32 v[10:11], v[24:25], v[10:11], v[16:17] op_sel_hi:[0,1,1]
	v_and_b32_e32 v17, 0x7fffffff, v11
	v_and_b32_e32 v16, 0x7fffffff, v10
	v_mul_f32_e32 v42, v44, v42
	v_max_f32_e32 v26, 0, v26
	v_xor_b32_e32 v13, -1, v11
	v_pk_add_f32 v[16:17], v[16:17], 0 neg_lo:[1,1] neg_hi:[1,1]
	v_cmp_gt_i32_e32 vcc, 0, v11
	v_mov_b32_e32 v43, v144
	v_mul_f32_e32 v26, v142, v26
	v_xor_b32_e32 v24, -1, v10
	v_cndmask_b32_e32 v142, v17, v13, vcc
	v_cmp_gt_i32_e32 vcc, 0, v10
	v_pk_add_f32 v[10:11], v[42:43], 0 op_sel_hi:[1,0]
	v_mov_b32_e32 v57, v145
	v_pk_add_f32 v[10:11], v[10:11], v[56:57]
	v_mov_b32_e32 v147, v160
	v_pk_add_f32 v[10:11], v[10:11], v[146:147]
	v_mov_b32_e32 v149, v161
	v_pk_add_f32 v[10:11], v[10:11], v[148:149]
	v_mov_b32_e32 v163, v166
	v_pk_add_f32 v[10:11], v[10:11], v[162:163]
	v_mov_b32_e32 v165, v167
	v_max_f32_e32 v12, 0, v12
	v_pk_add_f32 v[10:11], v[10:11], v[164:165]
	v_mov_b32_e32 v27, v14
	v_mul_f32_e32 v12, v143, v12
	v_pk_add_f32 v[10:11], v[10:11], v[26:27]
	v_mov_b32_e32 v13, v15
	v_pk_add_f32 v[10:11], v[10:11], v[12:13]
	v_cndmask_b32_e32 v143, v16, v24, vcc
	v_and_b32_e32 v13, 0x7fffffff, v11
	v_and_b32_e32 v12, 0x7fffffff, v10
	v_xor_b32_e32 v14, -1, v11
	v_pk_add_f32 v[12:13], v[12:13], 0 neg_lo:[1,1] neg_hi:[1,1]
	v_cmp_gt_i32_e32 vcc, 0, v11
	v_xor_b32_e32 v15, -1, v10
	s_nop 0
	v_cndmask_b32_e32 v144, v13, v14, vcc
	v_cmp_gt_i32_e32 vcc, 0, v10
	v_lshrrev_b32_e32 v10, 24, v143
	v_lshl_add_u32 v10, v10, 6, v0
	ds_add_u32 v10, v205 offset:16384
	v_lshrrev_b32_e32 v10, 24, v142
	v_cndmask_b32_e32 v145, v12, v15, vcc
	v_lshl_add_u32 v10, v10, 6, v0
	ds_add_u32 v10, v205 offset:16384
	v_lshrrev_b32_e32 v10, 24, v145
	v_lshl_add_u32 v10, v10, 6, v0
	ds_add_u32 v10, v205 offset:16384
	v_lshrrev_b32_e32 v10, 24, v144
	v_lshl_add_u32 v10, v10, 6, v0
	ds_add_u32 v10, v205 offset:16384
	ds_read_b128 v[10:13], v193
	ds_read_b128 v[14:17], v194
	ds_read_b128 v[24:27], v190
	ds_read_b128 v[28:31], v191
	ds_read2_b32 v[32:33], v137 offset0:80 offset1:96
	ds_read2_b32 v[40:41], v137 offset0:112 offset1:128
	s_waitcnt vmcnt(5) lgkmcnt(5)
; #define LAS __attribute__((address_space(3)))
; __device__ __forceinline__ unsigned fkey(float f) { const unsigned u = __float_as_uint(f); return (u & 0x80000000u) ? ~u : (u | 0x80000000u); }
; #define SEL_HADD(idx_) __hip_atomic_fetch_add(&hist[(idx_)], 1u, __ATOMIC_RELAXED, __HIP_MEMORY_SCOPE_WORKGROUP)
; __device__ __forceinline__ void sel_unit(LAS char* lds, int b, int u, const bf16_t* QI, const bf16_t* KIDX, const float* WIDX, unsigned long long* MASK) {
;     ...
;     for (int j = 0; j < 8; ++j) {
;         if (j < nj) {
;             int t = wid + 8 * j; asm volatile("" : "+s"(t));
; #pragma unroll
;             for (int kh = 0; kh < 2; ++kh) {
;             bf16x8 kf[2][2];
; #pragma unroll
;             for (int kb = 0; kb < 2; ++kb)
; #pragma unroll
;                 for (int ks = 0; ks < 2; ++ks) kf[kb][ks] = *(const bf16x8*)(KIDX + (rowbase + 64 * t + 32 * kh + 16 * kb + q16) * 64 + 32 * ks + 8 * kg);
; #pragma unroll
;             for (int kb = 0; kb < 2; ++kb) {
;                 f32x4 s = (f32x4){0.f, 0.f, 0.f, 0.f};
; #pragma unroll
;                 for (int hh = 0; hh < 8; ++hh) {
;                     f32x4 a = (f32x4){0.f, 0.f, 0.f, 0.f};
; #pragma unroll
;                     for (int ks = 0; ks < 2; ++ks) {
;                         const bf16x8 qv = *(const LAS bf16x8*)(lds + L_QI + q16 * 1024 + (((hh * 8 + 4 * ks + kg) ^ q16) << 4));
;                         a = __builtin_amdgcn_mfma_f32_16x16x32_bf16(kf[kb][ks], qv, a, 0, 0, 0);
;                     }
;                     const float wh = wl[hh * 16];
; #pragma unroll
;                     for (int i = 0; i < 4; ++i) s[i] += wh * fmaxf(a[i], 0.f);
;                 }
;                 u32x4 kk; kk.x = fkey(s[0]); kk.y = fkey(s[1]); kk.z = fkey(s[2]); kk.w = fkey(s[3]);
;                 sc[j][2 * kh + kb] = kk;
; #pragma unroll
;                 for (int i = 0; i < 4; ++i) SEL_HADD((kk[i] >> 24) * 16 + q16);
;                 __builtin_amdgcn_sched_barrier(0);
	v_mfma_f32_16x16x32_bf16 v[10:13], v[6:9], v[10:13], 0
	ds_read2_b32 v[52:53], v137 offset0:144 offset1:160
	s_waitcnt vmcnt(4) lgkmcnt(5)
	v_mfma_f32_16x16x32_bf16 v[10:13], v[2:5], v[14:17], v[10:13]
	ds_read_b128 v[14:17], v188
	s_waitcnt lgkmcnt(5)
	v_mfma_f32_16x16x32_bf16 v[24:27], v[6:9], v[24:27], 0
	s_nop 4
	v_max_f32_e32 v34, 0, v10
	v_max_f32_e32 v10, 0, v12
	v_max_f32_e32 v35, 0, v11
	s_waitcnt lgkmcnt(3)
	v_mul_f32_e32 v36, v32, v10
	v_max_f32_e32 v38, 0, v13
	v_mfma_f32_16x16x32_bf16 v[10:13], v[2:5], v[28:31], v[24:27]
	s_nop 2
	ds_read_b128 v[24:27], v187
	s_waitcnt lgkmcnt(1)
	v_mfma_f32_16x16x32_bf16 v[14:17], v[6:9], v[14:17], 0
	s_nop 1
	v_max_f32_e32 v28, 0, v10
	v_max_f32_e32 v29, 0, v11
	v_max_f32_e32 v10, 0, v12
	v_mul_f32_e32 v30, v33, v10
	v_max_f32_e32 v39, 0, v13
	s_waitcnt lgkmcnt(0)
	v_mfma_f32_16x16x32_bf16 v[10:13], v[2:5], v[24:27], v[14:17]
	ds_read_b128 v[24:27], v192
	v_pk_mul_f32 v[38:39], v[32:33], v[38:39]
	s_nop 0
	ds_read_b128 v[14:17], v189
	s_waitcnt lgkmcnt(0)
	v_mfma_f32_16x16x32_bf16 v[14:17], v[6:9], v[14:17], 0
	s_nop 1
	v_max_f32_e32 v42, 0, v10
	v_max_f32_e32 v43, 0, v11
	v_max_f32_e32 v10, 0, v12
	v_mul_f32_e32 v44, v40, v10
	s_nop 0
	v_max_f32_e32 v46, 0, v13
	v_mfma_f32_16x16x32_bf16 v[10:13], v[2:5], v[24:27], v[14:17]
	ds_read_b128 v[24:27], v196
	v_mov_b32_e32 v37, v38
	v_mov_b32_e32 v31, v39
	ds_read_b128 v[14:17], v195
	s_waitcnt lgkmcnt(0)
	v_mfma_f32_16x16x32_bf16 v[14:17], v[6:9], v[14:17], 0
	s_nop 1
	v_max_f32_e32 v48, 0, v10
	v_max_f32_e32 v49, 0, v11
	v_max_f32_e32 v10, 0, v12
	v_mul_f32_e32 v50, v41, v10
	s_nop 0
	v_max_f32_e32 v47, 0, v13
	v_mfma_f32_16x16x32_bf16 v[10:13], v[2:5], v[24:27], v[14:17]
	ds_read_b128 v[24:27], v198
	v_pk_mul_f32 v[46:47], v[40:41], v[46:47]
	s_nop 0
	ds_read_b128 v[14:17], v197
	s_waitcnt lgkmcnt(0)
	v_mfma_f32_16x16x32_bf16 v[14:17], v[6:9], v[14:17], 0
	s_nop 1
	v_max_f32_e32 v54, 0, v10
	v_max_f32_e32 v55, 0, v11
	v_max_f32_e32 v10, 0, v12
	v_mul_f32_e32 v56, v52, v10
	s_nop 0
	v_max_f32_e32 v146, 0, v13
	v_mfma_f32_16x16x32_bf16 v[10:13], v[2:5], v[24:27], v[14:17]
	ds_read_b128 v[24:27], v218
	v_mov_b32_e32 v45, v46
	v_mov_b32_e32 v51, v47
	ds_read_b128 v[14:17], v199
	s_waitcnt lgkmcnt(0)
	v_mfma_f32_16x16x32_bf16 v[14:17], v[6:9], v[14:17], 0
	s_nop 1
	v_max_f32_e32 v148, 0, v10
	v_max_f32_e32 v149, 0, v11
	v_max_f32_e32 v10, 0, v12
	v_mul_f32_e32 v160, v53, v10
	s_nop 0
	v_max_f32_e32 v147, 0, v13
	v_mfma_f32_16x16x32_bf16 v[10:13], v[2:5], v[24:27], v[14:17]
	ds_read_b128 v[24:27], v220
	v_pk_mul_f32 v[162:163], v[52:53], v[146:147]
	ds_read2_b32 v[146:147], v137 offset0:176 offset1:192
	ds_read_b128 v[14:17], v219
	s_waitcnt lgkmcnt(0)
	v_mfma_f32_16x16x32_bf16 v[6:9], v[6:9], v[14:17], 0
	s_nop 1
	s_nop 0
	v_max_f32_e32 v14, 0, v13
	s_nop 0
	v_mfma_f32_16x16x32_bf16 v[2:5], v[2:5], v[24:27], v[6:9]
	s_nop 0
	v_max_f32_e32 v10, 0, v10
	v_max_f32_e32 v11, 0, v11
	v_pk_fma_f32 v[8:9], v[32:33], v[34:35], 0 op_sel_hi:[0,1,0]
	s_nop 0
	s_nop 2
	v_max_f32_e32 v15, 0, v5
	v_pk_mul_f32 v[6:7], v[146:147], v[14:15]
	v_mov_b32_e32 v14, v33
	v_pk_fma_f32 v[8:9], v[14:15], v[28:29], v[8:9] op_sel_hi:[0,1,1]
	v_pk_fma_f32 v[8:9], v[40:41], v[42:43], v[8:9] op_sel_hi:[0,1,1]
	v_mov_b32_e32 v14, v41
	v_pk_fma_f32 v[8:9], v[14:15], v[48:49], v[8:9] op_sel_hi:[0,1,1]
	v_pk_fma_f32 v[8:9], v[52:53], v[54:55], v[8:9] op_sel_hi:[0,1,1]
	v_mov_b32_e32 v14, v53
	v_pk_fma_f32 v[8:9], v[14:15], v[148:149], v[8:9] op_sel_hi:[0,1,1]
	v_max_f32_e32 v2, 0, v2
	v_max_f32_e32 v3, 0, v3
	v_pk_fma_f32 v[8:9], v[146:147], v[10:11], v[8:9] op_sel_hi:[0,1,1]
	v_mov_b32_e32 v10, v147
	v_pk_fma_f32 v[2:3], v[10:11], v[2:3], v[8:9] op_sel_hi:[0,1,1]
	v_and_b32_e32 v9, 0x7fffffff, v3
	v_and_b32_e32 v8, 0x7fffffff, v2
	v_max_f32_e32 v12, 0, v12
	v_xor_b32_e32 v5, -1, v3
	v_pk_add_f32 v[8:9], v[8:9], 0 neg_lo:[1,1] neg_hi:[1,1]
	v_cmp_gt_i32_e32 vcc, 0, v3
	v_mul_f32_e32 v12, v146, v12
	v_xor_b32_e32 v10, -1, v2
	v_cndmask_b32_e32 v146, v9, v5, vcc
	v_cmp_gt_i32_e32 vcc, 0, v2
	v_pk_add_f32 v[2:3], v[36:37], 0 op_sel_hi:[1,0]
	v_mov_b32_e32 v57, v162
	v_pk_add_f32 v[2:3], v[2:3], v[30:31]
	v_pk_add_f32 v[2:3], v[2:3], v[44:45]
	v_mov_b32_e32 v161, v163
	v_pk_add_f32 v[2:3], v[2:3], v[50:51]
	v_max_f32_e32 v4, 0, v4
	v_pk_add_f32 v[2:3], v[2:3], v[56:57]
	v_mov_b32_e32 v13, v6
	v_pk_add_f32 v[2:3], v[2:3], v[160:161]
	v_mul_f32_e32 v4, v147, v4
	v_pk_add_f32 v[2:3], v[2:3], v[12:13]
	v_mov_b32_e32 v5, v7
	v_pk_add_f32 v[2:3], v[2:3], v[4:5]
	v_cndmask_b32_e32 v147, v8, v10, vcc
	v_and_b32_e32 v5, 0x7fffffff, v3
	v_and_b32_e32 v4, 0x7fffffff, v2
	v_xor_b32_e32 v6, -1, v3
	v_pk_add_f32 v[4:5], v[4:5], 0 neg_lo:[1,1] neg_hi:[1,1]
	v_cmp_gt_i32_e32 vcc, 0, v3
	v_xor_b32_e32 v7, -1, v2
	s_nop 0
	v_cndmask_b32_e32 v148, v5, v6, vcc
	v_cmp_gt_i32_e32 vcc, 0, v2
	v_lshrrev_b32_e32 v2, 24, v147
	v_lshl_add_u32 v2, v2, 6, v0
	ds_add_u32 v2, v205 offset:16384
	v_lshrrev_b32_e32 v2, 24, v146
	v_cndmask_b32_e32 v149, v4, v7, vcc
	v_lshl_add_u32 v2, v2, 6, v0
	ds_add_u32 v2, v205 offset:16384
	v_lshrrev_b32_e32 v2, 24, v149
	v_lshl_add_u32 v2, v2, 6, v0
	ds_add_u32 v2, v205 offset:16384
	v_lshrrev_b32_e32 v2, 24, v148
	v_lshl_add_u32 v2, v2, 6, v0
	ds_add_u32 v2, v205 offset:16384
	ds_read_b128 v[22:25], v193
	ds_read_b128 v[26:29], v194
	s_waitcnt vmcnt(3) lgkmcnt(1)
	v_mfma_f32_16x16x32_bf16 v[22:25], v[236:239], v[22:25], 0
	ds_read_b128 v[32:35], v191
	ds_read_b128 v[38:41], v187
	ds_read_b128 v[44:47], v192
	s_waitcnt vmcnt(2) lgkmcnt(3)
; #define LAS __attribute__((address_space(3)))
; __device__ __forceinline__ unsigned fkey(float f) { const unsigned u = __float_as_uint(f); return (u & 0x80000000u) ? ~u : (u | 0x80000000u); }
; #define SEL_HADD(idx_) __hip_atomic_fetch_add(&hist[(idx_)], 1u, __ATOMIC_RELAXED, __HIP_MEMORY_SCOPE_WORKGROUP)
; __device__ __forceinline__ void sel_unit(LAS char* lds, int b, int u, const bf16_t* QI, const bf16_t* KIDX, const float* WIDX, unsigned long long* MASK) {
;     ...
;     for (int j = 0; j < 8; ++j) {
;         if (j < nj) {
;             int t = wid + 8 * j; asm volatile("" : "+s"(t));
; #pragma unroll
;             for (int kh = 0; kh < 2; ++kh) {
;             bf16x8 kf[2][2];
; #pragma unroll
;             for (int kb = 0; kb < 2; ++kb)
; #pragma unroll
;                 for (int ks = 0; ks < 2; ++ks) kf[kb][ks] = *(const bf16x8*)(KIDX + (rowbase + 64 * t + 32 * kh + 16 * kb + q16) * 64 + 32 * ks + 8 * kg);
; #pragma unroll
;             for (int kb = 0; kb < 2; ++kb) {
;                 f32x4 s = (f32x4){0.f, 0.f, 0.f, 0.f};
; #pragma unroll
;                 for (int hh = 0; hh < 8; ++hh) {
;                     f32x4 a = (f32x4){0.f, 0.f, 0.f, 0.f};
; #pragma unroll
;                     for (int ks = 0; ks < 2; ++ks) {
;                         const bf16x8 qv = *(const LAS bf16x8*)(lds + L_QI + q16 * 1024 + (((hh * 8 + 4 * ks + kg) ^ q16) << 4));
;                         a = __builtin_amdgcn_mfma_f32_16x16x32_bf16(kf[kb][ks], qv, a, 0, 0, 0);
;                     }
;                     const float wh = wl[hh * 16];
; #pragma unroll
;                     for (int i = 0; i < 4; ++i) s[i] += wh * fmaxf(a[i], 0.f);
;                 }
;                 u32x4 kk; kk.x = fkey(s[0]); kk.y = fkey(s[1]); kk.z = fkey(s[2]); kk.w = fkey(s[3]);
;                 sc[j][2 * kh + kb] = kk;
; #pragma unroll
;                 for (int i = 0; i < 4; ++i) SEL_HADD((kk[i] >> 24) * 16 + q16);
;                 __builtin_amdgcn_sched_barrier(0);
	v_mfma_f32_16x16x32_bf16 v[26:29], v[240:243], v[26:29], v[22:25]
	ds_read_b128 v[50:53], v196
	ds_read_b128 v[160:163], v198
	s_nop 0
	ds_read2_b32 v[24:25], v137 offset0:80 offset1:96
	s_nop 3
	v_max_f32_e32 v26, 0, v26
	v_max_f32_e32 v27, 0, v27
	v_max_f32_e32 v22, v28, v28
	v_max_f32_e32 v23, v29, v29
	ds_read_b128 v[28:31], v190
	s_waitcnt lgkmcnt(0)
	v_mfma_f32_16x16x32_bf16 v[28:31], v[236:239], v[28:31], 0
	v_max_f32_e32 v36, 0, v23
	v_max_f32_e32 v22, 0, v22
	v_mul_f32_e32 v22, v24, v22
	v_mfma_f32_16x16x32_bf16 v[28:31], v[240:243], v[32:35], v[28:31]
	s_nop 7
	v_max_f32_e32 v32, 0, v28
	v_max_f32_e32 v33, 0, v29
	v_max_f32_e32 v23, 0, v30
	v_mul_f32_e32 v28, v25, v23
	v_max_f32_e32 v37, 0, v31
	v_pk_mul_f32 v[30:31], v[24:25], v[36:37]
	ds_read_b128 v[34:37], v188
	s_waitcnt lgkmcnt(0)
	v_mfma_f32_16x16x32_bf16 v[34:37], v[236:239], v[34:37], 0
	v_mov_b32_e32 v29, v31
	v_mfma_f32_16x16x32_bf16 v[38:41], v[240:243], v[38:41], v[34:37]
	s_nop 5
	ds_read2_b32 v[36:37], v137 offset0:112 offset1:128
	s_nop 0
	v_max_f32_e32 v38, 0, v38
	v_max_f32_e32 v39, 0, v39
	v_max_f32_e32 v23, 0, v40
	s_waitcnt lgkmcnt(0)
	v_mul_f32_e32 v34, v36, v23
	v_max_f32_e32 v23, v41, v41
	ds_read_b128 v[40:43], v189
	s_waitcnt lgkmcnt(0)
	v_mfma_f32_16x16x32_bf16 v[40:43], v[236:239], v[40:43], 0
	v_max_f32_e32 v48, 0, v23
	v_mfma_f32_16x16x32_bf16 v[40:43], v[240:243], v[44:47], v[40:43]
	s_nop 7
	v_max_f32_e32 v44, 0, v40
	v_max_f32_e32 v45, 0, v41
	v_max_f32_e32 v23, 0, v42
	v_mul_f32_e32 v40, v37, v23
	v_max_f32_e32 v49, 0, v43
	v_pk_mul_f32 v[42:43], v[36:37], v[48:49]
	ds_read_b128 v[46:49], v195
	s_waitcnt lgkmcnt(0)
	v_mfma_f32_16x16x32_bf16 v[46:49], v[236:239], v[46:49], 0
	v_mov_b32_e32 v35, v42
	v_mov_b32_e32 v41, v43
	v_mfma_f32_16x16x32_bf16 v[50:53], v[240:243], v[50:53], v[46:49]
	s_nop 4
	ds_read2_b32 v[48:49], v137 offset0:144 offset1:160
	s_nop 1
	v_max_f32_e32 v50, 0, v50
	v_max_f32_e32 v51, 0, v51
	v_max_f32_e32 v23, 0, v52
	s_waitcnt lgkmcnt(0)
	v_mul_f32_e32 v46, v48, v23
	v_max_f32_e32 v23, v53, v53
	ds_read_b128 v[52:55], v197
	s_waitcnt lgkmcnt(0)
	v_mfma_f32_16x16x32_bf16 v[52:55], v[236:239], v[52:55], 0
	v_max_f32_e32 v164, 0, v23
	v_mfma_f32_16x16x32_bf16 v[52:55], v[240:243], v[160:163], v[52:55]
	ds_read_b128 v[160:163], v199
	s_nop 6
	v_max_f32_e32 v56, 0, v52
	v_max_f32_e32 v57, 0, v53
	v_max_f32_e32 v23, 0, v54
	v_mul_f32_e32 v52, v49, v23
	v_max_f32_e32 v165, 0, v55
	v_pk_mul_f32 v[54:55], v[48:49], v[164:165]
	ds_read_b128 v[164:167], v218
	s_waitcnt lgkmcnt(1)
	v_mfma_f32_16x16x32_bf16 v[160:163], v[236:239], v[160:163], 0
	v_mov_b32_e32 v47, v54
	v_mov_b32_e32 v53, v55
	s_waitcnt lgkmcnt(0)
	v_mfma_f32_16x16x32_bf16 v[160:163], v[240:243], v[164:167], v[160:163]
	ds_read2_b32 v[164:165], v137 offset0:176 offset1:192
	s_nop 6
	v_max_f32_e32 v166, 0, v160
	v_max_f32_e32 v167, 0, v161
	v_max_f32_e32 v23, 0, v162
	s_waitcnt lgkmcnt(0)
	v_mul_f32_e32 v168, v164, v23
	v_max_f32_e32 v23, v163, v163
	ds_read_b128 v[160:163], v219
	s_waitcnt lgkmcnt(0)
	v_mfma_f32_16x16x32_bf16 v[14:17], v[236:239], v[160:163], 0
	ds_read_b128 v[160:163], v220
	v_max_f32_e32 v170, 0, v23
	s_waitcnt lgkmcnt(0)
	v_mfma_f32_16x16x32_bf16 v[10:13], v[240:243], v[160:163], v[14:17]
	s_nop 3
	v_fma_f32 v16, v24, v26, 0
	v_fma_f32 v17, v24, v27, 0
	v_mov_b32_e32 v24, v25
	v_pk_fma_f32 v[16:17], v[24:25], v[32:33], v[16:17] op_sel_hi:[0,1,1]
	v_pk_fma_f32 v[16:17], v[36:37], v[38:39], v[16:17] op_sel_hi:[0,1,1]
	v_mov_b32_e32 v24, v37
	v_pk_fma_f32 v[16:17], v[24:25], v[44:45], v[16:17] op_sel_hi:[0,1,1]
	v_pk_fma_f32 v[16:17], v[48:49], v[50:51], v[16:17] op_sel_hi:[0,1,1]
	v_mov_b32_e32 v24, v49
	v_pk_fma_f32 v[16:17], v[24:25], v[56:57], v[16:17] op_sel_hi:[0,1,1]
	v_max_f32_e32 v10, 0, v10
	v_max_f32_e32 v11, 0, v11
	v_pk_fma_f32 v[16:17], v[164:165], v[166:167], v[16:17] op_sel_hi:[0,1,1]
	v_mov_b32_e32 v24, v165
	v_pk_fma_f32 v[10:11], v[24:25], v[10:11], v[16:17] op_sel_hi:[0,1,1]
	v_and_b32_e32 v17, 0x7fffffff, v11
	v_and_b32_e32 v16, 0x7fffffff, v10
	v_xor_b32_e32 v23, -1, v10
	v_pk_add_f32 v[16:17], v[16:17], 0 neg_lo:[1,1] neg_hi:[1,1]
	v_cmp_gt_i32_e32 vcc, 0, v10
	v_max_f32_e32 v171, 0, v13
	s_nop 0
	v_cndmask_b32_e32 v178, v16, v23, vcc
	v_mov_b32_e32 v23, v30
	v_xor_b32_e32 v13, -1, v11
	v_cmp_gt_i32_e64 s[2:3], 0, v11
	v_pk_add_f32 v[10:11], v[22:23], 0 op_sel_hi:[1,0]
	v_pk_add_f32 v[10:11], v[10:11], v[28:29]
	v_pk_mul_f32 v[14:15], v[164:165], v[170:171]
	v_pk_add_f32 v[10:11], v[10:11], v[34:35]
	v_max_f32_e32 v12, 0, v12
	v_pk_add_f32 v[10:11], v[10:11], v[40:41]
	v_mov_b32_e32 v169, v14
	v_pk_add_f32 v[10:11], v[10:11], v[46:47]
	v_mul_f32_e32 v12, v165, v12
	v_pk_add_f32 v[10:11], v[10:11], v[52:53]
	v_cndmask_b32_e64 v177, v17, v13, s[2:3]
	v_pk_add_f32 v[10:11], v[10:11], v[168:169]
	v_mov_b32_e32 v13, v15
	v_pk_add_f32 v[10:11], v[10:11], v[12:13]
	s_nop 0
	v_xor_b32_e32 v15, -1, v10
	v_and_b32_e32 v12, 0x7fffffff, v10
	v_cmp_gt_i32_e32 vcc, 0, v10
	v_lshrrev_b32_e32 v10, 24, v178
	v_and_b32_e32 v13, 0x7fffffff, v11
	v_lshl_add_u32 v10, v10, 6, v0
	v_pk_add_f32 v[12:13], v[12:13], 0 neg_lo:[1,1] neg_hi:[1,1]
	ds_add_u32 v10, v205 offset:16384
	v_lshrrev_b32_e32 v10, 24, v177
	v_cndmask_b32_e32 v186, v12, v15, vcc
	v_lshl_add_u32 v10, v10, 6, v0
	v_xor_b32_e32 v14, -1, v11
	v_cmp_gt_i32_e64 s[2:3], 0, v11
	ds_add_u32 v10, v205 offset:16384
	v_lshrrev_b32_e32 v10, 24, v186
	v_cndmask_b32_e64 v181, v13, v14, s[2:3]
	v_lshl_add_u32 v10, v10, 6, v0
	ds_add_u32 v10, v205 offset:16384
	v_lshrrev_b32_e32 v10, 24, v181
	v_lshl_add_u32 v10, v10, 6, v0
	ds_add_u32 v10, v205 offset:16384
	ds_read_b128 v[10:13], v193
	ds_read_b128 v[14:17], v194
	ds_read_b128 v[22:25], v190
	ds_read_b128 v[26:29], v191
	ds_read2_b32 v[30:31], v137 offset0:80 offset1:96
	ds_read2_b32 v[38:39], v137 offset0:112 offset1:128
	s_waitcnt vmcnt(1) lgkmcnt(5)
; #define LAS __attribute__((address_space(3)))
; __device__ __forceinline__ unsigned fkey(float f) { const unsigned u = __float_as_uint(f); return (u & 0x80000000u) ? ~u : (u | 0x80000000u); }
; #define SEL_HADD(idx_) __hip_atomic_fetch_add(&hist[(idx_)], 1u, __ATOMIC_RELAXED, __HIP_MEMORY_SCOPE_WORKGROUP)
; __device__ __forceinline__ void sel_unit(LAS char* lds, int b, int u, const bf16_t* QI, const bf16_t* KIDX, const float* WIDX, unsigned long long* MASK) {
;     ...
;     for (int j = 0; j < 8; ++j) {
;         if (j < nj) {
;             int t = wid + 8 * j; asm volatile("" : "+s"(t));
; #pragma unroll
;             for (int kh = 0; kh < 2; ++kh) {
;             bf16x8 kf[2][2];
; #pragma unroll
;             for (int kb = 0; kb < 2; ++kb)
; #pragma unroll
;                 for (int ks = 0; ks < 2; ++ks) kf[kb][ks] = *(const bf16x8*)(KIDX + (rowbase + 64 * t + 32 * kh + 16 * kb + q16) * 64 + 32 * ks + 8 * kg);
; #pragma unroll
;             for (int kb = 0; kb < 2; ++kb) {
;                 f32x4 s = (f32x4){0.f, 0.f, 0.f, 0.f};
; #pragma unroll
;                 for (int hh = 0; hh < 8; ++hh) {
;                     f32x4 a = (f32x4){0.f, 0.f, 0.f, 0.f};
; #pragma unroll
;                     for (int ks = 0; ks < 2; ++ks) {
;                         const bf16x8 qv = *(const LAS bf16x8*)(lds + L_QI + q16 * 1024 + (((hh * 8 + 4 * ks + kg) ^ q16) << 4));
;                         a = __builtin_amdgcn_mfma_f32_16x16x32_bf16(kf[kb][ks], qv, a, 0, 0, 0);
;                     }
;                     const float wh = wl[hh * 16];
; #pragma unroll
;                     for (int i = 0; i < 4; ++i) s[i] += wh * fmaxf(a[i], 0.f);
;                 }
;                 u32x4 kk; kk.x = fkey(s[0]); kk.y = fkey(s[1]); kk.z = fkey(s[2]); kk.w = fkey(s[3]);
;                 sc[j][2 * kh + kb] = kk;
; #pragma unroll
;                 for (int i = 0; i < 4; ++i) SEL_HADD((kk[i] >> 24) * 16 + q16);
;                 __builtin_amdgcn_sched_barrier(0);
	v_mfma_f32_16x16x32_bf16 v[10:13], v[244:247], v[10:13], 0
	ds_read2_b32 v[50:51], v137 offset0:144 offset1:160
	ds_read2_b32 v[164:165], v137 offset0:176 offset1:192
	s_waitcnt vmcnt(0) lgkmcnt(6)
	v_mfma_f32_16x16x32_bf16 v[10:13], v[248:251], v[14:17], v[10:13]
	ds_read_b128 v[14:17], v188
	s_waitcnt lgkmcnt(6)
	v_mfma_f32_16x16x32_bf16 v[22:25], v[244:247], v[22:25], 0
	s_nop 4
	v_max_f32_e32 v32, 0, v10
	v_max_f32_e32 v10, 0, v12
	v_max_f32_e32 v33, 0, v11
	s_waitcnt lgkmcnt(4)
	v_mul_f32_e32 v34, v30, v10
	v_max_f32_e32 v36, 0, v13
	v_mfma_f32_16x16x32_bf16 v[10:13], v[248:251], v[26:29], v[22:25]
	s_nop 2
	ds_read_b128 v[22:25], v187
	s_waitcnt lgkmcnt(1)
	v_mfma_f32_16x16x32_bf16 v[14:17], v[244:247], v[14:17], 0
	s_nop 1
	v_max_f32_e32 v26, 0, v10
	v_max_f32_e32 v27, 0, v11
	v_max_f32_e32 v10, 0, v12
	v_mul_f32_e32 v28, v31, v10
	v_max_f32_e32 v37, 0, v13
	s_waitcnt lgkmcnt(0)
	v_mfma_f32_16x16x32_bf16 v[10:13], v[248:251], v[22:25], v[14:17]
	ds_read_b128 v[22:25], v192
	v_pk_mul_f32 v[36:37], v[30:31], v[36:37]
	s_nop 0
	ds_read_b128 v[14:17], v189
	s_waitcnt lgkmcnt(0)
	v_mfma_f32_16x16x32_bf16 v[14:17], v[244:247], v[14:17], 0
	s_nop 1
	v_max_f32_e32 v40, 0, v10
	v_max_f32_e32 v41, 0, v11
	v_max_f32_e32 v10, 0, v12
	v_mul_f32_e32 v42, v38, v10
	s_nop 0
	v_max_f32_e32 v44, 0, v13
	v_mfma_f32_16x16x32_bf16 v[10:13], v[248:251], v[22:25], v[14:17]
	ds_read_b128 v[22:25], v196
	v_mov_b32_e32 v35, v36
	v_mov_b32_e32 v29, v37
	ds_read_b128 v[14:17], v195
	s_waitcnt lgkmcnt(0)
	v_mfma_f32_16x16x32_bf16 v[14:17], v[244:247], v[14:17], 0
	s_nop 1
	v_max_f32_e32 v46, 0, v10
	v_max_f32_e32 v47, 0, v11
	v_max_f32_e32 v10, 0, v12
	v_mul_f32_e32 v48, v39, v10
	s_nop 0
	v_max_f32_e32 v45, 0, v13
	v_mfma_f32_16x16x32_bf16 v[10:13], v[248:251], v[22:25], v[14:17]
	ds_read_b128 v[22:25], v198
	v_pk_mul_f32 v[44:45], v[38:39], v[44:45]
	s_nop 0
	ds_read_b128 v[14:17], v197
	s_waitcnt lgkmcnt(0)
	v_mfma_f32_16x16x32_bf16 v[14:17], v[244:247], v[14:17], 0
	s_nop 1
	v_max_f32_e32 v52, 0, v10
	v_max_f32_e32 v53, 0, v11
	v_max_f32_e32 v10, 0, v12
	v_mul_f32_e32 v54, v50, v10
	s_nop 0
	v_max_f32_e32 v56, 0, v13
	v_mfma_f32_16x16x32_bf16 v[10:13], v[248:251], v[22:25], v[14:17]
	ds_read_b128 v[22:25], v218
	v_mov_b32_e32 v43, v44
	v_mov_b32_e32 v49, v45
	ds_read_b128 v[14:17], v199
	s_waitcnt lgkmcnt(0)
	v_mfma_f32_16x16x32_bf16 v[14:17], v[244:247], v[14:17], 0
	s_nop 1
	v_max_f32_e32 v160, 0, v10
	v_max_f32_e32 v161, 0, v11
	v_max_f32_e32 v10, 0, v12
	v_mul_f32_e32 v162, v51, v10
	s_nop 0
	v_max_f32_e32 v57, 0, v13
	v_mfma_f32_16x16x32_bf16 v[10:13], v[248:251], v[22:25], v[14:17]
	ds_read_b128 v[22:25], v220
	v_pk_mul_f32 v[56:57], v[50:51], v[56:57]
	s_nop 0
	ds_read_b128 v[14:17], v219
	s_waitcnt lgkmcnt(0)
	v_mfma_f32_16x16x32_bf16 v[6:9], v[244:247], v[14:17], 0
	s_nop 1
	s_nop 0
	v_max_f32_e32 v14, 0, v13
	s_nop 0
	v_mfma_f32_16x16x32_bf16 v[2:5], v[248:251], v[22:25], v[6:9]
	s_nop 0
	v_max_f32_e32 v10, 0, v10
	v_max_f32_e32 v11, 0, v11
	v_pk_fma_f32 v[8:9], v[30:31], v[32:33], 0 op_sel_hi:[0,1,0]
	s_nop 0
	s_nop 2
	v_max_f32_e32 v15, 0, v5
	v_pk_mul_f32 v[6:7], v[164:165], v[14:15]
	v_mov_b32_e32 v14, v31
	v_pk_fma_f32 v[8:9], v[14:15], v[26:27], v[8:9] op_sel_hi:[0,1,1]
	v_pk_fma_f32 v[8:9], v[38:39], v[40:41], v[8:9] op_sel_hi:[0,1,1]
	v_mov_b32_e32 v14, v39
	v_pk_fma_f32 v[8:9], v[14:15], v[46:47], v[8:9] op_sel_hi:[0,1,1]
	v_pk_fma_f32 v[8:9], v[50:51], v[52:53], v[8:9] op_sel_hi:[0,1,1]
	v_mov_b32_e32 v14, v51
	v_pk_fma_f32 v[8:9], v[14:15], v[160:161], v[8:9] op_sel_hi:[0,1,1]
	v_max_f32_e32 v2, 0, v2
	v_max_f32_e32 v3, 0, v3
	v_pk_fma_f32 v[8:9], v[164:165], v[10:11], v[8:9] op_sel_hi:[0,1,1]
	v_mov_b32_e32 v10, v165
	v_pk_fma_f32 v[2:3], v[10:11], v[2:3], v[8:9] op_sel_hi:[0,1,1]
	v_and_b32_e32 v9, 0x7fffffff, v3
	v_and_b32_e32 v8, 0x7fffffff, v2
	v_xor_b32_e32 v5, -1, v3
	v_pk_add_f32 v[8:9], v[8:9], 0 neg_lo:[1,1] neg_hi:[1,1]
	v_cmp_gt_i32_e32 vcc, 0, v3
	v_xor_b32_e32 v10, -1, v2
	v_mov_b32_e32 v55, v56
	v_cndmask_b32_e32 v187, v9, v5, vcc
	v_cmp_gt_i32_e32 vcc, 0, v2
	v_pk_add_f32 v[2:3], v[34:35], 0 op_sel_hi:[1,0]
	v_max_f32_e32 v12, 0, v12
	v_pk_add_f32 v[2:3], v[2:3], v[28:29]
	v_pk_add_f32 v[2:3], v[2:3], v[42:43]
	v_mov_b32_e32 v163, v57
	v_pk_add_f32 v[2:3], v[2:3], v[48:49]
	v_mul_f32_e32 v12, v164, v12
	v_pk_add_f32 v[2:3], v[2:3], v[54:55]
	v_max_f32_e32 v4, 0, v4
	v_pk_add_f32 v[2:3], v[2:3], v[162:163]
	v_mov_b32_e32 v13, v6
	v_mul_f32_e32 v4, v165, v4
	v_pk_add_f32 v[2:3], v[2:3], v[12:13]
	v_mov_b32_e32 v5, v7
	v_pk_add_f32 v[2:3], v[2:3], v[4:5]
	v_cndmask_b32_e32 v188, v8, v10, vcc
	v_and_b32_e32 v5, 0x7fffffff, v3
	v_and_b32_e32 v4, 0x7fffffff, v2
	v_xor_b32_e32 v6, -1, v3
	v_pk_add_f32 v[4:5], v[4:5], 0 neg_lo:[1,1] neg_hi:[1,1]
	v_cmp_gt_i32_e32 vcc, 0, v3
	v_xor_b32_e32 v7, -1, v2
	s_nop 0
	v_cndmask_b32_e32 v189, v5, v6, vcc
	v_cmp_gt_i32_e32 vcc, 0, v2
	v_lshrrev_b32_e32 v2, 24, v188
	v_lshl_add_u32 v2, v2, 6, v0
	ds_add_u32 v2, v205 offset:16384
	v_lshrrev_b32_e32 v2, 24, v187
	v_cndmask_b32_e32 v190, v4, v7, vcc
	v_lshl_add_u32 v2, v2, 6, v0
	ds_add_u32 v2, v205 offset:16384
	v_lshrrev_b32_e32 v2, 24, v190
	v_lshl_add_u32 v2, v2, 6, v0
	ds_add_u32 v2, v205 offset:16384
	v_lshrrev_b32_e32 v2, 24, v189
	v_lshl_add_u32 v2, v2, 6, v0
	ds_add_u32 v2, v205 offset:16384
; #define LAS __attribute__((address_space(3)))
; __device__ __forceinline__ unsigned fkey(float f) { const unsigned u = __float_as_uint(f); return (u & 0x80000000u) ? ~u : (u | 0x80000000u); }
; #define SEL_HADD(idx_) __hip_atomic_fetch_add(&hist[(idx_)], 1u, __ATOMIC_RELAXED, __HIP_MEMORY_SCOPE_WORKGROUP)
; __device__ __forceinline__ void sel_unit(LAS char* lds, int b, int u, const bf16_t* QI, const bf16_t* KIDX, const float* WIDX, unsigned long long* MASK) {
;     ...
;     for (int j = 0; j < 8; ++j) {
;         if (j < nj) {
;             int t = wid + 8 * j; asm volatile("" : "+s"(t));
; #pragma unroll
;             for (int kh = 0; kh < 2; ++kh) {
;             bf16x8 kf[2][2];
; #pragma unroll
;             for (int kb = 0; kb < 2; ++kb)
; #pragma unroll
;                 for (int ks = 0; ks < 2; ++ks) kf[kb][ks] = *(const bf16x8*)(KIDX + (rowbase + 64 * t + 32 * kh + 16 * kb + q16) * 64 + 32 * ks + 8 * kg);
; #pragma unroll
;             for (int kb = 0; kb < 2; ++kb) {
;                 f32x4 s = (f32x4){0.f, 0.f, 0.f, 0.f};
; #pragma unroll
;                 for (int hh = 0; hh < 8; ++hh) {
;                     f32x4 a = (f32x4){0.f, 0.f, 0.f, 0.f};
; #pragma unroll
;                     for (int ks = 0; ks < 2; ++ks) {
;                         const bf16x8 qv = *(const LAS bf16x8*)(lds + L_QI + q16 * 1024 + (((hh * 8 + 4 * ks + kg) ^ q16) << 4));
;                         a = __builtin_amdgcn_mfma_f32_16x16x32_bf16(kf[kb][ks], qv, a, 0, 0, 0);
;                     }
;                     const float wh = wl[hh * 16];
; #pragma unroll
;                     for (int i = 0; i < 4; ++i) s[i] += wh * fmaxf(a[i], 0.f);
;                 }
;                 u32x4 kk; kk.x = fkey(s[0]); kk.y = fkey(s[1]); kk.z = fkey(s[2]); kk.w = fkey(s[3]);
;                 sc[j][2 * kh + kb] = kk;
; #pragma unroll
;                 for (int i = 0; i < 4; ++i) SEL_HADD((kk[i] >> 24) * 16 + q16);
;                 __builtin_amdgcn_sched_barrier(0);
.LBB0_668:
	s_cmp_gt_i32 s4, 6
	s_cselect_b64 s[0:1], -1, 0
	s_cmp_lt_i32 s4, 7
	s_cbranch_scc1 .LBB0_670
	s_add_i32 s2, s46, 48
	s_lshl_b32 s2, s2, 6
	s_ashr_i32 s3, s2, 31
	v_lshl_add_u64 v[2:3], v[18:19], 0, s[2:3]
	v_lshlrev_b64 v[2:3], 7, v[2:3]
	v_lshl_add_u64 v[22:23], v[20:21], 0, v[2:3]
	global_load_dwordx4 v[14:17], v[22:23], off
	global_load_dwordx4 v[10:13], v[22:23], off offset:64
	v_lshl_add_u32 v223, v182, 4, v150
	v_lshl_add_u32 v224, v183, 4, v150
	v_lshl_add_u32 v221, v185, 4, v150
	v_lshl_add_u32 v199, v180, 4, v150
	v_lshl_add_u32 v222, v159, 4, v150
	v_lshl_add_u32 v220, v184, 4, v150
	ds_read_b128 v[2:5], v223
	v_lshl_add_u32 v218, v179, 4, v150
	ds_read_b128 v[6:9], v224
	ds_read_b128 v[24:27], v220
	v_lshl_add_u32 v219, v176, 4, v150
	ds_read_b128 v[28:31], v221
	ds_read_b128 v[32:35], v218
	ds_read_b128 v[36:39], v199
	ds_read_b128 v[40:43], v219
	v_lshl_add_u32 v225, v158, 4, v150
	ds_read_b128 v[44:47], v222
	ds_read_b128 v[48:51], v225
	v_lshl_add_u32 v226, v157, 4, v150
	ds_read_b128 v[52:55], v226
	v_lshl_add_u32 v227, v156, 4, v150
	v_lshl_add_u32 v228, v155, 4, v150
	ds_read_b128 v[160:163], v227
	ds_read_b128 v[164:167], v228
	v_lshl_add_u32 v229, v154, 4, v150
	v_lshl_add_u32 v230, v153, 4, v150
	v_lshl_add_u32 v231, v152, 4, v150
	v_lshl_add_u32 v232, v151, 4, v150
	s_waitcnt vmcnt(1) lgkmcnt(11)
	v_mfma_f32_16x16x32_bf16 v[2:5], v[14:17], v[2:5], 0
	s_waitcnt lgkmcnt(9)
	v_mfma_f32_16x16x32_bf16 v[24:27], v[14:17], v[24:27], 0
	s_waitcnt lgkmcnt(7)
	v_mfma_f32_16x16x32_bf16 v[32:35], v[14:17], v[32:35], 0
	s_waitcnt lgkmcnt(5)
	v_mfma_f32_16x16x32_bf16 v[40:43], v[14:17], v[40:43], 0
	s_waitcnt lgkmcnt(3)
	v_mfma_f32_16x16x32_bf16 v[48:51], v[14:17], v[48:51], 0
	s_waitcnt vmcnt(0)
	v_mfma_f32_16x16x32_bf16 v[168:171], v[10:13], v[6:9], v[2:5]
	v_mfma_f32_16x16x32_bf16 v[24:27], v[10:13], v[28:31], v[24:27]
	v_mfma_f32_16x16x32_bf16 v[28:31], v[10:13], v[36:39], v[32:35]
	v_mfma_f32_16x16x32_bf16 v[32:35], v[10:13], v[44:47], v[40:43]
	ds_read2_b32 v[44:45], v137 offset0:80 offset1:96
	ds_read2_b32 v[46:47], v137 offset0:112 offset1:128
	s_nop 3
	s_waitcnt lgkmcnt(4)
	v_mfma_f32_16x16x32_bf16 v[36:39], v[10:13], v[52:55], v[48:51]
	ds_read2_b32 v[48:49], v137 offset0:144 offset1:160
	global_load_dwordx4 v[6:9], v[22:23], off offset:2048
	global_load_dwordx4 v[2:5], v[22:23], off offset:2112
	v_mov_b32_e32 v252, 0x1000
	v_mov_b32_e32 v253, 0
	v_lshl_add_u64 v[252:253], v[252:253], 0, v[22:23]
	global_load_dwordx4 v[236:239], v[252:253], off
	global_load_dwordx4 v[240:243], v[252:253], off offset:64
	global_load_dwordx4 v[244:247], v[252:253], off offset:2048
	global_load_dwordx4 v[248:251], v[252:253], off offset:2112
	s_waitcnt lgkmcnt(4)
	v_mfma_f32_16x16x32_bf16 v[160:163], v[14:17], v[160:163], 0
	s_nop 0
	s_nop 0
	v_max_f32_e32 v54, v24, v24
	s_waitcnt lgkmcnt(3)
	v_mfma_f32_16x16x32_bf16 v[40:43], v[10:13], v[164:167], v[160:163]
	s_nop 0
	v_max_f32_e32 v24, 0, v171
	v_max_f32_e32 v164, 0, v26
	v_max_f32_e32 v160, v39, v39
	v_max_f32_e32 v39, 0, v25
	s_nop 2
	v_max_f32_e32 v25, 0, v27
	v_max_f32_e32 v26, 0, v31
	v_max_f32_e32 v27, 0, v35
	v_max_f32_e32 v55, v36, v36
	v_max_f32_e32 v57, v38, v38
	v_max_f32_e32 v36, 0, v168
	v_max_f32_e32 v38, 0, v54
	v_max_f32_e32 v50, 0, v32
	v_max_f32_e32 v32, 0, v160
	v_max_f32_e32 v54, 0, v40
	s_waitcnt lgkmcnt(2)
	v_pk_mul_f32 v[160:161], v[44:45], v[24:25]
	s_waitcnt lgkmcnt(1)
	v_pk_mul_f32 v[166:167], v[46:47], v[26:27]
	ds_read_b128 v[24:27], v229
	v_max_f32_e32 v162, v41, v41
	v_max_f32_e32 v163, v42, v42
	v_max_f32_e32 v40, 0, v28
	v_max_f32_e32 v28, 0, v30
	v_max_f32_e32 v42, 0, v170
	v_max_f32_e32 v41, 0, v29
	v_max_f32_e32 v29, 0, v34
	v_max_f32_e32 v52, 0, v55
	v_max_f32_e32 v30, 0, v57
	v_max_f32_e32 v55, 0, v162
	v_mul_f32_e32 v162, v46, v28
	v_max_f32_e32 v28, 0, v163
	v_max_f32_e32 v53, 0, v37
	v_mul_f32_e32 v56, v45, v164
	v_mul_f32_e32 v164, v47, v29
	s_waitcnt lgkmcnt(1)
	v_mul_f32_e32 v168, v48, v30
	v_mul_f32_e32 v170, v49, v28
	ds_read_b128 v[28:31], v230
	s_waitcnt lgkmcnt(1)
	v_mfma_f32_16x16x32_bf16 v[24:27], v[14:17], v[24:27], 0
	v_max_f32_e32 v37, 0, v169
	s_waitcnt lgkmcnt(0)
	v_mfma_f32_16x16x32_bf16 v[24:27], v[10:13], v[28:31], v[24:27]
	ds_read_b128 v[28:31], v231
	v_max_f32_e32 v51, 0, v33
	v_max_f32_e32 v33, 0, v43
	v_pk_mul_f32 v[172:173], v[48:49], v[32:33]
	ds_read_b128 v[32:35], v232
	s_waitcnt lgkmcnt(1)
	v_mfma_f32_16x16x32_bf16 v[14:17], v[14:17], v[28:31], 0
	ds_read2_b32 v[174:175], v137 offset0:176 offset1:192
	s_nop 0
	v_max_f32_e32 v28, 0, v27
	s_waitcnt lgkmcnt(1)
	v_mfma_f32_16x16x32_bf16 v[10:13], v[10:13], v[32:35], v[14:17]
	s_nop 0
	s_nop 0
	v_max_f32_e32 v24, 0, v24
	v_pk_fma_f32 v[16:17], v[44:45], v[36:37], 0 op_sel_hi:[0,1,0]
	v_max_f32_e32 v25, 0, v25
	s_nop 2
	v_max_f32_e32 v29, 0, v13
	s_waitcnt lgkmcnt(0)
; #define LAS __attribute__((address_space(3)))
; __device__ __forceinline__ unsigned fkey(float f) { const unsigned u = __float_as_uint(f); return (u & 0x80000000u) ? ~u : (u | 0x80000000u); }
; #define SEL_HADD(idx_) __hip_atomic_fetch_add(&hist[(idx_)], 1u, __ATOMIC_RELAXED, __HIP_MEMORY_SCOPE_WORKGROUP)
; __device__ __forceinline__ void sel_unit(LAS char* lds, int b, int u, const bf16_t* QI, const bf16_t* KIDX, const float* WIDX, unsigned long long* MASK) {
;     ...
;     for (int j = 0; j < 8; ++j) {
;         if (j < nj) {
;             int t = wid + 8 * j; asm volatile("" : "+s"(t));
; #pragma unroll
;             for (int kh = 0; kh < 2; ++kh) {
;             bf16x8 kf[2][2];
; #pragma unroll
;             for (int kb = 0; kb < 2; ++kb)
; #pragma unroll
;                 for (int ks = 0; ks < 2; ++ks) kf[kb][ks] = *(const bf16x8*)(KIDX + (rowbase + 64 * t + 32 * kh + 16 * kb + q16) * 64 + 32 * ks + 8 * kg);
; #pragma unroll
;             for (int kb = 0; kb < 2; ++kb) {
;                 f32x4 s = (f32x4){0.f, 0.f, 0.f, 0.f};
; #pragma unroll
;                 for (int hh = 0; hh < 8; ++hh) {
;                     f32x4 a = (f32x4){0.f, 0.f, 0.f, 0.f};
; #pragma unroll
;                     for (int ks = 0; ks < 2; ++ks) {
;                         const bf16x8 qv = *(const LAS bf16x8*)(lds + L_QI + q16 * 1024 + (((hh * 8 + 4 * ks + kg) ^ q16) << 4));
;                         a = __builtin_amdgcn_mfma_f32_16x16x32_bf16(kf[kb][ks], qv, a, 0, 0, 0);
;                     }
;                     const float wh = wl[hh * 16];
; #pragma unroll
;                     for (int i = 0; i < 4; ++i) s[i] += wh * fmaxf(a[i], 0.f);
;                 }
;                 u32x4 kk; kk.x = fkey(s[0]); kk.y = fkey(s[1]); kk.z = fkey(s[2]); kk.w = fkey(s[3]);
;                 sc[j][2 * kh + kb] = kk;
; #pragma unroll
;                 for (int i = 0; i < 4; ++i) SEL_HADD((kk[i] >> 24) * 16 + q16);
;                 __builtin_amdgcn_sched_barrier(0);
	v_pk_mul_f32 v[14:15], v[174:175], v[28:29]
	v_mov_b32_e32 v28, v45
	v_pk_fma_f32 v[16:17], v[28:29], v[38:39], v[16:17] op_sel_hi:[0,1,1]
	v_pk_fma_f32 v[16:17], v[46:47], v[40:41], v[16:17] op_sel_hi:[0,1,1]
	v_mov_b32_e32 v28, v47
	v_pk_fma_f32 v[16:17], v[28:29], v[50:51], v[16:17] op_sel_hi:[0,1,1]
	v_pk_fma_f32 v[16:17], v[48:49], v[52:53], v[16:17] op_sel_hi:[0,1,1]
	v_mov_b32_e32 v28, v49
	v_pk_fma_f32 v[16:17], v[28:29], v[54:55], v[16:17] op_sel_hi:[0,1,1]
	v_max_f32_e32 v10, 0, v10
	v_max_f32_e32 v11, 0, v11
	v_pk_fma_f32 v[16:17], v[174:175], v[24:25], v[16:17] op_sel_hi:[0,1,1]
	v_mov_b32_e32 v24, v175
	v_pk_fma_f32 v[10:11], v[24:25], v[10:11], v[16:17] op_sel_hi:[0,1,1]
	v_and_b32_e32 v17, 0x7fffffff, v11
	v_and_b32_e32 v16, 0x7fffffff, v10
	v_mul_f32_e32 v42, v44, v42
	v_xor_b32_e32 v13, -1, v11
	v_pk_add_f32 v[16:17], v[16:17], 0 neg_lo:[1,1] neg_hi:[1,1]
	v_cmp_gt_i32_e32 vcc, 0, v11
	v_mov_b32_e32 v43, v160
	v_xor_b32_e32 v24, -1, v10
	v_cndmask_b32_e32 v191, v17, v13, vcc
	v_cmp_gt_i32_e32 vcc, 0, v10
	v_pk_add_f32 v[10:11], v[42:43], 0 op_sel_hi:[1,0]
	v_mov_b32_e32 v57, v161
	v_pk_add_f32 v[10:11], v[10:11], v[56:57]
	v_mov_b32_e32 v163, v166
	v_pk_add_f32 v[10:11], v[10:11], v[162:163]
	v_mov_b32_e32 v165, v167
	v_pk_add_f32 v[10:11], v[10:11], v[164:165]
	v_mov_b32_e32 v169, v172
	v_max_f32_e32 v26, 0, v26
	v_pk_add_f32 v[10:11], v[10:11], v[168:169]
	v_mov_b32_e32 v171, v173
	v_mul_f32_e32 v26, v174, v26
	v_max_f32_e32 v12, 0, v12
	v_pk_add_f32 v[10:11], v[10:11], v[170:171]
	v_mov_b32_e32 v27, v14
	v_mul_f32_e32 v12, v175, v12
	v_pk_add_f32 v[10:11], v[10:11], v[26:27]
	v_mov_b32_e32 v13, v15
	v_pk_add_f32 v[10:11], v[10:11], v[12:13]
	v_cndmask_b32_e32 v192, v16, v24, vcc
	v_and_b32_e32 v13, 0x7fffffff, v11
	v_and_b32_e32 v12, 0x7fffffff, v10
	v_xor_b32_e32 v14, -1, v11
	v_pk_add_f32 v[12:13], v[12:13], 0 neg_lo:[1,1] neg_hi:[1,1]
	v_cmp_gt_i32_e32 vcc, 0, v11
	v_xor_b32_e32 v15, -1, v10
	s_nop 0
	v_cndmask_b32_e32 v193, v13, v14, vcc
	v_cmp_gt_i32_e32 vcc, 0, v10
	v_lshrrev_b32_e32 v10, 24, v192
	v_lshl_add_u32 v10, v10, 6, v0
	ds_add_u32 v10, v205 offset:16384
	v_lshrrev_b32_e32 v10, 24, v191
	v_cndmask_b32_e32 v194, v12, v15, vcc
	v_lshl_add_u32 v10, v10, 6, v0
	ds_add_u32 v10, v205 offset:16384
	v_lshrrev_b32_e32 v10, 24, v194
	v_lshl_add_u32 v10, v10, 6, v0
	ds_add_u32 v10, v205 offset:16384
	v_lshrrev_b32_e32 v10, 24, v193
	v_lshl_add_u32 v10, v10, 6, v0
	ds_add_u32 v10, v205 offset:16384
	ds_read_b128 v[10:13], v223
	ds_read_b128 v[14:17], v224
	ds_read_b128 v[24:27], v220
	ds_read_b128 v[28:31], v221
	ds_read2_b32 v[32:33], v137 offset0:80 offset1:96
	ds_read2_b32 v[40:41], v137 offset0:112 offset1:128
	s_waitcnt vmcnt(5) lgkmcnt(5)
	v_mfma_f32_16x16x32_bf16 v[10:13], v[6:9], v[10:13], 0
	ds_read2_b32 v[52:53], v137 offset0:144 offset1:160
	ds_read2_b32 v[166:167], v137 offset0:176 offset1:192
	s_waitcnt vmcnt(4) lgkmcnt(6)
	v_mfma_f32_16x16x32_bf16 v[10:13], v[2:5], v[14:17], v[10:13]
	ds_read_b128 v[14:17], v218
	s_waitcnt lgkmcnt(6)
	v_mfma_f32_16x16x32_bf16 v[24:27], v[6:9], v[24:27], 0
	s_nop 4
	v_max_f32_e32 v34, 0, v10
	v_max_f32_e32 v10, 0, v12
	v_max_f32_e32 v35, 0, v11
	s_waitcnt lgkmcnt(4)
	v_mul_f32_e32 v36, v32, v10
	v_max_f32_e32 v38, 0, v13
	v_mfma_f32_16x16x32_bf16 v[10:13], v[2:5], v[28:31], v[24:27]
	s_nop 2
	ds_read_b128 v[24:27], v199
	s_waitcnt lgkmcnt(1)
	v_mfma_f32_16x16x32_bf16 v[14:17], v[6:9], v[14:17], 0
	s_nop 1
	v_max_f32_e32 v28, 0, v10
	v_max_f32_e32 v29, 0, v11
	v_max_f32_e32 v10, 0, v12
	v_mul_f32_e32 v30, v33, v10
	v_max_f32_e32 v39, 0, v13
	s_waitcnt lgkmcnt(0)
	v_mfma_f32_16x16x32_bf16 v[10:13], v[2:5], v[24:27], v[14:17]
	ds_read_b128 v[24:27], v222
	v_pk_mul_f32 v[38:39], v[32:33], v[38:39]
	s_nop 0
	ds_read_b128 v[14:17], v219
	s_waitcnt lgkmcnt(0)
	v_mfma_f32_16x16x32_bf16 v[14:17], v[6:9], v[14:17], 0
	s_nop 1
	v_max_f32_e32 v42, 0, v10
	v_max_f32_e32 v43, 0, v11
	v_max_f32_e32 v10, 0, v12
	v_mul_f32_e32 v44, v40, v10
	s_nop 0
	v_max_f32_e32 v46, 0, v13
	v_mfma_f32_16x16x32_bf16 v[10:13], v[2:5], v[24:27], v[14:17]
	ds_read_b128 v[24:27], v226
	v_mov_b32_e32 v37, v38
	v_mov_b32_e32 v31, v39
	ds_read_b128 v[14:17], v225
	s_waitcnt lgkmcnt(0)
	v_mfma_f32_16x16x32_bf16 v[14:17], v[6:9], v[14:17], 0
	s_nop 1
	v_max_f32_e32 v48, 0, v10
	v_max_f32_e32 v49, 0, v11
	v_max_f32_e32 v10, 0, v12
	v_mul_f32_e32 v50, v41, v10
	s_nop 0
	v_max_f32_e32 v47, 0, v13
	v_mfma_f32_16x16x32_bf16 v[10:13], v[2:5], v[24:27], v[14:17]
	ds_read_b128 v[24:27], v228
	v_pk_mul_f32 v[46:47], v[40:41], v[46:47]
	s_nop 0
	ds_read_b128 v[14:17], v227
	s_waitcnt lgkmcnt(0)
	v_mfma_f32_16x16x32_bf16 v[14:17], v[6:9], v[14:17], 0
	s_nop 1
	v_max_f32_e32 v54, 0, v10
	v_max_f32_e32 v55, 0, v11
	v_max_f32_e32 v10, 0, v12
	v_mul_f32_e32 v56, v52, v10
	s_nop 0
	v_max_f32_e32 v160, 0, v13
	v_mfma_f32_16x16x32_bf16 v[10:13], v[2:5], v[24:27], v[14:17]
	ds_read_b128 v[24:27], v230
	v_mov_b32_e32 v45, v46
	v_mov_b32_e32 v51, v47
	ds_read_b128 v[14:17], v229
	s_waitcnt lgkmcnt(0)
	v_mfma_f32_16x16x32_bf16 v[14:17], v[6:9], v[14:17], 0
	s_nop 1
	v_max_f32_e32 v162, 0, v10
	v_max_f32_e32 v163, 0, v11
	v_max_f32_e32 v10, 0, v12
	v_mul_f32_e32 v164, v53, v10
	s_nop 0
	v_max_f32_e32 v161, 0, v13
	v_mfma_f32_16x16x32_bf16 v[10:13], v[2:5], v[24:27], v[14:17]
	ds_read_b128 v[24:27], v232
	v_pk_mul_f32 v[160:161], v[52:53], v[160:161]
	s_nop 0
	ds_read_b128 v[14:17], v231
	s_waitcnt lgkmcnt(0)
; #define LAS __attribute__((address_space(3)))
; __device__ __forceinline__ unsigned fkey(float f) { const unsigned u = __float_as_uint(f); return (u & 0x80000000u) ? ~u : (u | 0x80000000u); }
; #define SEL_HADD(idx_) __hip_atomic_fetch_add(&hist[(idx_)], 1u, __ATOMIC_RELAXED, __HIP_MEMORY_SCOPE_WORKGROUP)
; __device__ __forceinline__ void sel_unit(LAS char* lds, int b, int u, const bf16_t* QI, const bf16_t* KIDX, const float* WIDX, unsigned long long* MASK) {
;     ...
;     for (int j = 0; j < 8; ++j) {
;         if (j < nj) {
;             int t = wid + 8 * j; asm volatile("" : "+s"(t));
; #pragma unroll
;             for (int kh = 0; kh < 2; ++kh) {
;             bf16x8 kf[2][2];
; #pragma unroll
;             for (int kb = 0; kb < 2; ++kb)
; #pragma unroll
;                 for (int ks = 0; ks < 2; ++ks) kf[kb][ks] = *(const bf16x8*)(KIDX + (rowbase + 64 * t + 32 * kh + 16 * kb + q16) * 64 + 32 * ks + 8 * kg);
; #pragma unroll
;             for (int kb = 0; kb < 2; ++kb) {
;                 f32x4 s = (f32x4){0.f, 0.f, 0.f, 0.f};
; #pragma unroll
;                 for (int hh = 0; hh < 8; ++hh) {
;                     f32x4 a = (f32x4){0.f, 0.f, 0.f, 0.f};
; #pragma unroll
;                     for (int ks = 0; ks < 2; ++ks) {
;                         const bf16x8 qv = *(const LAS bf16x8*)(lds + L_QI + q16 * 1024 + (((hh * 8 + 4 * ks + kg) ^ q16) << 4));
;                         a = __builtin_amdgcn_mfma_f32_16x16x32_bf16(kf[kb][ks], qv, a, 0, 0, 0);
;                     }
;                     const float wh = wl[hh * 16];
; #pragma unroll
;                     for (int i = 0; i < 4; ++i) s[i] += wh * fmaxf(a[i], 0.f);
;                 }
;                 u32x4 kk; kk.x = fkey(s[0]); kk.y = fkey(s[1]); kk.z = fkey(s[2]); kk.w = fkey(s[3]);
;                 sc[j][2 * kh + kb] = kk;
; #pragma unroll
;                 for (int i = 0; i < 4; ++i) SEL_HADD((kk[i] >> 24) * 16 + q16);
;                 __builtin_amdgcn_sched_barrier(0);
	v_mfma_f32_16x16x32_bf16 v[6:9], v[6:9], v[14:17], 0
	s_nop 1
	s_nop 0
	v_max_f32_e32 v14, 0, v13
	s_nop 0
	v_mfma_f32_16x16x32_bf16 v[2:5], v[2:5], v[24:27], v[6:9]
	s_nop 0
	v_max_f32_e32 v10, 0, v10
	v_max_f32_e32 v11, 0, v11
	v_pk_fma_f32 v[8:9], v[32:33], v[34:35], 0 op_sel_hi:[0,1,0]
	s_nop 0
	s_nop 2
	v_max_f32_e32 v15, 0, v5
	v_pk_mul_f32 v[6:7], v[166:167], v[14:15]
	v_mov_b32_e32 v14, v33
	v_pk_fma_f32 v[8:9], v[14:15], v[28:29], v[8:9] op_sel_hi:[0,1,1]
	v_pk_fma_f32 v[8:9], v[40:41], v[42:43], v[8:9] op_sel_hi:[0,1,1]
	v_mov_b32_e32 v14, v41
	v_pk_fma_f32 v[8:9], v[14:15], v[48:49], v[8:9] op_sel_hi:[0,1,1]
	v_pk_fma_f32 v[8:9], v[52:53], v[54:55], v[8:9] op_sel_hi:[0,1,1]
	v_mov_b32_e32 v14, v53
	v_pk_fma_f32 v[8:9], v[14:15], v[162:163], v[8:9] op_sel_hi:[0,1,1]
	v_max_f32_e32 v2, 0, v2
	v_max_f32_e32 v3, 0, v3
	v_pk_fma_f32 v[8:9], v[166:167], v[10:11], v[8:9] op_sel_hi:[0,1,1]
	v_mov_b32_e32 v10, v167
	v_pk_fma_f32 v[2:3], v[10:11], v[2:3], v[8:9] op_sel_hi:[0,1,1]
	v_and_b32_e32 v9, 0x7fffffff, v3
	v_and_b32_e32 v8, 0x7fffffff, v2
	v_xor_b32_e32 v5, -1, v3
	v_pk_add_f32 v[8:9], v[8:9], 0 neg_lo:[1,1] neg_hi:[1,1]
	v_cmp_gt_i32_e32 vcc, 0, v3
	v_xor_b32_e32 v10, -1, v2
	v_mov_b32_e32 v57, v160
	v_cndmask_b32_e32 v195, v9, v5, vcc
	v_cmp_gt_i32_e32 vcc, 0, v2
	v_pk_add_f32 v[2:3], v[36:37], 0 op_sel_hi:[1,0]
	v_max_f32_e32 v12, 0, v12
	v_pk_add_f32 v[2:3], v[2:3], v[30:31]
	v_pk_add_f32 v[2:3], v[2:3], v[44:45]
	v_mov_b32_e32 v165, v161
	v_pk_add_f32 v[2:3], v[2:3], v[50:51]
	v_mul_f32_e32 v12, v166, v12
	v_pk_add_f32 v[2:3], v[2:3], v[56:57]
	v_max_f32_e32 v4, 0, v4
	v_pk_add_f32 v[2:3], v[2:3], v[164:165]
	v_mov_b32_e32 v13, v6
	v_mul_f32_e32 v4, v167, v4
	v_pk_add_f32 v[2:3], v[2:3], v[12:13]
	v_mov_b32_e32 v5, v7
	v_pk_add_f32 v[2:3], v[2:3], v[4:5]
	v_cndmask_b32_e32 v196, v8, v10, vcc
	v_and_b32_e32 v5, 0x7fffffff, v3
	v_and_b32_e32 v4, 0x7fffffff, v2
	v_xor_b32_e32 v6, -1, v3
	v_pk_add_f32 v[4:5], v[4:5], 0 neg_lo:[1,1] neg_hi:[1,1]
	v_cmp_gt_i32_e32 vcc, 0, v3
	v_xor_b32_e32 v7, -1, v2
	s_nop 0
	v_cndmask_b32_e32 v197, v5, v6, vcc
	v_cmp_gt_i32_e32 vcc, 0, v2
	v_lshrrev_b32_e32 v2, 24, v196
	v_lshl_add_u32 v2, v2, 6, v0
	ds_add_u32 v2, v205 offset:16384
	v_lshrrev_b32_e32 v2, 24, v195
	v_cndmask_b32_e32 v198, v4, v7, vcc
	v_lshl_add_u32 v2, v2, 6, v0
	ds_add_u32 v2, v205 offset:16384
	v_lshrrev_b32_e32 v2, 24, v198
	v_lshl_add_u32 v2, v2, 6, v0
	ds_add_u32 v2, v205 offset:16384
	v_lshrrev_b32_e32 v2, 24, v197
	v_lshl_add_u32 v2, v2, 6, v0
	ds_add_u32 v2, v205 offset:16384
	ds_read_b128 v[22:25], v223
	ds_read_b128 v[26:29], v224
	s_waitcnt vmcnt(3) lgkmcnt(1)
	v_mfma_f32_16x16x32_bf16 v[22:25], v[236:239], v[22:25], 0
	ds_read_b128 v[32:35], v221
	ds_read_b128 v[38:41], v199
	ds_read_b128 v[44:47], v222
	s_waitcnt vmcnt(2) lgkmcnt(3)
	v_mfma_f32_16x16x32_bf16 v[26:29], v[240:243], v[26:29], v[22:25]
	ds_read_b128 v[50:53], v226
	ds_read_b128 v[160:163], v228
	s_nop 0
	ds_read2_b32 v[24:25], v137 offset0:80 offset1:96
	s_nop 3
	v_max_f32_e32 v26, 0, v26
	v_max_f32_e32 v27, 0, v27
	v_max_f32_e32 v22, v28, v28
	v_max_f32_e32 v23, v29, v29
	ds_read_b128 v[28:31], v220
	s_waitcnt lgkmcnt(0)
	v_mfma_f32_16x16x32_bf16 v[28:31], v[236:239], v[28:31], 0
	v_max_f32_e32 v36, 0, v23
	v_max_f32_e32 v22, 0, v22
	v_mul_f32_e32 v22, v24, v22
	v_mfma_f32_16x16x32_bf16 v[28:31], v[240:243], v[32:35], v[28:31]
	s_nop 7
	v_max_f32_e32 v32, 0, v28
	v_max_f32_e32 v33, 0, v29
	v_max_f32_e32 v23, 0, v30
	v_mul_f32_e32 v28, v25, v23
	v_max_f32_e32 v37, 0, v31
	v_pk_mul_f32 v[30:31], v[24:25], v[36:37]
	ds_read_b128 v[34:37], v218
	s_waitcnt lgkmcnt(0)
	v_mfma_f32_16x16x32_bf16 v[34:37], v[236:239], v[34:37], 0
	v_mov_b32_e32 v29, v31
	v_mfma_f32_16x16x32_bf16 v[38:41], v[240:243], v[38:41], v[34:37]
	s_nop 5
	ds_read2_b32 v[36:37], v137 offset0:112 offset1:128
	s_nop 0
	v_max_f32_e32 v38, 0, v38
	v_max_f32_e32 v39, 0, v39
	v_max_f32_e32 v23, 0, v40
	s_waitcnt lgkmcnt(0)
	v_mul_f32_e32 v34, v36, v23
	v_max_f32_e32 v23, v41, v41
	ds_read_b128 v[40:43], v219
	s_waitcnt lgkmcnt(0)
	v_mfma_f32_16x16x32_bf16 v[40:43], v[236:239], v[40:43], 0
	v_max_f32_e32 v48, 0, v23
	v_mfma_f32_16x16x32_bf16 v[40:43], v[240:243], v[44:47], v[40:43]
	s_nop 7
	v_max_f32_e32 v44, 0, v40
	v_max_f32_e32 v45, 0, v41
	v_max_f32_e32 v23, 0, v42
	v_mul_f32_e32 v40, v37, v23
	v_max_f32_e32 v49, 0, v43
	v_pk_mul_f32 v[42:43], v[36:37], v[48:49]
	ds_read_b128 v[46:49], v225
	s_waitcnt lgkmcnt(0)
	v_mfma_f32_16x16x32_bf16 v[46:49], v[236:239], v[46:49], 0
	v_mov_b32_e32 v35, v42
	v_mov_b32_e32 v41, v43
	v_mfma_f32_16x16x32_bf16 v[50:53], v[240:243], v[50:53], v[46:49]
	s_nop 4
	ds_read2_b32 v[48:49], v137 offset0:144 offset1:160
	s_nop 1
	v_max_f32_e32 v50, 0, v50
	v_max_f32_e32 v51, 0, v51
	v_max_f32_e32 v23, 0, v52
	s_waitcnt lgkmcnt(0)
	v_mul_f32_e32 v46, v48, v23
	v_max_f32_e32 v23, v53, v53
	ds_read_b128 v[52:55], v227
	s_waitcnt lgkmcnt(0)
	v_mfma_f32_16x16x32_bf16 v[52:55], v[236:239], v[52:55], 0
	v_max_f32_e32 v164, 0, v23
	v_mfma_f32_16x16x32_bf16 v[52:55], v[240:243], v[160:163], v[52:55]
	ds_read_b128 v[160:163], v229
	s_nop 6
	v_max_f32_e32 v56, 0, v52
	v_max_f32_e32 v57, 0, v53
	v_max_f32_e32 v23, 0, v54
	v_mul_f32_e32 v52, v49, v23
	v_max_f32_e32 v165, 0, v55
	v_pk_mul_f32 v[54:55], v[48:49], v[164:165]
	ds_read_b128 v[164:167], v230
	s_waitcnt lgkmcnt(1)
	v_mfma_f32_16x16x32_bf16 v[160:163], v[236:239], v[160:163], 0
	v_mov_b32_e32 v47, v54
	v_mov_b32_e32 v53, v55
	s_waitcnt lgkmcnt(0)
	v_mfma_f32_16x16x32_bf16 v[160:163], v[240:243], v[164:167], v[160:163]
	ds_read2_b32 v[164:165], v137 offset0:176 offset1:192
	s_nop 6
	v_max_f32_e32 v166, 0, v160
	v_max_f32_e32 v167, 0, v161
	v_max_f32_e32 v23, 0, v162
	s_waitcnt lgkmcnt(0)
; #define LAS __attribute__((address_space(3)))
; __device__ __forceinline__ unsigned fkey(float f) { const unsigned u = __float_as_uint(f); return (u & 0x80000000u) ? ~u : (u | 0x80000000u); }
; #define SEL_HADD(idx_) __hip_atomic_fetch_add(&hist[(idx_)], 1u, __ATOMIC_RELAXED, __HIP_MEMORY_SCOPE_WORKGROUP)
; __device__ __forceinline__ void sel_unit(LAS char* lds, int b, int u, const bf16_t* QI, const bf16_t* KIDX, const float* WIDX, unsigned long long* MASK) {
;     ...
;     for (int j = 0; j < 8; ++j) {
;         if (j < nj) {
;             int t = wid + 8 * j; asm volatile("" : "+s"(t));
; #pragma unroll
;             for (int kh = 0; kh < 2; ++kh) {
;             bf16x8 kf[2][2];
; #pragma unroll
;             for (int kb = 0; kb < 2; ++kb)
; #pragma unroll
;                 for (int ks = 0; ks < 2; ++ks) kf[kb][ks] = *(const bf16x8*)(KIDX + (rowbase + 64 * t + 32 * kh + 16 * kb + q16) * 64 + 32 * ks + 8 * kg);
; #pragma unroll
;             for (int kb = 0; kb < 2; ++kb) {
;                 f32x4 s = (f32x4){0.f, 0.f, 0.f, 0.f};
; #pragma unroll
;                 for (int hh = 0; hh < 8; ++hh) {
;                     f32x4 a = (f32x4){0.f, 0.f, 0.f, 0.f};
; #pragma unroll
;                     for (int ks = 0; ks < 2; ++ks) {
;                         const bf16x8 qv = *(const LAS bf16x8*)(lds + L_QI + q16 * 1024 + (((hh * 8 + 4 * ks + kg) ^ q16) << 4));
;                         a = __builtin_amdgcn_mfma_f32_16x16x32_bf16(kf[kb][ks], qv, a, 0, 0, 0);
;                     }
;                     const float wh = wl[hh * 16];
; #pragma unroll
;                     for (int i = 0; i < 4; ++i) s[i] += wh * fmaxf(a[i], 0.f);
;                 }
;                 u32x4 kk; kk.x = fkey(s[0]); kk.y = fkey(s[1]); kk.z = fkey(s[2]); kk.w = fkey(s[3]);
;                 sc[j][2 * kh + kb] = kk;
; #pragma unroll
;                 for (int i = 0; i < 4; ++i) SEL_HADD((kk[i] >> 24) * 16 + q16);
;                 __builtin_amdgcn_sched_barrier(0);
	v_mul_f32_e32 v168, v164, v23
	v_max_f32_e32 v23, v163, v163
	ds_read_b128 v[160:163], v231
	s_waitcnt lgkmcnt(0)
	v_mfma_f32_16x16x32_bf16 v[14:17], v[236:239], v[160:163], 0
	ds_read_b128 v[160:163], v232
	v_max_f32_e32 v170, 0, v23
	s_waitcnt lgkmcnt(0)
	v_mfma_f32_16x16x32_bf16 v[10:13], v[240:243], v[160:163], v[14:17]
	s_nop 3
	v_fma_f32 v16, v24, v26, 0
	v_fma_f32 v17, v24, v27, 0
	v_mov_b32_e32 v24, v25
	v_pk_fma_f32 v[16:17], v[24:25], v[32:33], v[16:17] op_sel_hi:[0,1,1]
	v_pk_fma_f32 v[16:17], v[36:37], v[38:39], v[16:17] op_sel_hi:[0,1,1]
	v_mov_b32_e32 v24, v37
	v_pk_fma_f32 v[16:17], v[24:25], v[44:45], v[16:17] op_sel_hi:[0,1,1]
	v_pk_fma_f32 v[16:17], v[48:49], v[50:51], v[16:17] op_sel_hi:[0,1,1]
	v_mov_b32_e32 v24, v49
	v_pk_fma_f32 v[16:17], v[24:25], v[56:57], v[16:17] op_sel_hi:[0,1,1]
	v_max_f32_e32 v10, 0, v10
	v_max_f32_e32 v11, 0, v11
	v_pk_fma_f32 v[16:17], v[164:165], v[166:167], v[16:17] op_sel_hi:[0,1,1]
	v_mov_b32_e32 v24, v165
	v_pk_fma_f32 v[10:11], v[24:25], v[10:11], v[16:17] op_sel_hi:[0,1,1]
	v_and_b32_e32 v17, 0x7fffffff, v11
	v_and_b32_e32 v16, 0x7fffffff, v10
	v_xor_b32_e32 v23, -1, v10
	v_pk_add_f32 v[16:17], v[16:17], 0 neg_lo:[1,1] neg_hi:[1,1]
	v_cmp_gt_i32_e32 vcc, 0, v10
	v_max_f32_e32 v171, 0, v13
	s_nop 0
	v_cndmask_b32_e32 v57, v16, v23, vcc
	v_mov_b32_e32 v23, v30
	v_xor_b32_e32 v13, -1, v11
	v_cmp_gt_i32_e64 s[2:3], 0, v11
	v_pk_add_f32 v[10:11], v[22:23], 0 op_sel_hi:[1,0]
	v_pk_add_f32 v[10:11], v[10:11], v[28:29]
	v_pk_mul_f32 v[14:15], v[164:165], v[170:171]
	v_pk_add_f32 v[10:11], v[10:11], v[34:35]
	v_max_f32_e32 v12, 0, v12
	v_pk_add_f32 v[10:11], v[10:11], v[40:41]
	v_mov_b32_e32 v169, v14
	v_pk_add_f32 v[10:11], v[10:11], v[46:47]
	v_mul_f32_e32 v12, v165, v12
	v_pk_add_f32 v[10:11], v[10:11], v[52:53]
	v_cndmask_b32_e64 v56, v17, v13, s[2:3]
	v_pk_add_f32 v[10:11], v[10:11], v[168:169]
	v_mov_b32_e32 v13, v15
	v_pk_add_f32 v[10:11], v[10:11], v[12:13]
	s_nop 0
	v_xor_b32_e32 v15, -1, v10
	v_and_b32_e32 v12, 0x7fffffff, v10
	v_cmp_gt_i32_e32 vcc, 0, v10
	v_lshrrev_b32_e32 v10, 24, v57
	v_and_b32_e32 v13, 0x7fffffff, v11
	v_lshl_add_u32 v10, v10, 6, v0
	v_pk_add_f32 v[12:13], v[12:13], 0 neg_lo:[1,1] neg_hi:[1,1]
	ds_add_u32 v10, v205 offset:16384
	v_lshrrev_b32_e32 v10, 24, v56
	v_cndmask_b32_e32 v55, v12, v15, vcc
	v_lshl_add_u32 v10, v10, 6, v0
	v_xor_b32_e32 v14, -1, v11
	v_cmp_gt_i32_e64 s[2:3], 0, v11
	ds_add_u32 v10, v205 offset:16384
	v_lshrrev_b32_e32 v10, 24, v55
	v_cndmask_b32_e64 v54, v13, v14, s[2:3]
	v_lshl_add_u32 v10, v10, 6, v0
	ds_add_u32 v10, v205 offset:16384
	v_lshrrev_b32_e32 v10, 24, v54
	v_lshl_add_u32 v10, v10, 6, v0
	ds_add_u32 v10, v205 offset:16384
	ds_read_b128 v[10:13], v223
	ds_read_b128 v[14:17], v224
	ds_read_b128 v[22:25], v220
	ds_read_b128 v[26:29], v221
	ds_read2_b32 v[30:31], v137 offset0:80 offset1:96
	ds_read2_b32 v[38:39], v137 offset0:112 offset1:128
	s_waitcnt vmcnt(1) lgkmcnt(5)
	v_mfma_f32_16x16x32_bf16 v[10:13], v[244:247], v[10:13], 0
	ds_read2_b32 v[50:51], v137 offset0:144 offset1:160
	ds_read2_b32 v[168:169], v137 offset0:176 offset1:192
	s_waitcnt vmcnt(0) lgkmcnt(6)
	v_mfma_f32_16x16x32_bf16 v[10:13], v[248:251], v[14:17], v[10:13]
	ds_read_b128 v[14:17], v218
	s_waitcnt lgkmcnt(6)
	v_mfma_f32_16x16x32_bf16 v[22:25], v[244:247], v[22:25], 0
	s_nop 4
	v_max_f32_e32 v32, 0, v10
	v_max_f32_e32 v10, 0, v12
	v_max_f32_e32 v33, 0, v11
	s_waitcnt lgkmcnt(4)
	v_mul_f32_e32 v34, v30, v10
	v_max_f32_e32 v36, 0, v13
	v_mfma_f32_16x16x32_bf16 v[10:13], v[248:251], v[26:29], v[22:25]
	s_nop 2
	ds_read_b128 v[22:25], v199
	s_waitcnt lgkmcnt(1)
	v_mfma_f32_16x16x32_bf16 v[14:17], v[244:247], v[14:17], 0
	s_nop 1
	v_max_f32_e32 v26, 0, v10
	v_max_f32_e32 v27, 0, v11
	v_max_f32_e32 v10, 0, v12
	v_mul_f32_e32 v28, v31, v10
	v_max_f32_e32 v37, 0, v13
	s_waitcnt lgkmcnt(0)
	v_mfma_f32_16x16x32_bf16 v[10:13], v[248:251], v[22:25], v[14:17]
	ds_read_b128 v[22:25], v222
	v_pk_mul_f32 v[36:37], v[30:31], v[36:37]
	s_nop 0
	ds_read_b128 v[14:17], v219
	s_waitcnt lgkmcnt(0)
	v_mfma_f32_16x16x32_bf16 v[14:17], v[244:247], v[14:17], 0
	s_nop 1
	v_max_f32_e32 v40, 0, v10
	v_max_f32_e32 v41, 0, v11
	v_max_f32_e32 v10, 0, v12
	v_mul_f32_e32 v42, v38, v10
	s_nop 0
	v_max_f32_e32 v44, 0, v13
	v_mfma_f32_16x16x32_bf16 v[10:13], v[248:251], v[22:25], v[14:17]
	ds_read_b128 v[22:25], v226
	v_mov_b32_e32 v35, v36
	v_mov_b32_e32 v29, v37
	ds_read_b128 v[14:17], v225
	s_waitcnt lgkmcnt(0)
	v_mfma_f32_16x16x32_bf16 v[14:17], v[244:247], v[14:17], 0
	s_nop 1
	v_max_f32_e32 v46, 0, v10
	v_max_f32_e32 v47, 0, v11
	v_max_f32_e32 v10, 0, v12
	v_mul_f32_e32 v48, v39, v10
	s_nop 0
	v_max_f32_e32 v45, 0, v13
	v_mfma_f32_16x16x32_bf16 v[10:13], v[248:251], v[22:25], v[14:17]
	ds_read_b128 v[22:25], v228
	v_pk_mul_f32 v[44:45], v[38:39], v[44:45]
	s_nop 0
	ds_read_b128 v[14:17], v227
	s_waitcnt lgkmcnt(0)
	v_mfma_f32_16x16x32_bf16 v[14:17], v[244:247], v[14:17], 0
	s_nop 1
	v_max_f32_e32 v52, 0, v10
	v_max_f32_e32 v53, 0, v11
	v_max_f32_e32 v10, 0, v12
	v_mul_f32_e32 v160, v50, v10
	s_nop 0
	v_max_f32_e32 v162, 0, v13
	v_mfma_f32_16x16x32_bf16 v[10:13], v[248:251], v[22:25], v[14:17]
	ds_read_b128 v[22:25], v230
	v_mov_b32_e32 v43, v44
	v_mov_b32_e32 v49, v45
	ds_read_b128 v[14:17], v229
	s_waitcnt lgkmcnt(0)
	v_mfma_f32_16x16x32_bf16 v[14:17], v[244:247], v[14:17], 0
	s_nop 1
	v_max_f32_e32 v164, 0, v10
	v_max_f32_e32 v165, 0, v11
	v_max_f32_e32 v10, 0, v12
	v_mul_f32_e32 v166, v51, v10
	s_nop 0
	v_max_f32_e32 v163, 0, v13
	v_mfma_f32_16x16x32_bf16 v[10:13], v[248:251], v[22:25], v[14:17]
	ds_read_b128 v[22:25], v232
	v_pk_mul_f32 v[162:163], v[50:51], v[162:163]
	s_nop 0
	ds_read_b128 v[14:17], v231
	s_waitcnt lgkmcnt(0)
; #define LAS __attribute__((address_space(3)))
; __device__ __forceinline__ unsigned fkey(float f) { const unsigned u = __float_as_uint(f); return (u & 0x80000000u) ? ~u : (u | 0x80000000u); }
; #define SEL_HADD(idx_) __hip_atomic_fetch_add(&hist[(idx_)], 1u, __ATOMIC_RELAXED, __HIP_MEMORY_SCOPE_WORKGROUP)
; __device__ __forceinline__ void sel_unit(LAS char* lds, int b, int u, const bf16_t* QI, const bf16_t* KIDX, const float* WIDX, unsigned long long* MASK) {
;     ...
;     for (int j = 0; j < 8; ++j) {
;         if (j < nj) {
;             int t = wid + 8 * j; asm volatile("" : "+s"(t));
; #pragma unroll
;             for (int kh = 0; kh < 2; ++kh) {
;             bf16x8 kf[2][2];
; #pragma unroll
;             for (int kb = 0; kb < 2; ++kb)
; #pragma unroll
;                 for (int ks = 0; ks < 2; ++ks) kf[kb][ks] = *(const bf16x8*)(KIDX + (rowbase + 64 * t + 32 * kh + 16 * kb + q16) * 64 + 32 * ks + 8 * kg);
; #pragma unroll
;             for (int kb = 0; kb < 2; ++kb) {
;                 f32x4 s = (f32x4){0.f, 0.f, 0.f, 0.f};
; #pragma unroll
;                 for (int hh = 0; hh < 8; ++hh) {
;                     f32x4 a = (f32x4){0.f, 0.f, 0.f, 0.f};
; #pragma unroll
;                     for (int ks = 0; ks < 2; ++ks) {
;                         const bf16x8 qv = *(const LAS bf16x8*)(lds + L_QI + q16 * 1024 + (((hh * 8 + 4 * ks + kg) ^ q16) << 4));
;                         a = __builtin_amdgcn_mfma_f32_16x16x32_bf16(kf[kb][ks], qv, a, 0, 0, 0);
;                     }
;                     const float wh = wl[hh * 16];
; #pragma unroll
;                     for (int i = 0; i < 4; ++i) s[i] += wh * fmaxf(a[i], 0.f);
;                 }
;                 u32x4 kk; kk.x = fkey(s[0]); kk.y = fkey(s[1]); kk.z = fkey(s[2]); kk.w = fkey(s[3]);
;                 sc[j][2 * kh + kb] = kk;
; #pragma unroll
;                 for (int i = 0; i < 4; ++i) SEL_HADD((kk[i] >> 24) * 16 + q16);
;                 __builtin_amdgcn_sched_barrier(0);
	v_mfma_f32_16x16x32_bf16 v[6:9], v[244:247], v[14:17], 0
	s_nop 1
	s_nop 0
	v_max_f32_e32 v14, 0, v13
	s_nop 0
	v_mfma_f32_16x16x32_bf16 v[2:5], v[248:251], v[22:25], v[6:9]
	s_nop 0
	v_max_f32_e32 v10, 0, v10
	v_max_f32_e32 v11, 0, v11
	v_pk_fma_f32 v[8:9], v[30:31], v[32:33], 0 op_sel_hi:[0,1,0]
	s_nop 0
	s_nop 2
	v_max_f32_e32 v15, 0, v5
	v_pk_mul_f32 v[6:7], v[168:169], v[14:15]
	v_mov_b32_e32 v14, v31
	v_pk_fma_f32 v[8:9], v[14:15], v[26:27], v[8:9] op_sel_hi:[0,1,1]
	v_pk_fma_f32 v[8:9], v[38:39], v[40:41], v[8:9] op_sel_hi:[0,1,1]
	v_mov_b32_e32 v14, v39
	v_pk_fma_f32 v[8:9], v[14:15], v[46:47], v[8:9] op_sel_hi:[0,1,1]
	v_pk_fma_f32 v[8:9], v[50:51], v[52:53], v[8:9] op_sel_hi:[0,1,1]
	v_mov_b32_e32 v14, v51
	v_pk_fma_f32 v[8:9], v[14:15], v[164:165], v[8:9] op_sel_hi:[0,1,1]
	v_max_f32_e32 v2, 0, v2
	v_max_f32_e32 v3, 0, v3
	v_pk_fma_f32 v[8:9], v[168:169], v[10:11], v[8:9] op_sel_hi:[0,1,1]
	v_mov_b32_e32 v10, v169
	v_pk_fma_f32 v[2:3], v[10:11], v[2:3], v[8:9] op_sel_hi:[0,1,1]
	v_and_b32_e32 v9, 0x7fffffff, v3
	v_and_b32_e32 v8, 0x7fffffff, v2
	v_xor_b32_e32 v5, -1, v3
	v_pk_add_f32 v[8:9], v[8:9], 0 neg_lo:[1,1] neg_hi:[1,1]
	v_cmp_gt_i32_e32 vcc, 0, v3
	v_xor_b32_e32 v10, -1, v2
	v_mov_b32_e32 v161, v162
	v_cndmask_b32_e32 v199, v9, v5, vcc
	v_cmp_gt_i32_e32 vcc, 0, v2
	v_pk_add_f32 v[2:3], v[34:35], 0 op_sel_hi:[1,0]
	v_max_f32_e32 v12, 0, v12
	v_pk_add_f32 v[2:3], v[2:3], v[28:29]
	v_pk_add_f32 v[2:3], v[2:3], v[42:43]
	v_mov_b32_e32 v167, v163
	v_pk_add_f32 v[2:3], v[2:3], v[48:49]
	v_mul_f32_e32 v12, v168, v12
	v_pk_add_f32 v[2:3], v[2:3], v[160:161]
	v_max_f32_e32 v4, 0, v4
	v_pk_add_f32 v[2:3], v[2:3], v[166:167]
	v_mov_b32_e32 v13, v6
	v_mul_f32_e32 v4, v169, v4
	v_pk_add_f32 v[2:3], v[2:3], v[12:13]
	v_mov_b32_e32 v5, v7
	v_pk_add_f32 v[2:3], v[2:3], v[4:5]
	v_cndmask_b32_e32 v218, v8, v10, vcc
	v_and_b32_e32 v5, 0x7fffffff, v3
	v_and_b32_e32 v4, 0x7fffffff, v2
	v_xor_b32_e32 v6, -1, v3
	v_pk_add_f32 v[4:5], v[4:5], 0 neg_lo:[1,1] neg_hi:[1,1]
	v_cmp_gt_i32_e32 vcc, 0, v3
	v_xor_b32_e32 v7, -1, v2
	s_nop 0
	v_cndmask_b32_e32 v219, v5, v6, vcc
	v_cmp_gt_i32_e32 vcc, 0, v2
	v_lshrrev_b32_e32 v2, 24, v218
	v_lshl_add_u32 v2, v2, 6, v0
	ds_add_u32 v2, v205 offset:16384
	v_lshrrev_b32_e32 v2, 24, v199
	v_cndmask_b32_e32 v220, v4, v7, vcc
	v_lshl_add_u32 v2, v2, 6, v0
	ds_add_u32 v2, v205 offset:16384
	v_lshrrev_b32_e32 v2, 24, v220
	v_lshl_add_u32 v2, v2, 6, v0
	ds_add_u32 v2, v205 offset:16384
	v_lshrrev_b32_e32 v2, 24, v219
	v_lshl_add_u32 v2, v2, 6, v0
	ds_add_u32 v2, v205 offset:16384
.LBB0_670:
	s_cmp_gt_i32 s4, 7
	s_cselect_b64 s[26:27], -1, 0
	s_cmp_lt_i32 s4, 8
	s_cbranch_scc1 .LBB0_672
	s_add_i32 s2, s46, 56
	s_lshl_b32 s2, s2, 6
	s_ashr_i32 s3, s2, 31
	v_lshl_add_u64 v[2:3], v[18:19], 0, s[2:3]
	v_lshlrev_b64 v[2:3], 7, v[2:3]
	v_lshl_add_u64 v[18:19], v[20:21], 0, v[2:3]
	global_load_dwordx4 v[14:17], v[18:19], off
	global_load_dwordx4 v[10:13], v[18:19], off offset:64
	v_lshl_add_u32 v229, v182, 4, v150
	v_lshl_add_u32 v230, v183, 4, v150
	v_lshl_add_u32 v183, v184, 4, v150
	v_lshl_add_u32 v184, v185, 4, v150
	v_lshl_add_u32 v182, v179, 4, v150
	v_lshl_add_u32 v179, v180, 4, v150
	v_lshl_add_u32 v159, v159, 4, v150
	ds_read_b128 v[2:5], v229
	ds_read_b128 v[6:9], v230
	ds_read_b128 v[20:23], v183
	v_lshl_add_u32 v176, v176, 4, v150
	ds_read_b128 v[24:27], v184
	ds_read_b128 v[28:31], v182
	ds_read_b128 v[32:35], v179
	ds_read_b128 v[36:39], v176
	v_lshl_add_u32 v158, v158, 4, v150
	ds_read_b128 v[40:43], v159
	ds_read_b128 v[44:47], v158
	v_lshl_add_u32 v157, v157, 4, v150
	ds_read_b128 v[48:51], v157
	v_lshl_add_u32 v156, v156, 4, v150
	v_lshl_add_u32 v155, v155, 4, v150
	ds_read_b128 v[160:163], v156
	ds_read_b128 v[164:167], v155
	v_lshl_add_u32 v154, v154, 4, v150
	v_lshl_add_u32 v153, v153, 4, v150
	v_lshl_add_u32 v152, v152, 4, v150
	v_lshl_add_u32 v150, v151, 4, v150
	s_waitcnt vmcnt(1) lgkmcnt(11)
	v_mfma_f32_16x16x32_bf16 v[2:5], v[14:17], v[2:5], 0
	s_waitcnt lgkmcnt(9)
	v_mfma_f32_16x16x32_bf16 v[20:23], v[14:17], v[20:23], 0
	s_waitcnt lgkmcnt(7)
	v_mfma_f32_16x16x32_bf16 v[28:31], v[14:17], v[28:31], 0
	s_waitcnt lgkmcnt(5)
	v_mfma_f32_16x16x32_bf16 v[36:39], v[14:17], v[36:39], 0
	s_waitcnt lgkmcnt(3)
	v_mfma_f32_16x16x32_bf16 v[44:47], v[14:17], v[44:47], 0
	s_waitcnt vmcnt(0)
	v_mfma_f32_16x16x32_bf16 v[168:171], v[10:13], v[6:9], v[2:5]
	v_mfma_f32_16x16x32_bf16 v[20:23], v[10:13], v[24:27], v[20:23]
	v_mfma_f32_16x16x32_bf16 v[24:27], v[10:13], v[32:35], v[28:31]
	v_mfma_f32_16x16x32_bf16 v[28:31], v[10:13], v[40:43], v[36:39]
	ds_read2_b32 v[40:41], v137 offset0:80 offset1:96
	ds_read2_b32 v[42:43], v137 offset0:112 offset1:128
	s_nop 3
	s_waitcnt lgkmcnt(4)
	v_mfma_f32_16x16x32_bf16 v[32:35], v[10:13], v[48:51], v[44:47]
	ds_read2_b32 v[44:45], v137 offset0:144 offset1:160
	global_load_dwordx4 v[6:9], v[18:19], off offset:2048
	global_load_dwordx4 v[2:5], v[18:19], off offset:2112
	v_mov_b32_e32 v252, 0x1000
	v_mov_b32_e32 v253, 0
	v_lshl_add_u64 v[252:253], v[252:253], 0, v[18:19]
	global_load_dwordx4 v[236:239], v[252:253], off
	global_load_dwordx4 v[240:243], v[252:253], off offset:64
	global_load_dwordx4 v[244:247], v[252:253], off offset:2048
	global_load_dwordx4 v[248:251], v[252:253], off offset:2112
	s_waitcnt lgkmcnt(4)
	v_mfma_f32_16x16x32_bf16 v[160:163], v[14:17], v[160:163], 0
	s_nop 0
	s_nop 0
	v_max_f32_e32 v50, v20, v20
	s_waitcnt lgkmcnt(3)
; #define LAS __attribute__((address_space(3)))
; __device__ __forceinline__ unsigned fkey(float f) { const unsigned u = __float_as_uint(f); return (u & 0x80000000u) ? ~u : (u | 0x80000000u); }
; #define SEL_HADD(idx_) __hip_atomic_fetch_add(&hist[(idx_)], 1u, __ATOMIC_RELAXED, __HIP_MEMORY_SCOPE_WORKGROUP)
; __device__ __forceinline__ void sel_unit(LAS char* lds, int b, int u, const bf16_t* QI, const bf16_t* KIDX, const float* WIDX, unsigned long long* MASK) {
;     ...
;     for (int j = 0; j < 8; ++j) {
;         if (j < nj) {
;             int t = wid + 8 * j; asm volatile("" : "+s"(t));
; #pragma unroll
;             for (int kh = 0; kh < 2; ++kh) {
;             bf16x8 kf[2][2];
; #pragma unroll
;             for (int kb = 0; kb < 2; ++kb)
; #pragma unroll
;                 for (int ks = 0; ks < 2; ++ks) kf[kb][ks] = *(const bf16x8*)(KIDX + (rowbase + 64 * t + 32 * kh + 16 * kb + q16) * 64 + 32 * ks + 8 * kg);
; #pragma unroll
;             for (int kb = 0; kb < 2; ++kb) {
;                 f32x4 s = (f32x4){0.f, 0.f, 0.f, 0.f};
; #pragma unroll
;                 for (int hh = 0; hh < 8; ++hh) {
;                     f32x4 a = (f32x4){0.f, 0.f, 0.f, 0.f};
; #pragma unroll
;                     for (int ks = 0; ks < 2; ++ks) {
;                         const bf16x8 qv = *(const LAS bf16x8*)(lds + L_QI + q16 * 1024 + (((hh * 8 + 4 * ks + kg) ^ q16) << 4));
;                         a = __builtin_amdgcn_mfma_f32_16x16x32_bf16(kf[kb][ks], qv, a, 0, 0, 0);
;                     }
;                     const float wh = wl[hh * 16];
; #pragma unroll
;                     for (int i = 0; i < 4; ++i) s[i] += wh * fmaxf(a[i], 0.f);
;                 }
;                 u32x4 kk; kk.x = fkey(s[0]); kk.y = fkey(s[1]); kk.z = fkey(s[2]); kk.w = fkey(s[3]);
;                 sc[j][2 * kh + kb] = kk;
; #pragma unroll
;                 for (int i = 0; i < 4; ++i) SEL_HADD((kk[i] >> 24) * 16 + q16);
;                 __builtin_amdgcn_sched_barrier(0);
	v_mfma_f32_16x16x32_bf16 v[36:39], v[10:13], v[164:167], v[160:163]
	s_nop 0
	v_max_f32_e32 v20, 0, v171
	v_max_f32_e32 v164, 0, v22
	v_max_f32_e32 v160, v35, v35
	v_max_f32_e32 v35, 0, v21
	s_nop 2
	v_max_f32_e32 v21, 0, v23
	v_max_f32_e32 v22, 0, v27
	v_max_f32_e32 v23, 0, v31
	v_max_f32_e32 v51, v32, v32
	v_max_f32_e32 v53, v34, v34
	v_max_f32_e32 v32, 0, v168
	v_max_f32_e32 v34, 0, v50
	v_max_f32_e32 v46, 0, v28
	v_max_f32_e32 v28, 0, v160
	v_max_f32_e32 v50, 0, v36
	s_waitcnt lgkmcnt(2)
	v_pk_mul_f32 v[160:161], v[40:41], v[20:21]
	s_waitcnt lgkmcnt(1)
	v_pk_mul_f32 v[166:167], v[42:43], v[22:23]
	ds_read_b128 v[20:23], v154
	v_max_f32_e32 v162, v37, v37
	v_max_f32_e32 v163, v38, v38
	v_max_f32_e32 v36, 0, v24
	v_max_f32_e32 v24, 0, v26
	v_max_f32_e32 v38, 0, v170
	v_max_f32_e32 v37, 0, v25
	v_max_f32_e32 v25, 0, v30
	v_max_f32_e32 v48, 0, v51
	v_max_f32_e32 v26, 0, v53
	v_max_f32_e32 v51, 0, v162
	v_mul_f32_e32 v162, v42, v24
	v_max_f32_e32 v24, 0, v163
	v_max_f32_e32 v49, 0, v33
	v_mul_f32_e32 v52, v41, v164
	v_mul_f32_e32 v164, v43, v25
	s_waitcnt lgkmcnt(1)
	v_mul_f32_e32 v168, v44, v26
	v_mul_f32_e32 v170, v45, v24
	ds_read_b128 v[24:27], v153
	s_waitcnt lgkmcnt(1)
	v_mfma_f32_16x16x32_bf16 v[20:23], v[14:17], v[20:23], 0
	v_max_f32_e32 v33, 0, v169
	s_waitcnt lgkmcnt(0)
	v_mfma_f32_16x16x32_bf16 v[20:23], v[10:13], v[24:27], v[20:23]
	ds_read_b128 v[24:27], v152
	v_max_f32_e32 v47, 0, v29
	v_max_f32_e32 v29, 0, v39
	v_pk_mul_f32 v[172:173], v[44:45], v[28:29]
	ds_read_b128 v[28:31], v150
	s_waitcnt lgkmcnt(1)
	v_mfma_f32_16x16x32_bf16 v[14:17], v[14:17], v[24:27], 0
	ds_read2_b32 v[174:175], v137 offset0:176 offset1:192
	s_nop 0
	v_max_f32_e32 v24, 0, v23
	s_waitcnt lgkmcnt(1)
	v_mfma_f32_16x16x32_bf16 v[10:13], v[10:13], v[28:31], v[14:17]
	s_nop 0
	s_nop 0
	v_max_f32_e32 v20, 0, v20
	v_pk_fma_f32 v[16:17], v[40:41], v[32:33], 0 op_sel_hi:[0,1,0]
	v_max_f32_e32 v21, 0, v21
	s_nop 2
	v_max_f32_e32 v25, 0, v13
	s_waitcnt lgkmcnt(0)
	v_pk_mul_f32 v[14:15], v[174:175], v[24:25]
	v_mov_b32_e32 v24, v41
	v_pk_fma_f32 v[16:17], v[24:25], v[34:35], v[16:17] op_sel_hi:[0,1,1]
	v_pk_fma_f32 v[16:17], v[42:43], v[36:37], v[16:17] op_sel_hi:[0,1,1]
	v_mov_b32_e32 v24, v43
	v_pk_fma_f32 v[16:17], v[24:25], v[46:47], v[16:17] op_sel_hi:[0,1,1]
	v_pk_fma_f32 v[16:17], v[44:45], v[48:49], v[16:17] op_sel_hi:[0,1,1]
	v_mov_b32_e32 v24, v45
	v_pk_fma_f32 v[16:17], v[24:25], v[50:51], v[16:17] op_sel_hi:[0,1,1]
	v_max_f32_e32 v10, 0, v10
	v_max_f32_e32 v11, 0, v11
	v_pk_fma_f32 v[16:17], v[174:175], v[20:21], v[16:17] op_sel_hi:[0,1,1]
	v_mov_b32_e32 v20, v175
	v_pk_fma_f32 v[10:11], v[20:21], v[10:11], v[16:17] op_sel_hi:[0,1,1]
	v_and_b32_e32 v17, 0x7fffffff, v11
	v_and_b32_e32 v16, 0x7fffffff, v10
	v_mul_f32_e32 v38, v40, v38
	v_xor_b32_e32 v13, -1, v11
	v_pk_add_f32 v[16:17], v[16:17], 0 neg_lo:[1,1] neg_hi:[1,1]
	v_cmp_gt_i32_e32 vcc, 0, v11
	v_mov_b32_e32 v39, v160
	v_xor_b32_e32 v20, -1, v10
	v_cndmask_b32_e32 v221, v17, v13, vcc
	v_cmp_gt_i32_e32 vcc, 0, v10
	v_pk_add_f32 v[10:11], v[38:39], 0 op_sel_hi:[1,0]
	v_mov_b32_e32 v53, v161
	v_pk_add_f32 v[10:11], v[10:11], v[52:53]
	v_mov_b32_e32 v163, v166
	v_pk_add_f32 v[10:11], v[10:11], v[162:163]
	v_mov_b32_e32 v165, v167
	v_pk_add_f32 v[10:11], v[10:11], v[164:165]
	v_mov_b32_e32 v169, v172
	v_max_f32_e32 v22, 0, v22
	v_pk_add_f32 v[10:11], v[10:11], v[168:169]
	v_mov_b32_e32 v171, v173
	v_mul_f32_e32 v22, v174, v22
	v_max_f32_e32 v12, 0, v12
	v_pk_add_f32 v[10:11], v[10:11], v[170:171]
	v_mov_b32_e32 v23, v14
	v_mul_f32_e32 v12, v175, v12
	v_pk_add_f32 v[10:11], v[10:11], v[22:23]
	v_mov_b32_e32 v13, v15
	v_pk_add_f32 v[10:11], v[10:11], v[12:13]
	v_cndmask_b32_e32 v222, v16, v20, vcc
	v_and_b32_e32 v13, 0x7fffffff, v11
	v_and_b32_e32 v12, 0x7fffffff, v10
	v_xor_b32_e32 v14, -1, v11
	v_pk_add_f32 v[12:13], v[12:13], 0 neg_lo:[1,1] neg_hi:[1,1]
	v_cmp_gt_i32_e32 vcc, 0, v11
	v_xor_b32_e32 v15, -1, v10
	s_nop 0
	v_cndmask_b32_e32 v223, v13, v14, vcc
	v_cmp_gt_i32_e32 vcc, 0, v10
	v_lshrrev_b32_e32 v10, 24, v222
	v_lshl_add_u32 v10, v10, 6, v0
	ds_add_u32 v10, v205 offset:16384
	v_lshrrev_b32_e32 v10, 24, v221
	v_cndmask_b32_e32 v224, v12, v15, vcc
	v_lshl_add_u32 v10, v10, 6, v0
	ds_add_u32 v10, v205 offset:16384
	v_lshrrev_b32_e32 v10, 24, v224
	v_lshl_add_u32 v10, v10, 6, v0
	ds_add_u32 v10, v205 offset:16384
	v_lshrrev_b32_e32 v10, 24, v223
	v_lshl_add_u32 v10, v10, 6, v0
	ds_add_u32 v10, v205 offset:16384
	ds_read_b128 v[10:13], v229
	ds_read_b128 v[14:17], v230
	ds_read_b128 v[20:23], v183
	ds_read_b128 v[24:27], v184
	ds_read2_b32 v[28:29], v137 offset0:80 offset1:96
	ds_read2_b32 v[36:37], v137 offset0:112 offset1:128
	s_waitcnt vmcnt(5) lgkmcnt(5)
	v_mfma_f32_16x16x32_bf16 v[10:13], v[6:9], v[10:13], 0
	ds_read2_b32 v[48:49], v137 offset0:144 offset1:160
	ds_read2_b32 v[166:167], v137 offset0:176 offset1:192
	s_waitcnt vmcnt(4) lgkmcnt(6)
	v_mfma_f32_16x16x32_bf16 v[10:13], v[2:5], v[14:17], v[10:13]
	ds_read_b128 v[14:17], v182
	s_waitcnt lgkmcnt(6)
	v_mfma_f32_16x16x32_bf16 v[20:23], v[6:9], v[20:23], 0
	s_nop 4
	v_max_f32_e32 v30, 0, v10
	v_max_f32_e32 v10, 0, v12
	v_max_f32_e32 v31, 0, v11
	s_waitcnt lgkmcnt(4)
	v_mul_f32_e32 v32, v28, v10
	v_max_f32_e32 v34, 0, v13
	v_mfma_f32_16x16x32_bf16 v[10:13], v[2:5], v[24:27], v[20:23]
	s_nop 2
	ds_read_b128 v[20:23], v179
	s_waitcnt lgkmcnt(1)
	v_mfma_f32_16x16x32_bf16 v[14:17], v[6:9], v[14:17], 0
	s_nop 1
	v_max_f32_e32 v24, 0, v10
	v_max_f32_e32 v25, 0, v11
	v_max_f32_e32 v10, 0, v12
	v_mul_f32_e32 v26, v29, v10
	v_max_f32_e32 v35, 0, v13
	s_waitcnt lgkmcnt(0)
; #define LAS __attribute__((address_space(3)))
; __device__ __forceinline__ unsigned fkey(float f) { const unsigned u = __float_as_uint(f); return (u & 0x80000000u) ? ~u : (u | 0x80000000u); }
; #define SEL_HADD(idx_) __hip_atomic_fetch_add(&hist[(idx_)], 1u, __ATOMIC_RELAXED, __HIP_MEMORY_SCOPE_WORKGROUP)
; __device__ __forceinline__ void sel_unit(LAS char* lds, int b, int u, const bf16_t* QI, const bf16_t* KIDX, const float* WIDX, unsigned long long* MASK) {
;     ...
;     for (int j = 0; j < 8; ++j) {
;         if (j < nj) {
;             int t = wid + 8 * j; asm volatile("" : "+s"(t));
; #pragma unroll
;             for (int kh = 0; kh < 2; ++kh) {
;             bf16x8 kf[2][2];
; #pragma unroll
;             for (int kb = 0; kb < 2; ++kb)
; #pragma unroll
;                 for (int ks = 0; ks < 2; ++ks) kf[kb][ks] = *(const bf16x8*)(KIDX + (rowbase + 64 * t + 32 * kh + 16 * kb + q16) * 64 + 32 * ks + 8 * kg);
; #pragma unroll
;             for (int kb = 0; kb < 2; ++kb) {
;                 f32x4 s = (f32x4){0.f, 0.f, 0.f, 0.f};
; #pragma unroll
;                 for (int hh = 0; hh < 8; ++hh) {
;                     f32x4 a = (f32x4){0.f, 0.f, 0.f, 0.f};
; #pragma unroll
;                     for (int ks = 0; ks < 2; ++ks) {
;                         const bf16x8 qv = *(const LAS bf16x8*)(lds + L_QI + q16 * 1024 + (((hh * 8 + 4 * ks + kg) ^ q16) << 4));
;                         a = __builtin_amdgcn_mfma_f32_16x16x32_bf16(kf[kb][ks], qv, a, 0, 0, 0);
;                     }
;                     const float wh = wl[hh * 16];
; #pragma unroll
;                     for (int i = 0; i < 4; ++i) s[i] += wh * fmaxf(a[i], 0.f);
;                 }
;                 u32x4 kk; kk.x = fkey(s[0]); kk.y = fkey(s[1]); kk.z = fkey(s[2]); kk.w = fkey(s[3]);
;                 sc[j][2 * kh + kb] = kk;
; #pragma unroll
;                 for (int i = 0; i < 4; ++i) SEL_HADD((kk[i] >> 24) * 16 + q16);
;                 __builtin_amdgcn_sched_barrier(0);
	v_mfma_f32_16x16x32_bf16 v[10:13], v[2:5], v[20:23], v[14:17]
	ds_read_b128 v[20:23], v159
	v_pk_mul_f32 v[34:35], v[28:29], v[34:35]
	s_nop 0
	ds_read_b128 v[14:17], v176
	s_waitcnt lgkmcnt(0)
	v_mfma_f32_16x16x32_bf16 v[14:17], v[6:9], v[14:17], 0
	s_nop 1
	v_max_f32_e32 v38, 0, v10
	v_max_f32_e32 v39, 0, v11
	v_max_f32_e32 v10, 0, v12
	v_mul_f32_e32 v40, v36, v10
	s_nop 0
	v_max_f32_e32 v42, 0, v13
	v_mfma_f32_16x16x32_bf16 v[10:13], v[2:5], v[20:23], v[14:17]
	ds_read_b128 v[20:23], v157
	v_mov_b32_e32 v33, v34
	v_mov_b32_e32 v27, v35
	ds_read_b128 v[14:17], v158
	s_waitcnt lgkmcnt(0)
	v_mfma_f32_16x16x32_bf16 v[14:17], v[6:9], v[14:17], 0
	s_nop 1
	v_max_f32_e32 v44, 0, v10
	v_max_f32_e32 v45, 0, v11
	v_max_f32_e32 v10, 0, v12
	v_mul_f32_e32 v46, v37, v10
	s_nop 0
	v_max_f32_e32 v43, 0, v13
	v_mfma_f32_16x16x32_bf16 v[10:13], v[2:5], v[20:23], v[14:17]
	ds_read_b128 v[20:23], v155
	v_pk_mul_f32 v[42:43], v[36:37], v[42:43]
	s_nop 0
	ds_read_b128 v[14:17], v156
	s_waitcnt lgkmcnt(0)
	v_mfma_f32_16x16x32_bf16 v[14:17], v[6:9], v[14:17], 0
	s_nop 1
	v_max_f32_e32 v50, 0, v10
	v_max_f32_e32 v51, 0, v11
	v_max_f32_e32 v10, 0, v12
	v_mul_f32_e32 v52, v48, v10
	s_nop 0
	v_max_f32_e32 v160, 0, v13
	v_mfma_f32_16x16x32_bf16 v[10:13], v[2:5], v[20:23], v[14:17]
	ds_read_b128 v[20:23], v153
	v_mov_b32_e32 v41, v42
	v_mov_b32_e32 v47, v43
	ds_read_b128 v[14:17], v154
	s_waitcnt lgkmcnt(0)
	v_mfma_f32_16x16x32_bf16 v[14:17], v[6:9], v[14:17], 0
	s_nop 1
	v_max_f32_e32 v162, 0, v10
	v_max_f32_e32 v163, 0, v11
	v_max_f32_e32 v10, 0, v12
	v_mul_f32_e32 v164, v49, v10
	s_nop 0
	v_max_f32_e32 v161, 0, v13
	v_mfma_f32_16x16x32_bf16 v[10:13], v[2:5], v[20:23], v[14:17]
	ds_read_b128 v[20:23], v150
	v_pk_mul_f32 v[160:161], v[48:49], v[160:161]
	s_nop 0
	ds_read_b128 v[14:17], v152
	s_waitcnt lgkmcnt(0)
	v_mfma_f32_16x16x32_bf16 v[6:9], v[6:9], v[14:17], 0
	s_nop 1
	s_nop 0
	v_max_f32_e32 v14, 0, v13
	s_nop 0
	v_mfma_f32_16x16x32_bf16 v[2:5], v[2:5], v[20:23], v[6:9]
	s_nop 0
	v_max_f32_e32 v10, 0, v10
	v_max_f32_e32 v11, 0, v11
	v_pk_fma_f32 v[8:9], v[28:29], v[30:31], 0 op_sel_hi:[0,1,0]
	s_nop 0
	s_nop 2
	v_max_f32_e32 v15, 0, v5
	v_pk_mul_f32 v[6:7], v[166:167], v[14:15]
	v_mov_b32_e32 v14, v29
	v_pk_fma_f32 v[8:9], v[14:15], v[24:25], v[8:9] op_sel_hi:[0,1,1]
	v_pk_fma_f32 v[8:9], v[36:37], v[38:39], v[8:9] op_sel_hi:[0,1,1]
	v_mov_b32_e32 v14, v37
	v_pk_fma_f32 v[8:9], v[14:15], v[44:45], v[8:9] op_sel_hi:[0,1,1]
	v_pk_fma_f32 v[8:9], v[48:49], v[50:51], v[8:9] op_sel_hi:[0,1,1]
	v_mov_b32_e32 v14, v49
	v_pk_fma_f32 v[8:9], v[14:15], v[162:163], v[8:9] op_sel_hi:[0,1,1]
	v_max_f32_e32 v2, 0, v2
	v_max_f32_e32 v3, 0, v3
	v_pk_fma_f32 v[8:9], v[166:167], v[10:11], v[8:9] op_sel_hi:[0,1,1]
	v_mov_b32_e32 v10, v167
	v_pk_fma_f32 v[2:3], v[10:11], v[2:3], v[8:9] op_sel_hi:[0,1,1]
	v_and_b32_e32 v9, 0x7fffffff, v3
	v_and_b32_e32 v8, 0x7fffffff, v2
	v_xor_b32_e32 v5, -1, v3
	v_pk_add_f32 v[8:9], v[8:9], 0 neg_lo:[1,1] neg_hi:[1,1]
	v_cmp_gt_i32_e32 vcc, 0, v3
	v_xor_b32_e32 v10, -1, v2
	v_mov_b32_e32 v53, v160
	v_cndmask_b32_e32 v225, v9, v5, vcc
	v_cmp_gt_i32_e32 vcc, 0, v2
	v_pk_add_f32 v[2:3], v[32:33], 0 op_sel_hi:[1,0]
	v_max_f32_e32 v12, 0, v12
	v_pk_add_f32 v[2:3], v[2:3], v[26:27]
	v_pk_add_f32 v[2:3], v[2:3], v[40:41]
	v_mov_b32_e32 v165, v161
	v_pk_add_f32 v[2:3], v[2:3], v[46:47]
	v_mul_f32_e32 v12, v166, v12
	v_pk_add_f32 v[2:3], v[2:3], v[52:53]
	v_max_f32_e32 v4, 0, v4
	v_pk_add_f32 v[2:3], v[2:3], v[164:165]
	v_mov_b32_e32 v13, v6
	v_mul_f32_e32 v4, v167, v4
	v_pk_add_f32 v[2:3], v[2:3], v[12:13]
	v_mov_b32_e32 v5, v7
	v_pk_add_f32 v[2:3], v[2:3], v[4:5]
	v_cndmask_b32_e32 v226, v8, v10, vcc
	v_and_b32_e32 v5, 0x7fffffff, v3
	v_and_b32_e32 v4, 0x7fffffff, v2
	v_xor_b32_e32 v6, -1, v3
	v_pk_add_f32 v[4:5], v[4:5], 0 neg_lo:[1,1] neg_hi:[1,1]
	v_cmp_gt_i32_e32 vcc, 0, v3
	v_xor_b32_e32 v7, -1, v2
	s_nop 0
	v_cndmask_b32_e32 v227, v5, v6, vcc
	v_cmp_gt_i32_e32 vcc, 0, v2
	v_lshrrev_b32_e32 v2, 24, v226
	v_lshl_add_u32 v2, v2, 6, v0
	ds_add_u32 v2, v205 offset:16384
	v_lshrrev_b32_e32 v2, 24, v225
	v_cndmask_b32_e32 v228, v4, v7, vcc
	v_lshl_add_u32 v2, v2, 6, v0
	ds_add_u32 v2, v205 offset:16384
	v_lshrrev_b32_e32 v2, 24, v228
	v_lshl_add_u32 v2, v2, 6, v0
	ds_add_u32 v2, v205 offset:16384
	v_lshrrev_b32_e32 v2, 24, v227
	v_lshl_add_u32 v2, v2, 6, v0
	ds_add_u32 v2, v205 offset:16384
	ds_read_b128 v[18:21], v229
	ds_read_b128 v[22:25], v230
	s_waitcnt vmcnt(3) lgkmcnt(1)
	v_mfma_f32_16x16x32_bf16 v[18:21], v[236:239], v[18:21], 0
	ds_read_b128 v[28:31], v184
	ds_read_b128 v[34:37], v179
	ds_read_b128 v[40:43], v159
	s_waitcnt vmcnt(2) lgkmcnt(3)
	v_mfma_f32_16x16x32_bf16 v[22:25], v[240:243], v[22:25], v[18:21]
	ds_read_b128 v[46:49], v157
	ds_read_b128 v[160:163], v155
	s_nop 0
	ds_read2_b32 v[20:21], v137 offset0:80 offset1:96
	s_nop 3
	v_max_f32_e32 v22, 0, v22
	v_max_f32_e32 v23, 0, v23
	v_max_f32_e32 v18, v24, v24
	v_max_f32_e32 v19, v25, v25
	ds_read_b128 v[24:27], v183
	s_waitcnt lgkmcnt(0)
	v_mfma_f32_16x16x32_bf16 v[24:27], v[236:239], v[24:27], 0
	v_max_f32_e32 v32, 0, v19
	v_max_f32_e32 v18, 0, v18
	v_mul_f32_e32 v18, v20, v18
	v_mfma_f32_16x16x32_bf16 v[24:27], v[240:243], v[28:31], v[24:27]
	s_nop 7
	v_max_f32_e32 v28, 0, v24
	v_max_f32_e32 v29, 0, v25
	v_max_f32_e32 v19, 0, v26
	v_mul_f32_e32 v24, v21, v19
	v_max_f32_e32 v33, 0, v27
	v_pk_mul_f32 v[26:27], v[20:21], v[32:33]
	ds_read_b128 v[30:33], v182
	s_waitcnt lgkmcnt(0)
	v_mfma_f32_16x16x32_bf16 v[30:33], v[236:239], v[30:33], 0
	v_mov_b32_e32 v25, v27
	v_mfma_f32_16x16x32_bf16 v[34:37], v[240:243], v[34:37], v[30:33]
	s_nop 5
	ds_read2_b32 v[32:33], v137 offset0:112 offset1:128
	s_nop 0
	v_max_f32_e32 v34, 0, v34
	v_max_f32_e32 v35, 0, v35
	v_max_f32_e32 v19, 0, v36
	s_waitcnt lgkmcnt(0)
; #define LAS __attribute__((address_space(3)))
; __device__ __forceinline__ unsigned fkey(float f) { const unsigned u = __float_as_uint(f); return (u & 0x80000000u) ? ~u : (u | 0x80000000u); }
; #define SEL_HADD(idx_) __hip_atomic_fetch_add(&hist[(idx_)], 1u, __ATOMIC_RELAXED, __HIP_MEMORY_SCOPE_WORKGROUP)
; __device__ __forceinline__ void sel_unit(LAS char* lds, int b, int u, const bf16_t* QI, const bf16_t* KIDX, const float* WIDX, unsigned long long* MASK) {
;     ...
;     for (int j = 0; j < 8; ++j) {
;         if (j < nj) {
;             int t = wid + 8 * j; asm volatile("" : "+s"(t));
; #pragma unroll
;             for (int kh = 0; kh < 2; ++kh) {
;             bf16x8 kf[2][2];
; #pragma unroll
;             for (int kb = 0; kb < 2; ++kb)
; #pragma unroll
;                 for (int ks = 0; ks < 2; ++ks) kf[kb][ks] = *(const bf16x8*)(KIDX + (rowbase + 64 * t + 32 * kh + 16 * kb + q16) * 64 + 32 * ks + 8 * kg);
; #pragma unroll
;             for (int kb = 0; kb < 2; ++kb) {
;                 f32x4 s = (f32x4){0.f, 0.f, 0.f, 0.f};
; #pragma unroll
;                 for (int hh = 0; hh < 8; ++hh) {
;                     f32x4 a = (f32x4){0.f, 0.f, 0.f, 0.f};
; #pragma unroll
;                     for (int ks = 0; ks < 2; ++ks) {
;                         const bf16x8 qv = *(const LAS bf16x8*)(lds + L_QI + q16 * 1024 + (((hh * 8 + 4 * ks + kg) ^ q16) << 4));
;                         a = __builtin_amdgcn_mfma_f32_16x16x32_bf16(kf[kb][ks], qv, a, 0, 0, 0);
;                     }
;                     const float wh = wl[hh * 16];
; #pragma unroll
;                     for (int i = 0; i < 4; ++i) s[i] += wh * fmaxf(a[i], 0.f);
;                 }
;                 u32x4 kk; kk.x = fkey(s[0]); kk.y = fkey(s[1]); kk.z = fkey(s[2]); kk.w = fkey(s[3]);
;                 sc[j][2 * kh + kb] = kk;
; #pragma unroll
;                 for (int i = 0; i < 4; ++i) SEL_HADD((kk[i] >> 24) * 16 + q16);
;                 __builtin_amdgcn_sched_barrier(0);
	v_mul_f32_e32 v30, v32, v19
	v_max_f32_e32 v19, v37, v37
	ds_read_b128 v[36:39], v176
	s_waitcnt lgkmcnt(0)
	v_mfma_f32_16x16x32_bf16 v[36:39], v[236:239], v[36:39], 0
	v_max_f32_e32 v44, 0, v19
	v_mfma_f32_16x16x32_bf16 v[36:39], v[240:243], v[40:43], v[36:39]
	s_nop 7
	v_max_f32_e32 v40, 0, v36
	v_max_f32_e32 v41, 0, v37
	v_max_f32_e32 v19, 0, v38
	v_mul_f32_e32 v36, v33, v19
	v_max_f32_e32 v45, 0, v39
	v_pk_mul_f32 v[38:39], v[32:33], v[44:45]
	ds_read_b128 v[42:45], v158
	s_waitcnt lgkmcnt(0)
	v_mfma_f32_16x16x32_bf16 v[42:45], v[236:239], v[42:45], 0
	v_mov_b32_e32 v31, v38
	v_mov_b32_e32 v37, v39
	v_mfma_f32_16x16x32_bf16 v[46:49], v[240:243], v[46:49], v[42:45]
	s_nop 4
	ds_read2_b32 v[44:45], v137 offset0:144 offset1:160
	s_nop 1
	v_max_f32_e32 v46, 0, v46
	v_max_f32_e32 v47, 0, v47
	v_max_f32_e32 v19, 0, v48
	s_waitcnt lgkmcnt(0)
	v_mul_f32_e32 v42, v44, v19
	v_max_f32_e32 v19, v49, v49
	ds_read_b128 v[48:51], v156
	s_waitcnt lgkmcnt(0)
	v_mfma_f32_16x16x32_bf16 v[48:51], v[236:239], v[48:51], 0
	v_max_f32_e32 v164, 0, v19
	v_mfma_f32_16x16x32_bf16 v[48:51], v[240:243], v[160:163], v[48:51]
	ds_read_b128 v[160:163], v154
	s_nop 6
	v_max_f32_e32 v52, 0, v48
	v_max_f32_e32 v53, 0, v49
	v_max_f32_e32 v19, 0, v50
	v_mul_f32_e32 v48, v45, v19
	v_max_f32_e32 v165, 0, v51
	v_pk_mul_f32 v[50:51], v[44:45], v[164:165]
	ds_read_b128 v[164:167], v153
	s_waitcnt lgkmcnt(1)
	v_mfma_f32_16x16x32_bf16 v[160:163], v[236:239], v[160:163], 0
	v_mov_b32_e32 v43, v50
	v_mov_b32_e32 v49, v51
	s_waitcnt lgkmcnt(0)
	v_mfma_f32_16x16x32_bf16 v[160:163], v[240:243], v[164:167], v[160:163]
	ds_read2_b32 v[164:165], v137 offset0:176 offset1:192
	s_nop 6
	v_max_f32_e32 v166, 0, v160
	v_max_f32_e32 v167, 0, v161
	v_max_f32_e32 v19, 0, v162
	s_waitcnt lgkmcnt(0)
	v_mul_f32_e32 v168, v164, v19
	v_max_f32_e32 v19, v163, v163
	ds_read_b128 v[160:163], v152
	s_waitcnt lgkmcnt(0)
	v_mfma_f32_16x16x32_bf16 v[14:17], v[236:239], v[160:163], 0
	ds_read_b128 v[160:163], v150
	v_max_f32_e32 v170, 0, v19
	s_waitcnt lgkmcnt(0)
	v_mfma_f32_16x16x32_bf16 v[10:13], v[240:243], v[160:163], v[14:17]
	s_nop 3
	v_fma_f32 v16, v20, v22, 0
	v_fma_f32 v17, v20, v23, 0
	v_mov_b32_e32 v20, v21
	v_pk_fma_f32 v[16:17], v[20:21], v[28:29], v[16:17] op_sel_hi:[0,1,1]
	v_pk_fma_f32 v[16:17], v[32:33], v[34:35], v[16:17] op_sel_hi:[0,1,1]
	v_mov_b32_e32 v20, v33
	v_pk_fma_f32 v[16:17], v[20:21], v[40:41], v[16:17] op_sel_hi:[0,1,1]
	v_pk_fma_f32 v[16:17], v[44:45], v[46:47], v[16:17] op_sel_hi:[0,1,1]
	v_mov_b32_e32 v20, v45
	v_pk_fma_f32 v[16:17], v[20:21], v[52:53], v[16:17] op_sel_hi:[0,1,1]
	v_max_f32_e32 v10, 0, v10
	v_max_f32_e32 v11, 0, v11
	v_pk_fma_f32 v[16:17], v[164:165], v[166:167], v[16:17] op_sel_hi:[0,1,1]
	v_mov_b32_e32 v20, v165
	v_pk_fma_f32 v[10:11], v[20:21], v[10:11], v[16:17] op_sel_hi:[0,1,1]
	v_and_b32_e32 v17, 0x7fffffff, v11
	v_and_b32_e32 v16, 0x7fffffff, v10
	v_xor_b32_e32 v19, -1, v10
	v_pk_add_f32 v[16:17], v[16:17], 0 neg_lo:[1,1] neg_hi:[1,1]
	v_cmp_gt_i32_e32 vcc, 0, v10
	v_max_f32_e32 v171, 0, v13
	v_xor_b32_e32 v13, -1, v11
	v_cmp_gt_i32_e64 s[2:3], 0, v11
	v_cndmask_b32_e32 v11, v16, v19, vcc
	v_mov_b32_e32 v19, v26
	v_cndmask_b32_e64 v10, v17, v13, s[2:3]
	v_pk_add_f32 v[16:17], v[18:19], 0 op_sel_hi:[1,0]
	v_pk_add_f32 v[16:17], v[16:17], v[24:25]
	v_pk_mul_f32 v[14:15], v[164:165], v[170:171]
	v_pk_add_f32 v[16:17], v[16:17], v[30:31]
	v_max_f32_e32 v12, 0, v12
	v_pk_add_f32 v[16:17], v[16:17], v[36:37]
	v_mov_b32_e32 v169, v14
	v_pk_add_f32 v[16:17], v[16:17], v[42:43]
	v_mul_f32_e32 v12, v165, v12
	v_pk_add_f32 v[16:17], v[16:17], v[48:49]
	v_mov_b32_e32 v13, v15
	v_pk_add_f32 v[16:17], v[16:17], v[168:169]
	s_nop 0
	v_pk_add_f32 v[12:13], v[16:17], v[12:13]
	s_nop 0
	v_and_b32_e32 v15, 0x7fffffff, v13
	v_and_b32_e32 v14, 0x7fffffff, v12
	v_xor_b32_e32 v17, -1, v12
	v_pk_add_f32 v[14:15], v[14:15], 0 neg_lo:[1,1] neg_hi:[1,1]
	v_cmp_gt_i32_e32 vcc, 0, v12
	v_xor_b32_e32 v16, -1, v13
	v_cmp_gt_i32_e64 s[2:3], 0, v13
	v_cndmask_b32_e32 v13, v14, v17, vcc
	v_lshrrev_b32_e32 v14, 24, v11
	v_lshl_add_u32 v14, v14, 6, v0
	ds_add_u32 v14, v205 offset:16384
	v_lshrrev_b32_e32 v14, 24, v10
	v_lshl_add_u32 v14, v14, 6, v0
	ds_add_u32 v14, v205 offset:16384
	v_lshrrev_b32_e32 v14, 24, v13
	v_cndmask_b32_e64 v12, v15, v16, s[2:3]
	v_lshl_add_u32 v14, v14, 6, v0
	ds_add_u32 v14, v205 offset:16384
	v_lshrrev_b32_e32 v14, 24, v12
	v_lshl_add_u32 v14, v14, 6, v0
	ds_add_u32 v14, v205 offset:16384
	ds_read_b128 v[14:17], v229
	ds_read_b128 v[18:21], v230
	ds_read_b128 v[22:25], v183
	ds_read_b128 v[26:29], v184
	ds_read2_b32 v[30:31], v137 offset0:80 offset1:96
	ds_read2_b32 v[38:39], v137 offset0:112 offset1:128
	s_waitcnt vmcnt(1) lgkmcnt(5)
	v_mfma_f32_16x16x32_bf16 v[14:17], v[244:247], v[14:17], 0
	ds_read2_b32 v[50:51], v137 offset0:144 offset1:160
	ds_read2_b32 v[162:163], v137 offset0:176 offset1:192
	s_waitcnt vmcnt(0) lgkmcnt(6)
	v_mfma_f32_16x16x32_bf16 v[14:17], v[248:251], v[18:21], v[14:17]
	ds_read_b128 v[18:21], v182
	s_waitcnt lgkmcnt(6)
; #define LAS __attribute__((address_space(3)))
; __device__ __forceinline__ unsigned fkey(float f) { const unsigned u = __float_as_uint(f); return (u & 0x80000000u) ? ~u : (u | 0x80000000u); }
; #define SEL_HADD(idx_) __hip_atomic_fetch_add(&hist[(idx_)], 1u, __ATOMIC_RELAXED, __HIP_MEMORY_SCOPE_WORKGROUP)
; __device__ __forceinline__ void sel_unit(LAS char* lds, int b, int u, const bf16_t* QI, const bf16_t* KIDX, const float* WIDX, unsigned long long* MASK) {
;     ...
;     for (int j = 0; j < 8; ++j) {
;         if (j < nj) {
;             int t = wid + 8 * j; asm volatile("" : "+s"(t));
; #pragma unroll
;             for (int kh = 0; kh < 2; ++kh) {
;             bf16x8 kf[2][2];
; #pragma unroll
;             for (int kb = 0; kb < 2; ++kb)
; #pragma unroll
;                 for (int ks = 0; ks < 2; ++ks) kf[kb][ks] = *(const bf16x8*)(KIDX + (rowbase + 64 * t + 32 * kh + 16 * kb + q16) * 64 + 32 * ks + 8 * kg);
; #pragma unroll
;             for (int kb = 0; kb < 2; ++kb) {
;                 f32x4 s = (f32x4){0.f, 0.f, 0.f, 0.f};
; #pragma unroll
;                 for (int hh = 0; hh < 8; ++hh) {
;                     f32x4 a = (f32x4){0.f, 0.f, 0.f, 0.f};
; #pragma unroll
;                     for (int ks = 0; ks < 2; ++ks) {
;                         const bf16x8 qv = *(const LAS bf16x8*)(lds + L_QI + q16 * 1024 + (((hh * 8 + 4 * ks + kg) ^ q16) << 4));
;                         a = __builtin_amdgcn_mfma_f32_16x16x32_bf16(kf[kb][ks], qv, a, 0, 0, 0);
;                     }
;                     const float wh = wl[hh * 16];
; #pragma unroll
;                     for (int i = 0; i < 4; ++i) s[i] += wh * fmaxf(a[i], 0.f);
;                 }
;                 u32x4 kk; kk.x = fkey(s[0]); kk.y = fkey(s[1]); kk.z = fkey(s[2]); kk.w = fkey(s[3]);
;                 sc[j][2 * kh + kb] = kk;
; #pragma unroll
;                 for (int i = 0; i < 4; ++i) SEL_HADD((kk[i] >> 24) * 16 + q16);
;                 __builtin_amdgcn_sched_barrier(0);
	v_mfma_f32_16x16x32_bf16 v[22:25], v[244:247], v[22:25], 0
	s_nop 4
	v_max_f32_e32 v32, 0, v14
	v_max_f32_e32 v14, 0, v16
	v_max_f32_e32 v33, 0, v15
	s_waitcnt lgkmcnt(4)
	v_mul_f32_e32 v34, v30, v14
	v_max_f32_e32 v36, 0, v17
	v_mfma_f32_16x16x32_bf16 v[14:17], v[248:251], v[26:29], v[22:25]
	s_nop 2
	ds_read_b128 v[22:25], v179
	s_waitcnt lgkmcnt(1)
	v_mfma_f32_16x16x32_bf16 v[18:21], v[244:247], v[18:21], 0
	s_nop 1
	v_max_f32_e32 v26, 0, v14
	v_max_f32_e32 v27, 0, v15
	v_max_f32_e32 v14, 0, v16
	v_mul_f32_e32 v28, v31, v14
	v_max_f32_e32 v37, 0, v17
	s_waitcnt lgkmcnt(0)
	v_mfma_f32_16x16x32_bf16 v[14:17], v[248:251], v[22:25], v[18:21]
	ds_read_b128 v[22:25], v159
	v_pk_mul_f32 v[36:37], v[30:31], v[36:37]
	s_nop 0
	ds_read_b128 v[18:21], v176
	s_waitcnt lgkmcnt(0)
	v_mfma_f32_16x16x32_bf16 v[18:21], v[244:247], v[18:21], 0
	s_nop 1
	v_max_f32_e32 v40, 0, v14
	v_max_f32_e32 v41, 0, v15
	v_max_f32_e32 v14, 0, v16
	v_mul_f32_e32 v42, v38, v14
	s_nop 0
	v_max_f32_e32 v44, 0, v17
	v_mfma_f32_16x16x32_bf16 v[14:17], v[248:251], v[22:25], v[18:21]
	ds_read_b128 v[22:25], v157
	v_mov_b32_e32 v35, v36
	v_mov_b32_e32 v29, v37
	ds_read_b128 v[18:21], v158
	s_waitcnt lgkmcnt(0)
	v_mfma_f32_16x16x32_bf16 v[18:21], v[244:247], v[18:21], 0
	s_nop 1
	v_max_f32_e32 v46, 0, v14
	v_max_f32_e32 v47, 0, v15
	v_max_f32_e32 v14, 0, v16
	v_mul_f32_e32 v48, v39, v14
	s_nop 0
	v_max_f32_e32 v45, 0, v17
	v_mfma_f32_16x16x32_bf16 v[14:17], v[248:251], v[22:25], v[18:21]
	ds_read_b128 v[22:25], v155
	v_pk_mul_f32 v[44:45], v[38:39], v[44:45]
	s_nop 0
	ds_read_b128 v[18:21], v156
	s_waitcnt lgkmcnt(0)
	v_mfma_f32_16x16x32_bf16 v[18:21], v[244:247], v[18:21], 0
	s_nop 1
	v_max_f32_e32 v52, 0, v14
	v_max_f32_e32 v53, 0, v15
	v_max_f32_e32 v14, 0, v16
	v_mul_f32_e32 v156, v50, v14
	s_nop 0
	v_max_f32_e32 v158, 0, v17
	v_mfma_f32_16x16x32_bf16 v[14:17], v[248:251], v[22:25], v[18:21]
	ds_read_b128 v[22:25], v153
	v_mov_b32_e32 v43, v44
	v_mov_b32_e32 v49, v45
	ds_read_b128 v[18:21], v154
	s_waitcnt lgkmcnt(0)
	v_mfma_f32_16x16x32_bf16 v[18:21], v[244:247], v[18:21], 0
	s_nop 1
	v_max_f32_e32 v160, 0, v14
	v_max_f32_e32 v161, 0, v15
	v_max_f32_e32 v14, 0, v16
	v_mul_f32_e32 v154, v51, v14
	s_nop 0
	v_max_f32_e32 v159, 0, v17
	v_mfma_f32_16x16x32_bf16 v[14:17], v[248:251], v[22:25], v[18:21]
	ds_read_b128 v[22:25], v150
	v_pk_mul_f32 v[158:159], v[50:51], v[158:159]
	s_nop 0
	ds_read_b128 v[18:21], v152
	s_waitcnt lgkmcnt(0)
	v_mfma_f32_16x16x32_bf16 v[6:9], v[244:247], v[18:21], 0
	s_nop 1
	s_nop 0
	v_max_f32_e32 v18, 0, v17
	s_nop 0
	v_mfma_f32_16x16x32_bf16 v[2:5], v[248:251], v[22:25], v[6:9]
	s_nop 0
	v_max_f32_e32 v14, 0, v14
	v_max_f32_e32 v15, 0, v15
	v_pk_fma_f32 v[8:9], v[30:31], v[32:33], 0 op_sel_hi:[0,1,0]
	s_nop 0
	s_nop 2
	v_max_f32_e32 v19, 0, v5
	v_pk_mul_f32 v[6:7], v[162:163], v[18:19]
	v_mov_b32_e32 v18, v31
	v_pk_fma_f32 v[8:9], v[18:19], v[26:27], v[8:9] op_sel_hi:[0,1,1]
	v_pk_fma_f32 v[8:9], v[38:39], v[40:41], v[8:9] op_sel_hi:[0,1,1]
	v_mov_b32_e32 v18, v39
	v_pk_fma_f32 v[8:9], v[18:19], v[46:47], v[8:9] op_sel_hi:[0,1,1]
	v_pk_fma_f32 v[8:9], v[50:51], v[52:53], v[8:9] op_sel_hi:[0,1,1]
	v_mov_b32_e32 v18, v51
	v_pk_fma_f32 v[8:9], v[18:19], v[160:161], v[8:9] op_sel_hi:[0,1,1]
	v_max_f32_e32 v2, 0, v2
	v_max_f32_e32 v3, 0, v3
	v_pk_fma_f32 v[8:9], v[162:163], v[14:15], v[8:9] op_sel_hi:[0,1,1]
	v_mov_b32_e32 v14, v163
	v_pk_fma_f32 v[2:3], v[14:15], v[2:3], v[8:9] op_sel_hi:[0,1,1]
	v_and_b32_e32 v9, 0x7fffffff, v3
	v_and_b32_e32 v8, 0x7fffffff, v2
	v_xor_b32_e32 v5, -1, v3
	v_pk_add_f32 v[8:9], v[8:9], 0 neg_lo:[1,1] neg_hi:[1,1]
	v_cmp_gt_i32_e32 vcc, 0, v3
	v_xor_b32_e32 v15, -1, v2
	v_mov_b32_e32 v157, v158
	v_cndmask_b32_e32 v14, v9, v5, vcc
	v_cmp_gt_i32_e32 vcc, 0, v2
	v_pk_add_f32 v[2:3], v[34:35], 0 op_sel_hi:[1,0]
	v_max_f32_e32 v16, 0, v16
	v_pk_add_f32 v[2:3], v[2:3], v[28:29]
	v_pk_add_f32 v[2:3], v[2:3], v[42:43]
	v_mov_b32_e32 v155, v159
	v_pk_add_f32 v[2:3], v[2:3], v[48:49]
	v_mul_f32_e32 v16, v162, v16
	v_pk_add_f32 v[2:3], v[2:3], v[156:157]
	v_max_f32_e32 v4, 0, v4
	v_pk_add_f32 v[2:3], v[2:3], v[154:155]
	v_mov_b32_e32 v17, v6
	v_mul_f32_e32 v4, v163, v4
	v_pk_add_f32 v[2:3], v[2:3], v[16:17]
	v_mov_b32_e32 v5, v7
	v_pk_add_f32 v[2:3], v[2:3], v[4:5]
	v_cndmask_b32_e32 v15, v8, v15, vcc
	v_and_b32_e32 v5, 0x7fffffff, v3
	v_and_b32_e32 v4, 0x7fffffff, v2
	v_xor_b32_e32 v6, -1, v3
	v_pk_add_f32 v[4:5], v[4:5], 0 neg_lo:[1,1] neg_hi:[1,1]
	v_cmp_gt_i32_e32 vcc, 0, v3
	v_xor_b32_e32 v7, -1, v2
	s_nop 0
	v_cndmask_b32_e32 v16, v5, v6, vcc
	v_cmp_gt_i32_e32 vcc, 0, v2
	v_lshrrev_b32_e32 v2, 24, v15
	v_lshl_add_u32 v2, v2, 6, v0
	ds_add_u32 v2, v205 offset:16384
	v_lshrrev_b32_e32 v2, 24, v14
	v_cndmask_b32_e32 v17, v4, v7, vcc
	v_lshl_add_u32 v2, v2, 6, v0
	ds_add_u32 v2, v205 offset:16384
	v_lshrrev_b32_e32 v2, 24, v17
	v_lshl_add_u32 v2, v2, 6, v0
	ds_add_u32 v2, v205 offset:16384
	v_lshrrev_b32_e32 v2, 24, v16
	v_lshl_add_u32 v2, v2, 6, v0
	ds_add_u32 v2, v205 offset:16384
